# baseline (speedup 1.0000x reference)
; __device__ __forceinline__ void flash32L(const bf16x8 (&qf)[4], const char* ldsK, const char* ldsV, int sub, int fr, int fq, ...
;   f32x4 s0 = {0.f, 0.f, 0.f, 0.f}, s1 = {0.f, 0.f, 0.f, 0.f};
;   const char* kr = ldsK + (sub * 32 + fr) * 256;
; #pragma unroll
;   for (int ks = 0; ks < 4; ++ks) {
;     const int slot = ((ks * 4 + fq) ^ fr) * 16;
;     bf16x8 k0 = *reinterpret_cast<const bf16x8*>(kr + slot), k1 = *reinterpret_cast<const bf16x8*>(kr + 16 * 256 + slot);
;     s0 = MFMA(k0, qf[ks], s0);
;     s1 = MFMA(k1, qf[ks], s1);
;   }
;   float b0 = -sl * (float)dist0;
;   b0 = sel ? b0 : -1e30f;
;   const float b1 = b0 + 16.0f * sl;
;   float sv[8];
; #pragma unroll
;   for (int j = 0; j < 4; ++j) {
;     sv[j] = fmaf(s0[j], sc, b0 + slj[j]);
;     sv[4 + j] = fmaf(s1[j], sc, b1 + slj[j]);
;   }
;   if (bnd) {
; #pragma unroll
;     for (int j = 0; j < 4; ++j) {
; __device__ __forceinline__ void phase_xatt(const Params& p, char* lds) {
;     ...
;   for (int item = bid; item < 256; item += gridDim.x) {
;     const int tt = item & 15, hd = (item >> 4) & 3, b = item >> 6;
;     const int t = b * 2048 + tt * 128 + w * 16 + fr;
;     const u16* kbase = WSP(u16, WS_XKV) + (long)b * 256 * 1024 + hd * 128;
;     const u16* vbase = WSP(u16, WS_XVT) + ((long)(b * 512 + hd * 128)) * 256;
;     __syncthreads();
; #pragma unroll
;     for (int j = 0; j < 4; ++j) {
;       const u16* kb = uni_ptr(kbase + (long)j * 64 * 1024);
;       const u16* vb = uni_ptr(vbase + j * 64);
;       const unsigned dst = ldsb + j * NSA_STAGE_B;
;       glds16(kb, kvo[0], dst);
;       glds16(kb, kvo[1], dst + 8192);
;       glds16(vb, vvo[0], dst + 16384);
;       glds16(vb, vvo[1], dst + 16384 + 8192);
;     }
;     bf16x8 qf[4];
; #pragma unroll
;     for (int ks = 0; ks < 4; ++ks) qf[ks] = ld8(WSP(u16, WS_QX) + (long)t * 512 + hd * 128 + ks * 32 + fq * 8);
;     f32x4 o[8];
; #pragma unroll
;     for (int dt = 0; dt < 8; ++dt) o[dt] = f32x4{0.f, 0.f, 0.f, 0.f};
;     float m = -1e30f, ls = 0.f;
;     asm volatile("s_waitcnt vmcnt(0)" ::: "memory");
;     __syncthreads();
; #pragma unroll
;     for (int j = 0; j < 4; ++j) {
;       const char* sK = lds + j * NSA_STAGE_B;
; #pragma unroll
;       for (int sub = 0; sub < 2; ++sub)
;         flash32L(qf, sK, sK + 16384, sub, fr, fq, 0.08838834764831845f * LOG2E, 0.f, slj, 0, true, false, 0x7fffffff, o, m, ls);
.LBB0_30:
	s_ashr_i32 s30, s0, 6
	s_ashr_i32 s31, s30, 31
	s_and_b32 s29, s28, 0x780
	s_lshl_b64 s[34:35], s[30:31], 19
	s_add_u32 s31, s23, s34
	s_addc_u32 s35, s24, s35
	s_and_b32 s36, s27, 0x180
	s_lshl_b32 s96, s36, 1
	s_add_u32 s34, s31, s96
	s_addc_u32 s35, s35, 0
	s_lshl_b32 s31, s30, 9
	s_or_b32 s36, s31, s36
	s_ashr_i32 s37, s36, 31
	s_lshl_b64 s[36:37], s[36:37], 9
	s_add_u32 s36, s25, s36
	s_addc_u32 s37, s26, s37
	s_barrier
	s_mov_b32 s31, m0
	s_mov_b32 m0, s1
	s_nop 0
	global_load_lds_dwordx4 v71, s[34:35]
	s_mov_b32 m0, s31
	s_add_u32 s38, s34, 0x20000
	s_mov_b32 s31, m0
	s_mov_b32 m0, s2
	s_nop 0
	global_load_lds_dwordx4 v75, s[34:35]
	s_mov_b32 m0, s31
	s_addc_u32 s39, s35, 0
	s_mov_b32 s31, m0
	s_mov_b32 m0, s3
	s_nop 0
	global_load_lds_dwordx4 v73, s[36:37]
	s_mov_b32 m0, s31
	s_add_u32 s40, s36, 0x80
	s_mov_b32 s31, m0
	s_mov_b32 m0, s10
	s_nop 0
	global_load_lds_dwordx4 v77, s[36:37]
	s_mov_b32 m0, s31
	s_addc_u32 s41, s37, 0
	s_mov_b32 s31, m0
	s_mov_b32 m0, s11
	s_nop 0
	global_load_lds_dwordx4 v71, s[38:39]
	s_mov_b32 m0, s31
	v_cmp_lt_i32_e32 vcc, v177, v180
	s_mov_b32 s31, m0
	s_mov_b32 m0, s12
	s_nop 0
	global_load_lds_dwordx4 v75, s[38:39]
	s_mov_b32 m0, s31
	s_add_u32 s38, s34, 0x40000
	s_mov_b32 s31, m0
	s_mov_b32 m0, s13
	s_nop 0
	global_load_lds_dwordx4 v73, s[40:41]
	s_mov_b32 m0, s31
	s_addc_u32 s39, s35, 0
	s_mov_b32 s31, m0
	s_mov_b32 m0, s14
	s_nop 0
	global_load_lds_dwordx4 v77, s[40:41]
	s_mov_b32 m0, s31
	s_add_u32 s40, s36, 0x100
	s_addc_u32 s41, s37, 0
	s_add_u32 s34, s34, 0x60000
	s_addc_u32 s35, s35, 0
	s_add_u32 s36, s36, 0x180
	s_mov_b32 s31, m0
	s_mov_b32 m0, s15
	s_nop 0
	global_load_lds_dwordx4 v71, s[38:39]
	s_mov_b32 m0, s31
	s_addc_u32 s37, s37, 0
	s_lshl_b32 s30, s30, 11
	s_mov_b32 s31, m0
	s_mov_b32 m0, s16
	s_nop 0
	global_load_lds_dwordx4 v75, s[38:39]
	s_mov_b32 m0, s31
	s_or_b32 s29, s30, s29
	s_mov_b32 s31, m0
	s_mov_b32 m0, s17
	s_nop 0
	global_load_lds_dwordx4 v73, s[40:41]
	s_mov_b32 m0, s31
	v_add_u32_e32 v2, s29, v79
	s_mov_b32 s31, m0
	s_mov_b32 m0, s18
	s_nop 0
	global_load_lds_dwordx4 v77, s[40:41]
	s_mov_b32 m0, s31
	v_ashrrev_i32_e32 v3, 31, v2
	s_mov_b32 s31, m0
	s_mov_b32 m0, s19
	s_nop 0
	global_load_lds_dwordx4 v71, s[34:35]
	s_mov_b32 m0, s31
	v_lshlrev_b64 v[68:69], 10, v[2:3]
	s_mov_b32 s31, m0
	s_mov_b32 m0, s20
	s_nop 0
	global_load_lds_dwordx4 v75, s[34:35]
	s_mov_b32 m0, s31
	v_lshl_add_u64 v[2:3], s[6:7], 0, v[68:69]
	s_mov_b32 s31, m0
	s_mov_b32 m0, s21
	s_nop 0
	global_load_lds_dwordx4 v73, s[36:37]
	s_mov_b32 m0, s31
	v_lshl_add_u64 v[2:3], v[2:3], 0, s[96:97]
	s_mov_b32 s31, m0
	s_mov_b32 m0, s22
	s_nop 0
	global_load_lds_dwordx4 v77, s[36:37]
	s_mov_b32 m0, s31
	v_lshl_add_u64 v[2:3], v[2:3], 0, v[66:67]
	global_load_dwordx4 v[14:17], v[2:3], off
	global_load_dwordx4 v[10:13], v[2:3], off offset:64
	global_load_dwordx4 v[6:9], v[2:3], off offset:128
	s_nop 0
	global_load_dwordx4 v[2:5], v[2:3], off offset:192
	v_cndmask_b32_e32 v18, v176, v177, vcc
	v_cmp_lt_i32_e32 vcc, v179, v180
	v_lshlrev_b32_e32 v101, 2, v18
	s_waitcnt vmcnt(0)
	s_waitcnt lgkmcnt(0)
	v_cndmask_b32_e32 v18, v176, v179, vcc
	s_barrier
	v_lshlrev_b32_e32 v100, 2, v18
	ds_read_b128 v[18:21], v94
	ds_read_b128 v[22:25], v94 offset:4096
	ds_read_b128 v[26:29], v95
	ds_read_b128 v[30:33], v95 offset:4096
	s_waitcnt vmcnt(0) lgkmcnt(0)
	v_mfma_f32_16x16x32_bf16 v[18:21], v[18:21], v[14:17], 0
	v_mfma_f32_16x16x32_bf16 v[22:25], v[22:25], v[14:17], 0
	v_mfma_f32_16x16x32_bf16 v[18:21], v[26:29], v[10:13], v[18:21]
	v_mfma_f32_16x16x32_bf16 v[22:25], v[30:33], v[10:13], v[22:25]
	ds_read_b128 v[26:29], v96
	ds_read_b128 v[30:33], v96 offset:4096
	s_waitcnt lgkmcnt(1)
	v_mfma_f32_16x16x32_bf16 v[18:21], v[26:29], v[6:9], v[18:21]
	s_waitcnt lgkmcnt(0)
	v_mfma_f32_16x16x32_bf16 v[22:25], v[30:33], v[6:9], v[22:25]
	ds_read_b128 v[26:29], v97
	ds_read_b128 v[30:33], v97 offset:4096
	s_waitcnt lgkmcnt(0)
	v_mfma_f32_16x16x32_bf16 v[22:25], v[30:33], v[2:5], v[22:25]
	v_mfma_f32_16x16x32_bf16 v[18:21], v[26:29], v[2:5], v[18:21]
	s_nop 6
	v_fma_f32 v24, v24, s42, 0
	v_fma_f32 v25, v25, s42, 0
	v_fma_f32 v22, v22, s42, 0
	v_fma_f32 v23, v23, s42, 0
	v_max_f32_e32 v28, v24, v25
	v_fma_f32 v18, v18, s42, 0
	v_fma_f32 v19, v19, s42, 0
	v_fma_f32 v20, v20, s42, 0
	v_fma_f32 v21, v21, s42, 0
	v_max_f32_e32 v26, v18, v19
	v_max_f32_e32 v27, v20, v21
	v_max3_f32 v28, v22, v23, v28
	v_max3_f32 v26, v26, v27, v28
	ds_bpermute_b32 v27, v101, v26
	s_waitcnt lgkmcnt(0)
	v_max_f32_e32 v27, v27, v27
	v_max_f32_e32 v26, v26, v27
	ds_bpermute_b32 v27, v100, v26
	s_waitcnt lgkmcnt(0)
	v_max_f32_e32 v27, v27, v27
	v_max_f32_e32 v26, v26, v27
	v_max_f32_e32 v58, 0xf149f2ca, v26
	v_max_f32_e32 v26, 0xefa18f08, v26
	v_sub_f32_e32 v18, v18, v26
	v_exp_f32_e32 v102, v18
	v_sub_f32_e32 v18, v19, v26
	v_exp_f32_e32 v103, v18
	v_sub_f32_e32 v18, v20, v26
	v_exp_f32_e32 v104, v18
	v_sub_f32_e32 v18, v21, v26
	v_exp_f32_e32 v105, v18
	v_sub_f32_e32 v18, v22, v26
	v_exp_f32_e32 v106, v18
	v_sub_f32_e32 v18, v23, v26
	v_exp_f32_e32 v107, v18
	v_sub_f32_e32 v18, v24, v26
	v_sub_f32_e32 v27, 0xf149f2ca, v58
	v_exp_f32_e32 v108, v18
	v_sub_f32_e32 v18, v25, v26
	v_exp_f32_e32 v109, v18
	v_exp_f32_e32 v18, v27
	v_cvt_pk_bf16_f32 v26,v102,v103
	v_cvt_pk_bf16_f32 v27,v104,v105
	v_cvt_pk_bf16_f32 v28,v106,v107
	v_cvt_pk_bf16_f32 v29,v108,v109
	s_nop 0
	v_mul_f32_e32 v110, 0, v18
	v_cmp_neq_f32_e32 vcc, 1.0, v18
	ds_read2st64_b64 v[18:21], v98 offset0:32 offset1:36
	ds_read2st64_b64 v[34:37], v99 offset0:32 offset1:36
	s_cmp_eq_u64 vcc, 0
	s_cselect_b64 s[30:31], -1, 0
	v_cndmask_b32_e64 v30, v110, 0, s[30:31]
	v_mov_b32_e32 v31, v30
	s_waitcnt lgkmcnt(0)
; __device__ __forceinline__ void flash32L(const bf16x8 (&qf)[4], const char* ldsK, const char* ldsV, int sub, int fr, int fq, ...
;   f32x4 s0 = {0.f, 0.f, 0.f, 0.f}, s1 = {0.f, 0.f, 0.f, 0.f};
;   const char* kr = ldsK + (sub * 32 + fr) * 256;
; #pragma unroll
;   for (int ks = 0; ks < 4; ++ks) {
;     const int slot = ((ks * 4 + fq) ^ fr) * 16;
;     bf16x8 k0 = *reinterpret_cast<const bf16x8*>(kr + slot), k1 = *reinterpret_cast<const bf16x8*>(kr + 16 * 256 + slot);
;     s0 = MFMA(k0, qf[ks], s0);
;     s1 = MFMA(k1, qf[ks], s1);
;   }
;   float b0 = -sl * (float)dist0;
;   b0 = sel ? b0 : -1e30f;
;   const float b1 = b0 + 16.0f * sl;
;   float sv[8];
; #pragma unroll
;   for (int j = 0; j < 4; ++j) {
;     sv[j] = fmaf(s0[j], sc, b0 + slj[j]);
;     sv[4 + j] = fmaf(s1[j], sc, b1 + slj[j]);
;   }
;   if (bnd) {
; #pragma unroll
;     for (int j = 0; j < 4; ++j) {
;       const unsigned d0 = (unsigned)(dist0 - j), d1 = (unsigned)(dist0 - 16 - j);
;       sv[j] = d0 < (unsigned)wlim ? sv[j] : -1e30f;
;       sv[4 + j] = d1 < (unsigned)wlim ? sv[4 + j] : -1e30f;
;     }
;   }
;   float tmax = fmaxf(fmaxf(fmaxf(sv[0], sv[1]), fmaxf(sv[2], sv[3])), fmaxf(fmaxf(sv[4], sv[5]), fmaxf(sv[6], sv[7])));
;   tmax = fmaxf(tmax, __shfl_xor(tmax, 16));
;   tmax = fmaxf(tmax, __shfl_xor(tmax, 32));
;   const float mn = fmaxf(m, tmax);
;   const float alpha = fexp2(m - mn);
;   const float mc = fmaxf(mn, -1e29f);
;   m = mn;
;   float pv[8]; float ps = 0.f;
; #pragma unroll
;   for (int i = 0; i < 8; ++i) { pv[i] = fexp2(sv[i] - mc); ps += pv[i]; }
;   lsum = lsum * alpha + ps;
;   bf16x8 pf = mk8(u32x4{pk2(pv[0], pv[1]), pk2(pv[2], pv[3]), pk2(pv[4], pv[5]), pk2(pv[6], pv[7])});
;   if (__any(alpha != 1.0f)) {
; #pragma unroll
;     for (int dt = 0; dt < 8; ++dt)
; #pragma unroll
;       for (int j = 0; j < 4; ++j) o[dt][j] *= alpha;
;   }
;   const int c0 = (((sub * 4 + (fq >> 1)) ^ (fr & 7)) * 16) + (fq & 1) * 8;
;   const int c1 = (((sub * 4 + 2 + (fq >> 1)) ^ (fr & 7)) * 16) + (fq & 1) * 8;
;   const char* vr = ldsV + fr * 128;
; #pragma unroll
;   for (int dt = 0; dt < 8; ++dt) {
;     u32x2 a = *reinterpret_cast<const u32x2*>(vr + dt * 2048 + c0), b2 = *reinterpret_cast<const u32x2*>(vr + dt * 2048 + c1);
;     bf16x8 vf = mk8(u32x4{a[0], a[1], b2[0], b2[1]});
;     o[dt] = MFMA(vf, pf, o[dt]);
;   }
	v_mov_b32_e32 v24, v34
	v_mov_b32_e32 v25, v35
	v_mov_b32_e32 v34, v20
	v_mov_b32_e32 v35, v21
	v_mov_b32_e32 v32, v30
	v_mov_b32_e32 v33, v30
	v_mov_b32_e32 v22, v18
	v_mov_b32_e32 v23, v19
	v_mfma_f32_16x16x32_bf16 v[18:21], v[34:37], v[26:29], v[30:33]
	ds_read2st64_b64 v[36:39], v98 offset0:40 offset1:44
	ds_read2st64_b64 v[40:43], v99 offset0:40 offset1:44
	s_waitcnt lgkmcnt(1)
	v_mov_b32_e32 v34, v36
	v_mov_b32_e32 v35, v37
	s_waitcnt lgkmcnt(0)
	v_mov_b32_e32 v36, v40
	v_mov_b32_e32 v37, v41
	v_mov_b32_e32 v40, v38
	v_mov_b32_e32 v41, v39
	v_mfma_f32_16x16x32_bf16 v[22:25], v[22:25], v[26:29], v[30:33]
	s_nop 0
	v_mfma_f32_16x16x32_bf16 v[50:53], v[40:43], v[26:29], v[30:33]
	ds_read2st64_b64 v[38:41], v98 offset0:48 offset1:52
	ds_read2st64_b64 v[42:45], v99 offset0:48 offset1:52
	s_waitcnt lgkmcnt(1)
	v_mov_b32_e32 v46, v38
	v_mov_b32_e32 v47, v39
	s_waitcnt lgkmcnt(0)
	v_mov_b32_e32 v48, v42
	v_mov_b32_e32 v49, v43
	v_mov_b32_e32 v42, v40
	v_mov_b32_e32 v43, v41
	ds_read2st64_b64 v[38:41], v98 offset0:56 offset1:60
	ds_read2st64_b64 v[60:63], v99 offset0:56 offset1:60
	v_mfma_f32_16x16x32_bf16 v[54:57], v[46:49], v[26:29], v[30:33]
	v_mfma_f32_16x16x32_bf16 v[46:49], v[42:45], v[26:29], v[30:33]
	s_waitcnt lgkmcnt(1)
	v_mov_b32_e32 v42, v38
	v_mov_b32_e32 v43, v39
	s_waitcnt lgkmcnt(0)
	v_mov_b32_e32 v44, v60
	v_mov_b32_e32 v45, v61
	v_mov_b32_e32 v60, v40
	v_mov_b32_e32 v61, v41
	v_mfma_f32_16x16x32_bf16 v[34:37], v[34:37], v[26:29], v[30:33]
	v_mfma_f32_16x16x32_bf16 v[42:45], v[42:45], v[26:29], v[30:33]
	v_mfma_f32_16x16x32_bf16 v[38:41], v[60:63], v[26:29], v[30:33]
	ds_read_b128 v[26:29], v94 offset:8192
	s_nop 1
	ds_read_b128 v[30:33], v94 offset:12288
	ds_read_b128 v[60:63], v95 offset:8192
	ds_read_b128 v[112:115], v95 offset:12288
	s_waitcnt lgkmcnt(3)
	v_mfma_f32_16x16x32_bf16 v[26:29], v[26:29], v[14:17], 0
	s_waitcnt lgkmcnt(2)
	v_mfma_f32_16x16x32_bf16 v[30:33], v[30:33], v[14:17], 0
	s_waitcnt lgkmcnt(1)
	v_mfma_f32_16x16x32_bf16 v[26:29], v[60:63], v[10:13], v[26:29]
	s_waitcnt lgkmcnt(0)
	v_mfma_f32_16x16x32_bf16 v[30:33], v[112:115], v[10:13], v[30:33]
	ds_read_b128 v[60:63], v96 offset:8192
	ds_read_b128 v[112:115], v96 offset:12288
	s_waitcnt lgkmcnt(1)
	v_mfma_f32_16x16x32_bf16 v[26:29], v[60:63], v[6:9], v[26:29]
	s_waitcnt lgkmcnt(0)
	v_mfma_f32_16x16x32_bf16 v[30:33], v[112:115], v[6:9], v[30:33]
	ds_read_b128 v[60:63], v97 offset:8192
	ds_read_b128 v[112:115], v97 offset:12288
	s_waitcnt lgkmcnt(0)
	v_mfma_f32_16x16x32_bf16 v[30:33], v[112:115], v[2:5], v[30:33]
	v_mfma_f32_16x16x32_bf16 v[26:29], v[60:63], v[2:5], v[26:29]
	s_nop 6
	v_fma_f32 v32, v32, s42, 0
	v_fma_f32 v33, v33, s42, 0
	v_fma_f32 v30, v30, s42, 0
	v_fma_f32 v31, v31, s42, 0
	v_max_f32_e32 v61, v32, v33
	v_fma_f32 v26, v26, s42, 0
	v_fma_f32 v27, v27, s42, 0
	v_fma_f32 v28, v28, s42, 0
	v_fma_f32 v29, v29, s42, 0
	v_max_f32_e32 v59, v26, v27
	v_max_f32_e32 v60, v28, v29
	v_max3_f32 v61, v30, v31, v61
	v_max3_f32 v59, v59, v60, v61
	ds_bpermute_b32 v60, v101, v59
	s_waitcnt lgkmcnt(0)
	v_max_f32_e32 v60, v60, v60
	v_max_f32_e32 v59, v59, v60
	ds_bpermute_b32 v60, v100, v59
	s_waitcnt lgkmcnt(0)
	v_max3_f32 v64, v58, v59, v60
	v_max_f32_e32 v59, 0xefa18f08, v64
	v_sub_f32_e32 v26, v26, v59
	v_exp_f32_e32 v111, v26
	v_sub_f32_e32 v26, v27, v59
	v_exp_f32_e32 v112, v26
	v_sub_f32_e32 v26, v28, v59
	v_exp_f32_e32 v113, v26
	v_sub_f32_e32 v26, v29, v59
	v_exp_f32_e32 v114, v26
	v_sub_f32_e32 v26, v30, v59
	v_exp_f32_e32 v115, v26
	v_sub_f32_e32 v26, v31, v59
	v_sub_f32_e32 v58, v58, v64
	v_exp_f32_e32 v116, v26
	v_sub_f32_e32 v26, v32, v59
	v_exp_f32_e32 v117, v26
	v_sub_f32_e32 v26, v33, v59
	v_exp_f32_e32 v70, v58
	v_exp_f32_e32 v118, v26
	v_cvt_pk_bf16_f32 v58,v111,v112
	v_cvt_pk_bf16_f32 v59,v113,v114
	v_cmp_neq_f32_e32 vcc, 1.0, v70
	v_cvt_pk_bf16_f32 v60,v115,v116
	v_cvt_pk_bf16_f32 v61,v117,v118
	s_cbranch_vccz .LBB0_32
	v_pk_mul_f32 v[22:23], v[22:23], v[70:71] op_sel_hi:[1,0]
	v_pk_mul_f32 v[24:25], v[24:25], v[70:71] op_sel_hi:[1,0]
	v_pk_mul_f32 v[18:19], v[18:19], v[70:71] op_sel_hi:[1,0]
	v_pk_mul_f32 v[20:21], v[20:21], v[70:71] op_sel_hi:[1,0]
	v_pk_mul_f32 v[34:35], v[34:35], v[70:71] op_sel_hi:[1,0]
	v_pk_mul_f32 v[36:37], v[36:37], v[70:71] op_sel_hi:[1,0]
	v_pk_mul_f32 v[50:51], v[50:51], v[70:71] op_sel_hi:[1,0]
	v_pk_mul_f32 v[52:53], v[52:53], v[70:71] op_sel_hi:[1,0]
	v_pk_mul_f32 v[54:55], v[54:55], v[70:71] op_sel_hi:[1,0]
	v_pk_mul_f32 v[56:57], v[56:57], v[70:71] op_sel_hi:[1,0]
	v_pk_mul_f32 v[46:47], v[46:47], v[70:71] op_sel_hi:[1,0]
	v_pk_mul_f32 v[48:49], v[48:49], v[70:71] op_sel_hi:[1,0]
	v_pk_mul_f32 v[42:43], v[42:43], v[70:71] op_sel_hi:[1,0]
	v_pk_mul_f32 v[44:45], v[44:45], v[70:71] op_sel_hi:[1,0]
	v_pk_mul_f32 v[38:39], v[38:39], v[70:71] op_sel_hi:[1,0]
	v_pk_mul_f32 v[40:41], v[40:41], v[70:71] op_sel_hi:[1,0]

; __device__ __forceinline__ void nsa_item2(const Params& p, int item, char* lds, unsigned* lds_um, int tid) {
;   const int w = tid >> 6, l = tid & 63, fr = l & 15, fq = l >> 4;
;   const int hp = w & 1, tq = w >> 1;
;   const int tile = 31 - (item >> 4), bg = item & 15, b = bg >> 2, g = bg & 3;
;   const int ha = g * 4 + 2 * hp, hb = ha + 1;
;   const int t0 = tile * 64 + tq * 16, t = t0 + fr;
;   const float sc = 0.08838834764831845f * LOG2E;
;   const float sla = exp2f(-0.5f * (float)(ha + 1)) * LOG2E, slb = exp2f(-0.5f * (float)(hb + 1)) * LOG2E;
;   float* lds_imp = reinterpret_cast<float*>(lds + NSA2_IMP_OFF);
;   const u16* proj = WSP(u16, WS_PROJB) + (long)b * 2048 * INWP;
;   const unsigned ldsb = (unsigned)(size_t)(__attribute__((address_space(3))) char*)lds + __builtin_amdgcn_readfirstlane(w) * 1024;
;   {
;     const u16* kcg = uni_ptr(WSP(u16, WS_KC) + (long)bg * 128 * 128);
;     const u16* vcg = uni_ptr(WSP(u16, WS_VCT) + (long)bg * 128 * 128);
; #pragma unroll
;     for (int q = 0; q < 4; ++q) {
;       const int ci = w + 8 * q;
;       const int row = 4 * ci + (l >> 4), slot = l & 15;
;       const unsigned off = (unsigned)row * 256u + (unsigned)((slot ^ (row & 15)) * 16);
;       glds16(kcg, off, ldsb + q * 8192);
;       glds16(vcg, off, ldsb + 32768 + q * 8192);
;     }
;   }
;   bf16x8 qa[4], qb[4];
; #pragma unroll
;   for (int ks = 0; ks < 4; ++ks) {
;     qa[ks] = ld8(proj + (long)t * INWP + OFF_NQ + ha * 128 + ks * 32 + fq * 8);
;     qb[ks] = ld8(proj + (long)t * INWP + OFF_NQ + hb * 128 + ks * 32 + fq * 8);
;   }
;   const u16* grow = proj + (long)t * INWP + OFF_GT + ha;
;   const float gca = 1.0f / (1.0f + __expf(-bflo((unsigned)grow[0]))), gcb = 1.0f / (1.0f + __expf(-bflo((unsigned)grow[1])));
;   const float gsa = 1.0f / (1.0f + __expf(-bflo((unsigned)grow[16]))), gsb = 1.0f / (1.0f + __expf(-bflo((unsigned)grow[17])));
;   const float gwa = 1.0f / (1.0f + __expf(-bflo((unsigned)grow[32]))), gwb = 1.0f / (1.0f + __expf(-bflo((unsigned)grow[33])));
;   float* Pa = WSP(float, WS_RETO) + ((long)(b * 2048 + t)) * 2048 + ha * 128 + fq * 4;
;   float* Pb = Pa + 128;
;   if (tid == 0) *lds_um = 0u;
;   asm volatile("s_waitcnt vmcnt(0)" ::: "memory");
;   __syncthreads();
;   nsa_cmp_head(qa, lds, lds + 32768, t, l, fr, fq, sc, sla, gca, lds_imp + ((tq * 4 + 2 * hp) * 16 + fr) * 32, Pa);
.LBB0_63:
	s_or_b64 exec, exec, s[0:1]
	s_waitcnt lgkmcnt(0)
	s_barrier
	ds_read_b32 v0, v1 offset:32
	s_mov_b64 s[0:1], -1
	s_waitcnt lgkmcnt(0)
	v_readfirstlane_b32 s78, v0
	s_cmpk_gt_i32 s78, 0x1ff
	s_cbranch_scc1 .LBB0_60
	v_mov_b32_e32 v119, v136
	s_ashr_i32 s74, s78, 4
	v_ashrrev_i32_e32 v122, 6, v119
	v_lshlrev_b32_e32 v0, 1, v122
	s_sub_i32 s4, 31, s74
	s_and_b32 s1, s78, 3
	v_and_b32_e32 v113, 2, v0
	v_ashrrev_i32_e32 v112, 7, v119
	v_writelane_b32 v247, s1, 11
	v_lshl_or_b32 v108, s1, 2, v113
	s_lshl_b32 s1, s4, 6
	v_writelane_b32 v247, s1, 12
	v_lshl_add_u32 v138, v112, 4, s1
	v_readfirstlane_b32 s1, v122
	s_and_b32 s0, s78, 15
	s_lshl_b32 s77, s1, 10
	v_bfe_u32 v118, v119, 4, 2
	s_bfe_u32 s7, s78, 0x20002
	s_add_i32 s77, s77, 64
	s_lshl_b32 s2, s0, 15
	v_lshlrev_b32_e32 v0, 2, v122
	s_add_u32 s0, s85, s2
	v_or_b32_e32 v123, v0, v118
	v_bitop3_b32 v0, v0, v119, v118 bitop3:0x36
	s_addc_u32 s1, s76, 0
	v_lshlrev_b32_e32 v2, 8, v123
	v_lshlrev_b32_e32 v0, 4, v0
	s_movk_i32 s6, 0xf0
	s_add_u32 s2, s75, s2
	v_and_or_b32 v0, v0, s6, v2
	s_mov_b32 s6, m0
	s_mov_b32 m0, s77
	s_nop 0
	global_load_lds_dwordx4 v0, s[0:1]
	s_mov_b32 m0, s6
	s_addc_u32 s3, s90, 0
	s_add_i32 s93, s77, 0x8000
	s_mov_b32 s6, m0
	s_mov_b32 m0, s93
	s_nop 0
	global_load_lds_dwordx4 v0, s[2:3]
	s_mov_b32 m0, s6
	v_add_u32_e32 v2, 0x2000, v0
	s_add_i32 s5, s77, 0x2000
	s_mov_b32 s6, m0
	s_mov_b32 m0, s5
	s_nop 0
	global_load_lds_dwordx4 v2, s[0:1]
	s_mov_b32 m0, s6
	v_writelane_b32 v247, s5, 13
	s_add_i32 s5, s77, 0xa000
	s_mov_b32 s6, m0
	s_mov_b32 m0, s5
	s_nop 0
	global_load_lds_dwordx4 v2, s[2:3]
	s_mov_b32 m0, s6
	v_writelane_b32 v247, s5, 14
	v_add_u32_e32 v2, 0x4000, v0
	s_add_i32 s5, s77, 0x4000
	s_mov_b32 s6, m0
	s_mov_b32 m0, s5
	s_nop 0
	global_load_lds_dwordx4 v2, s[0:1]
	s_mov_b32 m0, s6
	v_writelane_b32 v247, s5, 15
	s_add_i32 s5, s77, 0xc000
	s_mov_b32 s6, m0
	s_mov_b32 m0, s5
	s_nop 0
	global_load_lds_dwordx4 v2, s[2:3]
	s_mov_b32 m0, s6
	v_writelane_b32 v247, s5, 16
	v_add_u32_e32 v0, 0x6000, v0
	s_add_i32 s5, s77, 0x6000
	s_mov_b32 s6, m0
	s_mov_b32 m0, s5
	s_nop 0
	global_load_lds_dwordx4 v0, s[0:1]
	s_mov_b32 m0, s6
	s_add_i32 s1, s77, 0xe000
	s_mov_b32 s0, m0
	s_mov_b32 m0, s1
	s_nop 0
	global_load_lds_dwordx4 v0, s[2:3]
	s_mov_b32 m0, s0
	v_writelane_b32 v247, s5, 17
	s_mul_i32 s0, s7, 0x3500000
	v_writelane_b32 v247, s1, 18
	s_add_u32 s0, s91, s0
	v_and_b32_e32 v120, 15, v119
	v_writelane_b32 v247, s7, 19
	s_addc_u32 s1, s92, 0
	v_or_b32_e32 v139, v138, v120
	v_writelane_b32 v247, s0, 20
	v_lshlrev_b32_e32 v0, 8, v108
	v_or_b32_e32 v3, 1, v108
	v_mov_b64_e32 v[4:5], s[0:1]
	v_writelane_b32 v247, s1, 21
	v_mad_i64_i32 v[36:37], s[0:1], v139, s95, v[4:5]
	s_mov_b64 s[0:1], 0x4000
	s_nop 0
	v_lshl_add_u64 v[4:5], v[36:37], 0, s[0:1]
	v_lshl_add_u64 v[6:7], v[4:5], 0, v[0:1]
	v_and_b32_e32 v0, 48, v119
	v_lshl_add_u64 v[24:25], v[6:7], 0, v[0:1]
	v_lshlrev_b32_e32 v6, 8, v3
	v_mov_b32_e32 v7, v1
	v_lshl_add_u64 v[4:5], v[4:5], 0, v[6:7]
	v_lshl_add_u64 v[32:33], v[4:5], 0, v[0:1]
	global_load_dwordx4 v[4:7], v[24:25], off
	global_load_dwordx4 v[8:11], v[24:25], off offset:64
	global_load_dwordx4 v[12:15], v[32:33], off
	global_load_dwordx4 v[16:19], v[32:33], off offset:64
	global_load_dwordx4 v[20:23], v[24:25], off offset:128
	s_nop 0
	global_load_dwordx4 v[24:27], v[24:25], off offset:192
	s_nop 0
	global_load_dwordx4 v[28:31], v[32:33], off offset:128
	s_nop 0
	global_load_dwordx4 v[32:35], v[32:33], off offset:192
	v_lshlrev_b32_e32 v0, 1, v108
	v_lshl_add_u64 v[36:37], v[36:37], 0, v[0:1]
	s_mov_b64 s[0:1], 0x6800
	v_lshl_add_u64 v[38:39], v[36:37], 0, s[0:1]
	v_add_co_u32_e32 v36, vcc, 0x6000, v36
	s_nop 1
	v_addc_co_u32_e32 v37, vcc, 0, v37, vcc
	global_load_dword v2, v[36:37], off offset:2048
	global_load_dword v121, v[38:39], off offset:32
	global_load_dword v137, v[38:39], off offset:64
	v_cmp_eq_u32_e32 vcc, 0, v119
	s_and_saveexec_b64 s[0:1], vcc
	ds_write_b32 v1, v1 offset:48
	s_or_b64 exec, exec, s[0:1]
	v_xor_b32_e32 v0, v118, v120
	v_lshl_add_u32 v114, v120, 8, 64
	v_lshlrev_b32_e32 v140, 4, v0
	v_add_u32_e32 v107, v114, v140
	s_waitcnt vmcnt(0)
	s_waitcnt lgkmcnt(0)
	s_barrier
	ds_read_b128 v[36:39], v107
	v_bitop3_b32 v0, v118, v120, 4 bitop3:0x36
	v_lshlrev_b32_e32 v141, 4, v0
	v_add_u32_e32 v106, v114, v141
	ds_read_b128 v[40:43], v106
	s_waitcnt vmcnt(0) lgkmcnt(0)
	v_mfma_f32_16x16x32_bf16 v[36:39], v[36:39], v[4:7], 0
	v_bitop3_b32 v0, v118, v120, 8 bitop3:0x36
	v_lshlrev_b32_e32 v142, 4, v0
	v_add_u32_e32 v105, v114, v142
	v_mfma_f32_16x16x32_bf16 v[36:39], v[40:43], v[8:11], v[36:39]
	ds_read_b128 v[40:43], v105
	v_bitop3_b32 v0, v118, v120, 12 bitop3:0x36
	v_lshlrev_b32_e32 v143, 4, v0
	v_add_u32_e32 v104, v114, v143
	ds_read_b128 v[44:47], v104
	s_waitcnt lgkmcnt(1)
	v_mfma_f32_16x16x32_bf16 v[36:39], v[40:43], v[20:23], v[36:39]
	ds_read_b128 v[40:43], v107 offset:4096
	v_cvt_f32_ubyte0_e32 v0, v3
	v_mul_f32_e32 v3, -0.5, v0
	s_waitcnt lgkmcnt(1)
	v_mfma_f32_16x16x32_bf16 v[56:59], v[44:47], v[24:27], v[36:39]
	ds_read_b128 v[44:47], v105 offset:4096
	v_cmp_gt_f32_e32 vcc, s80, v3
	v_mov_b32_e32 v96, v134
	ds_read_b128 v[36:39], v106 offset:4096
	s_waitcnt lgkmcnt(2)
	v_mfma_f32_16x16x32_bf16 v[40:43], v[40:43], v[4:7], 0
	v_cndmask_b32_e32 v3, 0, v169, vcc
	v_fmac_f32_e32 v3, -0.5, v0
	v_exp_f32_e32 v0, v3
	s_waitcnt lgkmcnt(0)
	v_mfma_f32_16x16x32_bf16 v[36:39], v[36:39], v[8:11], v[40:43]
	s_nop 2
	ds_read_b128 v[40:43], v104 offset:4096
	v_cndmask_b32_e32 v3, 0, v168, vcc
	v_ldexp_f32 v3, v0, v3
	v_mfma_f32_16x16x32_bf16 v[36:39], v[44:47], v[20:23], v[36:39]
	ds_read_b128 v[44:47], v107 offset:8192
	v_add_u32_e32 v0, 2, v108
	v_cvt_f32_ubyte0_e32 v109, v0
	s_waitcnt lgkmcnt(1)
; __device__ __forceinline__ float bflo(unsigned u) { return __uint_as_float(u << 16); }
; #define MFMA(a, b, c) __builtin_amdgcn_mfma_f32_16x16x32_bf16((a), (b), (c), 0, 0, 0)
; __device__ __forceinline__ void nsa_cmp_head(const bf16x8 (&qf)[4], const char* ldsKC, const char* ldsVC, int t, int l, int fr, int fq,
;                                              float sc, float sl, float g_cmp, float* imp_dst, float* P) {
;   f32x4 s[8];
; #pragma unroll
;   for (int kt = 0; kt < 8; ++kt) {
;     s[kt] = f32x4{0.f, 0.f, 0.f, 0.f};
; #pragma unroll
;     for (int ks = 0; ks < 4; ++ks)
;       s[kt] = MFMA(*reinterpret_cast<const bf16x8*>(ldsKC + (16 * kt + fr) * 256 + (((ks * 4 + fq) ^ fr) * 16)), qf[ks], s[kt]);
;   }
; __device__ __forceinline__ void nsa_item2(const Params& p, int item, char* lds, unsigned* lds_um, int tid) {
;     ...
;   const float gca = 1.0f / (1.0f + __expf(-bflo((unsigned)grow[0]))), gcb = 1.0f / (1.0f + __expf(-bflo((unsigned)grow[1])));
;   const float gsa = 1.0f / (1.0f + __expf(-bflo((unsigned)grow[16]))), gsb = 1.0f / (1.0f + __expf(-bflo((unsigned)grow[17])));
;   const float gwa = 1.0f / (1.0f + __expf(-bflo((unsigned)grow[32]))), gwb = 1.0f / (1.0f + __expf(-bflo((unsigned)grow[33])));
	v_mfma_f32_16x16x32_bf16 v[52:55], v[40:43], v[24:27], v[36:39]
	s_nop 2
	ds_read_b128 v[36:39], v106 offset:8192
	ds_read_b128 v[40:43], v105 offset:8192
	ds_read_b128 v[48:51], v104 offset:8192
	ds_read_b128 v[64:67], v104 offset:16384
	s_waitcnt lgkmcnt(4)
	v_mfma_f32_16x16x32_bf16 v[44:47], v[44:47], v[4:7], 0
	ds_read_b128 v[60:63], v107 offset:12288
	ds_read_b128 v[68:71], v107 offset:20480
	v_mul_f32_e32 v0, -0.5, v109
	s_waitcnt lgkmcnt(5)
	v_mfma_f32_16x16x32_bf16 v[36:39], v[36:39], v[8:11], v[44:47]
	v_cmp_gt_f32_e32 vcc, s80, v0
	ds_read_b128 v[72:75], v107 offset:24576
	v_lshlrev_b32_e32 v0, 16, v2
	s_waitcnt lgkmcnt(5)
	v_mfma_f32_16x16x32_bf16 v[36:39], v[40:43], v[20:23], v[36:39]
	ds_read_b128 v[40:43], v106 offset:12288
	v_mul_f32_e32 v0, 0xbfb8aa3b, v0
	v_exp_f32_e32 v0, v0
	s_waitcnt lgkmcnt(5)
	v_mfma_f32_16x16x32_bf16 v[44:47], v[48:51], v[24:27], v[36:39]
	v_mul_f32_e32 v125, 0x3fb8aa3b, v3
	v_cndmask_b32_e32 v110, 0, v169, vcc
	v_add_f32_e32 v0, 1.0, v0
	ds_read_b128 v[36:39], v105 offset:12288
	s_waitcnt lgkmcnt(4)
	v_mfma_f32_16x16x32_bf16 v[48:51], v[60:63], v[4:7], 0
	ds_read_b128 v[60:63], v104 offset:12288
	v_div_scale_f32 v76, s[0:1], v0, v0, 1.0
	s_waitcnt lgkmcnt(2)
	v_mfma_f32_16x16x32_bf16 v[40:43], v[40:43], v[8:11], v[48:51]
	v_rcp_f32_e32 v77, v76
	v_cndmask_b32_e32 v111, 0, v168, vcc
	v_and_b32_e32 v2, 0xffff0000, v2
	s_nop 0
	ds_read_b128 v[48:51], v107 offset:16384
	s_waitcnt lgkmcnt(2)
	v_mfma_f32_16x16x32_bf16 v[36:39], v[36:39], v[20:23], v[40:43]
	v_fma_f32 v3, -v76, v77, 1.0
	v_fmac_f32_e32 v77, v3, v77
	v_div_scale_f32 v3, vcc, 1.0, v0, 1.0
	ds_read_b128 v[40:43], v106 offset:16384
	s_waitcnt lgkmcnt(2)
	v_mfma_f32_16x16x32_bf16 v[60:63], v[60:63], v[24:27], v[36:39]
	v_mul_f32_e32 v78, v3, v77
	v_mul_f32_e32 v2, 0xbfb8aa3b, v2
	v_exp_f32_e32 v2, v2
	ds_read_b128 v[36:39], v105 offset:16384
	s_waitcnt lgkmcnt(2)
	v_mfma_f32_16x16x32_bf16 v[48:51], v[48:51], v[4:7], 0
	v_mov_b32_e32 v124, v56
	v_add_f32_e32 v102, 1.0, v2
	v_div_scale_f32 v2, s[0:1], v102, v102, 1.0
	s_waitcnt lgkmcnt(1)
	v_mfma_f32_16x16x32_bf16 v[40:43], v[40:43], v[8:11], v[48:51]
	v_mov_b32_e32 v98, v134
	v_mov_b32_e32 v100, v134
	s_movk_i32 s0, 0x4e
	s_waitcnt lgkmcnt(0)
	v_mfma_f32_16x16x32_bf16 v[36:39], v[36:39], v[20:23], v[40:43]
	v_mov_b32_e32 v80, v134
	v_mov_b32_e32 v82, v134
	s_mov_b32 s2, 0xf149f2ca
	ds_read_b128 v[40:43], v106 offset:20480
	v_mfma_f32_16x16x32_bf16 v[48:51], v[64:67], v[24:27], v[36:39]
	v_mov_b32_e32 v88, v134
	v_mov_b32_e32 v92, v134
	v_fmac_f32_e32 v110, -0.5, v109
	ds_read_b128 v[36:39], v105 offset:20480
	v_mfma_f32_16x16x32_bf16 v[64:67], v[68:71], v[4:7], 0
	ds_read_b128 v[68:71], v104 offset:20480
	s_cmp_lt_i32 s74, 16
	s_waitcnt lgkmcnt(2)
	v_mfma_f32_16x16x32_bf16 v[40:43], v[40:43], v[8:11], v[64:67]
	s_waitcnt lgkmcnt(1)
	v_mfma_f32_16x16x32_bf16 v[36:39], v[36:39], v[20:23], v[40:43]
	s_nop 1
	v_fma_f32 v64, -v76, v78, v3
	v_fmac_f32_e32 v78, v64, v77
	v_fma_f32 v3, -v76, v78, v3
	s_nop 0
	ds_read_b128 v[40:43], v106 offset:24576
	s_waitcnt lgkmcnt(1)
	v_mfma_f32_16x16x32_bf16 v[64:67], v[68:71], v[24:27], v[36:39]
	v_rcp_f32_e32 v76, v2
	v_div_fmas_f32 v126, v3, v77, v78
	v_fma_f32 v3, -v2, v76, 1.0
	ds_read_b128 v[36:39], v105 offset:24576
	v_mfma_f32_16x16x32_bf16 v[68:71], v[72:75], v[4:7], 0
	ds_read_b128 v[72:75], v104 offset:24576
	v_fmac_f32_e32 v76, v3, v76
	v_div_scale_f32 v3, vcc, 1.0, v102, 1.0
	s_waitcnt lgkmcnt(2)
	v_mfma_f32_16x16x32_bf16 v[40:43], v[40:43], v[8:11], v[68:71]
	v_mul_f32_e32 v77, v3, v76
	v_fma_f32 v78, -v2, v77, v3
	v_fmac_f32_e32 v77, v78, v76
	ds_read_b128 v[68:71], v107 offset:28672
	s_waitcnt lgkmcnt(2)
	v_mfma_f32_16x16x32_bf16 v[36:39], v[36:39], v[20:23], v[40:43]
	v_fma_f32 v2, -v2, v77, v3
	v_lshlrev_b32_e32 v3, 6, v118
	v_sub_u32_e32 v128, v139, v3
	ds_read_b128 v[40:43], v106 offset:28672
	s_waitcnt lgkmcnt(1)
	v_mfma_f32_16x16x32_bf16 v[68:71], v[68:71], v[4:7], 0
	v_div_fmas_f32 v103, v2, v76, v77
	v_cmp_lt_i32_e64 s[68:69], 46, v128
	v_cmp_lt_i32_e64 s[70:71], 62, v128
	s_waitcnt lgkmcnt(0)
	v_mfma_f32_16x16x32_bf16 v[40:43], v[40:43], v[8:11], v[68:71]
	v_cmp_lt_i32_e64 s[72:73], s0, v128
	v_mov_b32_e32 v76, v134
	s_nop 0
	ds_read_b128 v[68:71], v104 offset:28672
	v_mfma_f32_16x16x32_bf16 v[36:39], v[72:75], v[24:27], v[36:39]
	ds_read_b128 v[72:75], v105 offset:28672
	s_movk_i32 s0, 0x11e
	v_cmp_lt_i32_e64 s[40:41], s0, v128
	s_waitcnt lgkmcnt(0)
; __device__ __forceinline__ void nsa_cmp_head(const bf16x8 (&qf)[4], const char* ldsKC, const char* ldsVC, int t, int l, int fr, int fq,
;                                              float sc, float sl, float g_cmp, float* imp_dst, float* P) {
;     ...
;   float mx = -1e30f;
; #pragma unroll
;   for (int kt = 0; kt < 8; ++kt)
; #pragma unroll
;     for (int j = 0; j < 4; ++j) {
;       const int cd = t - (16 * (16 * kt + fq * 4 + j) + 31);
;       const float v = s[kt][j] * sc - sl * (float)cd;
;       s[kt][j] = cd >= 0 ? v : -1e30f;
;       mx = fmaxf(mx, s[kt][j]);
;     }
	v_mfma_f32_16x16x32_bf16 v[40:43], v[72:75], v[20:23], v[40:43]
	v_subrev_u32_e32 v72, 31, v128
	v_cvt_f32_i32_e32 v135, v72
	v_cmp_lt_i32_e64 s[66:67], -1, v72
	v_mov_b32_e32 v78, v134
	s_movk_i32 s0, 0x12e
	v_pk_mul_f32 v[2:3], v[124:125], v[134:135]
	v_mov_b32_e32 v124, v57
	v_sub_f32_e32 v2, v2, v3
	v_subrev_u32_e32 v3, 47, v128
	v_cvt_f32_i32_e32 v97, v3
	v_cndmask_b32_e64 v116, v170, v2, s[66:67]
	v_cmp_lt_i32_e64 s[42:43], s0, v128
	s_movk_i32 s0, 0x13e
	v_pk_mul_f32 v[2:3], v[124:125], v[96:97]
	v_mov_b32_e32 v124, v58
	v_sub_f32_e32 v2, v2, v3
	v_cndmask_b32_e64 v115, v170, v2, s[68:69]
	v_subrev_u32_e32 v2, 63, v128
	v_cvt_f32_i32_e32 v99, v2
	v_cmp_lt_i32_e64 s[44:45], s0, v128
	s_movk_i32 s0, 0x14e
	v_cmp_lt_i32_e64 s[46:47], s0, v128
	v_pk_mul_f32 v[2:3], v[124:125], v[98:99]
	v_mov_b32_e32 v124, v59
	v_sub_f32_e32 v2, v2, v3
	v_add_u32_e32 v3, 0xffffffb1, v128
	v_cvt_f32_i32_e32 v101, v3
	v_cndmask_b32_e64 v127, v170, v2, s[70:71]
	v_max3_f32 v56, v116, s2, v115
	s_movk_i32 s0, 0x21e
	v_pk_mul_f32 v[2:3], v[124:125], v[100:101]
	v_mov_b32_e32 v124, v52
	v_sub_f32_e32 v2, v2, v3
	v_cndmask_b32_e64 v117, v170, v2, s[72:73]
	v_add_u32_e32 v2, 0xfffffee1, v128
	v_cvt_f32_i32_e32 v77, v2
	v_max3_f32 v56, v56, v127, v117
	v_cmp_lt_i32_e64 s[6:7], s0, v128
	s_movk_i32 s0, 0x22e
	v_pk_mul_f32 v[2:3], v[124:125], v[76:77]
	v_mov_b32_e32 v124, v53
	v_sub_f32_e32 v2, v2, v3
	v_add_u32_e32 v3, 0xfffffed1, v128
	v_cvt_f32_i32_e32 v79, v3
	v_cndmask_b32_e64 v130, v170, v2, s[40:41]
	v_cmp_lt_i32_e64 s[8:9], s0, v128
	s_movk_i32 s0, 0x23e
	v_pk_mul_f32 v[2:3], v[124:125], v[78:79]
	v_mov_b32_e32 v124, v54
	v_sub_f32_e32 v2, v2, v3
	v_cndmask_b32_e64 v129, v170, v2, s[42:43]
	v_add_u32_e32 v2, 0xfffffec1, v128
	v_cvt_f32_i32_e32 v81, v2
	v_max3_f32 v52, v56, v130, v129
	v_cmp_lt_i32_e64 s[10:11], s0, v128
	s_movk_i32 s0, 0x24e
	v_pk_mul_f32 v[2:3], v[124:125], v[80:81]
	v_mov_b32_e32 v124, v55
	v_sub_f32_e32 v2, v2, v3
	v_add_u32_e32 v3, 0xfffffeb1, v128
	v_cvt_f32_i32_e32 v83, v3
	v_cndmask_b32_e64 v145, v170, v2, s[44:45]
	v_cmp_lt_i32_e64 s[12:13], s0, v128
	v_mfma_f32_16x16x32_bf16 v[40:43], v[68:71], v[24:27], v[40:43]
	v_mul_f32_e64 v2, v124, v82
	v_mul_f32_e64 v3, v125, v83
	v_mov_b32_e32 v124, v44
	v_sub_f32_e32 v2, v2, v3
	v_cndmask_b32_e64 v131, v170, v2, s[46:47]
	v_add_u32_e32 v2, 0xfffffde1, v128
	v_cvt_f32_i32_e32 v3, v2
	v_mov_b32_e32 v2, v134
	v_max3_f32 v54, v52, v145, v131
	s_movk_i32 s0, 0x31e
	v_pk_mul_f32 v[52:53], v[124:125], v[2:3]
	v_mov_b32_e32 v124, v45
	v_sub_f32_e32 v44, v52, v53
	v_add_u32_e32 v52, 0xfffffdd1, v128
	v_cvt_f32_i32_e32 v53, v52
	v_mov_b32_e32 v52, v134
	v_cndmask_b32_e64 v147, v170, v44, s[6:7]
	v_cmp_lt_i32_e64 s[14:15], s0, v128
	v_pk_mul_f32 v[44:45], v[124:125], v[52:53]
	v_mov_b32_e32 v124, v46
	v_sub_f32_e32 v44, v44, v45
	v_cndmask_b32_e64 v146, v170, v44, s[8:9]
	v_add_u32_e32 v44, 0xfffffdc1, v128
	v_cvt_f32_i32_e32 v45, v44
	v_mov_b32_e32 v44, v134
	v_max3_f32 v56, v54, v147, v146
	s_movk_i32 s0, 0x32e
	v_pk_mul_f32 v[54:55], v[124:125], v[44:45]
	v_mov_b32_e32 v124, v47
	v_sub_f32_e32 v46, v54, v55
	v_add_u32_e32 v54, 0xfffffdb1, v128
	v_cvt_f32_i32_e32 v55, v54
	v_mov_b32_e32 v54, v134
	v_cndmask_b32_e64 v149, v170, v46, s[10:11]
	v_cmp_lt_i32_e64 s[16:17], s0, v128
	v_pk_mul_f32 v[46:47], v[124:125], v[54:55]
	v_mov_b32_e32 v124, v60
	v_sub_f32_e32 v46, v46, v47
	v_cndmask_b32_e64 v148, v170, v46, s[12:13]
	v_add_u32_e32 v46, 0xfffffce1, v128
	v_cvt_f32_i32_e32 v47, v46
	v_mov_b32_e32 v46, v134
	v_max3_f32 v68, v56, v149, v148
	s_movk_i32 s0, 0x33e
	v_pk_mul_f32 v[56:57], v[124:125], v[46:47]
	v_mov_b32_e32 v124, v61
	v_sub_f32_e32 v56, v56, v57
	v_add_u32_e32 v57, 0xfffffcd1, v128
	v_cvt_f32_i32_e32 v57, v57
	v_cndmask_b32_e64 v152, v170, v56, s[14:15]
	v_mov_b32_e32 v56, v134
	v_cmp_lt_i32_e64 s[18:19], s0, v128
	v_pk_mul_f32 v[58:59], v[124:125], v[56:57]
	v_mov_b32_e32 v124, v62
	v_sub_f32_e32 v58, v58, v59
	v_cndmask_b32_e64 v151, v170, v58, s[16:17]
	v_add_u32_e32 v58, 0xfffffcc1, v128
	v_cvt_f32_i32_e32 v59, v58
	v_mov_b32_e32 v58, v134
	s_movk_i32 s0, 0x34e
	v_cmp_lt_i32_e64 s[20:21], s0, v128
	v_pk_mul_f32 v[60:61], v[124:125], v[58:59]
	v_mov_b32_e32 v124, v63
	v_sub_f32_e32 v60, v60, v61
	v_add_u32_e32 v61, 0xfffffcb1, v128
	v_cvt_f32_i32_e32 v61, v61
	v_cndmask_b32_e64 v154, v170, v60, s[18:19]
	v_mov_b32_e32 v60, v134
	v_max3_f32 v68, v68, v152, v151
	v_pk_mul_f32 v[62:63], v[124:125], v[60:61]
	v_mov_b32_e32 v124, v48
	v_sub_f32_e32 v62, v62, v63
	v_cndmask_b32_e64 v153, v170, v62, s[20:21]
	v_add_u32_e32 v62, 0xfffffbe1, v128
	v_cvt_f32_i32_e32 v63, v62
	v_mov_b32_e32 v62, v134
	v_max3_f32 v70, v68, v154, v153
	s_movk_i32 s0, 0x41e
	v_pk_mul_f32 v[68:69], v[124:125], v[62:63]
	v_cmp_lt_i32_e64 s[22:23], s0, v128
	v_sub_f32_e32 v48, v68, v69
	v_add_u32_e32 v68, 0xfffffbd1, v128
	v_cvt_f32_i32_e32 v69, v68
	v_mov_b32_e32 v124, v49
	v_mov_b32_e32 v68, v134
	v_cndmask_b32_e64 v156, v170, v48, s[22:23]
	v_pk_mul_f32 v[48:49], v[124:125], v[68:69]
	s_movk_i32 s0, 0x42e
	v_sub_f32_e32 v48, v48, v49
	v_cmp_lt_i32_e64 s[24:25], s0, v128
	v_mov_b32_e32 v124, v50
	s_movk_i32 s0, 0x43e
	v_cndmask_b32_e64 v155, v170, v48, s[24:25]
	v_add_u32_e32 v48, 0xfffffbc1, v128
	v_cvt_f32_i32_e32 v49, v48
	v_mov_b32_e32 v48, v134
	v_max3_f32 v72, v70, v156, v155
	v_cmp_lt_i32_e64 s[26:27], s0, v128
	v_pk_mul_f32 v[70:71], v[124:125], v[48:49]
	v_mov_b32_e32 v124, v51
	v_sub_f32_e32 v50, v70, v71
	v_add_u32_e32 v70, 0xfffffbb1, v128
	v_cvt_f32_i32_e32 v71, v70
	v_mov_b32_e32 v70, v134
	v_cndmask_b32_e64 v160, v170, v50, s[26:27]
	s_movk_i32 s0, 0x44e
	v_pk_mul_f32 v[50:51], v[124:125], v[70:71]
; __device__ __forceinline__ float fexp2(float x) { return __builtin_amdgcn_exp2f(x); }
; __device__ __forceinline__ void nsa_cmp_head(const bf16x8 (&qf)[4], const char* ldsKC, const char* ldsVC, int t, int l, int fr, int fq,
;                                              float sc, float sl, float g_cmp, float* imp_dst, float* P) {
;     ...
;   float mx = -1e30f;
; #pragma unroll
;   for (int kt = 0; kt < 8; ++kt)
; #pragma unroll
;     for (int j = 0; j < 4; ++j) {
;       const int cd = t - (16 * (16 * kt + fq * 4 + j) + 31);
;       const float v = s[kt][j] * sc - sl * (float)cd;
;       s[kt][j] = cd >= 0 ? v : -1e30f;
;       mx = fmaxf(mx, s[kt][j]);
;     }
;   mx = fmaxf(mx, __shfl_xor(mx, 16));
;   mx = fmaxf(mx, __shfl_xor(mx, 32));
;   float sum = 0.f;
; #pragma unroll
;   for (int kt = 0; kt < 8; ++kt)
; #pragma unroll
;     for (int j = 0; j < 4; ++j) {
;       const float e = s[kt][j] > -1e29f ? fexp2(s[kt][j] - mx) : 0.f;
;       s[kt][j] = e;
;       sum += e;
;     }
	v_cmp_lt_i32_e64 s[28:29], s0, v128
	v_sub_f32_e32 v50, v50, v51
	v_mov_b32_e32 v124, v64
	v_cndmask_b32_e64 v159, v170, v50, s[28:29]
	v_add_u32_e32 v50, 0xfffffae1, v128
	v_cvt_f32_i32_e32 v51, v50
	v_mov_b32_e32 v50, v134
	v_max3_f32 v74, v72, v160, v159
	s_movk_i32 s0, 0x51e
	v_pk_mul_f32 v[72:73], v[124:125], v[50:51]
	v_cmp_lt_i32_e64 s[30:31], s0, v128
	v_sub_f32_e32 v64, v72, v73
	v_add_u32_e32 v72, 0xfffffad1, v128
	v_cvt_f32_i32_e32 v73, v72
	v_mov_b32_e32 v124, v65
	v_mov_b32_e32 v72, v134
	v_cndmask_b32_e64 v163, v170, v64, s[30:31]
	v_pk_mul_f32 v[64:65], v[124:125], v[72:73]
	s_movk_i32 s0, 0x52e
	v_sub_f32_e32 v64, v64, v65
	v_cmp_lt_i32_e64 s[34:35], s0, v128
	v_mov_b32_e32 v124, v66
	s_movk_i32 s0, 0x53e
	v_cndmask_b32_e64 v162, v170, v64, s[34:35]
	v_add_u32_e32 v64, 0xfffffac1, v128
	v_cvt_f32_i32_e32 v65, v64
	v_mov_b32_e32 v64, v134
	v_max3_f32 v84, v74, v163, v162
	v_cmp_lt_i32_e64 s[36:37], s0, v128
	v_pk_mul_f32 v[74:75], v[124:125], v[64:65]
	v_mov_b32_e32 v124, v67
	v_sub_f32_e32 v66, v74, v75
	v_add_u32_e32 v74, 0xfffffab1, v128
	v_cvt_f32_i32_e32 v75, v74
	v_mov_b32_e32 v74, v134
	v_cndmask_b32_e64 v165, v170, v66, s[36:37]
	s_movk_i32 s0, 0x54e
	v_pk_mul_f32 v[66:67], v[124:125], v[74:75]
	v_cmp_lt_i32_e64 s[38:39], s0, v128
	v_sub_f32_e32 v66, v66, v67
	v_mov_b32_e32 v124, v36
	v_cndmask_b32_e64 v164, v170, v66, s[38:39]
	v_add_u32_e32 v66, 0xfffff9e1, v128
	v_cvt_f32_i32_e32 v67, v66
	v_mov_b32_e32 v66, v134
	v_max3_f32 v86, v84, v165, v164
	s_movk_i32 s0, 0x61e
	v_pk_mul_f32 v[84:85], v[124:125], v[66:67]
	v_cmp_lt_i32_e64 s[48:49], s0, v128
	v_sub_f32_e32 v36, v84, v85
	v_add_u32_e32 v84, 0xfffff9d1, v128
	v_cvt_f32_i32_e32 v85, v84
	v_mov_b32_e32 v124, v37
	v_mov_b32_e32 v84, v134
	v_cndmask_b32_e64 v182, v170, v36, s[48:49]
	v_pk_mul_f32 v[36:37], v[124:125], v[84:85]
	s_movk_i32 s0, 0x62e
	v_sub_f32_e32 v36, v36, v37
	v_cmp_lt_i32_e64 s[50:51], s0, v128
	v_mov_b32_e32 v124, v38
	s_movk_i32 s0, 0x63e
	v_cndmask_b32_e64 v183, v170, v36, s[50:51]
	v_add_u32_e32 v36, 0xfffff9c1, v128
	v_cvt_f32_i32_e32 v87, v36
	v_max3_f32 v90, v86, v182, v183
	v_mov_b32_e32 v86, v134
	v_cmp_lt_i32_e64 s[52:53], s0, v128
	v_pk_mul_f32 v[36:37], v[124:125], v[86:87]
	v_mov_b32_e32 v124, v39
	v_sub_f32_e32 v36, v36, v37
	v_add_u32_e32 v37, 0xfffff9b1, v128
	v_cvt_f32_i32_e32 v89, v37
	v_cndmask_b32_e64 v38, v170, v36, s[52:53]
	s_movk_i32 s0, 0x64e
	v_cmp_lt_i32_e64 s[54:55], s0, v128
	v_pk_mul_f32 v[36:37], v[124:125], v[88:89]
	v_mov_b32_e32 v124, v40
	v_sub_f32_e32 v36, v36, v37
	v_cndmask_b32_e64 v39, v170, v36, s[54:55]
	v_add_u32_e32 v36, 0xfffff8e1, v128
	v_cvt_f32_i32_e32 v91, v36
	v_max3_f32 v94, v90, v38, v39
	v_mov_b32_e32 v90, v134
	s_movk_i32 s0, 0x71e
	v_pk_mul_f32 v[36:37], v[124:125], v[90:91]
	v_cmp_lt_i32_e64 s[56:57], s0, v128
	v_sub_f32_e32 v36, v36, v37
	v_add_u32_e32 v37, 0xfffff8d1, v128
	v_cvt_f32_i32_e32 v93, v37
	v_mov_b32_e32 v124, v41
	v_cndmask_b32_e64 v184, v170, v36, s[56:57]
	s_movk_i32 s0, 0x72e
	v_pk_mul_f32 v[36:37], v[124:125], v[92:93]
	v_cmp_lt_i32_e64 s[58:59], s0, v128
	v_sub_f32_e32 v36, v36, v37
	v_mov_b32_e32 v124, v42
	v_cndmask_b32_e64 v185, v170, v36, s[58:59]
	v_add_u32_e32 v36, 0xfffff8c1, v128
	v_cvt_f32_i32_e32 v41, v36
	v_mov_b32_e32 v40, v134
	s_movk_i32 s0, 0x73e
	v_max3_f32 v157, v94, v184, v185
	v_pk_mul_f32 v[36:37], v[124:125], v[40:41]
	v_cmp_lt_i32_e64 s[60:61], s0, v128
	v_sub_f32_e32 v36, v36, v37
	v_add_u32_e32 v37, 0xfffff8b1, v128
	v_cvt_f32_i32_e32 v95, v37
	v_mov_b32_e32 v124, v43
	v_mov_b32_e32 v94, v134
	v_cndmask_b32_e64 v42, v170, v36, s[60:61]
	v_pk_mul_f32 v[36:37], v[124:125], v[94:95]
	s_movk_i32 s0, 0x74e
	v_cmp_lt_i32_e32 vcc, v177, v180
	v_sub_f32_e32 v36, v36, v37
	v_cmp_lt_i32_e64 s[62:63], s0, v128
	v_cndmask_b32_e32 v144, v176, v177, vcc
	v_lshlrev_b32_e32 v124, 2, v144
	v_cndmask_b32_e64 v186, v170, v36, s[62:63]
	v_max3_f32 v36, v157, v42, v186
	ds_bpermute_b32 v37, v124, v36
	v_cmp_lt_i32_e32 vcc, v179, v180
	s_waitcnt lgkmcnt(0)
	v_max_f32_e32 v37, v37, v37
	v_cndmask_b32_e32 v150, v176, v179, vcc
	v_max_f32_e32 v36, v36, v37
	v_lshlrev_b32_e32 v144, 2, v150
	ds_bpermute_b32 v37, v144, v36
	v_cmp_lt_f32_e32 vcc, s33, v116
	s_waitcnt lgkmcnt(0)
	v_max_f32_e32 v37, v37, v37
	v_max_f32_e32 v187, v36, v37
	v_sub_f32_e32 v36, v116, v187
	v_exp_f32_e32 v36, v36
	s_nop 0
	v_cndmask_b32_e32 v43, 0, v36, vcc
	v_sub_f32_e32 v36, v115, v187
	v_exp_f32_e32 v36, v36
	v_cmp_lt_f32_e32 vcc, s33, v115
	s_nop 1
	v_cndmask_b32_e32 v188, 0, v36, vcc
	v_sub_f32_e32 v36, v127, v187
	v_exp_f32_e32 v36, v36
	v_cmp_lt_f32_e32 vcc, s33, v127
	s_nop 1
	v_cndmask_b32_e32 v189, 0, v36, vcc
	v_sub_f32_e32 v36, v117, v187
	v_exp_f32_e32 v36, v36
	v_cmp_lt_f32_e32 vcc, s33, v117
	s_nop 1
	v_cndmask_b32_e32 v190, 0, v36, vcc
	v_sub_f32_e32 v36, v130, v187
	v_exp_f32_e32 v36, v36
	v_cmp_lt_f32_e32 vcc, s33, v130
	s_nop 1
	v_cndmask_b32_e32 v130, 0, v36, vcc
	v_sub_f32_e32 v36, v129, v187
	v_exp_f32_e32 v36, v36
	v_cmp_lt_f32_e32 vcc, s33, v129
	s_nop 1
	v_cndmask_b32_e32 v158, 0, v36, vcc
	v_sub_f32_e32 v36, v145, v187
	v_exp_f32_e32 v36, v36
	v_cmp_lt_f32_e32 vcc, s33, v145
	s_nop 1
	v_cndmask_b32_e32 v161, 0, v36, vcc
	v_sub_f32_e32 v36, v131, v187
	v_exp_f32_e32 v36, v36
	v_cmp_lt_f32_e32 vcc, s33, v131
	s_nop 1
	v_cndmask_b32_e32 v191, 0, v36, vcc
	v_sub_f32_e32 v36, v147, v187
	v_exp_f32_e32 v36, v36
	v_cmp_lt_f32_e32 vcc, s33, v147
	s_nop 1
	v_cndmask_b32_e32 v192, 0, v36, vcc
	v_sub_f32_e32 v36, v146, v187
	v_exp_f32_e32 v36, v36
	v_cmp_lt_f32_e32 vcc, s33, v146
	s_nop 1
	v_cndmask_b32_e32 v131, 0, v36, vcc
	v_sub_f32_e32 v36, v149, v187
	v_exp_f32_e32 v36, v36
; __device__ __forceinline__ float fexp2(float x) { return __builtin_amdgcn_exp2f(x); }
; __device__ __forceinline__ void nsa_cmp_head(const bf16x8 (&qf)[4], const char* ldsKC, const char* ldsVC, int t, int l, int fr, int fq,
;                                              float sc, float sl, float g_cmp, float* imp_dst, float* P) {
;     ...
;   float sum = 0.f;
; #pragma unroll
;   for (int kt = 0; kt < 8; ++kt)
; #pragma unroll
;     for (int j = 0; j < 4; ++j) {
;       const float e = s[kt][j] > -1e29f ? fexp2(s[kt][j] - mx) : 0.f;
;       s[kt][j] = e;
;       sum += e;
;     }
;   sum += __shfl_xor(sum, 16);
;   sum += __shfl_xor(sum, 32);
;   const float inv = sum > 0.f ? 1.0f / sum : 0.f;
; #pragma unroll
;   for (int kt = 0; kt < 8; ++kt)
; #pragma unroll
;     for (int j = 0; j < 4; ++j) s[kt][j] *= inv;
;   {
;     float prev3[8];
; #pragma unroll
;     for (int kt = 0; kt < 8; ++kt) prev3[kt] = __shfl(s[kt][3], (l + 48) & 63);
; #pragma unroll
;     for (int kt = 0; kt < 8; ++kt) {
;       const float hp = fq > 0 ? prev3[kt] : (kt > 0 ? prev3[kt > 0 ? kt - 1 : 0] : 0.f);
;       imp_dst[4 * kt + fq] = 0.5f * hp + s[kt][0] + s[kt][1] + s[kt][2] + 0.5f * s[kt][3];
;     }
;   }
	v_cmp_lt_f32_e32 vcc, s33, v149
	s_nop 1
	v_cndmask_b32_e32 v150, 0, v36, vcc
	v_sub_f32_e32 v36, v148, v187
	v_exp_f32_e32 v36, v36
	v_cmp_lt_f32_e32 vcc, s33, v148
	s_nop 1
	v_cndmask_b32_e32 v148, 0, v36, vcc
	v_sub_f32_e32 v36, v152, v187
	v_exp_f32_e32 v36, v36
	v_cmp_lt_f32_e32 vcc, s33, v152
	s_nop 1
	v_cndmask_b32_e32 v152, 0, v36, vcc
	v_sub_f32_e32 v36, v151, v187
	v_exp_f32_e32 v36, v36
	v_cmp_lt_f32_e32 vcc, s33, v151
	s_nop 1
	v_cndmask_b32_e32 v157, 0, v36, vcc
	v_sub_f32_e32 v36, v154, v187
	v_exp_f32_e32 v36, v36
	v_cmp_lt_f32_e32 vcc, s33, v154
	s_nop 1
	v_cndmask_b32_e32 v129, 0, v36, vcc
	v_sub_f32_e32 v36, v153, v187
	v_exp_f32_e32 v36, v36
	v_cmp_lt_f32_e32 vcc, s33, v153
	s_nop 1
	v_cndmask_b32_e32 v151, 0, v36, vcc
	v_sub_f32_e32 v36, v156, v187
	v_exp_f32_e32 v36, v36
	v_cmp_lt_f32_e32 vcc, s33, v156
	s_nop 1
	v_cndmask_b32_e32 v153, 0, v36, vcc
	v_sub_f32_e32 v36, v155, v187
	v_exp_f32_e32 v36, v36
	v_cmp_lt_f32_e32 vcc, s33, v155
	s_nop 1
	v_cndmask_b32_e32 v115, 0, v36, vcc
	v_sub_f32_e32 v36, v160, v187
	v_exp_f32_e32 v36, v36
	v_cmp_lt_f32_e32 vcc, s33, v160
	s_nop 1
	v_cndmask_b32_e32 v116, 0, v36, vcc
	v_sub_f32_e32 v36, v159, v187
	v_exp_f32_e32 v36, v36
	v_cmp_lt_f32_e32 vcc, s33, v159
	s_nop 1
	v_cndmask_b32_e32 v154, 0, v36, vcc
	v_sub_f32_e32 v36, v163, v187
	v_exp_f32_e32 v36, v36
	v_cmp_lt_f32_e32 vcc, s33, v163
	s_nop 1
	v_cndmask_b32_e32 v155, 0, v36, vcc
	v_sub_f32_e32 v36, v162, v187
	v_exp_f32_e32 v36, v36
	v_cmp_lt_f32_e32 vcc, s33, v162
	s_nop 1
	v_cndmask_b32_e32 v128, 0, v36, vcc
	v_sub_f32_e32 v36, v165, v187
	v_exp_f32_e32 v36, v36
	v_cmp_lt_f32_e32 vcc, s33, v165
	s_nop 1
	v_cndmask_b32_e32 v117, 0, v36, vcc
	v_sub_f32_e32 v36, v164, v187
	v_exp_f32_e32 v36, v36
	v_cmp_lt_f32_e32 vcc, s33, v164
	s_nop 1
	v_cndmask_b32_e32 v156, 0, v36, vcc
	v_sub_f32_e32 v36, v182, v187
	v_exp_f32_e32 v36, v36
	v_cmp_lt_f32_e32 vcc, s33, v182
	s_nop 1
	v_cndmask_b32_e32 v159, 0, v36, vcc
	v_sub_f32_e32 v36, v183, v187
	v_exp_f32_e32 v36, v36
	v_cmp_lt_f32_e32 vcc, s33, v183
	s_nop 1
	v_cndmask_b32_e32 v37, 0, v36, vcc
	v_sub_f32_e32 v36, v38, v187
	v_exp_f32_e32 v36, v36
	v_cmp_lt_f32_e32 vcc, s33, v38
	s_nop 1
	v_cndmask_b32_e32 v38, 0, v36, vcc
	v_sub_f32_e32 v36, v39, v187
	v_exp_f32_e32 v36, v36
	v_cmp_lt_f32_e32 vcc, s33, v39
	v_sub_f32_e32 v39, v42, v187
	v_exp_f32_e32 v39, v39
	v_cndmask_b32_e32 v160, 0, v36, vcc
	v_sub_f32_e32 v36, v184, v187
	v_exp_f32_e32 v36, v36
	v_cmp_lt_f32_e32 vcc, s33, v184
	s_nop 1
	v_cndmask_b32_e32 v162, 0, v36, vcc
	v_sub_f32_e32 v36, v185, v187
	v_exp_f32_e32 v36, v36
	v_cmp_lt_f32_e32 vcc, s33, v185
	s_nop 1
	v_cndmask_b32_e32 v36, 0, v36, vcc
	v_cmp_lt_f32_e32 vcc, s33, v42
	v_sub_f32_e32 v42, v186, v187
	v_exp_f32_e32 v42, v42
	v_cndmask_b32_e32 v39, 0, v39, vcc
	v_cmp_lt_f32_e32 vcc, s33, v186
	s_nop 1
	v_cndmask_b32_e32 v163, 0, v42, vcc
	v_add_f32_e32 v42, 0, v43
	v_add_f32_e32 v42, v188, v42
	v_add_f32_e32 v42, v189, v42
	v_add_f32_e32 v42, v190, v42
	v_add_f32_e32 v42, v130, v42
	v_add_f32_e32 v42, v158, v42
	v_add_f32_e32 v42, v161, v42
	v_add_f32_e32 v42, v191, v42
	v_add_f32_e32 v42, v192, v42
	v_add_f32_e32 v42, v131, v42
	v_add_f32_e32 v42, v150, v42
	v_add_f32_e32 v42, v148, v42
	v_add_f32_e32 v42, v152, v42
	v_add_f32_e32 v42, v157, v42
	v_add_f32_e32 v42, v129, v42
	v_add_f32_e32 v42, v151, v42
	v_add_f32_e32 v42, v153, v42
	v_add_f32_e32 v42, v115, v42
	v_add_f32_e32 v42, v116, v42
	v_add_f32_e32 v42, v154, v42
	v_add_f32_e32 v42, v155, v42
	v_add_f32_e32 v42, v128, v42
	v_add_f32_e32 v42, v117, v42
	v_add_f32_e32 v42, v156, v42
	v_add_f32_e32 v42, v159, v42
	v_add_f32_e32 v42, v37, v42
	v_add_f32_e32 v42, v38, v42
	v_add_f32_e32 v42, v160, v42
	v_add_f32_e32 v42, v162, v42
	v_add_f32_e32 v42, v36, v42
	v_add_f32_e32 v42, v39, v42
	v_add_f32_e32 v42, v163, v42
	ds_bpermute_b32 v127, v124, v42
	s_waitcnt lgkmcnt(0)
	v_add_f32_e32 v42, v42, v127
	ds_bpermute_b32 v127, v144, v42
	s_waitcnt lgkmcnt(0)
	v_add_f32_e32 v42, v42, v127
	v_div_scale_f32 v127, s[0:1], v42, v42, 1.0
	v_rcp_f32_e32 v145, v127
	v_readlane_b32 s0, v248, 50
	v_fma_f32 v146, -v127, v145, 1.0
	v_fmac_f32_e32 v145, v146, v145
	v_div_scale_f32 v146, vcc, 1.0, v42, 1.0
	v_mul_f32_e32 v147, v146, v145
	v_fma_f32 v149, -v127, v147, v146
	v_fmac_f32_e32 v147, v149, v145
	v_fma_f32 v127, -v127, v147, v146
	v_div_fmas_f32 v127, v127, v145, v147
	v_div_fixup_f32 v127, v127, v42, 1.0
	v_cmp_lt_f32_e32 vcc, 0, v42
	v_and_b32_e32 v149, 63, v119
	v_cmp_gt_u32_e64 s[64:65], 16, v149
	v_cndmask_b32_e32 v127, 0, v127, vcc
	v_mul_f32_e32 v214, v151, v127
	v_add_u32_e32 v151, 48, v119
	v_and_or_b32 v151, v151, 63, v178
	v_mul_f32_e32 v184, v190, v127
	v_lshlrev_b32_e32 v151, 2, v151
	v_mul_f32_e32 v216, v154, v127
	ds_bpermute_b32 v154, v151, v184
	v_mul_f32_e32 v186, v191, v127
	v_mul_f32_e32 v217, v155, v127
	ds_bpermute_b32 v155, v151, v186
	v_mul_f32_e32 v212, v152, v127
	s_waitcnt lgkmcnt(1)
	v_mul_f32_e32 v152, 0.5, v154
	v_lshl_add_u32 v42, v112, 13, s0
	v_mul_f32_e32 v211, v148, v127
	v_cndmask_b32_e64 v187, v152, 0, s[64:65]
	v_lshl_add_u32 v112, v113, 11, v42
	v_mul_f32_e32 v113, v43, v127
	v_mul_f32_e32 v185, v130, v127
	v_mul_f32_e32 v218, v156, v127
	v_mul_f32_e32 v148, v159, v127
	ds_bpermute_b32 v156, v151, v211
	ds_bpermute_b32 v159, v151, v214
	v_fmac_f32_e32 v187, v43, v127
	s_waitcnt lgkmcnt(2)
; #define MFMA(a, b, c) __builtin_amdgcn_mfma_f32_16x16x32_bf16((a), (b), (c), 0, 0, 0)
; __device__ __forceinline__ void nsa_cmp_head(const bf16x8 (&qf)[4], const char* ldsKC, const char* ldsVC, int t, int l, int fr, int fq,
;                                              float sc, float sl, float g_cmp, float* imp_dst, float* P) {
;     ...
;   {
;     float prev3[8];
; #pragma unroll
;     for (int kt = 0; kt < 8; ++kt) prev3[kt] = __shfl(s[kt][3], (l + 48) & 63);
; #pragma unroll
;     for (int kt = 0; kt < 8; ++kt) {
;       const float hp = fq > 0 ? prev3[kt] : (kt > 0 ? prev3[kt > 0 ? kt - 1 : 0] : 0.f);
;       imp_dst[4 * kt + fq] = 0.5f * hp + s[kt][0] + s[kt][1] + s[kt][2] + 0.5f * s[kt][3];
;     }
;   }
;   f32x4 oc[8];
; #pragma unroll
;   for (int dt = 0; dt < 8; ++dt) oc[dt] = f32x4{0.f, 0.f, 0.f, 0.f};
; #pragma unroll
;   for (int pp = 0; pp < 4; ++pp) {
;     const bf16x8 pf = mk8(u32x4{pk2(s[2 * pp][0], s[2 * pp][1]), pk2(s[2 * pp][2], s[2 * pp][3]),
;                                 pk2(s[2 * pp + 1][0], s[2 * pp + 1][1]), pk2(s[2 * pp + 1][2], s[2 * pp + 1][3])});
; #pragma unroll
;     for (int dt = 0; dt < 8; ++dt) {
;       const char* vr = ldsVC + (16 * dt + fr) * 256 + (fq & 1) * 8;
;       u32x2 a = *reinterpret_cast<const u32x2*>(vr + (((4 * pp + (fq >> 1)) ^ fr) * 16));
;       u32x2 b2 = *reinterpret_cast<const u32x2*>(vr + (((4 * pp + 2 + (fq >> 1)) ^ fr) * 16));
;       oc[dt] = MFMA(mk8(u32x4{a[0], a[1], b2[0], b2[1]}), pf, oc[dt]);
;     }
;   }
	v_cndmask_b32_e64 v43, v155, v154, s[64:65]
	v_fma_f32 v43, 0.5, v43, v185
	v_fmac_f32_e32 v187, v188, v127
	v_fmac_f32_e32 v43, v158, v127
	v_lshlrev_b32_e32 v145, 2, v118
	v_lshlrev_b32_e32 v147, 7, v120
	v_fmac_f32_e32 v187, v189, v127
	v_fmac_f32_e32 v43, v161, v127
	v_fmac_f32_e32 v187, 0.5, v184
	v_add3_u32 v152, v112, v147, v145
	v_fmac_f32_e32 v43, 0.5, v186
	v_mul_f32_e32 v210, v192, v127
	v_mul_f32_e32 v215, v153, v127
	v_mul_f32_e32 v153, v160, v127
	v_mul_f32_e32 v130, v163, v127
	ds_bpermute_b32 v160, v151, v216
	ds_bpermute_b32 v163, v151, v218
	ds_write2_b32 v152, v187, v43 offset1:4
	s_waitcnt lgkmcnt(4)
	v_cndmask_b32_e64 v43, v156, v155, s[64:65]
	s_waitcnt lgkmcnt(3)
	v_cndmask_b32_e64 v112, v159, v156, s[64:65]
	v_fma_f32 v43, 0.5, v43, v210
	v_fma_f32 v112, 0.5, v112, v212
	v_fmac_f32_e32 v43, v131, v127
	v_fmac_f32_e32 v112, v157, v127
	v_fmac_f32_e32 v43, v150, v127
	v_fmac_f32_e32 v112, v129, v127
	v_fmac_f32_e32 v43, 0.5, v211
	v_fmac_f32_e32 v112, 0.5, v214
	ds_bpermute_b32 v164, v151, v153
	ds_bpermute_b32 v165, v151, v130
	ds_write2_b32 v152, v43, v112 offset0:8 offset1:12
	s_waitcnt lgkmcnt(5)
	v_cndmask_b32_e64 v43, v160, v159, s[64:65]
	s_waitcnt lgkmcnt(4)
	v_cndmask_b32_e64 v112, v163, v160, s[64:65]
	v_fma_f32 v43, 0.5, v43, v215
	v_fma_f32 v112, 0.5, v112, v217
	v_fmac_f32_e32 v43, v115, v127
	v_fmac_f32_e32 v112, v128, v127
	v_fmac_f32_e32 v43, v116, v127
	v_fmac_f32_e32 v112, v117, v127
	v_fmac_f32_e32 v43, 0.5, v216
	v_fmac_f32_e32 v112, 0.5, v218
	ds_write2_b32 v152, v43, v112 offset0:16 offset1:20
	s_waitcnt lgkmcnt(3)
	v_cndmask_b32_e64 v43, v164, v163, s[64:65]
	s_waitcnt lgkmcnt(2)
	v_cndmask_b32_e64 v112, v165, v164, s[64:65]
	v_mul_f32_e32 v219, v162, v127
	v_fma_f32 v43, 0.5, v43, v148
	v_fma_f32 v112, 0.5, v112, v219
	v_fmac_f32_e32 v43, v37, v127
	v_fmac_f32_e32 v112, v36, v127
	v_fmac_f32_e32 v43, v38, v127
	v_fmac_f32_e32 v112, v39, v127
	v_lshlrev_b32_e32 v146, 3, v118
	v_fmac_f32_e32 v43, 0.5, v153
	v_fmac_f32_e32 v112, 0.5, v130
	ds_write2_b32 v152, v43, v112 offset0:24 offset1:28
	v_and_b32_e32 v43, 8, v146
	v_lshrrev_b32_e32 v221, 5, v149
	v_add_u32_e32 v220, v114, v43
	v_xor_b32_e32 v43, v221, v120
	v_bitop3_b32 v114, v221, v120, 2 bitop3:0x36
	v_lshl_add_u32 v112, v43, 4, v220
	v_lshl_add_u32 v43, v114, 4, v220
	ds_read_b64 v[162:163], v112 offset:32768
	ds_read_b64 v[164:165], v43 offset:32768
	v_mul_f32_e32 v182, v188, v127
	v_mul_f32_e32 v114, v158, v127
	v_cvt_pk_bf16_f32 v158,v113,v182
	v_bitop3_b32 v113, v221, v120, 4 bitop3:0x36
	v_bitop3_b32 v208, v221, v120, 6 bitop3:0x36
	v_mul_f32_e32 v183, v189, v127
	v_mul_f32_e32 v154, v161, v127
	v_cvt_pk_bf16_f32 v160,v185,v114
	v_lshl_add_u32 v114, v113, 4, v220
	v_lshl_add_u32 v113, v208, 4, v220
	v_cvt_pk_bf16_f32 v159,v183,v184
	ds_read_b64 v[182:183], v112 offset:36864
	ds_read_b64 v[184:185], v43 offset:36864
	v_cvt_pk_bf16_f32 v161,v154,v186
	ds_read_b64 v[186:187], v112 offset:40960
	ds_read_b64 v[188:189], v43 offset:40960
	ds_read_b64 v[190:191], v112 offset:45056
	ds_read_b64 v[192:193], v43 offset:45056
	ds_read_b64 v[194:195], v112 offset:49152
	ds_read_b64 v[196:197], v43 offset:49152
	ds_read_b64 v[198:199], v112 offset:53248
	ds_read_b64 v[200:201], v43 offset:53248
	ds_read_b64 v[202:203], v112 offset:57344
	ds_read_b64 v[204:205], v43 offset:57344
	v_mul_f32_e32 v213, v157, v127
	ds_read_b64 v[154:155], v112 offset:61440
	ds_read_b64 v[156:157], v43 offset:61440
	ds_read_b64 v[206:207], v114 offset:32768
	ds_read_b64 v[208:209], v113 offset:32768
	s_waitcnt lgkmcnt(14)
	v_mfma_f32_16x16x32_bf16 v[162:165], v[162:165], v[158:161], 0
	v_mul_f32_e32 v131, v131, v127
	v_mul_f32_e32 v150, v150, v127
	v_mul_f32_e32 v129, v129, v127
	v_mfma_f32_16x16x32_bf16 v[182:185], v[182:185], v[158:161], 0
	v_mul_f32_e32 v128, v128, v127
	v_mul_f32_e32 v117, v117, v127
	v_readlane_b32 s0, v247, 19
	s_waitcnt lgkmcnt(12)
	v_mfma_f32_16x16x32_bf16 v[186:189], v[186:189], v[158:161], 0
	s_waitcnt lgkmcnt(10)
	v_mfma_f32_16x16x32_bf16 v[190:193], v[190:193], v[158:161], 0
	s_waitcnt lgkmcnt(8)
	v_mfma_f32_16x16x32_bf16 v[194:197], v[194:197], v[158:161], 0
	s_waitcnt lgkmcnt(6)
	v_mfma_f32_16x16x32_bf16 v[198:201], v[198:201], v[158:161], 0
	s_waitcnt lgkmcnt(4)
	v_mfma_f32_16x16x32_bf16 v[202:205], v[202:205], v[158:161], 0
	s_waitcnt lgkmcnt(2)
	v_mfma_f32_16x16x32_bf16 v[154:157], v[154:157], v[158:161], 0
	v_cvt_pk_bf16_f32 v158,v210,v131
	v_cvt_pk_bf16_f32 v159,v150,v211
	v_cvt_pk_bf16_f32 v160,v212,v213
	ds_read_b64 v[210:211], v114 offset:36864
	ds_read_b64 v[212:213], v113 offset:36864
	v_cvt_pk_bf16_f32 v161,v129,v214
	v_mul_f32_e32 v129, v115, v127
	s_waitcnt lgkmcnt(2)
	v_mfma_f32_16x16x32_bf16 v[162:165], v[206:209], v[158:161], v[162:165]
	ds_read_b64 v[206:207], v114 offset:40960
	ds_read_b64 v[208:209], v113 offset:40960
	v_bitop3_b32 v115, v221, v120, 8 bitop3:0x36
	v_bitop3_b32 v150, v221, v120, 10 bitop3:0x36
	s_waitcnt lgkmcnt(2)
	v_mfma_f32_16x16x32_bf16 v[182:185], v[210:213], v[158:161], v[182:185]
	ds_read_b64 v[210:211], v114 offset:45056
	ds_read_b64 v[212:213], v113 offset:45056
	v_mul_f32_e32 v131, v116, v127
	v_lshl_add_u32 v116, v115, 4, v220
	s_waitcnt lgkmcnt(2)
	v_mfma_f32_16x16x32_bf16 v[186:189], v[206:209], v[158:161], v[186:189]
	ds_read_b64 v[206:207], v114 offset:49152
	ds_read_b64 v[208:209], v113 offset:49152
	v_lshl_add_u32 v115, v150, 4, v220
	s_waitcnt lgkmcnt(2)
	v_mfma_f32_16x16x32_bf16 v[190:193], v[210:213], v[158:161], v[190:193]
	ds_read_b64 v[210:211], v114 offset:53248
	ds_read_b64 v[212:213], v113 offset:53248
	s_waitcnt lgkmcnt(2)
; #define MFMA(a, b, c) __builtin_amdgcn_mfma_f32_16x16x32_bf16((a), (b), (c), 0, 0, 0)
; __device__ __forceinline__ void nsa_cmp_head(const bf16x8 (&qf)[4], const char* ldsKC, const char* ldsVC, int t, int l, int fr, int fq,
;                                              float sc, float sl, float g_cmp, float* imp_dst, float* P) {
;     ...
;   for (int pp = 0; pp < 4; ++pp) {
;     const bf16x8 pf = mk8(u32x4{pk2(s[2 * pp][0], s[2 * pp][1]), pk2(s[2 * pp][2], s[2 * pp][3]),
;                                 pk2(s[2 * pp + 1][0], s[2 * pp + 1][1]), pk2(s[2 * pp + 1][2], s[2 * pp + 1][3])});
; #pragma unroll
;     for (int dt = 0; dt < 8; ++dt) {
;       const char* vr = ldsVC + (16 * dt + fr) * 256 + (fq & 1) * 8;
;       u32x2 a = *reinterpret_cast<const u32x2*>(vr + (((4 * pp + (fq >> 1)) ^ fr) * 16));
;       u32x2 b2 = *reinterpret_cast<const u32x2*>(vr + (((4 * pp + 2 + (fq >> 1)) ^ fr) * 16));
;       oc[dt] = MFMA(mk8(u32x4{a[0], a[1], b2[0], b2[1]}), pf, oc[dt]);
;     }
;   }
; #pragma unroll
;   for (int dt = 0; dt < 8; ++dt)
;     *reinterpret_cast<f32x4*>(P + 16 * dt) = f32x4{oc[dt][0] * g_cmp, oc[dt][1] * g_cmp, oc[dt][2] * g_cmp, oc[dt][3] * g_cmp};
; __device__ __forceinline__ void nsa_item2(const Params& p, int item, char* lds, unsigned* lds_um, int tid) {
;     ...
;   nsa_cmp_head(qb, lds, lds + 32768, t, l, fr, fq, sc, slb, gcb, lds_imp + ((tq * 4 + 2 * hp + 1) * 16 + fr) * 32, Pb);
	v_mfma_f32_16x16x32_bf16 v[194:197], v[206:209], v[158:161], v[194:197]
	ds_read_b64 v[206:207], v114 offset:57344
	ds_read_b64 v[208:209], v113 offset:57344
	s_waitcnt lgkmcnt(2)
	v_mfma_f32_16x16x32_bf16 v[198:201], v[210:213], v[158:161], v[198:201]
	ds_read_b64 v[210:211], v114 offset:61440
	ds_read_b64 v[212:213], v113 offset:61440
	s_waitcnt lgkmcnt(2)
	v_mfma_f32_16x16x32_bf16 v[202:205], v[206:209], v[158:161], v[202:205]
	ds_read_b64 v[206:207], v116 offset:32768
	ds_read_b64 v[208:209], v115 offset:32768
	s_waitcnt lgkmcnt(2)
	v_mfma_f32_16x16x32_bf16 v[154:157], v[210:213], v[158:161], v[154:157]
	v_cvt_pk_bf16_f32 v158,v215,v129
	v_cvt_pk_bf16_f32 v159,v131,v216
	v_cvt_pk_bf16_f32 v160,v217,v128
	ds_read_b64 v[210:211], v116 offset:36864
	ds_read_b64 v[212:213], v115 offset:36864
	v_cvt_pk_bf16_f32 v161,v117,v218
	v_mul_f32_e32 v128, v37, v127
	s_waitcnt lgkmcnt(2)
	v_mfma_f32_16x16x32_bf16 v[162:165], v[206:209], v[158:161], v[162:165]
	ds_read_b64 v[206:207], v116 offset:40960
	ds_read_b64 v[208:209], v115 offset:40960
	v_mul_f32_e32 v129, v38, v127
	v_bitop3_b32 v37, v221, v120, 12 bitop3:0x36
	s_waitcnt lgkmcnt(2)
	v_mfma_f32_16x16x32_bf16 v[182:185], v[210:213], v[158:161], v[182:185]
	ds_read_b64 v[210:211], v116 offset:45056
	ds_read_b64 v[212:213], v115 offset:45056
	v_bitop3_b32 v38, v221, v120, 14 bitop3:0x36
	v_lshl_add_u32 v150, v37, 4, v220
	s_waitcnt lgkmcnt(2)
	v_mfma_f32_16x16x32_bf16 v[186:189], v[206:209], v[158:161], v[186:189]
	ds_read_b64 v[206:207], v116 offset:49152
	ds_read_b64 v[208:209], v115 offset:49152
	v_lshl_add_u32 v117, v38, 4, v220
	v_mul_f32_e32 v131, v39, v127
	s_waitcnt lgkmcnt(2)
	v_mfma_f32_16x16x32_bf16 v[190:193], v[210:213], v[158:161], v[190:193]
	ds_read_b64 v[210:211], v116 offset:53248
	ds_read_b64 v[212:213], v115 offset:53248
	v_mul_f32_e32 v127, v36, v127
	s_waitcnt lgkmcnt(2)
	v_mfma_f32_16x16x32_bf16 v[194:197], v[206:209], v[158:161], v[194:197]
	ds_read_b64 v[206:207], v116 offset:57344
	ds_read_b64 v[208:209], v115 offset:57344
	s_waitcnt lgkmcnt(2)
	v_mfma_f32_16x16x32_bf16 v[198:201], v[210:213], v[158:161], v[198:201]
	ds_read_b64 v[210:211], v116 offset:61440
	ds_read_b64 v[212:213], v115 offset:61440
	s_waitcnt lgkmcnt(2)
	v_mfma_f32_16x16x32_bf16 v[202:205], v[206:209], v[158:161], v[202:205]
	ds_read_b64 v[206:207], v150 offset:32768
	ds_read_b64 v[208:209], v117 offset:32768
	s_waitcnt lgkmcnt(2)
	v_mfma_f32_16x16x32_bf16 v[36:39], v[210:213], v[158:161], v[154:157]
	ds_read_b64 v[158:159], v150 offset:36864
	ds_read_b64 v[160:161], v117 offset:36864
	v_cvt_pk_bf16_f32 v154,v148,v128
	v_cvt_pk_bf16_f32 v155,v129,v153
	v_cvt_pk_bf16_f32 v156,v219,v127
	v_cvt_pk_bf16_f32 v157,v131,v130
	v_lshlrev_b32_e32 v148, 7, v108
	s_waitcnt lgkmcnt(2)
	v_mfma_f32_16x16x32_bf16 v[162:165], v[206:209], v[154:157], v[162:165]
	ds_read_b64 v[128:129], v150 offset:40960
	ds_read_b64 v[130:131], v117 offset:40960
	ds_read_b64 v[206:207], v150 offset:45056
	ds_read_b64 v[208:209], v117 offset:45056
	v_div_fixup_f32 v108, v126, v0, 1.0
	v_lshlrev_b32_e32 v0, 2, v148
	s_waitcnt lgkmcnt(4)
	v_mfma_f32_16x16x32_bf16 v[158:161], v[158:161], v[154:157], v[182:185]
	s_nop 2
	ds_read_b64 v[182:183], v150 offset:49152
	ds_read_b64 v[184:185], v117 offset:49152
	s_waitcnt lgkmcnt(4)
	v_mfma_f32_16x16x32_bf16 v[186:189], v[128:131], v[154:157], v[186:189]
	ds_read_b64 v[126:127], v150 offset:53248
	ds_read_b64 v[128:129], v117 offset:53248
	v_lshl_add_u32 v130, s0, 11, v139
	v_ashrrev_i32_e32 v131, 31, v130
	s_waitcnt lgkmcnt(4)
	v_mfma_f32_16x16x32_bf16 v[190:193], v[206:209], v[154:157], v[190:193]
	ds_read_b64 v[206:207], v150 offset:57344
	ds_read_b64 v[208:209], v117 offset:57344
	v_readlane_b32 s0, v247, 3
	v_readlane_b32 s1, v247, 4
	s_waitcnt lgkmcnt(4)
	v_mfma_f32_16x16x32_bf16 v[182:185], v[182:185], v[154:157], v[194:197]
	s_nop 2
	ds_read_b64 v[194:195], v150 offset:61440
	ds_read_b64 v[196:197], v117 offset:61440
	s_waitcnt lgkmcnt(4)
	v_mfma_f32_16x16x32_bf16 v[198:201], v[126:129], v[154:157], v[198:201]
	v_lshlrev_b64 v[128:129], 13, v[130:131]
	v_lshl_add_u64 v[126:127], s[0:1], 0, v[128:129]
	v_lshl_add_u64 v[126:127], v[126:127], 0, v[0:1]
	v_lshlrev_b32_e32 v0, 4, v118
	s_waitcnt lgkmcnt(2)
	v_mfma_f32_16x16x32_bf16 v[202:205], v[206:209], v[154:157], v[202:205]
	v_lshl_add_u64 v[126:127], v[126:127], 0, v[0:1]
	v_exp_f32_e32 v0, v110
	s_waitcnt lgkmcnt(0)
	v_mfma_f32_16x16x32_bf16 v[36:39], v[194:197], v[154:157], v[36:39]
	v_mul_f32_e64 v156, v108, v164
	v_mul_f32_e64 v157, v108, v165
	v_pk_mul_f32 v[154:155], v[108:109], v[162:163] op_sel_hi:[0,1]
	global_store_dwordx4 v[126:127], v[154:157], off
	v_ldexp_f32 v0, v0, v111
	v_mul_f32_e32 v131, 0x3fb8aa3b, v0
	v_pk_mul_f32 v[156:157], v[108:109], v[160:161] op_sel_hi:[0,1]
	v_pk_mul_f32 v[154:155], v[108:109], v[158:159] op_sel_hi:[0,1]
	global_store_dwordx4 v[126:127], v[154:157], off offset:64
	v_pk_mul_f32 v[38:39], v[108:109], v[38:39] op_sel_hi:[0,1]
	v_pk_mul_f32 v[36:37], v[108:109], v[36:37] op_sel_hi:[0,1]
	v_pk_mul_f32 v[156:157], v[108:109], v[188:189] op_sel_hi:[0,1]
	v_pk_mul_f32 v[154:155], v[108:109], v[186:187] op_sel_hi:[0,1]
	global_store_dwordx4 v[126:127], v[154:157], off offset:128
	global_store_dwordx4 v[126:127], v[36:39], off offset:448
	s_nop 0
	v_pk_mul_f32 v[156:157], v[108:109], v[192:193] op_sel_hi:[0,1]
	v_pk_mul_f32 v[154:155], v[108:109], v[190:191] op_sel_hi:[0,1]
	global_store_dwordx4 v[126:127], v[154:157], off offset:192
	s_nop 1
	v_pk_mul_f32 v[156:157], v[108:109], v[184:185] op_sel_hi:[0,1]
	v_pk_mul_f32 v[154:155], v[108:109], v[182:183] op_sel_hi:[0,1]
	global_store_dwordx4 v[126:127], v[154:157], off offset:256
	s_nop 1
	v_pk_mul_f32 v[156:157], v[108:109], v[200:201] op_sel_hi:[0,1]
	v_pk_mul_f32 v[154:155], v[108:109], v[198:199] op_sel_hi:[0,1]
	global_store_dwordx4 v[126:127], v[154:157], off offset:320
	s_nop 1
	v_pk_mul_f32 v[156:157], v[108:109], v[204:205] op_sel_hi:[0,1]
	v_pk_mul_f32 v[154:155], v[108:109], v[202:203] op_sel_hi:[0,1]
	global_store_dwordx4 v[126:127], v[154:157], off offset:384
	ds_read_b128 v[36:39], v107
	ds_read_b128 v[154:157], v106
	s_waitcnt lgkmcnt(0)
; #define MFMA(a, b, c) __builtin_amdgcn_mfma_f32_16x16x32_bf16((a), (b), (c), 0, 0, 0)
; __device__ __forceinline__ void nsa_cmp_head(const bf16x8 (&qf)[4], const char* ldsKC, const char* ldsVC, int t, int l, int fr, int fq,
;                                              float sc, float sl, float g_cmp, float* imp_dst, float* P) {
;   f32x4 s[8];
; #pragma unroll
;   for (int kt = 0; kt < 8; ++kt) {
;     s[kt] = f32x4{0.f, 0.f, 0.f, 0.f};
; #pragma unroll
;     for (int ks = 0; ks < 4; ++ks)
;       s[kt] = MFMA(*reinterpret_cast<const bf16x8*>(ldsKC + (16 * kt + fr) * 256 + (((ks * 4 + fq) ^ fr) * 16)), qf[ks], s[kt]);
;   }
;   float mx = -1e30f;
; #pragma unroll
;   for (int kt = 0; kt < 8; ++kt)
; #pragma unroll
;     for (int j = 0; j < 4; ++j) {
;       const int cd = t - (16 * (16 * kt + fq * 4 + j) + 31);
;       const float v = s[kt][j] * sc - sl * (float)cd;
;       s[kt][j] = cd >= 0 ? v : -1e30f;
;       mx = fmaxf(mx, s[kt][j]);
;     }
	v_mfma_f32_16x16x32_bf16 v[36:39], v[36:39], v[12:15], 0
	v_mfma_f32_16x16x32_bf16 v[36:39], v[154:157], v[16:19], v[36:39]
	ds_read_b128 v[154:157], v105
	ds_read_b128 v[158:161], v104
	ds_read_b128 v[162:165], v106 offset:24576
	ds_read_b128 v[182:185], v106 offset:28672
	s_waitcnt lgkmcnt(0)
	v_mfma_f32_16x16x32_bf16 v[36:39], v[154:157], v[28:31], v[36:39]
	ds_read_b128 v[154:157], v106 offset:16384
	v_mfma_f32_16x16x32_bf16 v[36:39], v[158:161], v[32:35], v[36:39]
	ds_read_b128 v[158:161], v106 offset:20480
	s_nop 6
	v_mov_b32_e32 v130, v36
	v_pk_mul_f32 v[108:109], v[130:131], v[134:135]
	v_mov_b32_e32 v130, v37
	v_sub_f32_e32 v0, v108, v109
	v_pk_mul_f32 v[36:37], v[130:131], v[96:97]
	v_mov_b32_e32 v130, v38
	v_cndmask_b32_e64 v108, v170, v0, s[66:67]
	v_sub_f32_e32 v0, v36, v37
	v_pk_mul_f32 v[36:37], v[130:131], v[98:99]
	v_mov_b32_e32 v130, v39
	v_cndmask_b32_e64 v97, v170, v0, s[68:69]
	v_sub_f32_e32 v0, v36, v37
	v_pk_mul_f32 v[36:37], v[130:131], v[100:101]
	v_cndmask_b32_e64 v96, v170, v0, s[70:71]
	v_sub_f32_e32 v0, v36, v37
	ds_read_b128 v[36:39], v107 offset:4096
	ds_read_b128 v[98:101], v106 offset:4096
	s_waitcnt lgkmcnt(0)
	v_mfma_f32_16x16x32_bf16 v[36:39], v[36:39], v[12:15], 0
	v_cndmask_b32_e64 v0, v170, v0, s[72:73]
	v_cmp_lt_f32_e32 vcc, s33, v108
	v_mfma_f32_16x16x32_bf16 v[36:39], v[98:101], v[16:19], v[36:39]
	ds_read_b128 v[98:101], v105 offset:4096
	s_waitcnt lgkmcnt(0)
	v_mfma_f32_16x16x32_bf16 v[36:39], v[98:101], v[28:31], v[36:39]
	ds_read_b128 v[98:101], v104 offset:4096
	s_waitcnt lgkmcnt(0)
	v_mfma_f32_16x16x32_bf16 v[36:39], v[98:101], v[32:35], v[36:39]
	ds_read_b128 v[98:101], v106 offset:12288
	s_nop 6
	v_mov_b32_e32 v130, v36
	v_pk_mul_f32 v[76:77], v[130:131], v[76:77]
	v_mov_b32_e32 v130, v37
	v_sub_f32_e32 v36, v76, v77
	v_cndmask_b32_e64 v109, v170, v36, s[40:41]
	v_pk_mul_f32 v[36:37], v[130:131], v[78:79]
	v_mov_b32_e32 v130, v38
	v_sub_f32_e32 v36, v36, v37
	v_cndmask_b32_e64 v110, v170, v36, s[42:43]
	v_pk_mul_f32 v[36:37], v[130:131], v[80:81]
	v_mov_b32_e32 v130, v39
	v_sub_f32_e32 v36, v36, v37
	v_cndmask_b32_e64 v77, v170, v36, s[44:45]
	v_pk_mul_f32 v[36:37], v[130:131], v[82:83]
	ds_read_b128 v[78:81], v106 offset:8192
	v_sub_f32_e32 v36, v36, v37
	v_cndmask_b32_e64 v76, v170, v36, s[46:47]
	ds_read_b128 v[36:39], v107 offset:8192
	s_waitcnt lgkmcnt(0)
	v_mfma_f32_16x16x32_bf16 v[36:39], v[36:39], v[12:15], 0
	v_max3_f32 v82, v108, s2, v97
	v_max3_f32 v82, v82, v96, v0
	v_max3_f32 v82, v82, v109, v110
	v_mfma_f32_16x16x32_bf16 v[36:39], v[78:81], v[16:19], v[36:39]
	ds_read_b128 v[78:81], v105 offset:8192
	v_max3_f32 v82, v82, v77, v76
	s_cselect_b64 s[2:3], -1, 0
	s_waitcnt lgkmcnt(0)
	v_mfma_f32_16x16x32_bf16 v[36:39], v[78:81], v[28:31], v[36:39]
	ds_read_b128 v[78:81], v104 offset:8192
	s_waitcnt lgkmcnt(0)
	v_mfma_f32_16x16x32_bf16 v[36:39], v[78:81], v[32:35], v[36:39]
	ds_read_b128 v[78:81], v107 offset:12288
	s_nop 6
	v_mov_b32_e32 v130, v36
	s_waitcnt lgkmcnt(0)
	v_mfma_f32_16x16x32_bf16 v[78:81], v[78:81], v[12:15], 0
	v_mul_f32_e64 v2, v130, v2
	v_mul_f32_e64 v3, v131, v3
	v_mov_b32_e32 v130, v37
	v_sub_f32_e32 v2, v2, v3
	v_mfma_f32_16x16x32_bf16 v[78:81], v[98:101], v[16:19], v[78:81]
	ds_read_b128 v[98:101], v105 offset:12288
	v_cndmask_b32_e64 v36, v170, v2, s[6:7]
	v_pk_mul_f32 v[2:3], v[130:131], v[52:53]
	s_waitcnt lgkmcnt(0)
	v_mfma_f32_16x16x32_bf16 v[78:81], v[98:101], v[28:31], v[78:81]
	ds_read_b128 v[98:101], v104 offset:12288
	v_sub_f32_e32 v2, v2, v3
	v_mov_b32_e32 v130, v38
	s_waitcnt lgkmcnt(0)
	v_mfma_f32_16x16x32_bf16 v[78:81], v[98:101], v[32:35], v[78:81]
	ds_read_b128 v[98:101], v107 offset:16384
	v_cndmask_b32_e64 v37, v170, v2, s[8:9]
	v_pk_mul_f32 v[2:3], v[130:131], v[44:45]
	s_waitcnt lgkmcnt(0)
	v_mfma_f32_16x16x32_bf16 v[98:101], v[98:101], v[12:15], 0
	v_sub_f32_e32 v2, v2, v3
	v_mov_b32_e32 v130, v39
	v_cndmask_b32_e64 v38, v170, v2, s[10:11]
	v_mfma_f32_16x16x32_bf16 v[98:101], v[154:157], v[16:19], v[98:101]
	ds_read_b128 v[154:157], v105 offset:16384
	v_pk_mul_f32 v[2:3], v[130:131], v[54:55]
	v_mov_b32_e32 v130, v78
	s_waitcnt lgkmcnt(0)
	v_mfma_f32_16x16x32_bf16 v[98:101], v[154:157], v[28:31], v[98:101]
	ds_read_b128 v[154:157], v104 offset:16384
	v_sub_f32_e32 v2, v2, v3
	v_cndmask_b32_e64 v39, v170, v2, s[12:13]
	s_waitcnt lgkmcnt(0)
	v_mfma_f32_16x16x32_bf16 v[98:101], v[154:157], v[32:35], v[98:101]
	ds_read_b128 v[154:157], v107 offset:20480
	v_pk_mul_f32 v[2:3], v[130:131], v[46:47]
	v_mov_b32_e32 v130, v79
	s_waitcnt lgkmcnt(0)
	v_mfma_f32_16x16x32_bf16 v[154:157], v[154:157], v[12:15], 0
	v_sub_f32_e32 v2, v2, v3
	v_cndmask_b32_e64 v46, v170, v2, s[14:15]
	v_pk_mul_f32 v[2:3], v[130:131], v[56:57]
	v_mfma_f32_16x16x32_bf16 v[154:157], v[158:161], v[16:19], v[154:157]
	ds_read_b128 v[158:161], v105 offset:20480
	v_sub_f32_e32 v2, v2, v3
	v_mov_b32_e32 v130, v80
	s_waitcnt lgkmcnt(0)
	v_mfma_f32_16x16x32_bf16 v[154:157], v[158:161], v[28:31], v[154:157]
	ds_read_b128 v[158:161], v104 offset:20480
	v_cndmask_b32_e64 v47, v170, v2, s[16:17]
	v_pk_mul_f32 v[2:3], v[130:131], v[58:59]
	s_waitcnt lgkmcnt(0)
	v_mfma_f32_16x16x32_bf16 v[154:157], v[158:161], v[32:35], v[154:157]
	ds_read_b128 v[158:161], v107 offset:24576
	v_max3_f32 v52, v82, v36, v37
	v_sub_f32_e32 v2, v2, v3
	s_waitcnt lgkmcnt(0)
	v_mfma_f32_16x16x32_bf16 v[158:161], v[158:161], v[12:15], 0
	v_mov_b32_e32 v130, v81
	v_max3_f32 v44, v52, v38, v39
	v_cndmask_b32_e64 v52, v170, v2, s[18:19]
	v_mfma_f32_16x16x32_bf16 v[158:161], v[162:165], v[16:19], v[158:161]
	ds_read_b128 v[162:165], v105 offset:24576
	v_pk_mul_f32 v[2:3], v[130:131], v[60:61]
	v_mov_b32_e32 v130, v98
	s_waitcnt lgkmcnt(0)
; __device__ __forceinline__ float fexp2(float x) { return __builtin_amdgcn_exp2f(x); }
; __device__ __forceinline__ void nsa_cmp_head(const bf16x8 (&qf)[4], const char* ldsKC, const char* ldsVC, int t, int l, int fr, int fq,
;                                              float sc, float sl, float g_cmp, float* imp_dst, float* P) {
;     ...
;   float mx = -1e30f;
; #pragma unroll
;   for (int kt = 0; kt < 8; ++kt)
; #pragma unroll
;     for (int j = 0; j < 4; ++j) {
;       const int cd = t - (16 * (16 * kt + fq * 4 + j) + 31);
;       const float v = s[kt][j] * sc - sl * (float)cd;
;       s[kt][j] = cd >= 0 ? v : -1e30f;
;       mx = fmaxf(mx, s[kt][j]);
;     }
;   mx = fmaxf(mx, __shfl_xor(mx, 16));
;   mx = fmaxf(mx, __shfl_xor(mx, 32));
;   float sum = 0.f;
; #pragma unroll
;   for (int kt = 0; kt < 8; ++kt)
; #pragma unroll
;     for (int j = 0; j < 4; ++j) {
;       const float e = s[kt][j] > -1e29f ? fexp2(s[kt][j] - mx) : 0.f;
;       s[kt][j] = e;
;       sum += e;
;     }
	v_mfma_f32_16x16x32_bf16 v[158:161], v[162:165], v[28:31], v[158:161]
	ds_read_b128 v[162:165], v104 offset:24576
	v_sub_f32_e32 v2, v2, v3
	v_cndmask_b32_e64 v53, v170, v2, s[20:21]
	s_waitcnt lgkmcnt(0)
	v_mfma_f32_16x16x32_bf16 v[158:161], v[162:165], v[32:35], v[158:161]
	ds_read_b128 v[162:165], v107 offset:28672
	v_pk_mul_f32 v[2:3], v[130:131], v[62:63]
	v_mov_b32_e32 v130, v99
	v_sub_f32_e32 v2, v2, v3
	s_waitcnt lgkmcnt(0)
	v_mfma_f32_16x16x32_bf16 v[162:165], v[162:165], v[12:15], 0
	v_cndmask_b32_e64 v54, v170, v2, s[22:23]
	v_pk_mul_f32 v[2:3], v[130:131], v[68:69]
	v_mov_b32_e32 v130, v100
	v_sub_f32_e32 v2, v2, v3
	v_cndmask_b32_e64 v55, v170, v2, s[24:25]
	v_pk_mul_f32 v[2:3], v[130:131], v[48:49]
	v_mov_b32_e32 v130, v101
	v_sub_f32_e32 v2, v2, v3
	v_mfma_f32_16x16x32_bf16 v[162:165], v[182:185], v[16:19], v[162:165]
	ds_read_b128 v[182:185], v105 offset:28672
	v_cndmask_b32_e64 v48, v170, v2, s[26:27]
	v_pk_mul_f32 v[2:3], v[130:131], v[70:71]
	v_mov_b32_e32 v130, v154
	v_sub_f32_e32 v2, v2, v3
	v_cndmask_b32_e64 v56, v170, v2, s[28:29]
	v_pk_mul_f32 v[2:3], v[130:131], v[50:51]
	v_mov_b32_e32 v130, v155
	v_sub_f32_e32 v2, v2, v3
	ds_read_b128 v[104:107], v104 offset:28672
	v_cndmask_b32_e64 v51, v170, v2, s[30:31]
	v_pk_mul_f32 v[2:3], v[130:131], v[72:73]
	v_mov_b32_e32 v130, v156
	v_sub_f32_e32 v2, v2, v3
	v_cndmask_b32_e64 v57, v170, v2, s[34:35]
	v_pk_mul_f32 v[2:3], v[130:131], v[64:65]
	v_mov_b32_e32 v130, v157
	v_sub_f32_e32 v2, v2, v3
	v_cndmask_b32_e64 v58, v170, v2, s[36:37]
	v_pk_mul_f32 v[2:3], v[130:131], v[74:75]
	s_waitcnt lgkmcnt(0)
	v_mfma_f32_16x16x32_bf16 v[162:165], v[182:185], v[28:31], v[162:165]
	v_sub_f32_e32 v2, v2, v3
	v_mov_b32_e32 v130, v158
	v_cndmask_b32_e64 v59, v170, v2, s[38:39]
	v_pk_mul_f32 v[2:3], v[130:131], v[66:67]
	v_mov_b32_e32 v130, v159
	v_sub_f32_e32 v2, v2, v3
	v_cndmask_b32_e64 v60, v170, v2, s[48:49]
	v_pk_mul_f32 v[2:3], v[130:131], v[84:85]
	v_mfma_f32_16x16x32_bf16 v[104:107], v[104:107], v[32:35], v[162:165]
	v_sub_f32_e32 v2, v2, v3
	v_mov_b32_e32 v130, v160
	v_cndmask_b32_e64 v61, v170, v2, s[50:51]
	v_pk_mul_f32 v[2:3], v[130:131], v[86:87]
	v_mov_b32_e32 v130, v161
	v_sub_f32_e32 v2, v2, v3
	v_cndmask_b32_e64 v62, v170, v2, s[52:53]
	v_pk_mul_f32 v[2:3], v[130:131], v[88:89]
	v_mov_b32_e32 v130, v104
	v_sub_f32_e32 v2, v2, v3
	v_max3_f32 v44, v44, v46, v47
	v_cndmask_b32_e64 v63, v170, v2, s[54:55]
	v_pk_mul_f32 v[2:3], v[130:131], v[90:91]
	v_max3_f32 v44, v44, v52, v53
	v_sub_f32_e32 v2, v2, v3
	v_mov_b32_e32 v130, v105
	v_max3_f32 v44, v44, v54, v55
	v_cndmask_b32_e64 v64, v170, v2, s[56:57]
	v_pk_mul_f32 v[2:3], v[130:131], v[92:93]
	v_max3_f32 v44, v44, v48, v56
	v_sub_f32_e32 v2, v2, v3
	v_mov_b32_e32 v130, v106
	v_max3_f32 v44, v44, v51, v57
	v_cndmask_b32_e64 v65, v170, v2, s[58:59]
	v_pk_mul_f32 v[2:3], v[130:131], v[40:41]
	v_max3_f32 v44, v44, v58, v59
	v_sub_f32_e32 v2, v2, v3
	v_mov_b32_e32 v130, v107
	v_max3_f32 v44, v44, v60, v61
	v_cndmask_b32_e64 v66, v170, v2, s[60:61]
	v_pk_mul_f32 v[2:3], v[130:131], v[94:95]
	v_max3_f32 v44, v44, v62, v63
	v_sub_f32_e32 v2, v2, v3
	v_max3_f32 v44, v44, v64, v65
	v_cndmask_b32_e64 v67, v170, v2, s[62:63]
	v_max3_f32 v2, v44, v66, v67
	ds_bpermute_b32 v3, v124, v2
	s_waitcnt lgkmcnt(0)
	v_max_f32_e32 v3, v3, v3
	v_max_f32_e32 v2, v2, v3
	ds_bpermute_b32 v3, v144, v2
	s_waitcnt lgkmcnt(0)
	v_max_f32_e32 v3, v3, v3
	v_max_f32_e32 v68, v2, v3
	v_sub_f32_e32 v2, v108, v68
	v_exp_f32_e32 v2, v2
	v_sub_f32_e32 v3, v97, v68
	v_exp_f32_e32 v3, v3
	v_sub_f32_e32 v40, v0, v68
	v_cndmask_b32_e32 v69, 0, v2, vcc
	v_cmp_lt_f32_e32 vcc, s33, v97
	v_exp_f32_e32 v40, v40
	v_add_f32_e32 v2, 0, v69
	v_cndmask_b32_e32 v70, 0, v3, vcc
	v_sub_f32_e32 v3, v96, v68
	v_exp_f32_e32 v3, v3
	v_cmp_lt_f32_e32 vcc, s33, v96
	v_add_f32_e32 v2, v70, v2
	s_nop 0
	v_cndmask_b32_e32 v71, 0, v3, vcc
	v_cmp_lt_f32_e32 vcc, s33, v0
	v_add_f32_e32 v2, v71, v2
	v_sub_f32_e32 v3, v110, v68
	v_cndmask_b32_e32 v72, 0, v40, vcc
	v_add_f32_e32 v0, v72, v2
	v_sub_f32_e32 v2, v109, v68
	v_exp_f32_e32 v2, v2
	v_exp_f32_e32 v3, v3
	v_cmp_lt_f32_e32 vcc, s33, v109
	s_nop 1
	v_cndmask_b32_e32 v73, 0, v2, vcc
	v_cmp_lt_f32_e32 vcc, s33, v110
	v_sub_f32_e32 v2, v77, v68
	v_exp_f32_e32 v2, v2
	v_cndmask_b32_e32 v74, 0, v3, vcc
	v_sub_f32_e32 v3, v76, v68
	v_exp_f32_e32 v3, v3
	v_cmp_lt_f32_e32 vcc, s33, v77
	v_add_f32_e32 v0, v73, v0
	v_add_f32_e32 v0, v74, v0
	v_cndmask_b32_e32 v75, 0, v2, vcc
	v_cmp_lt_f32_e32 vcc, s33, v76
	v_sub_f32_e32 v2, v36, v68
	v_exp_f32_e32 v2, v2
	v_cndmask_b32_e32 v76, 0, v3, vcc
	v_sub_f32_e32 v3, v37, v68
	v_exp_f32_e32 v3, v3
	v_cmp_lt_f32_e32 vcc, s33, v36
	v_add_f32_e32 v0, v75, v0
	v_add_f32_e32 v0, v76, v0
	v_cndmask_b32_e32 v77, 0, v2, vcc
	v_cmp_lt_f32_e32 vcc, s33, v37
	v_sub_f32_e32 v2, v38, v68
	v_exp_f32_e32 v2, v2
	v_cndmask_b32_e32 v40, 0, v3, vcc
	v_sub_f32_e32 v3, v39, v68
	v_exp_f32_e32 v3, v3
	v_cmp_lt_f32_e32 vcc, s33, v38
	v_add_f32_e32 v0, v77, v0
	v_add_f32_e32 v0, v40, v0
	v_cndmask_b32_e32 v45, 0, v2, vcc
	v_cmp_lt_f32_e32 vcc, s33, v39
	v_sub_f32_e32 v2, v46, v68
	v_exp_f32_e32 v2, v2
	v_cndmask_b32_e32 v78, 0, v3, vcc
	v_sub_f32_e32 v3, v47, v68
	v_exp_f32_e32 v3, v3
	v_cmp_lt_f32_e32 vcc, s33, v46
	v_add_f32_e32 v0, v45, v0
	v_add_f32_e32 v0, v78, v0
	v_cndmask_b32_e32 v46, 0, v2, vcc
	v_cmp_lt_f32_e32 vcc, s33, v47
	v_sub_f32_e32 v2, v52, v68
	v_exp_f32_e32 v2, v2
	v_cndmask_b32_e32 v50, 0, v3, vcc
	v_sub_f32_e32 v3, v53, v68
	v_exp_f32_e32 v3, v3
	v_cmp_lt_f32_e32 vcc, s33, v52
	v_add_f32_e32 v0, v46, v0
	v_add_f32_e32 v0, v50, v0
	v_cndmask_b32_e32 v49, 0, v2, vcc
	v_cmp_lt_f32_e32 vcc, s33, v53
; __device__ __forceinline__ float fexp2(float x) { return __builtin_amdgcn_exp2f(x); }
; __device__ __forceinline__ void nsa_cmp_head(const bf16x8 (&qf)[4], const char* ldsKC, const char* ldsVC, int t, int l, int fr, int fq,
;                                              float sc, float sl, float g_cmp, float* imp_dst, float* P) {
;     ...
;   float sum = 0.f;
; #pragma unroll
;   for (int kt = 0; kt < 8; ++kt)
; #pragma unroll
;     for (int j = 0; j < 4; ++j) {
;       const float e = s[kt][j] > -1e29f ? fexp2(s[kt][j] - mx) : 0.f;
;       s[kt][j] = e;
;       sum += e;
;     }
;   sum += __shfl_xor(sum, 16);
;   sum += __shfl_xor(sum, 32);
;   const float inv = sum > 0.f ? 1.0f / sum : 0.f;
; #pragma unroll
;   for (int kt = 0; kt < 8; ++kt)
; #pragma unroll
;     for (int j = 0; j < 4; ++j) s[kt][j] *= inv;
;   {
;     float prev3[8];
; #pragma unroll
;     for (int kt = 0; kt < 8; ++kt) prev3[kt] = __shfl(s[kt][3], (l + 48) & 63);
; #pragma unroll
;     for (int kt = 0; kt < 8; ++kt) {
;       const float hp = fq > 0 ? prev3[kt] : (kt > 0 ? prev3[kt > 0 ? kt - 1 : 0] : 0.f);
;       imp_dst[4 * kt + fq] = 0.5f * hp + s[kt][0] + s[kt][1] + s[kt][2] + 0.5f * s[kt][3];
;     }
;   }
	v_sub_f32_e32 v2, v54, v68
	v_exp_f32_e32 v2, v2
	v_cndmask_b32_e32 v47, 0, v3, vcc
	v_sub_f32_e32 v3, v55, v68
	v_exp_f32_e32 v3, v3
	v_cmp_lt_f32_e32 vcc, s33, v54
	v_add_f32_e32 v0, v49, v0
	v_add_f32_e32 v0, v47, v0
	v_cndmask_b32_e32 v52, 0, v2, vcc
	v_cmp_lt_f32_e32 vcc, s33, v55
	v_sub_f32_e32 v2, v48, v68
	v_exp_f32_e32 v2, v2
	v_cndmask_b32_e32 v37, 0, v3, vcc
	v_sub_f32_e32 v3, v56, v68
	v_exp_f32_e32 v3, v3
	v_cmp_lt_f32_e32 vcc, s33, v48
	v_add_f32_e32 v0, v52, v0
	v_add_f32_e32 v0, v37, v0
	v_cndmask_b32_e32 v38, 0, v2, vcc
	v_cmp_lt_f32_e32 vcc, s33, v56
	v_sub_f32_e32 v2, v51, v68
	v_exp_f32_e32 v2, v2
	v_cndmask_b32_e32 v48, 0, v3, vcc
	v_sub_f32_e32 v3, v57, v68
	v_exp_f32_e32 v3, v3
	v_cmp_lt_f32_e32 vcc, s33, v51
	v_add_f32_e32 v0, v38, v0
	v_add_f32_e32 v0, v48, v0
	v_cndmask_b32_e32 v51, 0, v2, vcc
	v_cmp_lt_f32_e32 vcc, s33, v57
	v_sub_f32_e32 v2, v58, v68
	v_exp_f32_e32 v2, v2
	v_cndmask_b32_e32 v44, 0, v3, vcc
	v_sub_f32_e32 v3, v59, v68
	v_exp_f32_e32 v3, v3
	v_cmp_lt_f32_e32 vcc, s33, v58
	v_add_f32_e32 v0, v51, v0
	v_add_f32_e32 v0, v44, v0
	v_cndmask_b32_e32 v41, 0, v2, vcc
	v_cmp_lt_f32_e32 vcc, s33, v59
	v_sub_f32_e32 v2, v60, v68
	v_exp_f32_e32 v2, v2
	v_cndmask_b32_e32 v53, 0, v3, vcc
	v_sub_f32_e32 v3, v61, v68
	v_exp_f32_e32 v3, v3
	v_add_f32_e32 v0, v41, v0
	v_cmp_lt_f32_e32 vcc, s33, v60
	v_add_f32_e32 v0, v53, v0
	v_sub_f32_e32 v36, v63, v68
	v_cndmask_b32_e32 v54, 0, v2, vcc
	v_cmp_lt_f32_e32 vcc, s33, v61
	v_add_f32_e32 v0, v54, v0
	v_exp_f32_e32 v36, v36
	v_cndmask_b32_e32 v2, 0, v3, vcc
	v_add_f32_e32 v3, v2, v0
	v_sub_f32_e32 v0, v62, v68
	v_exp_f32_e32 v0, v0
	v_cmp_lt_f32_e32 vcc, s33, v62
	v_sub_f32_e32 v39, v65, v68
	v_exp_f32_e32 v39, v39
	v_cndmask_b32_e32 v0, 0, v0, vcc
	v_cmp_lt_f32_e32 vcc, s33, v63
	v_add_f32_e32 v3, v0, v3
	v_sub_f32_e32 v57, v67, v68
	v_cndmask_b32_e32 v55, 0, v36, vcc
	v_sub_f32_e32 v36, v64, v68
	v_exp_f32_e32 v36, v36
	v_cmp_lt_f32_e32 vcc, s33, v64
	v_add_f32_e32 v3, v55, v3
	v_exp_f32_e32 v57, v57
	v_cndmask_b32_e32 v56, 0, v36, vcc
	v_cmp_lt_f32_e32 vcc, s33, v65
	v_add_f32_e32 v36, v56, v3
	s_nop 0
	v_cndmask_b32_e32 v3, 0, v39, vcc
	v_add_f32_e32 v39, v3, v36
	v_sub_f32_e32 v36, v66, v68
	v_exp_f32_e32 v36, v36
	v_cmp_lt_f32_e32 vcc, s33, v66
	s_nop 1
	v_cndmask_b32_e32 v36, 0, v36, vcc
	v_cmp_lt_f32_e32 vcc, s33, v67
	v_add_f32_e32 v39, v36, v39
	v_add_u32_e32 v67, 0x800, v152
	v_cndmask_b32_e32 v57, 0, v57, vcc
	v_add_f32_e32 v39, v57, v39
	ds_bpermute_b32 v58, v124, v39
	s_waitcnt lgkmcnt(0)
	v_add_f32_e32 v39, v39, v58
	ds_bpermute_b32 v58, v144, v39
	s_waitcnt lgkmcnt(0)
	v_add_f32_e32 v39, v39, v58
	v_div_scale_f32 v58, s[0:1], v39, v39, 1.0
	v_rcp_f32_e32 v59, v58
	v_cmp_lt_f32_e64 s[6:7], 0, v39
	s_mov_b64 s[0:1], -1
	v_fma_f32 v60, -v58, v59, 1.0
	v_fmac_f32_e32 v59, v60, v59
	v_div_scale_f32 v60, vcc, 1.0, v39, 1.0
	v_mul_f32_e32 v61, v60, v59
	v_fma_f32 v62, -v58, v61, v60
	v_fmac_f32_e32 v61, v62, v59
	v_fma_f32 v58, -v58, v61, v60
	v_div_fmas_f32 v58, v58, v59, v61
	v_div_fixup_f32 v39, v58, v39, 1.0
	v_cndmask_b32_e64 v39, 0, v39, s[6:7]
	v_mul_f32_e32 v61, v72, v39
	v_mul_f32_e32 v64, v76, v39
	v_mul_f32_e32 v104, v51, v39
	ds_bpermute_b32 v51, v151, v61
	v_mul_f32_e32 v100, v52, v39
	ds_bpermute_b32 v52, v151, v64
	v_mul_f32_e32 v93, v78, v39
	v_mul_f32_e32 v96, v47, v39
	s_waitcnt lgkmcnt(0)
	v_mul_f32_e32 v66, 0.5, v51
	v_mul_f32_e32 v62, v73, v39
	v_mul_f32_e32 v94, v46, v39
	v_mul_f32_e32 v105, v53, v39
	v_mul_f32_e32 v46, v54, v39
	ds_bpermute_b32 v53, v151, v93
	ds_bpermute_b32 v54, v151, v96
	v_cndmask_b32_e64 v66, v66, 0, s[64:65]
	v_cndmask_b32_e64 v51, v52, v51, s[64:65]
	v_fmac_f32_e32 v66, v69, v39
	v_fma_f32 v51, 0.5, v51, v62
	v_fmac_f32_e32 v66, v70, v39
	v_fmac_f32_e32 v51, v74, v39
	v_fmac_f32_e32 v66, v71, v39
	v_fmac_f32_e32 v51, v75, v39
	v_mul_f32_e32 v101, v48, v39
	v_fmac_f32_e32 v66, 0.5, v61
	v_fmac_f32_e32 v51, 0.5, v64
	v_mul_f32_e32 v92, v77, v39
	v_mul_f32_e32 v48, v55, v39
	v_mul_f32_e32 v47, v57, v39
	ds_bpermute_b32 v55, v151, v101
	ds_bpermute_b32 v57, v151, v105
	ds_write2_b32 v67, v66, v51 offset1:4
	s_waitcnt lgkmcnt(0)
	v_cndmask_b32_e64 v51, v53, v52, s[64:65]
	v_cndmask_b32_e64 v52, v54, v53, s[64:65]
	v_fma_f32 v51, 0.5, v51, v92
	v_fma_f32 v52, 0.5, v52, v94
	v_fmac_f32_e32 v51, v40, v39
	v_fmac_f32_e32 v52, v50, v39
	v_fmac_f32_e32 v51, v45, v39
	v_fmac_f32_e32 v52, v49, v39
	v_fmac_f32_e32 v51, 0.5, v93
	v_fmac_f32_e32 v52, 0.5, v96
	ds_bpermute_b32 v63, v151, v48
	ds_bpermute_b32 v65, v151, v47
	ds_write2_b32 v67, v51, v52 offset0:8 offset1:12
	v_cndmask_b32_e64 v51, v55, v54, s[64:65]
	v_cndmask_b32_e64 v52, v57, v55, s[64:65]
	v_fma_f32 v51, 0.5, v51, v100
	v_fma_f32 v52, 0.5, v52, v104
	v_fmac_f32_e32 v51, v37, v39
	v_fmac_f32_e32 v52, v44, v39
	v_fmac_f32_e32 v51, v38, v39
	v_fmac_f32_e32 v52, v41, v39
	v_fmac_f32_e32 v51, 0.5, v101
	v_fmac_f32_e32 v52, 0.5, v105
	ds_write2_b32 v67, v51, v52 offset0:16 offset1:20
	s_waitcnt lgkmcnt(0)
; #define MFMA(a, b, c) __builtin_amdgcn_mfma_f32_16x16x32_bf16((a), (b), (c), 0, 0, 0)
; __device__ __forceinline__ void nsa_cmp_head(const bf16x8 (&qf)[4], const char* ldsKC, const char* ldsVC, int t, int l, int fr, int fq,
;                                              float sc, float sl, float g_cmp, float* imp_dst, float* P) {
;     ...
;     for (int kt = 0; kt < 8; ++kt) {
;       const float hp = fq > 0 ? prev3[kt] : (kt > 0 ? prev3[kt > 0 ? kt - 1 : 0] : 0.f);
;       imp_dst[4 * kt + fq] = 0.5f * hp + s[kt][0] + s[kt][1] + s[kt][2] + 0.5f * s[kt][3];
;     }
;   }
;   f32x4 oc[8];
; #pragma unroll
;   for (int dt = 0; dt < 8; ++dt) oc[dt] = f32x4{0.f, 0.f, 0.f, 0.f};
; #pragma unroll
;   for (int pp = 0; pp < 4; ++pp) {
;     const bf16x8 pf = mk8(u32x4{pk2(s[2 * pp][0], s[2 * pp][1]), pk2(s[2 * pp][2], s[2 * pp][3]),
;                                 pk2(s[2 * pp + 1][0], s[2 * pp + 1][1]), pk2(s[2 * pp + 1][2], s[2 * pp + 1][3])});
; #pragma unroll
;     for (int dt = 0; dt < 8; ++dt) {
;       const char* vr = ldsVC + (16 * dt + fr) * 256 + (fq & 1) * 8;
;       u32x2 a = *reinterpret_cast<const u32x2*>(vr + (((4 * pp + (fq >> 1)) ^ fr) * 16));
;       u32x2 b2 = *reinterpret_cast<const u32x2*>(vr + (((4 * pp + 2 + (fq >> 1)) ^ fr) * 16));
;       oc[dt] = MFMA(mk8(u32x4{a[0], a[1], b2[0], b2[1]}), pf, oc[dt]);
;     }
;   }
; #pragma unroll
;   for (int dt = 0; dt < 8; ++dt)
;     *reinterpret_cast<f32x4*>(P + 16 * dt) = f32x4{oc[dt][0] * g_cmp, oc[dt][1] * g_cmp, oc[dt][2] * g_cmp, oc[dt][3] * g_cmp};
	v_cndmask_b32_e64 v51, v63, v57, s[64:65]
	v_cndmask_b32_e64 v52, v65, v63, s[64:65]
	v_mul_f32_e32 v106, v56, v39
	v_fma_f32 v51, 0.5, v51, v46
	v_fma_f32 v52, 0.5, v52, v106
	v_fmac_f32_e32 v51, v2, v39
	v_fmac_f32_e32 v52, v3, v39
	v_fmac_f32_e32 v51, v0, v39
	v_fmac_f32_e32 v52, v36, v39
	v_fmac_f32_e32 v51, 0.5, v48
	v_fmac_f32_e32 v52, 0.5, v47
	ds_write2_b32 v67, v51, v52 offset0:24 offset1:28
	ds_read_b64 v[52:53], v112 offset:32768
	ds_read_b64 v[54:55], v43 offset:32768
	v_mul_f32_e32 v58, v69, v39
	v_mul_f32_e32 v59, v70, v39
	v_mul_f32_e32 v60, v71, v39
	v_mul_f32_e32 v65, v75, v39
	v_mul_f32_e32 v51, v74, v39
	v_cvt_pk_bf16_f32 v56,v58,v59
	v_cvt_pk_bf16_f32 v57,v60,v61
	v_cvt_pk_bf16_f32 v58,v62,v51
	ds_read_b64 v[60:61], v112 offset:36864
	ds_read_b64 v[62:63], v43 offset:36864
	v_cvt_pk_bf16_f32 v59,v65,v64
	ds_read_b64 v[64:65], v112 offset:40960
	ds_read_b64 v[66:67], v43 offset:40960
	ds_read_b64 v[68:69], v112 offset:45056
	ds_read_b64 v[70:71], v43 offset:45056
	ds_read_b64 v[72:73], v112 offset:49152
	ds_read_b64 v[74:75], v43 offset:49152
	ds_read_b64 v[76:77], v112 offset:53248
	ds_read_b64 v[78:79], v43 offset:53248
	ds_read_b64 v[80:81], v112 offset:57344
	ds_read_b64 v[82:83], v43 offset:57344
	ds_read_b64 v[84:85], v112 offset:61440
	ds_read_b64 v[86:87], v43 offset:61440
	ds_read_b64 v[88:89], v114 offset:32768
	ds_read_b64 v[90:91], v113 offset:32768
	s_waitcnt lgkmcnt(0)
	v_mfma_f32_16x16x32_bf16 v[52:55], v[52:55], v[56:59], 0
	v_mul_f32_e32 v40, v40, v39
	v_mul_f32_e32 v43, v45, v39
	v_mul_f32_e32 v45, v50, v39
	v_mfma_f32_16x16x32_bf16 v[60:63], v[60:63], v[56:59], 0
	v_mul_f32_e32 v49, v49, v39
	v_mul_f32_e32 v37, v37, v39
	v_mul_f32_e32 v38, v38, v39
	v_mfma_f32_16x16x32_bf16 v[64:67], v[64:67], v[56:59], 0
	v_mul_f32_e32 v41, v41, v39
	v_mul_f32_e32 v2, v2, v39
	v_mul_f32_e32 v0, v0, v39
	v_mfma_f32_16x16x32_bf16 v[68:71], v[68:71], v[56:59], 0
	v_mul_f32_e32 v3, v3, v39
	v_cmp_lt_u32_e64 s[6:7], 15, v149
	s_and_b64 vcc, exec, s[2:3]
	v_mfma_f32_16x16x32_bf16 v[72:75], v[72:75], v[56:59], 0
	v_mfma_f32_16x16x32_bf16 v[76:79], v[76:79], v[56:59], 0
	v_mfma_f32_16x16x32_bf16 v[80:83], v[80:83], v[56:59], 0
	v_mfma_f32_16x16x32_bf16 v[56:59], v[84:87], v[56:59], 0
	v_cvt_pk_bf16_f32 v84,v92,v40
	v_cvt_pk_bf16_f32 v85,v43,v93
	v_cvt_pk_bf16_f32 v86,v94,v45
	ds_read_b64 v[92:93], v114 offset:36864
	ds_read_b64 v[94:95], v113 offset:36864
	v_cvt_pk_bf16_f32 v87,v49,v96
	v_mul_f32_e32 v40, v44, v39
	v_mfma_f32_16x16x32_bf16 v[50:53], v[88:91], v[84:87], v[52:55]
	ds_read_b64 v[88:89], v114 offset:40960
	ds_read_b64 v[90:91], v113 offset:40960
	v_cvt_pk_bf16_f32 v44,v46,v2
	v_cvt_pk_bf16_f32 v45,v0,v48
	s_waitcnt lgkmcnt(0)
	v_mfma_f32_16x16x32_bf16 v[60:63], v[92:95], v[84:87], v[60:63]
	ds_read_b64 v[92:93], v114 offset:45056
	ds_read_b64 v[94:95], v113 offset:45056
	v_cvt_pk_bf16_f32 v46,v106,v3
	v_div_fixup_f32 v0, v103, v102, 1.0
	v_mfma_f32_16x16x32_bf16 v[64:67], v[88:91], v[84:87], v[64:67]
	ds_read_b64 v[88:89], v114 offset:49152
	ds_read_b64 v[90:91], v113 offset:49152
	s_waitcnt lgkmcnt(0)
	v_mfma_f32_16x16x32_bf16 v[68:71], v[92:95], v[84:87], v[68:71]
	ds_read_b64 v[92:93], v114 offset:53248
	ds_read_b64 v[94:95], v113 offset:53248
	v_mfma_f32_16x16x32_bf16 v[72:75], v[88:91], v[84:87], v[72:75]
	ds_read_b64 v[88:89], v114 offset:57344
	ds_read_b64 v[90:91], v113 offset:57344
	ds_read_b64 v[96:97], v114 offset:61440
	ds_read_b64 v[98:99], v113 offset:61440
	s_waitcnt lgkmcnt(0)
	v_mfma_f32_16x16x32_bf16 v[80:83], v[88:91], v[84:87], v[80:83]
	ds_read_b64 v[88:89], v116 offset:32768
	ds_read_b64 v[90:91], v115 offset:32768
	v_mfma_f32_16x16x32_bf16 v[76:79], v[92:95], v[84:87], v[76:79]
	ds_read_b64 v[92:93], v116 offset:36864
	ds_read_b64 v[94:95], v115 offset:36864
	v_mfma_f32_16x16x32_bf16 v[54:57], v[96:99], v[84:87], v[56:59]
	v_cvt_pk_bf16_f32 v84,v100,v37
	v_cvt_pk_bf16_f32 v85,v38,v101
	v_cvt_pk_bf16_f32 v86,v104,v40
	v_cvt_pk_bf16_f32 v87,v41,v105
	v_mul_f32_e32 v40, v36, v39
	s_waitcnt lgkmcnt(0)
	v_mfma_f32_16x16x32_bf16 v[50:53], v[88:91], v[84:87], v[50:53]
	ds_read_b64 v[88:89], v116 offset:40960
	ds_read_b64 v[90:91], v115 offset:40960
	v_cvt_pk_bf16_f32 v47,v40,v47
	v_mfma_f32_16x16x32_bf16 v[58:61], v[92:95], v[84:87], v[60:63]
	ds_read_b64 v[92:93], v116 offset:45056
	ds_read_b64 v[94:95], v115 offset:45056
	s_waitcnt lgkmcnt(0)
	v_mfma_f32_16x16x32_bf16 v[62:65], v[88:91], v[84:87], v[64:67]
	ds_read_b64 v[88:89], v116 offset:49152
	ds_read_b64 v[90:91], v115 offset:49152
	v_mfma_f32_16x16x32_bf16 v[66:69], v[92:95], v[84:87], v[68:71]
	ds_read_b64 v[92:93], v116 offset:53248
	ds_read_b64 v[94:95], v115 offset:53248
	s_waitcnt lgkmcnt(0)
	v_mfma_f32_16x16x32_bf16 v[70:73], v[88:91], v[84:87], v[72:75]
	ds_read_b64 v[88:89], v116 offset:57344
	ds_read_b64 v[90:91], v115 offset:57344
	v_mfma_f32_16x16x32_bf16 v[74:77], v[92:95], v[84:87], v[76:79]
	ds_read_b64 v[92:93], v116 offset:61440
	ds_read_b64 v[94:95], v115 offset:61440
	s_waitcnt lgkmcnt(0)
	v_mfma_f32_16x16x32_bf16 v[78:81], v[88:91], v[84:87], v[80:83]
	ds_read_b64 v[88:89], v150 offset:32768
	ds_read_b64 v[90:91], v117 offset:32768
	v_mfma_f32_16x16x32_bf16 v[36:39], v[92:95], v[84:87], v[54:57]
	s_waitcnt lgkmcnt(0)
	v_mfma_f32_16x16x32_bf16 v[48:51], v[88:91], v[44:47], v[50:53]
	s_nop 2
	ds_read_b64 v[52:53], v150 offset:36864
	ds_read_b64 v[54:55], v117 offset:36864
	s_waitcnt lgkmcnt(0)
	v_mfma_f32_16x16x32_bf16 v[52:55], v[52:55], v[44:47], v[58:61]
	ds_read_b64 v[56:57], v150 offset:40960
	s_nop 1
	ds_read_b64 v[58:59], v117 offset:40960
	s_waitcnt lgkmcnt(0)
; __device__ __forceinline__ void nsa_cmp_head(const bf16x8 (&qf)[4], const char* ldsKC, const char* ldsVC, int t, int l, int fr, int fq,
;                                              float sc, float sl, float g_cmp, float* imp_dst, float* P) {
;     ...
; #pragma unroll
;   for (int dt = 0; dt < 8; ++dt)
;     *reinterpret_cast<f32x4*>(P + 16 * dt) = f32x4{oc[dt][0] * g_cmp, oc[dt][1] * g_cmp, oc[dt][2] * g_cmp, oc[dt][3] * g_cmp};
; __device__ __forceinline__ void nsa_item2(const Params& p, int item, char* lds, unsigned* lds_um, int tid) {
;     ...
;   __syncthreads();
;   const int cur = tile;
;   unsigned selmask;
;   if (cur < 16) {
;     selmask = (2u << cur) - 1u;
;   } else {
;     const float* src = lds_imp + (tq * 4 * 16 + fr) * 32;
;     float vals[32];
; #pragma unroll
;     for (int q4 = 0; q4 < 8; ++q4) {
;       f32x4 a = *reinterpret_cast<const f32x4*>(src + q4 * 4);
;       f32x4 b1 = *reinterpret_cast<const f32x4*>(src + 512 + q4 * 4);
;       f32x4 c1 = *reinterpret_cast<const f32x4*>(src + 1024 + q4 * 4);
;       f32x4 d1 = *reinterpret_cast<const f32x4*>(src + 1536 + q4 * 4);
; #pragma unroll
;       for (int e = 0; e < 4; ++e) {
;         const int sidx = q4 * 4 + e;
;         const float v = (a[e] + b1[e]) + (c1[e] + d1[e]);
;         const bool forced = (sidx == 0) || (sidx == cur) || (sidx == cur - 1);
;         vals[sidx] = forced ? 1e9f : (sidx > cur ? -1e9f : v);
;       }
;     }
	v_mfma_f32_16x16x32_bf16 v[56:59], v[56:59], v[44:47], v[62:65]
	ds_read_b64 v[60:61], v150 offset:45056
	s_nop 1
	ds_read_b64 v[62:63], v117 offset:45056
	s_waitcnt lgkmcnt(0)
	v_mfma_f32_16x16x32_bf16 v[60:63], v[60:63], v[44:47], v[66:69]
	ds_read_b64 v[64:65], v150 offset:49152
	s_nop 1
	ds_read_b64 v[66:67], v117 offset:49152
	s_waitcnt lgkmcnt(0)
	v_mfma_f32_16x16x32_bf16 v[64:67], v[64:67], v[44:47], v[70:73]
	ds_read_b64 v[68:69], v150 offset:53248
	s_nop 1
	ds_read_b64 v[70:71], v117 offset:53248
	s_waitcnt lgkmcnt(0)
	v_mfma_f32_16x16x32_bf16 v[68:71], v[68:71], v[44:47], v[74:77]
	ds_read_b64 v[72:73], v150 offset:57344
	s_nop 1
	ds_read_b64 v[74:75], v117 offset:57344
	s_waitcnt lgkmcnt(0)
	v_mfma_f32_16x16x32_bf16 v[72:75], v[72:75], v[44:47], v[78:81]
	ds_read_b64 v[76:77], v150 offset:61440
	s_nop 1
	ds_read_b64 v[78:79], v117 offset:61440
	s_waitcnt lgkmcnt(0)
	v_mfma_f32_16x16x32_bf16 v[36:39], v[76:79], v[44:47], v[36:39]
	v_mul_f32_e64 v46, v0, v50
	v_mul_f32_e64 v47, v0, v51
	v_pk_mul_f32 v[44:45], v[0:1], v[48:49] op_sel_hi:[0,1]
	global_store_dwordx4 v[126:127], v[44:47], off offset:512
	s_nop 3
	v_pk_mul_f32 v[38:39], v[0:1], v[38:39] op_sel_hi:[0,1]
	v_pk_mul_f32 v[36:37], v[0:1], v[36:37] op_sel_hi:[0,1]
	v_pk_mul_f32 v[46:47], v[0:1], v[54:55] op_sel_hi:[0,1]
	v_pk_mul_f32 v[44:45], v[0:1], v[52:53] op_sel_hi:[0,1]
	global_store_dwordx4 v[126:127], v[44:47], off offset:576
	global_store_dwordx4 v[126:127], v[36:39], off offset:960
	s_nop 0
	v_pk_mul_f32 v[46:47], v[0:1], v[58:59] op_sel_hi:[0,1]
	v_pk_mul_f32 v[44:45], v[0:1], v[56:57] op_sel_hi:[0,1]
	global_store_dwordx4 v[126:127], v[44:47], off offset:640
	s_nop 1
	v_pk_mul_f32 v[46:47], v[0:1], v[62:63] op_sel_hi:[0,1]
	v_pk_mul_f32 v[44:45], v[0:1], v[60:61] op_sel_hi:[0,1]
	global_store_dwordx4 v[126:127], v[44:47], off offset:704
	s_nop 1
	v_pk_mul_f32 v[46:47], v[0:1], v[66:67] op_sel_hi:[0,1]
	v_pk_mul_f32 v[44:45], v[0:1], v[64:65] op_sel_hi:[0,1]
	global_store_dwordx4 v[126:127], v[44:47], off offset:768
	s_nop 1
	v_pk_mul_f32 v[46:47], v[0:1], v[70:71] op_sel_hi:[0,1]
	v_pk_mul_f32 v[44:45], v[0:1], v[68:69] op_sel_hi:[0,1]
	global_store_dwordx4 v[126:127], v[44:47], off offset:832
	s_nop 1
	v_pk_mul_f32 v[46:47], v[0:1], v[74:75] op_sel_hi:[0,1]
	v_pk_mul_f32 v[44:45], v[0:1], v[72:73] op_sel_hi:[0,1]
	global_store_dwordx4 v[126:127], v[44:47], off offset:896
	s_waitcnt lgkmcnt(0)
	s_barrier
	s_cbranch_vccz .LBB0_139
	v_lshlrev_b32_e32 v0, 5, v120
	v_lshl_add_u32 v96, v0, 2, v42
	ds_read_b128 v[100:103], v96
	ds_read_b128 v[52:55], v96 offset:16
	ds_read_b128 v[40:43], v96 offset:32
	ds_read_b128 v[36:39], v96 offset:48
	ds_read_b128 v[112:115], v96 offset:2048
	ds_read_b128 v[104:107], v96 offset:4096
	ds_read_b128 v[108:111], v96 offset:6144
	ds_read_b128 v[56:59], v96 offset:2064
	ds_read_b128 v[60:63], v96 offset:4112
	ds_read_b128 v[64:67], v96 offset:6160
	ds_read_b128 v[44:47], v96 offset:2080
	ds_read_b128 v[48:51], v96 offset:4128
	ds_read_b128 v[68:71], v96 offset:6176
	s_cmp_eq_u32 s74, 15
	s_cselect_b64 vcc, -1, 0
	s_waitcnt lgkmcnt(0)
	v_pk_add_f32 v[2:3], v[42:43], v[46:47]
	v_pk_add_f32 v[40:41], v[40:41], v[44:45]
	v_pk_add_f32 v[42:43], v[50:51], v[70:71]
	v_pk_add_f32 v[44:45], v[48:49], v[68:69]
	v_pk_add_f32 v[116:117], v[2:3], v[42:43]
	v_pk_add_f32 v[2:3], v[40:41], v[44:45]
	ds_read_b128 v[40:43], v96 offset:2096
	ds_read_b128 v[44:47], v96 offset:4144
	ds_read_b128 v[48:51], v96 offset:6192
	ds_read_b128 v[68:71], v96 offset:64
	ds_read_b128 v[72:75], v96 offset:2112
	ds_read_b128 v[76:79], v96 offset:4160
	ds_read_b128 v[80:83], v96 offset:6208
	s_and_b32 s14, s78, 0xffffffe0
	s_waitcnt lgkmcnt(0)
	v_mov_b32_e32 v84, v68
	s_add_i32 s0, s74, -13
	v_mov_b32_e32 v85, v76
	v_mov_b32_e32 v87, v80
	v_mov_b32_e32 v76, v69
	v_mov_b32_e32 v80, v73
	v_pk_add_f32 v[68:69], v[76:77], v[80:81]
	s_add_i32 s1, s74, -11
	v_add_f32_e32 v0, v68, v69
	v_pk_add_f32 v[68:69], v[70:71], v[74:75]
	v_pk_add_f32 v[70:71], v[78:79], v[82:83]
	s_cmp_lt_i32 s74, 14
	v_pk_add_f32 v[68:69], v[68:69], v[70:71]
	s_cselect_b64 s[8:9], -1, 0
	s_cmp_lt_i32 s74, 13
	v_cndmask_b32_e64 v68, v171, v68, s[8:9]
	s_cselect_b64 s[8:9], -1, 0
	s_cmp_gt_u32 s0, 1
	v_cndmask_b32_e32 v0, v0, v171, vcc
	v_cndmask_b32_e64 v69, v171, v69, s[8:9]
	s_cselect_b64 s[8:9], -1, 0
	s_cmp_gt_u32 s1, 1
	v_mov_b32_e32 v86, v72
	v_cndmask_b32_e64 v0, v172, v0, s[8:9]
	s_cselect_b64 s[8:9], -1, 0
	s_cmpk_lg_i32 s14, 0xc0
	v_pk_add_f32 v[84:85], v[84:85], v[86:87]
	v_cndmask_b32_e64 v135, v172, v69, s[8:9]
	s_cselect_b64 s[8:9], -1, 0
	s_cmpk_lg_i32 s14, 0xe0
	v_pk_add_f32 v[84:85], v[84:85], v[84:85] op_sel:[0,1] op_sel_hi:[1,0]
	v_cndmask_b32_e64 v150, v172, v68, s[8:9]
	s_cselect_b64 s[8:9], -1, 0
	v_cndmask_b32_e64 v130, v172, v84, s[8:9]
	ds_read_b128 v[72:75], v96 offset:80
	ds_read_b128 v[68:71], v96 offset:2128
	ds_read_b128 v[76:79], v96 offset:4176
	ds_read_b128 v[80:83], v96 offset:6224
	ds_read_b128 v[84:87], v96 offset:96
	ds_read_b128 v[88:91], v96 offset:2144
	ds_read_b128 v[92:95], v96 offset:4192
	ds_read_b128 v[152:155], v96 offset:6240
	s_add_i32 s0, s74, -5
	s_add_i32 s1, s74, -3
	s_waitcnt lgkmcnt(0)
	v_pk_add_f32 v[86:87], v[86:87], v[90:91]
	v_pk_add_f32 v[84:85], v[84:85], v[88:89]
	v_pk_add_f32 v[88:89], v[94:95], v[154:155]
	s_cmp_lt_i32 s74, 6
	v_pk_add_f32 v[86:87], v[86:87], v[88:89]
	s_cselect_b64 s[8:9], -1, 0
	s_cmp_lt_i32 s74, 5
	v_pk_add_f32 v[90:91], v[92:93], v[152:153]
	v_cndmask_b32_e64 v86, v171, v86, s[8:9]
	s_cselect_b64 s[8:9], -1, 0
	s_cmp_lt_i32 s74, 8
	v_pk_add_f32 v[84:85], v[84:85], v[90:91]
	v_cndmask_b32_e64 v87, v171, v87, s[8:9]
	s_cselect_b64 s[8:9], -1, 0
	s_cmp_lt_i32 s74, 7
	v_cndmask_b32_e64 v84, v171, v84, s[8:9]
	s_cselect_b64 s[8:9], -1, 0
	s_cmp_gt_u32 s1, 1
	v_cndmask_b32_e64 v85, v171, v85, s[8:9]
	s_cselect_b64 s[8:9], -1, 0
	s_cmp_lg_u32 s14, 64
	v_cndmask_b32_e64 v151, v172, v87, s[8:9]
	s_cselect_b64 s[8:9], -1, 0
	s_cmp_gt_u32 s0, 1
	v_cndmask_b32_e64 v152, v172, v86, s[8:9]
	s_cselect_b64 s[8:9], -1, 0
	s_cmpk_lg_i32 s14, 0x60
	v_cndmask_b32_e64 v153, v172, v85, s[8:9]
	s_cselect_b64 s[8:9], -1, 0
	v_cndmask_b32_e64 v154, v172, v84, s[8:9]
	ds_read_b128 v[84:87], v96 offset:112
	ds_read_b128 v[88:91], v96 offset:2160
	ds_read_b128 v[92:95], v96 offset:4208
	ds_read_b128 v[96:99], v96 offset:6256
	v_writelane_b32 v247, s2, 22
	s_nop 1
	v_writelane_b32 v247, s3, 23
	s_and_saveexec_b64 s[0:1], s[6:7]
	s_xor_b64 s[0:1], exec, s[0:1]
	s_cbranch_execz .LBB0_73
	v_cmp_lt_i32_e64 s[8:9], 1, v118
	s_mov_b64 s[2:3], 0
	s_and_saveexec_b64 s[10:11], s[8:9]
	s_xor_b64 s[10:11], exec, s[10:11]
	s_cbranch_execnz .LBB0_189
	s_andn2_saveexec_b64 s[10:11], s[10:11]
	s_cbranch_execnz .LBB0_192

; __device__ __forceinline__ float bflo(unsigned u) { return __uint_as_float(u << 16); }
; __device__ __forceinline__ float bfhi(unsigned u) { return __uint_as_float(u & 0xffff0000u); }
; #define MFMA(a, b, c) __builtin_amdgcn_mfma_f32_16x16x32_bf16((a), (b), (c), 0, 0, 0)
; __device__ __forceinline__ void compress_unit(const Params& p, int unit, char* lds, int tid) {
;     ...
;   for (int ib = 0; ib < 8; ++ib) {
;     u32x4 raw[16]; bf16x8 wf[16];
; #pragma unroll
;     for (int ii = 0; ii < 4; ++ii)
; #pragma unroll
;       for (int q4 = 0; q4 < 4; ++q4) {
;         const int i = ib * 4 + ii;
;         raw[ii * 4 + q4] = *reinterpret_cast<const u32x4*>(srow + (long)i * INWP + q4 * 32);
;         wf[ii * 4 + q4] = ld8(wrow + i * 128 + q4 * 32);
;       }
;     __builtin_amdgcn_sched_barrier(0);
; #pragma unroll
;     for (int ii = 0; ii < 4; ++ii)
; #pragma unroll
;       for (int q4 = 0; q4 < 4; ++q4) {
;         const int i = ib * 4 + ii;
;         const float* pp = lpos + i * 128 + q4 * 32 + fq * 8;
;         const f32x4 p0 = *reinterpret_cast<const f32x4*>(pp), p1 = *reinterpret_cast<const f32x4*>(pp + 4);
;         const u32x4 r = raw[ii * 4 + q4];
;         u32x4 bb = {pk2(bflo(r[0]) + p0[0], bfhi(r[0]) + p0[1]), pk2(bflo(r[1]) + p0[2], bfhi(r[1]) + p0[3]),
;                     pk2(bflo(r[2]) + p1[0], bfhi(r[2]) + p1[1]), pk2(bflo(r[3]) + p1[2], bfhi(r[3]) + p1[3])};
;         acc = MFMA(wf[ii * 4 + q4], mk8(bb), acc);
.LBB0_218:
	v_lshl_add_u64 v[2:3], v[120:121], 0, v[0:1]
	v_add_co_u32_e32 v6, vcc, 0x1e410000, v2
	v_lshl_add_u64 v[4:5], v[118:119], 0, v[0:1]
	s_nop 0
	v_addc_co_u32_e32 v7, vcc, 0, v3, vcc
	v_add_co_u32_e32 v4, vcc, 0x13000000, v4
	s_nop 1
	v_addc_co_u32_e32 v5, vcc, 0, v5, vcc
	v_add_co_u32_e32 v10, vcc, 0x1e416000, v2
	global_load_dwordx4 v[126:129], v[6:7], off
	global_load_dwordx4 v[136:139], v[6:7], off offset:64
	global_load_dwordx4 v[102:105], v[4:5], off
	global_load_dwordx4 v[86:89], v[4:5], off offset:64
	global_load_dwordx4 v[140:143], v[6:7], off offset:128
	global_load_dwordx4 v[144:147], v[6:7], off offset:192
	global_load_dwordx4 v[54:57], v[4:5], off offset:128
	s_nop 0
	global_load_dwordx4 v[6:9], v[4:5], off offset:192
	v_addc_co_u32_e32 v11, vcc, 0, v3, vcc
	v_add_co_u32_e32 v14, vcc, 0x1e41d000, v2
	global_load_dwordx4 v[148:151], v[10:11], off offset:2560
	global_load_dwordx4 v[110:113], v[10:11], off offset:2624
	global_load_dwordx4 v[42:45], v[4:5], off offset:256
	global_load_dwordx4 v[18:21], v[4:5], off offset:320
	global_load_dwordx4 v[106:109], v[10:11], off offset:2688
	global_load_dwordx4 v[98:101], v[10:11], off offset:2752
	global_load_dwordx4 v[22:25], v[4:5], off offset:384
	s_nop 0
	global_load_dwordx4 v[10:13], v[4:5], off offset:448
	v_addc_co_u32_e32 v15, vcc, 0, v3, vcc
	v_add_co_u32_e32 v2, vcc, 0x1e423000, v2
	global_load_dwordx4 v[94:97], v[14:15], off offset:1024
	global_load_dwordx4 v[90:93], v[14:15], off offset:1088
	global_load_dwordx4 v[46:49], v[4:5], off offset:512
	global_load_dwordx4 v[26:29], v[4:5], off offset:576
	global_load_dwordx4 v[82:85], v[14:15], off offset:1152
	global_load_dwordx4 v[78:81], v[14:15], off offset:1216
	global_load_dwordx4 v[30:33], v[4:5], off offset:640
	s_nop 0
	global_load_dwordx4 v[14:17], v[4:5], off offset:704
	v_addc_co_u32_e32 v3, vcc, 0, v3, vcc
	global_load_dwordx4 v[74:77], v[2:3], off offset:3584
	global_load_dwordx4 v[70:73], v[2:3], off offset:3648
	global_load_dwordx4 v[50:53], v[4:5], off offset:768
	global_load_dwordx4 v[34:37], v[4:5], off offset:832
	global_load_dwordx4 v[62:65], v[2:3], off offset:3712
	global_load_dwordx4 v[58:61], v[2:3], off offset:3776
	global_load_dwordx4 v[38:41], v[4:5], off offset:896
	s_nop 0
	global_load_dwordx4 v[2:5], v[4:5], off offset:960
	v_add_u32_e32 v124, s0, v117
	s_waitcnt vmcnt(0) lgkmcnt(0)
	v_lshlrev_b32_e32 v125, 16, v126
	v_and_b32_e32 v130, 0xffff0000, v126
	v_lshlrev_b32_e32 v131, 16, v127
	v_and_b32_e32 v152, 0xffff0000, v127
	v_lshlrev_b32_e32 v153, 16, v128
	v_and_b32_e32 v154, 0xffff0000, v128
	v_lshlrev_b32_e32 v155, 16, v129
	v_and_b32_e32 v156, 0xffff0000, v129
	ds_read_b128 v[126:129], v124
	v_lshlrev_b32_e32 v210, 16, v90
	v_and_b32_e32 v211, 0xffff0000, v90
	v_lshlrev_b32_e32 v212, 16, v91
	v_and_b32_e32 v213, 0xffff0000, v91
	v_lshlrev_b32_e32 v214, 16, v92
	v_and_b32_e32 v215, 0xffff0000, v92
	v_lshlrev_b32_e32 v216, 16, v93
	v_and_b32_e32 v217, 0xffff0000, v93
	ds_read_b128 v[90:93], v124 offset:272
	s_waitcnt lgkmcnt(1)
	v_add_f32_e32 v125, v126, v125
	v_add_f32_e32 v130, v127, v130
	v_add_f32_e32 v131, v128, v131
	v_add_f32_e32 v152, v129, v152
	ds_read_b128 v[126:129], v124 offset:16
	v_lshlrev_b32_e32 v187, 16, v111
	v_and_b32_e32 v188, 0xffff0000, v111
	v_lshlrev_b32_e32 v189, 16, v112
	v_and_b32_e32 v190, 0xffff0000, v112
	s_waitcnt lgkmcnt(0)
	v_add_f32_e32 v126, v126, v153
	v_add_f32_e32 v127, v127, v154
	v_add_f32_e32 v128, v128, v155
	v_add_f32_e32 v129, v129, v156
	v_lshlrev_b32_e32 v155, 16, v110
	v_and_b32_e32 v156, 0xffff0000, v110
	v_lshlrev_b32_e32 v191, 16, v113
	v_and_b32_e32 v192, 0xffff0000, v113
	v_cvt_pk_bf16_f32 v110,v125,v130
	v_cvt_pk_bf16_f32 v111,v131,v152
	v_cvt_pk_bf16_f32 v112,v126,v127
	v_cvt_pk_bf16_f32 v113,v128,v129
	v_lshlrev_b32_e32 v157, 16, v136
	v_mfma_f32_16x16x32_bf16 v[66:69], v[102:105], v[110:113], v[66:69]
	ds_read_b128 v[102:105], v124 offset:128
	ds_read_b128 v[128:131], v124 offset:656
	v_and_b32_e32 v136, 0xffff0000, v136
	v_lshlrev_b32_e32 v158, 16, v137
	v_and_b32_e32 v137, 0xffff0000, v137
	v_lshlrev_b32_e32 v125, 16, v106
	v_and_b32_e32 v126, 0xffff0000, v106
	v_lshlrev_b32_e32 v152, 16, v107
	v_and_b32_e32 v193, 0xffff0000, v107
	v_lshlrev_b32_e32 v194, 16, v108
	v_and_b32_e32 v195, 0xffff0000, v108
	v_lshlrev_b32_e32 v198, 16, v98
	v_and_b32_e32 v199, 0xffff0000, v98
	s_waitcnt lgkmcnt(1)
	v_add_f32_e32 v98, v102, v157
	v_add_f32_e32 v106, v103, v136
	v_add_f32_e32 v107, v104, v158
	v_add_f32_e32 v108, v105, v137
	ds_read_b128 v[102:105], v124 offset:144
	v_lshlrev_b32_e32 v159, 16, v138
	v_and_b32_e32 v138, 0xffff0000, v138
	v_lshlrev_b32_e32 v160, 16, v139
	v_and_b32_e32 v139, 0xffff0000, v139
	v_lshlrev_b32_e32 v196, 16, v109
	v_and_b32_e32 v197, 0xffff0000, v109
	v_lshlrev_b32_e32 v202, 16, v94
	v_and_b32_e32 v203, 0xffff0000, v94
	v_lshlrev_b32_e32 v204, 16, v95
	v_and_b32_e32 v205, 0xffff0000, v95
	v_lshlrev_b32_e32 v206, 16, v96
	v_and_b32_e32 v207, 0xffff0000, v96
	v_lshlrev_b32_e32 v208, 16, v97
	v_and_b32_e32 v209, 0xffff0000, v97
	v_cvt_pk_bf16_f32 v94,v98,v106
	v_cvt_pk_bf16_f32 v95,v107,v108
	ds_read_b128 v[108:111], v124 offset:528
	s_waitcnt lgkmcnt(1)
; __device__ __forceinline__ float bflo(unsigned u) { return __uint_as_float(u << 16); }
; __device__ __forceinline__ float bfhi(unsigned u) { return __uint_as_float(u & 0xffff0000u); }
; #define MFMA(a, b, c) __builtin_amdgcn_mfma_f32_16x16x32_bf16((a), (b), (c), 0, 0, 0)
; __device__ __forceinline__ void compress_unit(const Params& p, int unit, char* lds, int tid) {
;     ...
; #pragma unroll
;     for (int ii = 0; ii < 4; ++ii)
; #pragma unroll
;       for (int q4 = 0; q4 < 4; ++q4) {
;         const int i = ib * 4 + ii;
;         const float* pp = lpos + i * 128 + q4 * 32 + fq * 8;
;         const f32x4 p0 = *reinterpret_cast<const f32x4*>(pp), p1 = *reinterpret_cast<const f32x4*>(pp + 4);
;         const u32x4 r = raw[ii * 4 + q4];
;         u32x4 bb = {pk2(bflo(r[0]) + p0[0], bfhi(r[0]) + p0[1]), pk2(bflo(r[1]) + p0[2], bfhi(r[1]) + p0[3]),
;                     pk2(bflo(r[2]) + p1[0], bfhi(r[2]) + p1[1]), pk2(bflo(r[3]) + p1[2], bfhi(r[3]) + p1[3])};
;         acc = MFMA(wf[ii * 4 + q4], mk8(bb), acc);
	v_add_f32_e32 v102, v102, v159
	v_add_f32_e32 v103, v103, v138
	v_add_f32_e32 v104, v104, v160
	v_add_f32_e32 v105, v105, v139
	v_cvt_pk_bf16_f32 v96,v102,v103
	v_cvt_pk_bf16_f32 v97,v104,v105
	v_lshlrev_b32_e32 v200, 16, v99
	v_and_b32_e32 v157, 0xffff0000, v99
	v_lshlrev_b32_e32 v158, 16, v100
	v_and_b32_e32 v159, 0xffff0000, v100
	v_lshlrev_b32_e32 v160, 16, v101
	v_and_b32_e32 v201, 0xffff0000, v101
	v_mfma_f32_16x16x32_bf16 v[66:69], v[86:89], v[94:97], v[66:69]
	ds_read_b128 v[86:89], v124 offset:256
	ds_read_b128 v[94:97], v124 offset:384
	ds_read_b128 v[98:101], v124 offset:400
	ds_read_b128 v[102:105], v124 offset:512
	v_lshlrev_b32_e32 v161, 16, v140
	v_and_b32_e32 v140, 0xffff0000, v140
	v_lshlrev_b32_e32 v162, 16, v141
	v_and_b32_e32 v141, 0xffff0000, v141
	v_lshlrev_b32_e32 v163, 16, v142
	v_and_b32_e32 v142, 0xffff0000, v142
	v_lshlrev_b32_e32 v164, 16, v143
	v_and_b32_e32 v143, 0xffff0000, v143
	v_lshlrev_b32_e32 v165, 16, v144
	v_and_b32_e32 v144, 0xffff0000, v144
	v_lshlrev_b32_e32 v182, 16, v145
	v_and_b32_e32 v145, 0xffff0000, v145
	v_lshlrev_b32_e32 v183, 16, v146
	v_and_b32_e32 v146, 0xffff0000, v146
	v_lshlrev_b32_e32 v184, 16, v147
	v_and_b32_e32 v147, 0xffff0000, v147
	v_lshlrev_b32_e32 v185, 16, v148
	v_and_b32_e32 v148, 0xffff0000, v148
	v_lshlrev_b32_e32 v186, 16, v149
	v_and_b32_e32 v149, 0xffff0000, v149
	v_lshlrev_b32_e32 v154, 16, v151
	v_and_b32_e32 v151, 0xffff0000, v151
	v_lshlrev_b32_e32 v218, 16, v82
	v_and_b32_e32 v219, 0xffff0000, v82
	s_waitcnt lgkmcnt(3)
	v_add_f32_e32 v82, v86, v161
	v_add_f32_e32 v86, v87, v140
	v_add_f32_e32 v87, v88, v162
	v_add_f32_e32 v88, v89, v141
	v_add_f32_e32 v89, v90, v163
	v_add_f32_e32 v90, v91, v142
	v_add_f32_e32 v91, v92, v164
	v_add_f32_e32 v92, v93, v143
	s_waitcnt lgkmcnt(2)
	v_add_f32_e32 v93, v94, v165
	v_add_f32_e32 v94, v95, v144
	v_add_f32_e32 v95, v96, v182
	v_add_f32_e32 v96, v97, v145
	s_waitcnt lgkmcnt(1)
	v_add_f32_e32 v97, v98, v183
	v_add_f32_e32 v98, v99, v146
	v_add_f32_e32 v99, v100, v184
	v_add_f32_e32 v100, v101, v147
	s_waitcnt lgkmcnt(0)
	v_add_f32_e32 v101, v102, v185
	v_add_f32_e32 v102, v103, v148
	v_add_f32_e32 v103, v104, v186
	v_add_f32_e32 v104, v105, v149
	v_add_f32_e32 v105, v110, v154
	v_add_f32_e32 v107, v111, v151
	ds_read_b128 v[110:113], v124 offset:640
	ds_read_b128 v[138:141], v124 offset:768
	v_lshlrev_b32_e32 v153, 16, v150
	v_and_b32_e32 v150, 0xffff0000, v150
	v_add_f32_e32 v106, v108, v153
	v_add_f32_e32 v108, v109, v150
	s_waitcnt lgkmcnt(1)
	v_add_f32_e32 v109, v110, v155
	v_add_f32_e32 v127, v113, v188
	v_add_f32_e32 v113, v128, v189
	v_add_f32_e32 v128, v129, v190
	v_add_f32_e32 v129, v130, v191
	s_waitcnt lgkmcnt(0)
	v_add_f32_e32 v125, v138, v125
	v_add_f32_e32 v130, v139, v126
	v_add_f32_e32 v110, v140, v152
	v_add_f32_e32 v126, v141, v193
	ds_read_b128 v[138:141], v124 offset:784
	ds_read_b128 v[146:149], v124 offset:912
	v_add_f32_e32 v136, v131, v192
	ds_read_b128 v[152:155], v124 offset:1040
	v_add_f32_e32 v111, v111, v156
	s_waitcnt lgkmcnt(2)
	v_add_f32_e32 v131, v138, v194
	v_add_f32_e32 v137, v139, v195
	v_add_f32_e32 v138, v140, v196
	v_add_f32_e32 v139, v141, v197
	ds_read_b128 v[140:143], v124 offset:896
	s_waitcnt lgkmcnt(2)
	v_add_f32_e32 v144, v146, v158
	v_add_f32_e32 v146, v147, v159
	v_add_f32_e32 v145, v148, v160
	ds_read_b128 v[158:161], v124 offset:1152
	v_add_f32_e32 v147, v149, v201
	ds_read_b128 v[148:151], v124 offset:1024
	s_waitcnt lgkmcnt(2)
	v_add_f32_e32 v143, v143, v157
	ds_read_b128 v[182:185], v124 offset:1280
	s_waitcnt lgkmcnt(2)
	v_add_f32_e32 v156, v158, v210
	v_add_f32_e32 v158, v159, v211
	v_add_f32_e32 v157, v160, v212
	v_add_f32_e32 v159, v161, v213
	ds_read_b128 v[160:163], v124 offset:1168
	v_lshlrev_b32_e32 v220, 16, v83
	v_and_b32_e32 v83, 0xffff0000, v83
	v_add_f32_e32 v112, v112, v187
	s_waitcnt lgkmcnt(1)
	v_add_f32_e32 v164, v182, v218
	v_add_f32_e32 v182, v184, v220
	v_add_f32_e32 v83, v185, v83
	ds_read_b128 v[184:187], v124 offset:1296
	v_add_f32_e32 v165, v183, v219
	v_lshlrev_b32_e32 v183, 16, v84
	v_and_b32_e32 v188, 0xffff0000, v84
	v_lshlrev_b32_e32 v189, 16, v85
	v_and_b32_e32 v190, 0xffff0000, v85
	s_waitcnt lgkmcnt(0)
	v_add_f32_e32 v84, v184, v183
	v_add_f32_e32 v183, v185, v188
	v_add_f32_e32 v85, v186, v189
	v_add_f32_e32 v184, v187, v190
	ds_read_b128 v[186:189], v124 offset:1408
	v_lshlrev_b32_e32 v185, 16, v78
	v_and_b32_e32 v78, 0xffff0000, v78
	v_and_b32_e32 v192, 0xffff0000, v80
	v_lshlrev_b32_e32 v193, 16, v81
	s_waitcnt lgkmcnt(0)
	v_add_f32_e32 v185, v186, v185
	v_lshlrev_b32_e32 v186, 16, v79
	v_and_b32_e32 v79, 0xffff0000, v79
	v_add_f32_e32 v186, v188, v186
	v_add_f32_e32 v79, v189, v79
	ds_read_b128 v[188:191], v124 offset:1424
	v_add_f32_e32 v78, v187, v78
	v_lshlrev_b32_e32 v187, 16, v80
	v_and_b32_e32 v194, 0xffff0000, v81
	v_add_f32_e32 v140, v140, v198
	s_waitcnt lgkmcnt(0)
	v_add_f32_e32 v80, v188, v187
	v_add_f32_e32 v81, v189, v192
	v_add_f32_e32 v187, v190, v193
	v_add_f32_e32 v188, v191, v194
	ds_read_b128 v[190:193], v124 offset:1536
	v_lshlrev_b32_e32 v189, 16, v74
	v_and_b32_e32 v74, 0xffff0000, v74
	v_and_b32_e32 v196, 0xffff0000, v76
	v_lshlrev_b32_e32 v197, 16, v77
	s_waitcnt lgkmcnt(0)
	v_add_f32_e32 v189, v190, v189
	v_lshlrev_b32_e32 v190, 16, v75
	v_and_b32_e32 v75, 0xffff0000, v75
	v_add_f32_e32 v190, v192, v190
	v_add_f32_e32 v75, v193, v75
	ds_read_b128 v[192:195], v124 offset:1552
	v_add_f32_e32 v74, v191, v74
	v_lshlrev_b32_e32 v191, 16, v76
	v_and_b32_e32 v198, 0xffff0000, v77
	v_add_f32_e32 v141, v141, v199
	s_waitcnt lgkmcnt(0)
; __device__ __forceinline__ float bflo(unsigned u) { return __uint_as_float(u << 16); }
; __device__ __forceinline__ float bfhi(unsigned u) { return __uint_as_float(u & 0xffff0000u); }
; #define MFMA(a, b, c) __builtin_amdgcn_mfma_f32_16x16x32_bf16((a), (b), (c), 0, 0, 0)
; __device__ __forceinline__ void compress_unit(const Params& p, int unit, char* lds, int tid) {
;     ...
; #pragma unroll
;     for (int ii = 0; ii < 4; ++ii)
; #pragma unroll
;       for (int q4 = 0; q4 < 4; ++q4) {
;         const int i = ib * 4 + ii;
;         const float* pp = lpos + i * 128 + q4 * 32 + fq * 8;
;         const f32x4 p0 = *reinterpret_cast<const f32x4*>(pp), p1 = *reinterpret_cast<const f32x4*>(pp + 4);
;         const u32x4 r = raw[ii * 4 + q4];
;         u32x4 bb = {pk2(bflo(r[0]) + p0[0], bfhi(r[0]) + p0[1]), pk2(bflo(r[1]) + p0[2], bfhi(r[1]) + p0[3]),
;                     pk2(bflo(r[2]) + p1[0], bfhi(r[2]) + p1[1]), pk2(bflo(r[3]) + p1[2], bfhi(r[3]) + p1[3])};
;         acc = MFMA(wf[ii * 4 + q4], mk8(bb), acc);
;       }
;     __builtin_amdgcn_sched_barrier(0);
;   }
;   float* part = reinterpret_cast<float*>(lds);
;   *reinterpret_cast<f32x4*>(part + fr * 128 + 16 * w + fq * 4) = acc;
;   __syncthreads();
	v_add_f32_e32 v76, v192, v191
	v_add_f32_e32 v77, v193, v196
	v_add_f32_e32 v191, v194, v197
	v_add_f32_e32 v192, v195, v198
	ds_read_b128 v[194:197], v124 offset:1664
	v_lshlrev_b32_e32 v193, 16, v70
	v_and_b32_e32 v70, 0xffff0000, v70
	v_add_f32_e32 v142, v142, v200
	v_lshlrev_b32_e32 v199, 16, v72
	s_waitcnt lgkmcnt(0)
	v_add_f32_e32 v193, v194, v193
	v_lshlrev_b32_e32 v194, 16, v71
	v_and_b32_e32 v71, 0xffff0000, v71
	v_add_f32_e32 v70, v195, v70
	v_add_f32_e32 v198, v196, v194
	v_add_f32_e32 v71, v197, v71
	ds_read_b128 v[194:197], v124 offset:1680
	v_and_b32_e32 v72, 0xffff0000, v72
	v_lshlrev_b32_e32 v200, 16, v73
	v_and_b32_e32 v73, 0xffff0000, v73
	v_lshlrev_b32_e32 v201, 16, v62
	s_waitcnt lgkmcnt(0)
	v_add_f32_e32 v199, v194, v199
	v_add_f32_e32 v72, v195, v72
	v_add_f32_e32 v200, v196, v200
	v_add_f32_e32 v73, v197, v73
	ds_read_b128 v[194:197], v124 offset:1792
	v_and_b32_e32 v62, 0xffff0000, v62
	v_add_f32_e32 v148, v148, v202
	v_add_f32_e32 v149, v149, v203
	v_add_f32_e32 v150, v150, v204
	s_waitcnt lgkmcnt(0)
	v_add_f32_e32 v195, v195, v62
	v_lshlrev_b32_e32 v62, 16, v63
	v_add_f32_e32 v196, v196, v62
	v_and_b32_e32 v62, 0xffff0000, v63
	v_add_f32_e32 v194, v194, v201
	v_add_f32_e32 v197, v197, v62
	v_lshlrev_b32_e32 v201, 16, v64
	v_and_b32_e32 v202, 0xffff0000, v64
	v_lshlrev_b32_e32 v203, 16, v65
	v_and_b32_e32 v204, 0xffff0000, v65
	ds_read_b128 v[62:65], v124 offset:1808
	v_add_f32_e32 v151, v151, v205
	v_lshlrev_b32_e32 v205, 16, v58
	v_and_b32_e32 v58, 0xffff0000, v58
	v_add_f32_e32 v152, v152, v206
	s_waitcnt lgkmcnt(0)
	v_add_f32_e32 v201, v62, v201
	v_add_f32_e32 v202, v63, v202
	v_add_f32_e32 v203, v64, v203
	v_add_f32_e32 v204, v65, v204
	ds_read_b128 v[62:65], v124 offset:1920
	v_add_f32_e32 v153, v153, v207
	v_add_f32_e32 v154, v154, v208
	v_add_f32_e32 v155, v155, v209
	v_add_f32_e32 v160, v160, v214
	s_waitcnt lgkmcnt(0)
	v_add_f32_e32 v206, v63, v58
	v_lshlrev_b32_e32 v58, 16, v59
	v_add_f32_e32 v207, v64, v58
	v_and_b32_e32 v58, 0xffff0000, v59
	v_add_f32_e32 v205, v62, v205
	v_add_f32_e32 v208, v65, v58
	v_lshlrev_b32_e32 v62, 16, v60
	v_and_b32_e32 v63, 0xffff0000, v60
	v_lshlrev_b32_e32 v64, 16, v61
	v_and_b32_e32 v65, 0xffff0000, v61
	ds_read_b128 v[58:61], v124 offset:1936
	v_add_f32_e32 v161, v161, v215
	v_add_f32_e32 v162, v162, v216
	v_add_f32_e32 v163, v163, v217
	s_waitcnt lgkmcnt(0)
	v_add_f32_e32 v124, v58, v62
	v_add_f32_e32 v209, v59, v63
	v_add_f32_e32 v210, v60, v64
	v_add_f32_e32 v211, v61, v65
	v_cvt_pk_bf16_f32 v58,v82,v86
	v_cvt_pk_bf16_f32 v59,v87,v88
	v_cvt_pk_bf16_f32 v60,v89,v90
	v_cvt_pk_bf16_f32 v61,v91,v92
	v_cvt_pk_bf16_f32 v62,v93,v94
	v_cvt_pk_bf16_f32 v63,v95,v96
	v_cvt_pk_bf16_f32 v64,v97,v98
	v_cvt_pk_bf16_f32 v65,v99,v100
	v_cvt_pk_bf16_f32 v86,v101,v102
	s_nop 0
	v_mfma_f32_16x16x32_bf16 v[54:57], v[54:57], v[58:61], v[66:69]
	v_cvt_pk_bf16_f32 v87,v103,v104
	v_cvt_pk_bf16_f32 v88,v106,v108
	v_cvt_pk_bf16_f32 v89,v105,v107
	v_mfma_f32_16x16x32_bf16 v[6:9], v[6:9], v[62:65], v[54:57]
	v_cvt_pk_bf16_f32 v90,v109,v111
	v_cvt_pk_bf16_f32 v91,v112,v127
	v_cvt_pk_bf16_f32 v92,v113,v128
	v_mfma_f32_16x16x32_bf16 v[6:9], v[42:45], v[86:89], v[6:9]
	v_cvt_pk_bf16_f32 v93,v129,v136
	v_cvt_pk_bf16_f32 v58,v125,v130
	v_cvt_pk_bf16_f32 v59,v110,v126
	v_cvt_pk_bf16_f32 v60,v131,v137
	v_cvt_pk_bf16_f32 v61,v138,v139
	v_cvt_pk_bf16_f32 v54,v140,v141
	s_nop 0
	v_mfma_f32_16x16x32_bf16 v[6:9], v[18:21], v[90:93], v[6:9]
	v_cvt_pk_bf16_f32 v55,v142,v143
	v_cvt_pk_bf16_f32 v56,v144,v146
	v_cvt_pk_bf16_f32 v57,v145,v147
	v_mfma_f32_16x16x32_bf16 v[6:9], v[22:25], v[58:61], v[6:9]
	v_cvt_pk_bf16_f32 v42,v148,v149
	v_cvt_pk_bf16_f32 v43,v150,v151
	v_cvt_pk_bf16_f32 v44,v152,v153
	s_nop 2
	v_mfma_f32_16x16x32_bf16 v[6:9], v[10:13], v[54:57], v[6:9]
	v_cvt_pk_bf16_f32 v45,v154,v155
	v_cvt_pk_bf16_f32 v18,v156,v158
	v_cvt_pk_bf16_f32 v19,v157,v159
	v_cvt_pk_bf16_f32 v20,v160,v161
	v_cvt_pk_bf16_f32 v21,v162,v163
	v_cvt_pk_bf16_f32 v10,v164,v165
	s_nop 0
	v_mfma_f32_16x16x32_bf16 v[6:9], v[46:49], v[42:45], v[6:9]
	v_cvt_pk_bf16_f32 v11,v182,v83
	v_cvt_pk_bf16_f32 v12,v84,v183
	v_cvt_pk_bf16_f32 v13,v85,v184
	v_mfma_f32_16x16x32_bf16 v[6:9], v[26:29], v[18:21], v[6:9]
	v_cvt_pk_bf16_f32 v22,v185,v78
	v_cvt_pk_bf16_f32 v23,v186,v79
	v_cvt_pk_bf16_f32 v24,v80,v81
	v_mfma_f32_16x16x32_bf16 v[6:9], v[30:33], v[10:13], v[6:9]
	v_cvt_pk_bf16_f32 v25,v187,v188
	v_cvt_pk_bf16_f32 v18,v189,v74
	v_cvt_pk_bf16_f32 v19,v190,v75
	v_cvt_pk_bf16_f32 v20,v76,v77
	v_cvt_pk_bf16_f32 v21,v191,v192
	v_cvt_pk_bf16_f32 v10,v193,v70
	s_nop 0
	v_mfma_f32_16x16x32_bf16 v[6:9], v[14:17], v[22:25], v[6:9]
	v_cvt_pk_bf16_f32 v11,v198,v71
	v_cvt_pk_bf16_f32 v12,v199,v72
	v_cvt_pk_bf16_f32 v13,v200,v73
	v_mfma_f32_16x16x32_bf16 v[6:9], v[50:53], v[18:21], v[6:9]
	v_cvt_pk_bf16_f32 v14,v194,v195
	v_cvt_pk_bf16_f32 v15,v196,v197
	v_cvt_pk_bf16_f32 v16,v201,v202
	v_mfma_f32_16x16x32_bf16 v[6:9], v[34:37], v[10:13], v[6:9]
	v_cvt_pk_bf16_f32 v17,v203,v204
	v_cvt_pk_bf16_f32 v10,v205,v206
	v_cvt_pk_bf16_f32 v11,v207,v208
	v_cvt_pk_bf16_f32 v12,v124,v209
	v_cvt_pk_bf16_f32 v13,v210,v211
	s_nop 0
	v_mfma_f32_16x16x32_bf16 v[6:9], v[38:41], v[14:17], v[6:9]
	v_mfma_f32_16x16x32_bf16 v[66:69], v[2:5], v[10:13], v[6:9]
	s_mov_b64 s[24:25], 0x400
	s_addk_i32 s0, 0x800
	v_lshl_add_u64 v[118:119], v[118:119], 0, s[24:25]
	s_mov_b64 s[24:25], 0x1a800
	s_cmpk_eq_i32 s0, 0x4000
	v_lshl_add_u64 v[120:121], v[120:121], 0, s[24:25]
	s_cbranch_scc0 .LBB0_218
	v_lshlrev_b32_e32 v2, 9, v123
	v_add3_u32 v25, 64, v2, v0
	v_lshl_add_u32 v0, v114, 2, v25
	ds_write_b128 v0, v[66:69]
	s_waitcnt lgkmcnt(0)
	s_barrier
; __device__ __forceinline__ float fexp2(float x) { return __builtin_amdgcn_exp2f(x); }
; #define MFMA(a, b, c) __builtin_amdgcn_mfma_f32_16x16x32_bf16((a), (b), (c), 0, 0, 0)
; __device__ __forceinline__ float gelu_tanh(float x) {
;   float u = 0.7978845608028654f * (x + 0.044715f * x * x * x);
;   float e = fexp2(u * (2.0f * LOG2E));
;   float th = 1.0f - 2.0f / (e + 1.0f);
;   return 0.5f * x * (1.0f + th);
; }
; __device__ __forceinline__ void compress_unit(const Params& p, int unit, char* lds, int tid) {
;     ...
;   f32x4 out = {0.f, 0.f, 0.f, 0.f};
; #pragma unroll
;   for (int pp = 0; pp < 4; ++pp) {
;     const float* rp = part + fr * 128 + 32 * pp + fq * 4;
;     f32x4 h0 = *reinterpret_cast<const f32x4*>(rp), h1 = *reinterpret_cast<const f32x4*>(rp + 16);
;     bf16x8 hb = mk8(u32x4{pk2(gelu_tanh(h0[0]), gelu_tanh(h0[1])), pk2(gelu_tanh(h0[2]), gelu_tanh(h0[3])),
;                           pk2(gelu_tanh(h1[0]), gelu_tanh(h1[1])), pk2(gelu_tanh(h1[2]), gelu_tanh(h1[3]))});
;     const u16* wp = w2t + (16 * w + fr) * 128 + 32 * pp + fq * 4;
;     out = MFMA(ld44(wp, wp + 16), hb, out);
	ds_read_b128 v[8:11], v25
	ds_read_b128 v[4:7], v25 offset:64
	s_lshl_b64 s[0:1], s[20:21], 15
	s_add_u32 s0, s2, s0
	v_lshlrev_b32_e32 v2, 7, v116
	s_waitcnt lgkmcnt(1)
	v_mul_f32_e32 v0, 0x3d372713, v8
	v_mul_f32_e32 v0, v8, v0
	v_fma_f32 v0, v8, v0, v8
	v_mul_f32_e32 v0, 0x3f4c422a, v0
	v_mul_f32_e32 v0, 0x4038aa3b, v0
	v_exp_f32_e32 v0, v0
	s_addc_u32 s1, s3, s1
	v_ashrrev_i32_e32 v3, 31, v2
	v_lshl_add_u64 v[2:3], v[2:3], 1, s[0:1]
	v_add_f32_e32 v12, 1.0, v0
	v_div_scale_f32 v13, s[20:21], v12, v12, 2.0
	v_rcp_f32_e32 v14, v13
	v_lshlrev_b32_e32 v0, 3, v115
	v_lshl_add_u64 v[22:23], v[2:3], 0, v[0:1]
	v_mul_f32_e32 v8, 0.5, v8
	v_fma_f32 v0, -v13, v14, 1.0
	v_fmac_f32_e32 v14, v0, v14
	v_div_scale_f32 v0, vcc, 2.0, v12, 2.0
	v_mul_f32_e32 v2, v0, v14
	v_fma_f32 v3, -v13, v2, v0
	v_fmac_f32_e32 v2, v3, v14
	v_mul_f32_e32 v3, 0x3d372713, v9
	v_mul_f32_e32 v3, v9, v3
	v_fma_f32 v3, v9, v3, v9
	v_mul_f32_e32 v3, 0x3f4c422a, v3
	v_mul_f32_e32 v3, 0x4038aa3b, v3
	v_exp_f32_e32 v3, v3
	v_fma_f32 v0, -v13, v2, v0
	v_div_fmas_f32 v0, v0, v14, v2
	v_div_fixup_f32 v0, v0, v12, 2.0
	v_add_f32_e32 v2, 1.0, v3
	v_div_scale_f32 v3, s[0:1], v2, v2, 2.0
	v_rcp_f32_e32 v12, v3
	v_sub_f32_e32 v0, 1.0, v0
	v_add_f32_e32 v0, 1.0, v0
	v_mul_f32_e32 v0, v8, v0
	v_fma_f32 v8, -v3, v12, 1.0
	v_fmac_f32_e32 v12, v8, v12
	v_div_scale_f32 v8, vcc, 2.0, v2, 2.0
	v_mul_f32_e32 v13, v8, v12
	v_fma_f32 v14, -v3, v13, v8
	v_fmac_f32_e32 v13, v14, v12
	v_fma_f32 v3, -v3, v13, v8
	v_mul_f32_e32 v8, 0x3d372713, v10
	v_mul_f32_e32 v8, v10, v8
	v_fma_f32 v8, v10, v8, v10
	v_mul_f32_e32 v8, 0x3f4c422a, v8
	v_mul_f32_e32 v8, 0x4038aa3b, v8
	v_exp_f32_e32 v8, v8
	v_div_fmas_f32 v3, v3, v12, v13
	v_div_fixup_f32 v2, v3, v2, 2.0
	v_mul_f32_e32 v3, 0.5, v9
	v_add_f32_e32 v8, 1.0, v8
	v_div_scale_f32 v9, s[0:1], v8, v8, 2.0
	v_rcp_f32_e32 v12, v9
	v_sub_f32_e32 v2, 1.0, v2
	v_add_f32_e32 v2, 1.0, v2
	v_mul_f32_e32 v2, v3, v2
	v_cvt_pk_bf16_f32 v2,v0,v2
	v_fma_f32 v0, -v9, v12, 1.0
	v_fmac_f32_e32 v12, v0, v12
	v_div_scale_f32 v0, vcc, 2.0, v8, 2.0
	v_mul_f32_e32 v3, v0, v12
	v_fma_f32 v13, -v9, v3, v0
	v_fmac_f32_e32 v3, v13, v12
	v_fma_f32 v0, -v9, v3, v0
	v_mul_f32_e32 v9, 0x3d372713, v11
	v_mul_f32_e32 v9, v11, v9
	v_fma_f32 v9, v11, v9, v11
	v_mul_f32_e32 v9, 0x3f4c422a, v9
	v_mul_f32_e32 v9, 0x4038aa3b, v9
	v_exp_f32_e32 v9, v9
	v_div_fmas_f32 v0, v0, v12, v3
	v_div_fixup_f32 v0, v0, v8, 2.0
	v_sub_f32_e32 v0, 1.0, v0
	v_add_f32_e32 v3, 1.0, v9
	v_div_scale_f32 v8, s[0:1], v3, v3, 2.0
	v_rcp_f32_e32 v9, v8
	v_mul_f32_e32 v10, 0.5, v10
	v_add_f32_e32 v0, 1.0, v0
	v_mul_f32_e32 v0, v10, v0
	v_fma_f32 v10, -v8, v9, 1.0
	v_fmac_f32_e32 v9, v10, v9
	v_div_scale_f32 v10, vcc, 2.0, v3, 2.0
	v_mul_f32_e32 v12, v10, v9
	v_fma_f32 v13, -v8, v12, v10
	v_fmac_f32_e32 v12, v13, v9
	v_fma_f32 v8, -v8, v12, v10
	v_div_fmas_f32 v8, v8, v9, v12
	s_waitcnt lgkmcnt(0)
	v_mul_f32_e32 v9, 0x3d372713, v4
	v_mul_f32_e32 v9, v4, v9
	v_fma_f32 v9, v4, v9, v4
	v_mul_f32_e32 v9, 0x3f4c422a, v9
	v_mul_f32_e32 v9, 0x4038aa3b, v9
	v_exp_f32_e32 v9, v9
	v_div_fixup_f32 v3, v8, v3, 2.0
	v_mul_f32_e32 v8, 0.5, v11
	v_sub_f32_e32 v3, 1.0, v3
	v_add_f32_e32 v9, 1.0, v9
	v_div_scale_f32 v10, s[0:1], v9, v9, 2.0
	v_rcp_f32_e32 v11, v10
	v_add_f32_e32 v3, 1.0, v3
	v_mul_f32_e32 v3, v8, v3
	v_cvt_pk_bf16_f32 v3,v0,v3
	v_fma_f32 v0, -v10, v11, 1.0
	v_fmac_f32_e32 v11, v0, v11
	v_div_scale_f32 v0, vcc, 2.0, v9, 2.0
	v_mul_f32_e32 v8, v0, v11
	v_fma_f32 v12, -v10, v8, v0
	v_fmac_f32_e32 v8, v12, v11
	v_fma_f32 v0, -v10, v8, v0
	v_div_fmas_f32 v0, v0, v11, v8
	v_mul_f32_e32 v8, 0x3d372713, v5
	v_mul_f32_e32 v8, v5, v8
	global_load_dwordx2 v[14:15], v[22:23], off
	global_load_dwordx2 v[16:17], v[22:23], off offset:32
	v_fma_f32 v8, v5, v8, v5
	v_mul_f32_e32 v8, 0x3f4c422a, v8
	v_mul_f32_e32 v8, 0x4038aa3b, v8
	v_exp_f32_e32 v8, v8
	v_div_fixup_f32 v0, v0, v9, 2.0
	v_sub_f32_e32 v0, 1.0, v0
	v_mul_f32_e32 v4, 0.5, v4
	v_add_f32_e32 v8, 1.0, v8
	v_div_scale_f32 v9, s[0:1], v8, v8, 2.0
	v_rcp_f32_e32 v10, v9
	v_add_f32_e32 v0, 1.0, v0
	v_mul_f32_e32 v0, v4, v0
	v_mul_f32_e32 v5, 0.5, v5
	v_fma_f32 v4, -v9, v10, 1.0
	v_fmac_f32_e32 v10, v4, v10
	v_div_scale_f32 v4, vcc, 2.0, v8, 2.0
	v_mul_f32_e32 v11, v4, v10
	v_fma_f32 v12, -v9, v11, v4
	v_fmac_f32_e32 v11, v12, v10
	v_fma_f32 v4, -v9, v11, v4
	v_mul_f32_e32 v9, 0x3d372713, v6
	v_mul_f32_e32 v9, v6, v9
	v_fma_f32 v9, v6, v9, v6
	v_mul_f32_e32 v9, 0x3f4c422a, v9
	v_mul_f32_e32 v9, 0x4038aa3b, v9
	v_exp_f32_e32 v9, v9
	v_div_fmas_f32 v4, v4, v10, v11
	v_div_fixup_f32 v4, v4, v8, 2.0
	v_sub_f32_e32 v4, 1.0, v4
	v_add_f32_e32 v8, 1.0, v9
	v_div_scale_f32 v9, s[0:1], v8, v8, 2.0
	v_rcp_f32_e32 v10, v9
	v_add_f32_e32 v4, 1.0, v4
	v_mul_f32_e32 v4, v5, v4
	v_cvt_pk_bf16_f32 v4,v0,v4
	v_fma_f32 v0, -v9, v10, 1.0
	v_fmac_f32_e32 v10, v0, v10
	v_div_scale_f32 v0, vcc, 2.0, v8, 2.0
	v_mul_f32_e32 v5, v0, v10
	v_fma_f32 v11, -v9, v5, v0
	v_fmac_f32_e32 v5, v11, v10
	v_fma_f32 v0, -v9, v5, v0
	v_mul_f32_e32 v9, 0x3d372713, v7
	v_mul_f32_e32 v9, v7, v9
	v_fma_f32 v9, v7, v9, v7
	v_mul_f32_e32 v9, 0x3f4c422a, v9
	v_mul_f32_e32 v9, 0x4038aa3b, v9
	v_exp_f32_e32 v9, v9
	v_div_fmas_f32 v0, v0, v10, v5
	v_div_fixup_f32 v0, v0, v8, 2.0
	v_sub_f32_e32 v0, 1.0, v0
	v_add_f32_e32 v5, 1.0, v9
	v_div_scale_f32 v8, s[0:1], v5, v5, 2.0
	v_rcp_f32_e32 v9, v8
	v_mul_f32_e32 v6, 0.5, v6
	v_add_f32_e32 v0, 1.0, v0
	v_mul_f32_e32 v0, v6, v0
	v_fma_f32 v6, -v8, v9, 1.0
	v_fmac_f32_e32 v9, v6, v9
	v_div_scale_f32 v6, vcc, 2.0, v5, 2.0
	v_mul_f32_e32 v10, v6, v9
	v_fma_f32 v11, -v8, v10, v6
	v_fmac_f32_e32 v10, v11, v9
	v_fma_f32 v6, -v8, v10, v6
	v_div_fmas_f32 v6, v6, v9, v10
	ds_read_b128 v[10:13], v25 offset:128
	v_div_fixup_f32 v5, v6, v5, 2.0
	v_mul_f32_e32 v18, 0.5, v7
	ds_read_b128 v[6:9], v25 offset:192
	v_sub_f32_e32 v5, 1.0, v5
	s_waitcnt lgkmcnt(0)
; __device__ __forceinline__ float fexp2(float x) { return __builtin_amdgcn_exp2f(x); }
; #define MFMA(a, b, c) __builtin_amdgcn_mfma_f32_16x16x32_bf16((a), (b), (c), 0, 0, 0)
; __device__ __forceinline__ float gelu_tanh(float x) {
;   float u = 0.7978845608028654f * (x + 0.044715f * x * x * x);
;   float e = fexp2(u * (2.0f * LOG2E));
;   float th = 1.0f - 2.0f / (e + 1.0f);
;   return 0.5f * x * (1.0f + th);
; }
; __device__ __forceinline__ void compress_unit(const Params& p, int unit, char* lds, int tid) {
;     ...
;   f32x4 out = {0.f, 0.f, 0.f, 0.f};
; #pragma unroll
;   for (int pp = 0; pp < 4; ++pp) {
;     const float* rp = part + fr * 128 + 32 * pp + fq * 4;
;     f32x4 h0 = *reinterpret_cast<const f32x4*>(rp), h1 = *reinterpret_cast<const f32x4*>(rp + 16);
;     bf16x8 hb = mk8(u32x4{pk2(gelu_tanh(h0[0]), gelu_tanh(h0[1])), pk2(gelu_tanh(h0[2]), gelu_tanh(h0[3])),
;                           pk2(gelu_tanh(h1[0]), gelu_tanh(h1[1])), pk2(gelu_tanh(h1[2]), gelu_tanh(h1[3]))});
;     const u16* wp = w2t + (16 * w + fr) * 128 + 32 * pp + fq * 4;
;     out = MFMA(ld44(wp, wp + 16), hb, out);
	v_mul_f32_e32 v19, 0x3d372713, v10
	v_mul_f32_e32 v19, v10, v19
	v_fma_f32 v19, v10, v19, v10
	v_mul_f32_e32 v19, 0x3f4c422a, v19
	v_mul_f32_e32 v19, 0x4038aa3b, v19
	v_exp_f32_e32 v19, v19
	v_add_f32_e32 v5, 1.0, v5
	v_mul_f32_e32 v5, v18, v5
	v_cvt_pk_bf16_f32 v5,v0,v5
	v_add_f32_e32 v0, 1.0, v19
	v_div_scale_f32 v26, s[0:1], v0, v0, 2.0
	v_rcp_f32_e32 v27, v26
	s_waitcnt vmcnt(0)
	v_mfma_f32_16x16x32_bf16 v[2:5], v[14:17], v[2:5], 0
	v_mul_f32_e32 v10, 0.5, v10
	global_load_dwordx2 v[18:19], v[22:23], off offset:64
	global_load_dwordx2 v[20:21], v[22:23], off offset:96
	v_fma_f32 v14, -v26, v27, 1.0
	v_fmac_f32_e32 v27, v14, v27
	v_div_scale_f32 v14, vcc, 2.0, v0, 2.0
	v_mul_f32_e32 v15, v14, v27
	v_fma_f32 v16, -v26, v15, v14
	v_fmac_f32_e32 v15, v16, v27
	v_mul_f32_e32 v16, 0x3d372713, v11
	v_mul_f32_e32 v16, v11, v16
	v_fma_f32 v16, v11, v16, v11
	v_mul_f32_e32 v16, 0x3f4c422a, v16
	v_mul_f32_e32 v16, 0x4038aa3b, v16
	v_exp_f32_e32 v16, v16
	v_fma_f32 v14, -v26, v15, v14
	v_div_fmas_f32 v14, v14, v27, v15
	v_div_fixup_f32 v0, v14, v0, 2.0
	v_add_f32_e32 v14, 1.0, v16
	v_div_scale_f32 v15, s[0:1], v14, v14, 2.0
	v_rcp_f32_e32 v16, v15
	v_sub_f32_e32 v0, 1.0, v0
	v_add_f32_e32 v0, 1.0, v0
	v_mul_f32_e32 v0, v10, v0
	v_fma_f32 v10, -v15, v16, 1.0
	v_fmac_f32_e32 v16, v10, v16
	v_div_scale_f32 v10, vcc, 2.0, v14, 2.0
	v_mul_f32_e32 v17, v10, v16
	v_fma_f32 v26, -v15, v17, v10
	v_fmac_f32_e32 v17, v26, v16
	v_fma_f32 v10, -v15, v17, v10
	v_mul_f32_e32 v15, 0x3d372713, v12
	v_mul_f32_e32 v15, v12, v15
	v_fma_f32 v15, v12, v15, v12
	v_mul_f32_e32 v15, 0x3f4c422a, v15
	v_mul_f32_e32 v15, 0x4038aa3b, v15
	v_exp_f32_e32 v15, v15
	v_div_fmas_f32 v10, v10, v16, v17
	v_div_fixup_f32 v10, v10, v14, 2.0
	v_sub_f32_e32 v10, 1.0, v10
	v_add_f32_e32 v15, 1.0, v15
	v_div_scale_f32 v16, s[0:1], v15, v15, 2.0
	v_rcp_f32_e32 v17, v16
	v_mul_f32_e32 v11, 0.5, v11
	v_add_f32_e32 v10, 1.0, v10
	v_mul_f32_e32 v10, v11, v10
	v_cvt_pk_bf16_f32 v14,v0,v10
	v_fma_f32 v0, -v16, v17, 1.0
	v_fmac_f32_e32 v17, v0, v17
	v_div_scale_f32 v0, vcc, 2.0, v15, 2.0
	v_mul_f32_e32 v10, v0, v17
	v_fma_f32 v11, -v16, v10, v0
	v_fmac_f32_e32 v10, v11, v17
	v_mul_f32_e32 v11, 0x3d372713, v13
	v_mul_f32_e32 v11, v13, v11
	v_fma_f32 v11, v13, v11, v13
	v_mul_f32_e32 v11, 0x3f4c422a, v11
	v_mul_f32_e32 v11, 0x4038aa3b, v11
	v_exp_f32_e32 v11, v11
	v_fma_f32 v0, -v16, v10, v0
	v_div_fmas_f32 v0, v0, v17, v10
	v_div_fixup_f32 v0, v0, v15, 2.0
	v_add_f32_e32 v10, 1.0, v11
	v_div_scale_f32 v11, s[0:1], v10, v10, 2.0
	v_rcp_f32_e32 v15, v11
	v_sub_f32_e32 v0, 1.0, v0
	v_mul_f32_e32 v12, 0.5, v12
	v_add_f32_e32 v0, 1.0, v0
	v_mul_f32_e32 v0, v12, v0
	v_fma_f32 v12, -v11, v15, 1.0
	v_fmac_f32_e32 v15, v12, v15
	v_div_scale_f32 v12, vcc, 2.0, v10, 2.0
	v_mul_f32_e32 v16, v12, v15
	v_fma_f32 v17, -v11, v16, v12
	v_fmac_f32_e32 v16, v17, v15
	v_fma_f32 v11, -v11, v16, v12
	v_mul_f32_e32 v12, 0x3d372713, v6
	v_mul_f32_e32 v12, v6, v12
	v_fma_f32 v12, v6, v12, v6
	v_mul_f32_e32 v12, 0x3f4c422a, v12
	v_mul_f32_e32 v12, 0x4038aa3b, v12
	v_exp_f32_e32 v12, v12
	v_div_fmas_f32 v11, v11, v15, v16
	v_div_fixup_f32 v10, v11, v10, 2.0
	v_mul_f32_e32 v11, 0.5, v13
	v_add_f32_e32 v12, 1.0, v12
	v_div_scale_f32 v13, s[0:1], v12, v12, 2.0
	v_rcp_f32_e32 v16, v13
	v_sub_f32_e32 v10, 1.0, v10
	v_add_f32_e32 v10, 1.0, v10
	v_mul_f32_e32 v10, v11, v10
	v_cvt_pk_bf16_f32 v15,v0,v10
	v_fma_f32 v0, -v13, v16, 1.0
	v_fmac_f32_e32 v16, v0, v16
	v_div_scale_f32 v0, vcc, 2.0, v12, 2.0
	v_mul_f32_e32 v10, v0, v16
	v_fma_f32 v11, -v13, v10, v0
	v_fmac_f32_e32 v10, v11, v16
	v_mul_f32_e32 v11, 0x3d372713, v7
	v_mul_f32_e32 v11, v7, v11
	v_fma_f32 v11, v7, v11, v7
	v_mul_f32_e32 v11, 0x3f4c422a, v11
	v_mul_f32_e32 v11, 0x4038aa3b, v11
	v_exp_f32_e32 v11, v11
	v_fma_f32 v0, -v13, v10, v0
	v_div_fmas_f32 v0, v0, v16, v10
	v_div_fixup_f32 v0, v0, v12, 2.0
	v_add_f32_e32 v10, 1.0, v11
	v_div_scale_f32 v11, s[0:1], v10, v10, 2.0
	v_rcp_f32_e32 v12, v11
	v_sub_f32_e32 v0, 1.0, v0
	v_mul_f32_e32 v6, 0.5, v6
	v_add_f32_e32 v0, 1.0, v0
	v_mul_f32_e32 v0, v6, v0
	v_fma_f32 v6, -v11, v12, 1.0
	v_fmac_f32_e32 v12, v6, v12
	v_div_scale_f32 v6, vcc, 2.0, v10, 2.0
	v_mul_f32_e32 v13, v6, v12
	v_fma_f32 v16, -v11, v13, v6
	v_fmac_f32_e32 v13, v16, v12
	v_fma_f32 v6, -v11, v13, v6
	v_mul_f32_e32 v11, 0x3d372713, v8
	v_mul_f32_e32 v11, v8, v11
	v_fma_f32 v11, v8, v11, v8
	v_mul_f32_e32 v11, 0x3f4c422a, v11
	v_mul_f32_e32 v11, 0x4038aa3b, v11
	v_exp_f32_e32 v11, v11
	v_div_fmas_f32 v6, v6, v12, v13
	v_div_fixup_f32 v6, v6, v10, 2.0
	v_sub_f32_e32 v6, 1.0, v6
	v_add_f32_e32 v10, 1.0, v11
	v_div_scale_f32 v11, s[0:1], v10, v10, 2.0
	v_rcp_f32_e32 v12, v11
	v_mul_f32_e32 v7, 0.5, v7
	v_add_f32_e32 v6, 1.0, v6
	v_mul_f32_e32 v6, v7, v6
	v_cvt_pk_bf16_f32 v16,v0,v6
	v_fma_f32 v0, -v11, v12, 1.0
	v_fmac_f32_e32 v12, v0, v12
	v_div_scale_f32 v0, vcc, 2.0, v10, 2.0
	v_mul_f32_e32 v6, v0, v12
	v_fma_f32 v7, -v11, v6, v0
	v_fmac_f32_e32 v6, v7, v12
	v_mul_f32_e32 v7, 0x3d372713, v9
	v_mul_f32_e32 v7, v9, v7
	v_fma_f32 v7, v9, v7, v9
	v_mul_f32_e32 v7, 0x3f4c422a, v7
	v_mul_f32_e32 v7, 0x4038aa3b, v7
	v_exp_f32_e32 v7, v7
	v_fma_f32 v0, -v11, v6, v0
	v_div_fmas_f32 v0, v0, v12, v6
	v_div_fixup_f32 v0, v0, v10, 2.0
	v_add_f32_e32 v6, 1.0, v7
	v_div_scale_f32 v7, s[0:1], v6, v6, 2.0
	v_rcp_f32_e32 v10, v7
	v_sub_f32_e32 v0, 1.0, v0
	v_mul_f32_e32 v8, 0.5, v8
	v_add_f32_e32 v0, 1.0, v0
	v_mul_f32_e32 v0, v8, v0
	v_fma_f32 v8, -v7, v10, 1.0
	v_fmac_f32_e32 v10, v8, v10
	v_div_scale_f32 v8, vcc, 2.0, v6, 2.0
	v_mul_f32_e32 v11, v8, v10
	ds_read_b128 v[26:29], v25 offset:256
	v_fma_f32 v12, -v7, v11, v8
	v_fmac_f32_e32 v11, v12, v10
	v_fma_f32 v7, -v7, v11, v8
	v_div_fmas_f32 v7, v7, v10, v11
	v_div_fixup_f32 v6, v7, v6, 2.0
	ds_read_b128 v[10:13], v25 offset:320
	s_waitcnt lgkmcnt(0)
; __device__ __forceinline__ float fexp2(float x) { return __builtin_amdgcn_exp2f(x); }
; #define MFMA(a, b, c) __builtin_amdgcn_mfma_f32_16x16x32_bf16((a), (b), (c), 0, 0, 0)
; __device__ __forceinline__ float gelu_tanh(float x) {
;   float u = 0.7978845608028654f * (x + 0.044715f * x * x * x);
;   float e = fexp2(u * (2.0f * LOG2E));
;   float th = 1.0f - 2.0f / (e + 1.0f);
;   return 0.5f * x * (1.0f + th);
; }
; __device__ __forceinline__ void compress_unit(const Params& p, int unit, char* lds, int tid) {
;     ...
;   f32x4 out = {0.f, 0.f, 0.f, 0.f};
; #pragma unroll
;   for (int pp = 0; pp < 4; ++pp) {
;     const float* rp = part + fr * 128 + 32 * pp + fq * 4;
;     f32x4 h0 = *reinterpret_cast<const f32x4*>(rp), h1 = *reinterpret_cast<const f32x4*>(rp + 16);
;     bf16x8 hb = mk8(u32x4{pk2(gelu_tanh(h0[0]), gelu_tanh(h0[1])), pk2(gelu_tanh(h0[2]), gelu_tanh(h0[3])),
;                           pk2(gelu_tanh(h1[0]), gelu_tanh(h1[1])), pk2(gelu_tanh(h1[2]), gelu_tanh(h1[3]))});
;     const u16* wp = w2t + (16 * w + fr) * 128 + 32 * pp + fq * 4;
;     out = MFMA(ld44(wp, wp + 16), hb, out);
	v_mul_f32_e32 v7, 0x3d372713, v26
	v_mul_f32_e32 v7, v26, v7
	v_fma_f32 v7, v26, v7, v26
	v_mul_f32_e32 v7, 0x3f4c422a, v7
	v_mul_f32_e32 v7, 0x4038aa3b, v7
	v_exp_f32_e32 v7, v7
	v_mul_f32_e32 v8, 0.5, v9
	v_sub_f32_e32 v6, 1.0, v6
	v_add_f32_e32 v6, 1.0, v6
	v_add_f32_e32 v7, 1.0, v7
	v_div_scale_f32 v9, s[0:1], v7, v7, 2.0
	v_rcp_f32_e32 v30, v9
	v_mul_f32_e32 v6, v8, v6
	v_cvt_pk_bf16_f32 v17,v0,v6
	v_lshlrev_b32_e32 v24, 2, v115
	v_fma_f32 v0, -v9, v30, 1.0
	v_fmac_f32_e32 v30, v0, v30
	v_div_scale_f32 v0, vcc, 2.0, v7, 2.0
	v_mul_f32_e32 v6, v0, v30
	v_fma_f32 v8, -v9, v6, v0
	v_fmac_f32_e32 v6, v8, v30
	v_mul_f32_e32 v8, 0x3d372713, v27
	v_mul_f32_e32 v8, v27, v8
	v_fma_f32 v8, v27, v8, v27
	v_mul_f32_e32 v8, 0x3f4c422a, v8
	v_mul_f32_e32 v8, 0x4038aa3b, v8
	v_exp_f32_e32 v8, v8
	v_fma_f32 v0, -v9, v6, v0
	v_div_fmas_f32 v0, v0, v30, v6
	v_div_fixup_f32 v0, v0, v7, 2.0
	v_add_f32_e32 v6, 1.0, v8
	v_div_scale_f32 v7, s[0:1], v6, v6, 2.0
	v_rcp_f32_e32 v8, v7
	v_sub_f32_e32 v0, 1.0, v0
	v_mul_f32_e32 v9, 0.5, v26
	v_add_f32_e32 v0, 1.0, v0
	v_mul_f32_e32 v0, v9, v0
	v_fma_f32 v9, -v7, v8, 1.0
	v_fmac_f32_e32 v8, v9, v8
	v_div_scale_f32 v9, vcc, 2.0, v6, 2.0
	s_waitcnt vmcnt(0)
	v_mfma_f32_16x16x32_bf16 v[2:5], v[18:21], v[14:17], v[2:5]
	v_mul_f32_e32 v14, v9, v8
	v_fma_f32 v15, -v7, v14, v9
	v_fmac_f32_e32 v14, v15, v8
	v_fma_f32 v7, -v7, v14, v9
	v_div_fmas_f32 v7, v7, v8, v14
	v_mul_f32_e32 v8, 0x3d372713, v28
	v_mul_f32_e32 v8, v28, v8
	v_fma_f32 v8, v28, v8, v28
	v_mul_f32_e32 v8, 0x3f4c422a, v8
	v_mul_f32_e32 v8, 0x4038aa3b, v8
	v_exp_f32_e32 v8, v8
	v_div_fixup_f32 v6, v7, v6, 2.0
	v_sub_f32_e32 v6, 1.0, v6
	v_mul_f32_e32 v7, 0.5, v27
	v_add_f32_e32 v8, 1.0, v8
	v_div_scale_f32 v9, s[0:1], v8, v8, 2.0
	v_rcp_f32_e32 v14, v9
	v_add_f32_e32 v6, 1.0, v6
	v_mul_f32_e32 v6, v7, v6
	v_cvt_pk_bf16_f32 v6,v0,v6
	v_fma_f32 v0, -v9, v14, 1.0
	v_fmac_f32_e32 v14, v0, v14
	v_div_scale_f32 v0, vcc, 2.0, v8, 2.0
	v_mul_f32_e32 v7, v0, v14
	v_fma_f32 v15, -v9, v7, v0
	v_fmac_f32_e32 v7, v15, v14
	v_fma_f32 v0, -v9, v7, v0
	v_mul_f32_e32 v9, 0x3d372713, v29
	v_mul_f32_e32 v9, v29, v9
	v_fma_f32 v9, v29, v9, v29
	v_mul_f32_e32 v9, 0x3f4c422a, v9
	v_mul_f32_e32 v9, 0x4038aa3b, v9
	v_exp_f32_e32 v9, v9
	v_div_fmas_f32 v0, v0, v14, v7
	v_div_fixup_f32 v0, v0, v8, 2.0
	v_sub_f32_e32 v0, 1.0, v0
	v_add_f32_e32 v7, 1.0, v9
	v_div_scale_f32 v8, s[0:1], v7, v7, 2.0
	v_rcp_f32_e32 v9, v8
	v_mul_f32_e32 v14, 0.5, v28
	v_add_f32_e32 v0, 1.0, v0
	v_mul_f32_e32 v0, v14, v0
	v_fma_f32 v14, -v8, v9, 1.0
	v_fmac_f32_e32 v9, v14, v9
	v_div_scale_f32 v14, vcc, 2.0, v7, 2.0
	v_mul_f32_e32 v15, v14, v9
	v_fma_f32 v16, -v8, v15, v14
	v_fmac_f32_e32 v15, v16, v9
	v_fma_f32 v8, -v8, v15, v14
	v_div_fmas_f32 v8, v8, v9, v15
	v_mul_f32_e32 v9, 0x3d372713, v10
	v_mul_f32_e32 v9, v10, v9
	v_fma_f32 v9, v10, v9, v10
	v_mul_f32_e32 v9, 0x3f4c422a, v9
	v_mul_f32_e32 v9, 0x4038aa3b, v9
	v_exp_f32_e32 v9, v9
	v_div_fixup_f32 v7, v8, v7, 2.0
	v_sub_f32_e32 v7, 1.0, v7
	v_mul_f32_e32 v8, 0.5, v29
	v_add_f32_e32 v9, 1.0, v9
	v_div_scale_f32 v14, s[0:1], v9, v9, 2.0
	v_rcp_f32_e32 v15, v14
	v_add_f32_e32 v7, 1.0, v7
	v_mul_f32_e32 v7, v8, v7
	v_cvt_pk_bf16_f32 v7,v0,v7
	v_fma_f32 v0, -v14, v15, 1.0
	v_fmac_f32_e32 v15, v0, v15
	v_div_scale_f32 v0, vcc, 2.0, v9, 2.0
	v_mul_f32_e32 v8, v0, v15
	v_fma_f32 v16, -v14, v8, v0
	v_fmac_f32_e32 v8, v16, v15
	v_fma_f32 v0, -v14, v8, v0
	v_div_fmas_f32 v0, v0, v15, v8
	v_mul_f32_e32 v8, 0x3d372713, v11
	v_mul_f32_e32 v8, v11, v8
	global_load_dwordx2 v[18:19], v[22:23], off offset:128
	global_load_dwordx2 v[20:21], v[22:23], off offset:160
	v_fma_f32 v8, v11, v8, v11
	v_mul_f32_e32 v8, 0x3f4c422a, v8
	v_mul_f32_e32 v8, 0x4038aa3b, v8
	v_exp_f32_e32 v8, v8
	v_div_fixup_f32 v0, v0, v9, 2.0
	v_mul_f32_e32 v9, 0.5, v10
	v_sub_f32_e32 v0, 1.0, v0
	v_add_f32_e32 v8, 1.0, v8
	v_div_scale_f32 v10, s[0:1], v8, v8, 2.0
	v_rcp_f32_e32 v14, v10
	v_add_f32_e32 v0, 1.0, v0
	v_mul_f32_e32 v0, v9, v0
	v_mul_f32_e32 v26, 0.5, v13
	v_fma_f32 v9, -v10, v14, 1.0
	v_fmac_f32_e32 v14, v9, v14
	v_div_scale_f32 v9, vcc, 2.0, v8, 2.0
	v_mul_f32_e32 v15, v9, v14
	v_fma_f32 v16, -v10, v15, v9
	v_fmac_f32_e32 v15, v16, v14
	v_fma_f32 v9, -v10, v15, v9
	v_mul_f32_e32 v10, 0x3d372713, v12
	v_mul_f32_e32 v10, v12, v10
	v_fma_f32 v10, v12, v10, v12
	v_mul_f32_e32 v10, 0x3f4c422a, v10
	v_mul_f32_e32 v10, 0x4038aa3b, v10
	v_exp_f32_e32 v10, v10
	v_div_fmas_f32 v9, v9, v14, v15
	v_div_fixup_f32 v8, v9, v8, 2.0
	v_mul_f32_e32 v9, 0.5, v11
	v_add_f32_e32 v10, 1.0, v10
	v_div_scale_f32 v11, s[0:1], v10, v10, 2.0
	v_rcp_f32_e32 v14, v11
	v_sub_f32_e32 v8, 1.0, v8
	v_add_f32_e32 v8, 1.0, v8
	v_mul_f32_e32 v8, v9, v8
	v_cvt_pk_bf16_f32 v8,v0,v8
	v_fma_f32 v0, -v11, v14, 1.0
	v_fmac_f32_e32 v14, v0, v14
	v_div_scale_f32 v0, vcc, 2.0, v10, 2.0
	v_mul_f32_e32 v9, v0, v14
	v_fma_f32 v15, -v11, v9, v0
	v_fmac_f32_e32 v9, v15, v14
	v_fma_f32 v0, -v11, v9, v0
	v_mul_f32_e32 v11, 0x3d372713, v13
	v_mul_f32_e32 v11, v13, v11
	v_fma_f32 v11, v13, v11, v13
	v_mul_f32_e32 v11, 0x3f4c422a, v11
	v_mul_f32_e32 v11, 0x4038aa3b, v11
	v_exp_f32_e32 v11, v11
	v_div_fmas_f32 v0, v0, v14, v9
	v_div_fixup_f32 v0, v0, v10, 2.0
	v_sub_f32_e32 v0, 1.0, v0
	v_add_f32_e32 v9, 1.0, v11
	v_div_scale_f32 v10, s[0:1], v9, v9, 2.0
	v_rcp_f32_e32 v11, v10
	v_mul_f32_e32 v12, 0.5, v12
	v_add_f32_e32 v0, 1.0, v0
	v_mul_f32_e32 v0, v12, v0
	v_fma_f32 v12, -v10, v11, 1.0
	v_fmac_f32_e32 v11, v12, v11
	v_div_scale_f32 v12, vcc, 2.0, v9, 2.0
	v_mul_f32_e32 v14, v12, v11
	v_fma_f32 v15, -v10, v14, v12
	v_fmac_f32_e32 v14, v15, v11
	v_fma_f32 v10, -v10, v14, v12
	v_div_fmas_f32 v10, v10, v11, v14
	ds_read_b128 v[14:17], v25 offset:384
	v_div_fixup_f32 v9, v10, v9, 2.0
	ds_read_b128 v[10:13], v25 offset:448
	v_sub_f32_e32 v9, 1.0, v9
	v_add_f32_e32 v9, 1.0, v9
	s_waitcnt lgkmcnt(0)
; #define MFMA(a, b, c) __builtin_amdgcn_mfma_f32_16x16x32_bf16((a), (b), (c), 0, 0, 0)
; __device__ __forceinline__ void compress_unit(const Params& p, int unit, char* lds, int tid) {
;     ...
;   f32x4 out = {0.f, 0.f, 0.f, 0.f};
; #pragma unroll
;   for (int pp = 0; pp < 4; ++pp) {
;     const float* rp = part + fr * 128 + 32 * pp + fq * 4;
;     f32x4 h0 = *reinterpret_cast<const f32x4*>(rp), h1 = *reinterpret_cast<const f32x4*>(rp + 16);
;     bf16x8 hb = mk8(u32x4{pk2(gelu_tanh(h0[0]), gelu_tanh(h0[1])), pk2(gelu_tanh(h0[2]), gelu_tanh(h0[3])),
;                           pk2(gelu_tanh(h1[0]), gelu_tanh(h1[1])), pk2(gelu_tanh(h1[2]), gelu_tanh(h1[3]))});
;     const u16* wp = w2t + (16 * w + fr) * 128 + 32 * pp + fq * 4;
;     out = MFMA(ld44(wp, wp + 16), hb, out);
;   }
;   const bool valid = c < 127;
;   if (kv == 0) {
;     u16* kc = WSP(u16, WS_KC) + ((long)(bg * 128 + c)) * 128 + 16 * w + fq * 4;
;     u32x2 pk = {pk2(out[0], out[1]), pk2(out[2], out[3])};
;     if (!valid) pk = u32x2{0u, 0u};
;     *reinterpret_cast<u32x2*>(kc) = pk;
;   } else {
;     u16* vct = WSP(u16, WS_VCT) + ((long)bg * 128 + 16 * w + fq * 4) * 128 + c;
; #pragma unroll
;     for (int j = 0; j < 4; ++j) vct[j * 128] = valid ? (u16)(pk2(out[j], 0.f) & 0xffff) : (u16)0;
	v_mul_f32_e32 v25, 0x3d372713, v14
	v_mul_f32_e32 v25, v14, v25
	v_fma_f32 v25, v14, v25, v14
	v_mul_f32_e32 v25, 0x3f4c422a, v25
	v_mul_f32_e32 v25, 0x4038aa3b, v25
	v_exp_f32_e32 v25, v25
	v_mul_f32_e32 v9, v26, v9
	v_cvt_pk_bf16_f32 v9,v0,v9
	global_load_dwordx2 v[26:27], v[22:23], off offset:192
	global_load_dwordx2 v[28:29], v[22:23], off offset:224
	v_add_f32_e32 v0, 1.0, v25
	v_div_scale_f32 v25, s[0:1], v0, v0, 2.0
	v_rcp_f32_e32 v30, v25
	s_waitcnt vmcnt(0)
	v_mfma_f32_16x16x32_bf16 v[2:5], v[18:21], v[6:9], v[2:5]
	v_mul_f32_e32 v9, 0.5, v14
	v_ashrrev_i32_e32 v115, 31, v114
	v_fma_f32 v6, -v25, v30, 1.0
	v_fmac_f32_e32 v30, v6, v30
	v_div_scale_f32 v6, vcc, 2.0, v0, 2.0
	v_mul_f32_e32 v7, v6, v30
	v_fma_f32 v8, -v25, v7, v6
	v_fmac_f32_e32 v7, v8, v30
	v_mul_f32_e32 v8, 0x3d372713, v15
	v_mul_f32_e32 v8, v15, v8
	v_fma_f32 v8, v15, v8, v15
	v_mul_f32_e32 v8, 0x3f4c422a, v8
	v_mul_f32_e32 v8, 0x4038aa3b, v8
	v_exp_f32_e32 v8, v8
	v_fma_f32 v6, -v25, v7, v6
	v_div_fmas_f32 v6, v6, v30, v7
	v_div_fixup_f32 v0, v6, v0, 2.0
	v_add_f32_e32 v6, 1.0, v8
	v_div_scale_f32 v7, s[0:1], v6, v6, 2.0
	v_rcp_f32_e32 v8, v7
	v_sub_f32_e32 v0, 1.0, v0
	v_add_f32_e32 v0, 1.0, v0
	v_mul_f32_e32 v0, v9, v0
	v_fma_f32 v9, -v7, v8, 1.0
	v_fmac_f32_e32 v8, v9, v8
	v_div_scale_f32 v9, vcc, 2.0, v6, 2.0
	v_mul_f32_e32 v14, v9, v8
	v_fma_f32 v18, -v7, v14, v9
	v_fmac_f32_e32 v14, v18, v8
	v_fma_f32 v7, -v7, v14, v9
	v_div_fmas_f32 v7, v7, v8, v14
	v_mul_f32_e32 v8, 0x3d372713, v16
	v_mul_f32_e32 v8, v16, v8
	v_fma_f32 v8, v16, v8, v16
	v_mul_f32_e32 v8, 0x3f4c422a, v8
	v_mul_f32_e32 v8, 0x4038aa3b, v8
	v_exp_f32_e32 v8, v8
	v_div_fixup_f32 v6, v7, v6, 2.0
	v_sub_f32_e32 v6, 1.0, v6
	v_mul_f32_e32 v7, 0.5, v15
	v_add_f32_e32 v8, 1.0, v8
	v_div_scale_f32 v9, s[0:1], v8, v8, 2.0
	v_rcp_f32_e32 v14, v9
	v_add_f32_e32 v6, 1.0, v6
	v_mul_f32_e32 v6, v7, v6
	v_cvt_pk_bf16_f32 v6,v0,v6
	v_fma_f32 v0, -v9, v14, 1.0
	v_fmac_f32_e32 v14, v0, v14
	v_div_scale_f32 v0, vcc, 2.0, v8, 2.0
	v_mul_f32_e32 v7, v0, v14
	v_fma_f32 v15, -v9, v7, v0
	v_fmac_f32_e32 v7, v15, v14
	v_fma_f32 v0, -v9, v7, v0
	v_mul_f32_e32 v9, 0x3d372713, v17
	v_mul_f32_e32 v9, v17, v9
	v_fma_f32 v9, v17, v9, v17
	v_mul_f32_e32 v9, 0x3f4c422a, v9
	v_mul_f32_e32 v9, 0x4038aa3b, v9
	v_exp_f32_e32 v9, v9
	v_div_fmas_f32 v0, v0, v14, v7
	v_div_fixup_f32 v0, v0, v8, 2.0
	v_sub_f32_e32 v0, 1.0, v0
	v_add_f32_e32 v7, 1.0, v9
	v_div_scale_f32 v8, s[0:1], v7, v7, 2.0
	v_rcp_f32_e32 v9, v8
	v_mul_f32_e32 v14, 0.5, v16
	v_add_f32_e32 v0, 1.0, v0
	v_mul_f32_e32 v0, v14, v0
	v_fma_f32 v14, -v8, v9, 1.0
	v_fmac_f32_e32 v9, v14, v9
	v_div_scale_f32 v14, vcc, 2.0, v7, 2.0
	v_mul_f32_e32 v15, v14, v9
	v_fma_f32 v16, -v8, v15, v14
	v_fmac_f32_e32 v15, v16, v9
	v_fma_f32 v8, -v8, v15, v14
	v_div_fmas_f32 v8, v8, v9, v15
	v_mul_f32_e32 v9, 0x3d372713, v10
	v_mul_f32_e32 v9, v10, v9
	v_fma_f32 v9, v10, v9, v10
	v_mul_f32_e32 v9, 0x3f4c422a, v9
	v_mul_f32_e32 v9, 0x4038aa3b, v9
	v_exp_f32_e32 v9, v9
	v_div_fixup_f32 v7, v8, v7, 2.0
	v_sub_f32_e32 v7, 1.0, v7
	v_mul_f32_e32 v8, 0.5, v17
	v_add_f32_e32 v9, 1.0, v9
	v_div_scale_f32 v14, s[0:1], v9, v9, 2.0
	v_rcp_f32_e32 v15, v14
	v_add_f32_e32 v7, 1.0, v7
	v_mul_f32_e32 v7, v8, v7
	v_cvt_pk_bf16_f32 v7,v0,v7
	v_fma_f32 v0, -v14, v15, 1.0
	v_fmac_f32_e32 v15, v0, v15
	v_div_scale_f32 v0, vcc, 2.0, v9, 2.0
	v_mul_f32_e32 v8, v0, v15
	v_fma_f32 v16, -v14, v8, v0
	v_fmac_f32_e32 v8, v16, v15
	v_fma_f32 v0, -v14, v8, v0
	v_mul_f32_e32 v14, 0x3d372713, v11
	v_mul_f32_e32 v14, v11, v14
	v_fma_f32 v14, v11, v14, v11
	v_mul_f32_e32 v14, 0x3f4c422a, v14
	v_mul_f32_e32 v14, 0x4038aa3b, v14
	v_exp_f32_e32 v14, v14
	v_div_fmas_f32 v0, v0, v15, v8
	v_div_fixup_f32 v0, v0, v9, 2.0
	v_sub_f32_e32 v0, 1.0, v0
	v_add_f32_e32 v8, 1.0, v14
	v_div_scale_f32 v9, s[0:1], v8, v8, 2.0
	v_rcp_f32_e32 v14, v9
	v_mul_f32_e32 v10, 0.5, v10
	v_add_f32_e32 v0, 1.0, v0
	v_mul_f32_e32 v0, v10, v0
	v_fma_f32 v10, -v9, v14, 1.0
	v_fmac_f32_e32 v14, v10, v14
	v_div_scale_f32 v10, vcc, 2.0, v8, 2.0
	v_mul_f32_e32 v15, v10, v14
	v_fma_f32 v16, -v9, v15, v10
	v_fmac_f32_e32 v15, v16, v14
	v_fma_f32 v9, -v9, v15, v10
	v_mul_f32_e32 v10, 0x3d372713, v12
	v_mul_f32_e32 v10, v12, v10
	v_fma_f32 v10, v12, v10, v12
	v_mul_f32_e32 v10, 0x3f4c422a, v10
	v_mul_f32_e32 v10, 0x4038aa3b, v10
	v_exp_f32_e32 v10, v10
	v_div_fmas_f32 v9, v9, v14, v15
	v_div_fixup_f32 v8, v9, v8, 2.0
	v_mul_f32_e32 v9, 0.5, v11
	v_add_f32_e32 v10, 1.0, v10
	v_div_scale_f32 v11, s[0:1], v10, v10, 2.0
	v_rcp_f32_e32 v14, v11
	v_sub_f32_e32 v8, 1.0, v8
	v_add_f32_e32 v8, 1.0, v8
	v_mul_f32_e32 v8, v9, v8
	v_cvt_pk_bf16_f32 v8,v0,v8
	v_fma_f32 v0, -v11, v14, 1.0
	v_fmac_f32_e32 v14, v0, v14
	v_div_scale_f32 v0, vcc, 2.0, v10, 2.0
	v_mul_f32_e32 v9, v0, v14
	v_fma_f32 v15, -v11, v9, v0
	v_fmac_f32_e32 v9, v15, v14
	v_fma_f32 v0, -v11, v9, v0
	v_mul_f32_e32 v11, 0x3d372713, v13
	v_mul_f32_e32 v11, v13, v11
	v_fma_f32 v11, v13, v11, v13
	v_mul_f32_e32 v11, 0x3f4c422a, v11
	v_mul_f32_e32 v11, 0x4038aa3b, v11
	v_exp_f32_e32 v11, v11
	v_div_fmas_f32 v0, v0, v14, v9
	v_div_fixup_f32 v0, v0, v10, 2.0
	v_sub_f32_e32 v0, 1.0, v0
	v_add_f32_e32 v9, 1.0, v11
	v_div_scale_f32 v10, s[0:1], v9, v9, 2.0
	v_rcp_f32_e32 v11, v10
	v_mul_f32_e32 v12, 0.5, v12
	v_add_f32_e32 v0, 1.0, v0
	v_mul_f32_e32 v0, v12, v0
	v_fma_f32 v12, -v10, v11, 1.0
	v_fmac_f32_e32 v11, v12, v11
	v_div_scale_f32 v12, vcc, 2.0, v9, 2.0
	v_mul_f32_e32 v14, v12, v11
	v_fma_f32 v15, -v10, v14, v12
	v_fmac_f32_e32 v14, v15, v11
	v_fma_f32 v10, -v10, v14, v12
	v_div_fmas_f32 v10, v10, v11, v14
	v_div_fixup_f32 v9, v10, v9, 2.0
	v_sub_f32_e32 v9, 1.0, v9
	v_mul_f32_e32 v10, 0.5, v13
	v_add_f32_e32 v9, 1.0, v9
	v_mul_f32_e32 v9, v10, v9
	v_cvt_pk_bf16_f32 v9,v0,v9
	s_mov_b64 s[0:1], -1
	s_and_b64 vcc, exec, s[18:19]
	s_waitcnt lgkmcnt(0)
	v_mfma_f32_16x16x32_bf16 v[2:5], v[26:29], v[6:9], v[2:5]
	s_cbranch_vccz .LBB0_223
	v_mov_b32_e32 v6, 0
	v_mov_b32_e32 v7, 0
	v_mov_b32_e32 v8, 0
	v_mov_b32_e32 v9, 0
	s_and_saveexec_b64 s[0:1], s[8:9]
	s_cbranch_execz .LBB0_222
	v_cvt_pk_bf16_f32 v6,v2,v1
	v_cvt_pk_bf16_f32 v7,v3,v1
	v_cvt_pk_bf16_f32 v8,v4,v1
	v_cvt_pk_bf16_f32 v9,v5,v1

; __device__ __forceinline__ void retq_item(const Params& p, int item, char* lds, int tid) {
;     ...
;   float sm = 0.f;
; #pragma unroll
;   for (int et = 0; et < 16; ++et) sm += (o[et][0] + o[et][1]) + (o[et][2] + o[et][3]);
;   sm += __shfl_xor(sm, 16);
;   sm += __shfl_xor(sm, 32);
;   const float mu = sm * (1.0f / 256.0f);
;   float q2 = 0.f;
; #pragma unroll
;   for (int et = 0; et < 16; ++et)
; #pragma unroll
;     for (int j = 0; j < 4; ++j) { float d = o[et][j] - mu; q2 += d * d; }
;   q2 += __shfl_xor(q2, 16);
;   q2 += __shfl_xor(q2, 32);
.LBB0_230:
	v_mov_b32_e32 v2, v57
	v_mov_b32_e32 v3, v58
	s_waitcnt vmcnt(0) lgkmcnt(0)
	v_mov_b32_e32 v68, v56
	v_mov_b32_e32 v69, v59
	v_pk_add_f32 v[2:3], v[2:3], v[68:69]
	v_mov_b32_e32 v68, v53
	v_mov_b32_e32 v69, v54
	v_mov_b32_e32 v70, v52
	v_mov_b32_e32 v71, v55
	v_pk_add_f32 v[68:69], v[68:69], v[70:71]
	v_add_f32_e32 v0, v2, v3
	v_pk_add_f32 v[68:69], v[68:69], v[68:69] op_sel_hi:[0,1]
	v_add_f32_e32 v3, 0, v0
	v_add_f32_e32 v71, v48, v49
	v_add_f32_e32 v73, v50, v51
	v_mov_b32_e32 v70, v44
	v_mov_b32_e32 v72, v45
	v_mov_b32_e32 v68, v46
	v_mov_b32_e32 v2, v47
	v_pk_add_f32 v[70:71], v[70:71], v[72:73]
	v_pk_add_f32 v[2:3], v[68:69], v[2:3]
	v_mov_b32_e32 v68, v41
	v_pk_add_f32 v[2:3], v[70:71], v[2:3]
	v_mov_b32_e32 v69, v42
	v_mov_b32_e32 v70, v40
	v_mov_b32_e32 v71, v43
	v_pk_add_f32 v[68:69], v[68:69], v[70:71]
	v_pk_add_f32 v[2:3], v[2:3], v[2:3] op_sel_hi:[0,1]
	v_pk_add_f32 v[68:69], v[68:69], v[68:69] op_sel_hi:[0,1]
	v_add_f32_e32 v71, v36, v37
	v_add_f32_e32 v73, v38, v39
	v_mov_b32_e32 v70, v32
	v_mov_b32_e32 v72, v33
	v_mov_b32_e32 v68, v34
	v_mov_b32_e32 v2, v35
	v_pk_add_f32 v[70:71], v[70:71], v[72:73]
	v_pk_add_f32 v[2:3], v[68:69], v[2:3]
	v_mov_b32_e32 v68, v29
	v_pk_add_f32 v[2:3], v[70:71], v[2:3]
	v_mov_b32_e32 v69, v30
	v_mov_b32_e32 v70, v28
	v_mov_b32_e32 v71, v31
	v_pk_add_f32 v[68:69], v[68:69], v[70:71]
	v_pk_add_f32 v[2:3], v[2:3], v[2:3] op_sel_hi:[0,1]
	v_pk_add_f32 v[68:69], v[68:69], v[68:69] op_sel_hi:[0,1]
	v_add_f32_e32 v71, v24, v25
	v_add_f32_e32 v73, v26, v27
	v_mov_b32_e32 v70, v20
	v_mov_b32_e32 v72, v21
	v_mov_b32_e32 v68, v22
	v_mov_b32_e32 v2, v23
	v_pk_add_f32 v[70:71], v[70:71], v[72:73]
	v_pk_add_f32 v[2:3], v[68:69], v[2:3]
	v_mov_b32_e32 v68, v17
	v_pk_add_f32 v[2:3], v[70:71], v[2:3]
	v_mov_b32_e32 v69, v18
	v_mov_b32_e32 v70, v16
	v_mov_b32_e32 v71, v19
	v_pk_add_f32 v[68:69], v[68:69], v[70:71]
	v_pk_add_f32 v[2:3], v[2:3], v[2:3] op_sel_hi:[0,1]
	v_pk_add_f32 v[68:69], v[68:69], v[68:69] op_sel_hi:[0,1]
	v_add_f32_e32 v71, v12, v13
	v_add_f32_e32 v73, v14, v15
	v_mov_b32_e32 v70, v8
	v_mov_b32_e32 v72, v9
	v_mov_b32_e32 v68, v10
	v_mov_b32_e32 v2, v11
	v_pk_add_f32 v[70:71], v[70:71], v[72:73]
	v_pk_add_f32 v[2:3], v[68:69], v[2:3]
	v_mov_b32_e32 v68, v5
	v_pk_add_f32 v[2:3], v[70:71], v[2:3]
	v_mov_b32_e32 v69, v6
	v_mov_b32_e32 v70, v4
	v_mov_b32_e32 v71, v7
	v_pk_add_f32 v[68:69], v[68:69], v[70:71]
	v_pk_add_f32 v[2:3], v[2:3], v[2:3] op_sel_hi:[0,1]
	v_pk_add_f32 v[68:69], v[68:69], v[68:69] op_sel_hi:[0,1]
	v_add_f32_e32 v71, v64, v65
	v_add_f32_e32 v73, v66, v67
	v_mov_b32_e32 v70, v60
	v_mov_b32_e32 v72, v61
	v_mov_b32_e32 v68, v62
	v_mov_b32_e32 v2, v63
	v_pk_add_f32 v[70:71], v[70:71], v[72:73]
	v_pk_add_f32 v[2:3], v[68:69], v[2:3]
	v_cmp_lt_i32_e32 vcc, v177, v180
	v_pk_add_f32 v[2:3], v[70:71], v[2:3]
	s_lshl_b32 s96, s36, 1
	v_add_f32_e32 v0, v2, v3
	v_cndmask_b32_e32 v2, v176, v177, vcc
	v_lshlrev_b32_e32 v70, 2, v2
	ds_bpermute_b32 v2, v70, v0
	v_cmp_lt_i32_e32 vcc, v179, v180
	v_mov_b32_e32 v137, v1
	s_mov_b64 s[0:1], 0x3000
	s_waitcnt lgkmcnt(0)
	v_add_f32_e32 v0, v0, v2
	v_cndmask_b32_e32 v2, v176, v179, vcc
	v_lshlrev_b32_e32 v71, 2, v2
	ds_bpermute_b32 v2, v71, v0
	s_waitcnt lgkmcnt(0)
	v_add_f32_e32 v2, v0, v2
	v_fmac_f32_e32 v57, 0xbb800000, v2
	v_fmac_f32_e32 v56, 0xbb800000, v2
	v_mul_f32_e32 v72, v57, v57
	v_fmac_f32_e32 v72, v56, v56
	v_fmac_f32_e32 v58, 0xbb800000, v2
	v_fmac_f32_e32 v72, v58, v58
	v_fmac_f32_e32 v59, 0xbb800000, v2
	v_fmac_f32_e32 v72, v59, v59
	v_fmac_f32_e32 v52, 0xbb800000, v2
	v_fmac_f32_e32 v72, v52, v52
	v_fmac_f32_e32 v53, 0xbb800000, v2
	v_fmac_f32_e32 v72, v53, v53
	v_fmac_f32_e32 v54, 0xbb800000, v2
	v_fmac_f32_e32 v72, v54, v54
	v_fmac_f32_e32 v55, 0xbb800000, v2
	v_fmac_f32_e32 v72, v55, v55
	v_fmac_f32_e32 v48, 0xbb800000, v2
	v_fmac_f32_e32 v72, v48, v48
	v_fmac_f32_e32 v49, 0xbb800000, v2
	v_fmac_f32_e32 v72, v49, v49
	v_fmac_f32_e32 v50, 0xbb800000, v2
	v_fmac_f32_e32 v72, v50, v50
	v_fmac_f32_e32 v51, 0xbb800000, v2
	v_fmac_f32_e32 v72, v51, v51
	v_fmac_f32_e32 v44, 0xbb800000, v2
	v_fmac_f32_e32 v72, v44, v44
	v_fmac_f32_e32 v45, 0xbb800000, v2
	v_fmac_f32_e32 v72, v45, v45
	v_fmac_f32_e32 v46, 0xbb800000, v2
	v_fmac_f32_e32 v72, v46, v46
	v_fmac_f32_e32 v47, 0xbb800000, v2
	v_fmac_f32_e32 v72, v47, v47
	v_fmac_f32_e32 v40, 0xbb800000, v2
	v_fmac_f32_e32 v72, v40, v40
	v_fmac_f32_e32 v41, 0xbb800000, v2
	v_fmac_f32_e32 v72, v41, v41
	v_fmac_f32_e32 v42, 0xbb800000, v2
	v_fmac_f32_e32 v72, v42, v42
	v_fmac_f32_e32 v43, 0xbb800000, v2
	v_fmac_f32_e32 v72, v43, v43
	v_fmac_f32_e32 v36, 0xbb800000, v2
	v_fmac_f32_e32 v72, v36, v36
	v_fmac_f32_e32 v37, 0xbb800000, v2
	v_fmac_f32_e32 v72, v37, v37
	v_fmac_f32_e32 v38, 0xbb800000, v2
	v_fmac_f32_e32 v72, v38, v38
	v_fmac_f32_e32 v39, 0xbb800000, v2
	v_fmac_f32_e32 v72, v39, v39
	v_fmac_f32_e32 v32, 0xbb800000, v2
	v_fmac_f32_e32 v72, v32, v32
	v_fmac_f32_e32 v33, 0xbb800000, v2
	v_fmac_f32_e32 v72, v33, v33
	v_fmac_f32_e32 v34, 0xbb800000, v2
	v_fmac_f32_e32 v72, v34, v34
	v_fmac_f32_e32 v35, 0xbb800000, v2
	v_fmac_f32_e32 v72, v35, v35
	v_fmac_f32_e32 v28, 0xbb800000, v2
	v_fmac_f32_e32 v72, v28, v28
	v_fmac_f32_e32 v29, 0xbb800000, v2
	v_fmac_f32_e32 v72, v29, v29
	v_fmac_f32_e32 v30, 0xbb800000, v2
	v_fmac_f32_e32 v72, v30, v30
	v_fmac_f32_e32 v31, 0xbb800000, v2
	v_fmac_f32_e32 v72, v31, v31
	v_fmac_f32_e32 v24, 0xbb800000, v2
	v_fmac_f32_e32 v72, v24, v24
	v_fmac_f32_e32 v25, 0xbb800000, v2
	v_fmac_f32_e32 v72, v25, v25
	v_fmac_f32_e32 v26, 0xbb800000, v2
	v_fmac_f32_e32 v72, v26, v26
	v_fmac_f32_e32 v27, 0xbb800000, v2
	v_fmac_f32_e32 v72, v27, v27
; __device__ __forceinline__ float bflo(unsigned u) { return __uint_as_float(u << 16); }
; __device__ __forceinline__ float bfhi(unsigned u) { return __uint_as_float(u & 0xffff0000u); }
; __device__ __forceinline__ void retq_item(const Params& p, int item, char* lds, int tid) {
;     ...
;     for (int j = 0; j < 4; ++j) { float d = o[et][j] - mu; q2 += d * d; }
;   q2 += __shfl_xor(q2, 16);
;   q2 += __shfl_xor(q2, 32);
;   const float rstd = rsqrtf(q2 * (1.0f / 256.0f) + LN_EPS);
;   const u16* grow = proj + (long)t * INWP + OFF_RG + h * 256 + fq * 4;
;   u16* mix = WSP(u16, WS_MIX) + ((long)(b * 2048 + t)) * D + h * 256 + fq * 4;
; #pragma unroll
;   for (int et = 0; et < 16; ++et) {
;     u32x2 graw = *reinterpret_cast<const u32x2*>(grow + 16 * et);
;     float gv[4] = {bflo(graw[0]), bfhi(graw[0]), bflo(graw[1]), bfhi(graw[1])};
;     float y[4];
; #pragma unroll
;     for (int j = 0; j < 4; ++j) y[j] = (o[et][j] - mu) * rstd * (gv[j] / (1.0f + __expf(-gv[j])));
	v_fmac_f32_e32 v20, 0xbb800000, v2
	v_fmac_f32_e32 v72, v20, v20
	v_fmac_f32_e32 v21, 0xbb800000, v2
	v_fmac_f32_e32 v72, v21, v21
	v_fmac_f32_e32 v22, 0xbb800000, v2
	v_fmac_f32_e32 v72, v22, v22
	v_fmac_f32_e32 v23, 0xbb800000, v2
	v_fmac_f32_e32 v72, v23, v23
	v_fmac_f32_e32 v16, 0xbb800000, v2
	v_fmac_f32_e32 v72, v16, v16
	v_fmac_f32_e32 v17, 0xbb800000, v2
	v_fmac_f32_e32 v72, v17, v17
	v_fmac_f32_e32 v18, 0xbb800000, v2
	v_fmac_f32_e32 v72, v18, v18
	v_fmac_f32_e32 v19, 0xbb800000, v2
	v_fmac_f32_e32 v72, v19, v19
	v_fmac_f32_e32 v12, 0xbb800000, v2
	v_fmac_f32_e32 v72, v12, v12
	v_fmac_f32_e32 v13, 0xbb800000, v2
	v_fmac_f32_e32 v72, v13, v13
	v_fmac_f32_e32 v14, 0xbb800000, v2
	v_fmac_f32_e32 v72, v14, v14
	v_fmac_f32_e32 v15, 0xbb800000, v2
	v_fmac_f32_e32 v72, v15, v15
	v_fmac_f32_e32 v8, 0xbb800000, v2
	v_fmac_f32_e32 v72, v8, v8
	v_fmac_f32_e32 v9, 0xbb800000, v2
	v_fmac_f32_e32 v72, v9, v9
	v_fmac_f32_e32 v10, 0xbb800000, v2
	v_fmac_f32_e32 v72, v10, v10
	v_fmac_f32_e32 v11, 0xbb800000, v2
	v_fmac_f32_e32 v72, v11, v11
	v_fmac_f32_e32 v4, 0xbb800000, v2
	v_fmac_f32_e32 v72, v4, v4
	v_fmac_f32_e32 v5, 0xbb800000, v2
	v_mul_f32_e32 v0, 0x3b800000, v2
	v_fmac_f32_e32 v72, v5, v5
	v_fmac_f32_e32 v6, 0xbb800000, v2
	v_fmac_f32_e32 v72, v6, v6
	v_fmac_f32_e32 v7, 0xbb800000, v2
	v_pk_add_f32 v[68:69], v[64:65], v[0:1] op_sel_hi:[1,0] neg_lo:[0,1] neg_hi:[0,1]
	v_fmac_f32_e32 v72, v7, v7
	v_pk_mul_f32 v[2:3], v[68:69], v[68:69]
	v_pk_add_f32 v[66:67], v[66:67], v[0:1] op_sel_hi:[1,0] neg_lo:[0,1] neg_hi:[0,1]
	v_add_f32_e32 v2, v2, v72
	v_add_f32_e32 v64, v3, v2
	v_pk_mul_f32 v[2:3], v[66:67], v[66:67]
	v_pk_add_f32 v[60:61], v[60:61], v[0:1] op_sel_hi:[1,0] neg_lo:[0,1] neg_hi:[0,1]
	v_add_f32_e32 v2, v2, v64
	v_add_f32_e32 v64, v3, v2
	v_pk_mul_f32 v[2:3], v[60:61], v[60:61]
	s_nop 0
	v_add_f32_e32 v2, v2, v64
	v_add_f32_e32 v64, v3, v2
	v_pk_add_f32 v[2:3], v[62:63], v[0:1] op_sel_hi:[1,0] neg_lo:[0,1] neg_hi:[0,1]
	s_nop 0
	v_pk_mul_f32 v[62:63], v[2:3], v[2:3]
	s_nop 0
	v_add_f32_e32 v0, v62, v64
	v_add_f32_e32 v0, v63, v0
	ds_bpermute_b32 v62, v70, v0
	s_waitcnt lgkmcnt(0)
	v_add_f32_e32 v0, v0, v62
	ds_bpermute_b32 v62, v71, v0
	s_waitcnt lgkmcnt(0)
	v_add_f32_e32 v0, v0, v62
	v_fmamk_f32 v0, v0, 0x3b800000, v167
	v_cmp_gt_f32_e32 vcc, s52, v0
	v_mul_f32_e32 v62, 0x4b800000, v0
	s_nop 0
	v_cndmask_b32_e32 v0, v0, v62, vcc
	v_rsq_f32_e32 v0, v0
	s_nop 0
	v_mul_f32_e32 v62, 0x45800000, v0
	v_cndmask_b32_e32 v0, v0, v62, vcc
	v_lshl_add_u64 v[62:63], v[138:139], 0, s[96:97]
	v_lshl_add_u64 v[70:71], v[62:63], 0, v[136:137]
	v_lshl_add_u64 v[64:65], v[70:71], 0, s[0:1]
	global_load_dwordx2 v[100:101], v[64:65], off offset:32
	global_load_dwordx2 v[102:103], v[64:65], off offset:64
	global_load_dwordx2 v[104:105], v[64:65], off offset:96
	global_load_dwordx2 v[106:107], v[64:65], off offset:128
	global_load_dwordx2 v[108:109], v[64:65], off offset:160
	global_load_dwordx2 v[110:111], v[64:65], off offset:192
	global_load_dwordx2 v[112:113], v[64:65], off offset:224
	global_load_dwordx2 v[114:115], v[64:65], off offset:256
	global_load_dwordx2 v[116:117], v[64:65], off offset:288
	global_load_dwordx2 v[118:119], v[64:65], off offset:320
	global_load_dwordx2 v[120:121], v[64:65], off offset:352
	global_load_dwordx2 v[122:123], v[64:65], off offset:384
	global_load_dwordx2 v[124:125], v[64:65], off offset:416
	global_load_dwordx2 v[126:127], v[64:65], off offset:448
	global_load_dwordx2 v[128:129], v[64:65], off offset:480
	s_movk_i32 s0, 0x3000
	v_add_co_u32_e32 v70, vcc, s0, v70
	v_mul_f32_e32 v56, v56, v0
	s_nop 0
	v_addc_co_u32_e32 v71, vcc, 0, v71, vcc
	global_load_dwordx2 v[70:71], v[70:71], off
	v_mul_f32_e32 v57, v57, v0
	v_mul_f32_e32 v58, v58, v0
	v_add_u32_e32 v62, s37, v154
	v_ashrrev_i32_e32 v63, 31, v62
	v_lshlrev_b64 v[62:63], 13, v[62:63]
	v_lshl_add_u64 v[62:63], s[6:7], 0, v[62:63]
	v_lshl_add_u64 v[62:63], v[62:63], 0, s[96:97]
	v_mul_f32_e32 v59, v59, v0
	v_lshl_add_u64 v[62:63], v[62:63], 0, v[136:137]
	v_mul_f32_e32 v52, v52, v0
	v_mul_f32_e32 v53, v53, v0
	v_mul_f32_e32 v54, v54, v0
	v_mul_f32_e32 v55, v55, v0
	v_mul_f32_e32 v48, v48, v0
	v_mul_f32_e32 v49, v49, v0
	v_mul_f32_e32 v50, v50, v0
	v_mul_f32_e32 v51, v51, v0
	v_mul_f32_e32 v44, v44, v0
	v_mul_f32_e32 v45, v45, v0
	v_mul_f32_e32 v46, v46, v0
	v_mul_f32_e32 v47, v47, v0
	v_mul_f32_e32 v40, v40, v0
	v_mul_f32_e32 v41, v41, v0
	v_mul_f32_e32 v42, v42, v0
	v_mul_f32_e32 v43, v43, v0
	v_mul_f32_e32 v36, v36, v0
	v_mul_f32_e32 v37, v37, v0
	v_mul_f32_e32 v38, v38, v0
	v_mul_f32_e32 v39, v39, v0
	v_mul_f32_e32 v32, v32, v0
	v_mul_f32_e32 v33, v33, v0
	v_mul_f32_e32 v34, v34, v0
	v_mul_f32_e32 v35, v35, v0
	v_mul_f32_e32 v28, v28, v0
	v_mul_f32_e32 v29, v29, v0
	v_mul_f32_e32 v30, v30, v0
	v_mul_f32_e32 v31, v31, v0
	v_mul_f32_e32 v24, v24, v0
	v_mul_f32_e32 v25, v25, v0
	v_mul_f32_e32 v26, v26, v0
	v_mul_f32_e32 v27, v27, v0
	v_mul_f32_e32 v20, v20, v0
	v_mul_f32_e32 v21, v21, v0
	v_mul_f32_e32 v22, v22, v0
	v_mul_f32_e32 v23, v23, v0
	v_mul_f32_e32 v16, v16, v0
	v_mul_f32_e32 v17, v17, v0
	v_mul_f32_e32 v18, v18, v0
	v_mul_f32_e32 v19, v19, v0
	v_mul_f32_e32 v12, v12, v0
	v_mul_f32_e32 v13, v13, v0
	v_mul_f32_e32 v14, v14, v0
	v_mul_f32_e32 v15, v15, v0
	v_mul_f32_e32 v8, v8, v0
	v_mul_f32_e32 v9, v9, v0
	v_mul_f32_e32 v10, v10, v0
	v_mul_f32_e32 v11, v11, v0
	v_mul_f32_e32 v4, v4, v0
	v_mul_f32_e32 v5, v5, v0
	v_mul_f32_e32 v6, v6, v0
	v_mul_f32_e32 v7, v7, v0
	v_mul_f32_e32 v2, v2, v0
	s_waitcnt vmcnt(0) lgkmcnt(0)
; __device__ __forceinline__ float bflo(unsigned u) { return __uint_as_float(u << 16); }
; __device__ __forceinline__ float bfhi(unsigned u) { return __uint_as_float(u & 0xffff0000u); }
; __device__ __forceinline__ void retq_item(const Params& p, int item, char* lds, int tid) {
;     ...
; #pragma unroll
;   for (int et = 0; et < 16; ++et) {
;     u32x2 graw = *reinterpret_cast<const u32x2*>(grow + 16 * et);
;     float gv[4] = {bflo(graw[0]), bfhi(graw[0]), bflo(graw[1]), bfhi(graw[1])};
;     float y[4];
; #pragma unroll
;     for (int j = 0; j < 4; ++j) y[j] = (o[et][j] - mu) * rstd * (gv[j] / (1.0f + __expf(-gv[j])));
;     *reinterpret_cast<u32x2*>(mix + 16 * et) = u32x2{pk2(y[0], y[1]), pk2(y[2], y[3])};
;   }
	v_lshlrev_b32_e32 v72, 16, v70
	v_mul_f32_e32 v74, 0xbfb8aa3b, v72
	v_exp_f32_e32 v74, v74
	v_and_b32_e32 v70, 0xffff0000, v70
	v_lshlrev_b32_e32 v73, 16, v71
	v_and_b32_e32 v71, 0xffff0000, v71
	v_add_f32_e32 v74, 1.0, v74
	v_div_scale_f32 v75, s[0:1], v74, v74, v72
	v_rcp_f32_e32 v76, v75
	s_nop 0
	v_fma_f32 v77, -v75, v76, 1.0
	v_fmac_f32_e32 v76, v77, v76
	v_div_scale_f32 v77, vcc, v72, v74, v72
	v_mul_f32_e32 v78, v77, v76
	v_fma_f32 v79, -v75, v78, v77
	v_fmac_f32_e32 v78, v79, v76
	v_fma_f32 v75, -v75, v78, v77
	v_div_fmas_f32 v75, v75, v76, v78
	v_div_fixup_f32 v72, v75, v74, v72
	v_mul_f32_e32 v56, v72, v56
	v_mul_f32_e32 v72, 0xbfb8aa3b, v70
	v_exp_f32_e32 v72, v72
	s_nop 0
	v_add_f32_e32 v72, 1.0, v72
	v_div_scale_f32 v74, s[0:1], v72, v72, v70
	v_rcp_f32_e32 v75, v74
	s_nop 0
	v_fma_f32 v76, -v74, v75, 1.0
	v_fmac_f32_e32 v75, v76, v75
	v_div_scale_f32 v76, vcc, v70, v72, v70
	v_mul_f32_e32 v77, v76, v75
	v_fma_f32 v78, -v74, v77, v76
	v_fmac_f32_e32 v77, v78, v75
	v_fma_f32 v74, -v74, v77, v76
	v_div_fmas_f32 v74, v74, v75, v77
	v_div_fixup_f32 v70, v74, v72, v70
	v_mul_f32_e32 v57, v70, v57
	v_mul_f32_e32 v70, 0xbfb8aa3b, v73
	v_exp_f32_e32 v70, v70
	v_cvt_pk_bf16_f32 v56,v56,v57
	s_nop 0
	v_add_f32_e32 v70, 1.0, v70
	v_div_scale_f32 v72, s[0:1], v70, v70, v73
	v_rcp_f32_e32 v74, v72
	s_nop 0
	v_fma_f32 v75, -v72, v74, 1.0
	v_fmac_f32_e32 v74, v75, v74
	v_div_scale_f32 v75, vcc, v73, v70, v73
	v_mul_f32_e32 v76, v75, v74
	v_fma_f32 v77, -v72, v76, v75
	v_fmac_f32_e32 v76, v77, v74
	v_fma_f32 v72, -v72, v76, v75
	v_div_fmas_f32 v72, v72, v74, v76
	v_div_fixup_f32 v70, v72, v70, v73
	v_mul_f32_e32 v58, v70, v58
	v_mul_f32_e32 v70, 0xbfb8aa3b, v71
	v_exp_f32_e32 v70, v70
	s_nop 0
	v_add_f32_e32 v70, 1.0, v70
	v_div_scale_f32 v72, s[0:1], v70, v70, v71
	v_rcp_f32_e32 v73, v72
	s_nop 0
	v_fma_f32 v74, -v72, v73, 1.0
	v_fmac_f32_e32 v73, v74, v73
	v_div_scale_f32 v74, vcc, v71, v70, v71
	v_mul_f32_e32 v75, v74, v73
	v_fma_f32 v76, -v72, v75, v74
	v_fmac_f32_e32 v75, v76, v73
	v_fma_f32 v72, -v72, v75, v74
	v_div_fmas_f32 v72, v72, v73, v75
	v_div_fixup_f32 v70, v72, v70, v71
	v_mul_f32_e32 v59, v70, v59
	v_cvt_pk_bf16_f32 v57,v58,v59
	flat_store_dwordx2 v[62:63], v[56:57]
	v_mov_b32_e32 v56, v100
	v_mov_b32_e32 v57, v101
	v_lshlrev_b32_e32 v58, 16, v56
	v_mul_f32_e32 v70, 0xbfb8aa3b, v58
	v_exp_f32_e32 v70, v70
	v_and_b32_e32 v56, 0xffff0000, v56
	v_lshlrev_b32_e32 v59, 16, v57
	v_and_b32_e32 v57, 0xffff0000, v57
	v_add_f32_e32 v70, 1.0, v70
	v_div_scale_f32 v71, s[0:1], v70, v70, v58
	v_rcp_f32_e32 v72, v71
	s_nop 0
	v_fma_f32 v73, -v71, v72, 1.0
	v_fmac_f32_e32 v72, v73, v72
	v_div_scale_f32 v73, vcc, v58, v70, v58
	v_mul_f32_e32 v74, v73, v72
	v_fma_f32 v75, -v71, v74, v73
	v_fmac_f32_e32 v74, v75, v72
	v_fma_f32 v71, -v71, v74, v73
	v_div_fmas_f32 v71, v71, v72, v74
	v_div_fixup_f32 v58, v71, v70, v58
	v_mul_f32_e32 v52, v58, v52
	v_mul_f32_e32 v58, 0xbfb8aa3b, v56
	v_exp_f32_e32 v58, v58
	s_nop 0
	v_add_f32_e32 v58, 1.0, v58
	v_div_scale_f32 v70, s[0:1], v58, v58, v56
	v_rcp_f32_e32 v71, v70
	s_nop 0
	v_fma_f32 v72, -v70, v71, 1.0
	v_fmac_f32_e32 v71, v72, v71
	v_div_scale_f32 v72, vcc, v56, v58, v56
	v_mul_f32_e32 v73, v72, v71
	v_fma_f32 v74, -v70, v73, v72
	v_fmac_f32_e32 v73, v74, v71
	v_fma_f32 v70, -v70, v73, v72
	v_div_fmas_f32 v70, v70, v71, v73
	v_div_fixup_f32 v56, v70, v58, v56
	v_mul_f32_e32 v53, v56, v53
	v_mul_f32_e32 v56, 0xbfb8aa3b, v59
	v_exp_f32_e32 v56, v56
	v_cvt_pk_bf16_f32 v52,v52,v53
	s_nop 0
	v_add_f32_e32 v56, 1.0, v56
	v_div_scale_f32 v58, s[0:1], v56, v56, v59
	v_rcp_f32_e32 v70, v58
	s_nop 0
	v_fma_f32 v71, -v58, v70, 1.0
	v_fmac_f32_e32 v70, v71, v70
	v_div_scale_f32 v71, vcc, v59, v56, v59
	v_mul_f32_e32 v72, v71, v70
	v_fma_f32 v73, -v58, v72, v71
	v_fmac_f32_e32 v72, v73, v70
	v_fma_f32 v58, -v58, v72, v71
	v_div_fmas_f32 v58, v58, v70, v72
	v_div_fixup_f32 v56, v58, v56, v59
	v_mul_f32_e32 v54, v56, v54
	v_mul_f32_e32 v56, 0xbfb8aa3b, v57
	v_exp_f32_e32 v56, v56
	s_nop 0
	v_add_f32_e32 v56, 1.0, v56
	v_div_scale_f32 v58, s[0:1], v56, v56, v57
	v_rcp_f32_e32 v59, v58
	s_nop 0
	v_fma_f32 v70, -v58, v59, 1.0
	v_fmac_f32_e32 v59, v70, v59
	v_div_scale_f32 v70, vcc, v57, v56, v57
	v_mul_f32_e32 v71, v70, v59
	v_fma_f32 v72, -v58, v71, v70
	v_fmac_f32_e32 v71, v72, v59
	v_fma_f32 v58, -v58, v71, v70
	v_div_fmas_f32 v58, v58, v59, v71
	v_div_fixup_f32 v56, v58, v56, v57
	v_mul_f32_e32 v55, v56, v55
	v_cvt_pk_bf16_f32 v53,v54,v55
	flat_store_dwordx2 v[62:63], v[52:53] offset:32
	v_mov_b32_e32 v52, v102
	v_mov_b32_e32 v53, v103
	v_lshlrev_b32_e32 v54, 16, v52
	v_mul_f32_e32 v56, 0xbfb8aa3b, v54
	v_exp_f32_e32 v56, v56
	v_and_b32_e32 v52, 0xffff0000, v52
	v_lshlrev_b32_e32 v55, 16, v53
	v_and_b32_e32 v53, 0xffff0000, v53
	v_add_f32_e32 v56, 1.0, v56
	v_div_scale_f32 v57, s[0:1], v56, v56, v54
	v_rcp_f32_e32 v58, v57
	s_nop 0
	v_fma_f32 v59, -v57, v58, 1.0
	v_fmac_f32_e32 v58, v59, v58
	v_div_scale_f32 v59, vcc, v54, v56, v54
	v_mul_f32_e32 v70, v59, v58
	v_fma_f32 v71, -v57, v70, v59
	v_fmac_f32_e32 v70, v71, v58
	v_fma_f32 v57, -v57, v70, v59
	v_div_fmas_f32 v57, v57, v58, v70
	v_div_fixup_f32 v54, v57, v56, v54
	v_mul_f32_e32 v48, v54, v48
	v_mul_f32_e32 v54, 0xbfb8aa3b, v52
	v_exp_f32_e32 v54, v54
	s_nop 0
	v_add_f32_e32 v54, 1.0, v54
	v_div_scale_f32 v56, s[0:1], v54, v54, v52
	v_rcp_f32_e32 v57, v56
	s_nop 0
	v_fma_f32 v58, -v56, v57, 1.0
	v_fmac_f32_e32 v57, v58, v57
	v_div_scale_f32 v58, vcc, v52, v54, v52
	v_mul_f32_e32 v59, v58, v57
	v_fma_f32 v70, -v56, v59, v58
	v_fmac_f32_e32 v59, v70, v57
	v_fma_f32 v56, -v56, v59, v58
	v_div_fmas_f32 v56, v56, v57, v59
	v_div_fixup_f32 v52, v56, v54, v52
; __device__ __forceinline__ float bflo(unsigned u) { return __uint_as_float(u << 16); }
; __device__ __forceinline__ float bfhi(unsigned u) { return __uint_as_float(u & 0xffff0000u); }
; __device__ __forceinline__ void retq_item(const Params& p, int item, char* lds, int tid) {
;     ...
; #pragma unroll
;   for (int et = 0; et < 16; ++et) {
;     u32x2 graw = *reinterpret_cast<const u32x2*>(grow + 16 * et);
;     float gv[4] = {bflo(graw[0]), bfhi(graw[0]), bflo(graw[1]), bfhi(graw[1])};
;     float y[4];
; #pragma unroll
;     for (int j = 0; j < 4; ++j) y[j] = (o[et][j] - mu) * rstd * (gv[j] / (1.0f + __expf(-gv[j])));
;     *reinterpret_cast<u32x2*>(mix + 16 * et) = u32x2{pk2(y[0], y[1]), pk2(y[2], y[3])};
;   }
	v_mul_f32_e32 v49, v52, v49
	v_mul_f32_e32 v52, 0xbfb8aa3b, v55
	v_exp_f32_e32 v52, v52
	v_cvt_pk_bf16_f32 v48,v48,v49
	s_nop 0
	v_add_f32_e32 v52, 1.0, v52
	v_div_scale_f32 v54, s[0:1], v52, v52, v55
	v_rcp_f32_e32 v56, v54
	s_nop 0
	v_fma_f32 v57, -v54, v56, 1.0
	v_fmac_f32_e32 v56, v57, v56
	v_div_scale_f32 v57, vcc, v55, v52, v55
	v_mul_f32_e32 v58, v57, v56
	v_fma_f32 v59, -v54, v58, v57
	v_fmac_f32_e32 v58, v59, v56
	v_fma_f32 v54, -v54, v58, v57
	v_div_fmas_f32 v54, v54, v56, v58
	v_div_fixup_f32 v52, v54, v52, v55
	v_mul_f32_e32 v50, v52, v50
	v_mul_f32_e32 v52, 0xbfb8aa3b, v53
	v_exp_f32_e32 v52, v52
	s_nop 0
	v_add_f32_e32 v52, 1.0, v52
	v_div_scale_f32 v54, s[0:1], v52, v52, v53
	v_rcp_f32_e32 v55, v54
	s_nop 0
	v_fma_f32 v56, -v54, v55, 1.0
	v_fmac_f32_e32 v55, v56, v55
	v_div_scale_f32 v56, vcc, v53, v52, v53
	v_mul_f32_e32 v57, v56, v55
	v_fma_f32 v58, -v54, v57, v56
	v_fmac_f32_e32 v57, v58, v55
	v_fma_f32 v54, -v54, v57, v56
	v_div_fmas_f32 v54, v54, v55, v57
	v_div_fixup_f32 v52, v54, v52, v53
	v_mul_f32_e32 v51, v52, v51
	v_cvt_pk_bf16_f32 v49,v50,v51
	flat_store_dwordx2 v[62:63], v[48:49] offset:64
	v_mov_b32_e32 v48, v104
	v_mov_b32_e32 v49, v105
	v_lshlrev_b32_e32 v50, 16, v48
	v_mul_f32_e32 v52, 0xbfb8aa3b, v50
	v_exp_f32_e32 v52, v52
	v_and_b32_e32 v48, 0xffff0000, v48
	v_lshlrev_b32_e32 v51, 16, v49
	v_and_b32_e32 v49, 0xffff0000, v49
	v_add_f32_e32 v52, 1.0, v52
	v_div_scale_f32 v53, s[0:1], v52, v52, v50
	v_rcp_f32_e32 v54, v53
	s_nop 0
	v_fma_f32 v55, -v53, v54, 1.0
	v_fmac_f32_e32 v54, v55, v54
	v_div_scale_f32 v55, vcc, v50, v52, v50
	v_mul_f32_e32 v56, v55, v54
	v_fma_f32 v57, -v53, v56, v55
	v_fmac_f32_e32 v56, v57, v54
	v_fma_f32 v53, -v53, v56, v55
	v_div_fmas_f32 v53, v53, v54, v56
	v_div_fixup_f32 v50, v53, v52, v50
	v_mul_f32_e32 v44, v50, v44
	v_mul_f32_e32 v50, 0xbfb8aa3b, v48
	v_exp_f32_e32 v50, v50
	s_nop 0
	v_add_f32_e32 v50, 1.0, v50
	v_div_scale_f32 v52, s[0:1], v50, v50, v48
	v_rcp_f32_e32 v53, v52
	s_nop 0
	v_fma_f32 v54, -v52, v53, 1.0
	v_fmac_f32_e32 v53, v54, v53
	v_div_scale_f32 v54, vcc, v48, v50, v48
	v_mul_f32_e32 v55, v54, v53
	v_fma_f32 v56, -v52, v55, v54
	v_fmac_f32_e32 v55, v56, v53
	v_fma_f32 v52, -v52, v55, v54
	v_div_fmas_f32 v52, v52, v53, v55
	v_div_fixup_f32 v48, v52, v50, v48
	v_mul_f32_e32 v45, v48, v45
	v_mul_f32_e32 v48, 0xbfb8aa3b, v51
	v_exp_f32_e32 v48, v48
	v_cvt_pk_bf16_f32 v44,v44,v45
	s_nop 0
	v_add_f32_e32 v48, 1.0, v48
	v_div_scale_f32 v50, s[0:1], v48, v48, v51
	v_rcp_f32_e32 v52, v50
	s_nop 0
	v_fma_f32 v53, -v50, v52, 1.0
	v_fmac_f32_e32 v52, v53, v52
	v_div_scale_f32 v53, vcc, v51, v48, v51
	v_mul_f32_e32 v54, v53, v52
	v_fma_f32 v55, -v50, v54, v53
	v_fmac_f32_e32 v54, v55, v52
	v_fma_f32 v50, -v50, v54, v53
	v_div_fmas_f32 v50, v50, v52, v54
	v_div_fixup_f32 v48, v50, v48, v51
	v_mul_f32_e32 v46, v48, v46
	v_mul_f32_e32 v48, 0xbfb8aa3b, v49
	v_exp_f32_e32 v48, v48
	s_nop 0
	v_add_f32_e32 v48, 1.0, v48
	v_div_scale_f32 v50, s[0:1], v48, v48, v49
	v_rcp_f32_e32 v51, v50
	s_nop 0
	v_fma_f32 v52, -v50, v51, 1.0
	v_fmac_f32_e32 v51, v52, v51
	v_div_scale_f32 v52, vcc, v49, v48, v49
	v_mul_f32_e32 v53, v52, v51
	v_fma_f32 v54, -v50, v53, v52
	v_fmac_f32_e32 v53, v54, v51
	v_fma_f32 v50, -v50, v53, v52
	v_div_fmas_f32 v50, v50, v51, v53
	v_div_fixup_f32 v48, v50, v48, v49
	v_mul_f32_e32 v47, v48, v47
	v_cvt_pk_bf16_f32 v45,v46,v47
	flat_store_dwordx2 v[62:63], v[44:45] offset:96
	v_mov_b32_e32 v44, v106
	v_mov_b32_e32 v45, v107
	v_lshlrev_b32_e32 v46, 16, v44
	v_mul_f32_e32 v48, 0xbfb8aa3b, v46
	v_exp_f32_e32 v48, v48
	v_and_b32_e32 v44, 0xffff0000, v44
	v_lshlrev_b32_e32 v47, 16, v45
	v_and_b32_e32 v45, 0xffff0000, v45
	v_add_f32_e32 v48, 1.0, v48
	v_div_scale_f32 v49, s[0:1], v48, v48, v46
	v_rcp_f32_e32 v50, v49
	s_nop 0
	v_fma_f32 v51, -v49, v50, 1.0
	v_fmac_f32_e32 v50, v51, v50
	v_div_scale_f32 v51, vcc, v46, v48, v46
	v_mul_f32_e32 v52, v51, v50
	v_fma_f32 v53, -v49, v52, v51
	v_fmac_f32_e32 v52, v53, v50
	v_fma_f32 v49, -v49, v52, v51
	v_div_fmas_f32 v49, v49, v50, v52
	v_div_fixup_f32 v46, v49, v48, v46
	v_mul_f32_e32 v40, v46, v40
	v_mul_f32_e32 v46, 0xbfb8aa3b, v44
	v_exp_f32_e32 v46, v46
	s_nop 0
	v_add_f32_e32 v46, 1.0, v46
	v_div_scale_f32 v48, s[0:1], v46, v46, v44
	v_rcp_f32_e32 v49, v48
	s_nop 0
	v_fma_f32 v50, -v48, v49, 1.0
	v_fmac_f32_e32 v49, v50, v49
	v_div_scale_f32 v50, vcc, v44, v46, v44
	v_mul_f32_e32 v51, v50, v49
	v_fma_f32 v52, -v48, v51, v50
	v_fmac_f32_e32 v51, v52, v49
	v_fma_f32 v48, -v48, v51, v50
	v_div_fmas_f32 v48, v48, v49, v51
	v_div_fixup_f32 v44, v48, v46, v44
	v_mul_f32_e32 v41, v44, v41
	v_mul_f32_e32 v44, 0xbfb8aa3b, v47
	v_exp_f32_e32 v44, v44
	v_cvt_pk_bf16_f32 v40,v40,v41
	s_nop 0
	v_add_f32_e32 v44, 1.0, v44
	v_div_scale_f32 v46, s[0:1], v44, v44, v47
	v_rcp_f32_e32 v48, v46
	s_nop 0
	v_fma_f32 v49, -v46, v48, 1.0
	v_fmac_f32_e32 v48, v49, v48
	v_div_scale_f32 v49, vcc, v47, v44, v47
	v_mul_f32_e32 v50, v49, v48
	v_fma_f32 v51, -v46, v50, v49
	v_fmac_f32_e32 v50, v51, v48
	v_fma_f32 v46, -v46, v50, v49
	v_div_fmas_f32 v46, v46, v48, v50
	v_div_fixup_f32 v44, v46, v44, v47
	v_mul_f32_e32 v42, v44, v42
	v_mul_f32_e32 v44, 0xbfb8aa3b, v45
	v_exp_f32_e32 v44, v44
	s_nop 0
	v_add_f32_e32 v44, 1.0, v44
	v_div_scale_f32 v46, s[0:1], v44, v44, v45
	v_rcp_f32_e32 v47, v46
	s_nop 0
	v_fma_f32 v48, -v46, v47, 1.0
	v_fmac_f32_e32 v47, v48, v47
	v_div_scale_f32 v48, vcc, v45, v44, v45
	v_mul_f32_e32 v49, v48, v47
	v_fma_f32 v50, -v46, v49, v48
	v_fmac_f32_e32 v49, v50, v47
	v_fma_f32 v46, -v46, v49, v48
	v_div_fmas_f32 v46, v46, v47, v49
	v_div_fixup_f32 v44, v46, v44, v45
	v_mul_f32_e32 v43, v44, v43
	v_cvt_pk_bf16_f32 v41,v42,v43
; __device__ __forceinline__ float bflo(unsigned u) { return __uint_as_float(u << 16); }
; __device__ __forceinline__ float bfhi(unsigned u) { return __uint_as_float(u & 0xffff0000u); }
; __device__ __forceinline__ void retq_item(const Params& p, int item, char* lds, int tid) {
;     ...
; #pragma unroll
;   for (int et = 0; et < 16; ++et) {
;     u32x2 graw = *reinterpret_cast<const u32x2*>(grow + 16 * et);
;     float gv[4] = {bflo(graw[0]), bfhi(graw[0]), bflo(graw[1]), bfhi(graw[1])};
;     float y[4];
; #pragma unroll
;     for (int j = 0; j < 4; ++j) y[j] = (o[et][j] - mu) * rstd * (gv[j] / (1.0f + __expf(-gv[j])));
;     *reinterpret_cast<u32x2*>(mix + 16 * et) = u32x2{pk2(y[0], y[1]), pk2(y[2], y[3])};
;   }
	flat_store_dwordx2 v[62:63], v[40:41] offset:128
	v_mov_b32_e32 v40, v108
	v_mov_b32_e32 v41, v109
	v_lshlrev_b32_e32 v42, 16, v40
	v_mul_f32_e32 v44, 0xbfb8aa3b, v42
	v_exp_f32_e32 v44, v44
	v_and_b32_e32 v40, 0xffff0000, v40
	v_lshlrev_b32_e32 v43, 16, v41
	v_and_b32_e32 v41, 0xffff0000, v41
	v_add_f32_e32 v44, 1.0, v44
	v_div_scale_f32 v45, s[0:1], v44, v44, v42
	v_rcp_f32_e32 v46, v45
	s_nop 0
	v_fma_f32 v47, -v45, v46, 1.0
	v_fmac_f32_e32 v46, v47, v46
	v_div_scale_f32 v47, vcc, v42, v44, v42
	v_mul_f32_e32 v48, v47, v46
	v_fma_f32 v49, -v45, v48, v47
	v_fmac_f32_e32 v48, v49, v46
	v_fma_f32 v45, -v45, v48, v47
	v_div_fmas_f32 v45, v45, v46, v48
	v_div_fixup_f32 v42, v45, v44, v42
	v_mul_f32_e32 v36, v42, v36
	v_mul_f32_e32 v42, 0xbfb8aa3b, v40
	v_exp_f32_e32 v42, v42
	s_nop 0
	v_add_f32_e32 v42, 1.0, v42
	v_div_scale_f32 v44, s[0:1], v42, v42, v40
	v_rcp_f32_e32 v45, v44
	s_nop 0
	v_fma_f32 v46, -v44, v45, 1.0
	v_fmac_f32_e32 v45, v46, v45
	v_div_scale_f32 v46, vcc, v40, v42, v40
	v_mul_f32_e32 v47, v46, v45
	v_fma_f32 v48, -v44, v47, v46
	v_fmac_f32_e32 v47, v48, v45
	v_fma_f32 v44, -v44, v47, v46
	v_div_fmas_f32 v44, v44, v45, v47
	v_div_fixup_f32 v40, v44, v42, v40
	v_mul_f32_e32 v37, v40, v37
	v_mul_f32_e32 v40, 0xbfb8aa3b, v43
	v_exp_f32_e32 v40, v40
	v_cvt_pk_bf16_f32 v36,v36,v37
	s_nop 0
	v_add_f32_e32 v40, 1.0, v40
	v_div_scale_f32 v42, s[0:1], v40, v40, v43
	v_rcp_f32_e32 v44, v42
	s_nop 0
	v_fma_f32 v45, -v42, v44, 1.0
	v_fmac_f32_e32 v44, v45, v44
	v_div_scale_f32 v45, vcc, v43, v40, v43
	v_mul_f32_e32 v46, v45, v44
	v_fma_f32 v47, -v42, v46, v45
	v_fmac_f32_e32 v46, v47, v44
	v_fma_f32 v42, -v42, v46, v45
	v_div_fmas_f32 v42, v42, v44, v46
	v_div_fixup_f32 v40, v42, v40, v43
	v_mul_f32_e32 v38, v40, v38
	v_mul_f32_e32 v40, 0xbfb8aa3b, v41
	v_exp_f32_e32 v40, v40
	s_nop 0
	v_add_f32_e32 v40, 1.0, v40
	v_div_scale_f32 v42, s[0:1], v40, v40, v41
	v_rcp_f32_e32 v43, v42
	s_nop 0
	v_fma_f32 v44, -v42, v43, 1.0
	v_fmac_f32_e32 v43, v44, v43
	v_div_scale_f32 v44, vcc, v41, v40, v41
	v_mul_f32_e32 v45, v44, v43
	v_fma_f32 v46, -v42, v45, v44
	v_fmac_f32_e32 v45, v46, v43
	v_fma_f32 v42, -v42, v45, v44
	v_div_fmas_f32 v42, v42, v43, v45
	v_div_fixup_f32 v40, v42, v40, v41
	v_mul_f32_e32 v39, v40, v39
	v_cvt_pk_bf16_f32 v37,v38,v39
	flat_store_dwordx2 v[62:63], v[36:37] offset:160
	v_mov_b32_e32 v36, v110
	v_mov_b32_e32 v37, v111
	v_lshlrev_b32_e32 v38, 16, v36
	v_mul_f32_e32 v40, 0xbfb8aa3b, v38
	v_exp_f32_e32 v40, v40
	v_and_b32_e32 v36, 0xffff0000, v36
	v_lshlrev_b32_e32 v39, 16, v37
	v_and_b32_e32 v37, 0xffff0000, v37
	v_add_f32_e32 v40, 1.0, v40
	v_div_scale_f32 v41, s[0:1], v40, v40, v38
	v_rcp_f32_e32 v42, v41
	s_nop 0
	v_fma_f32 v43, -v41, v42, 1.0
	v_fmac_f32_e32 v42, v43, v42
	v_div_scale_f32 v43, vcc, v38, v40, v38
	v_mul_f32_e32 v44, v43, v42
	v_fma_f32 v45, -v41, v44, v43
	v_fmac_f32_e32 v44, v45, v42
	v_fma_f32 v41, -v41, v44, v43
	v_div_fmas_f32 v41, v41, v42, v44
	v_div_fixup_f32 v38, v41, v40, v38
	v_mul_f32_e32 v32, v38, v32
	v_mul_f32_e32 v38, 0xbfb8aa3b, v36
	v_exp_f32_e32 v38, v38
	s_nop 0
	v_add_f32_e32 v38, 1.0, v38
	v_div_scale_f32 v40, s[0:1], v38, v38, v36
	v_rcp_f32_e32 v41, v40
	s_nop 0
	v_fma_f32 v42, -v40, v41, 1.0
	v_fmac_f32_e32 v41, v42, v41
	v_div_scale_f32 v42, vcc, v36, v38, v36
	v_mul_f32_e32 v43, v42, v41
	v_fma_f32 v44, -v40, v43, v42
	v_fmac_f32_e32 v43, v44, v41
	v_fma_f32 v40, -v40, v43, v42
	v_div_fmas_f32 v40, v40, v41, v43
	v_div_fixup_f32 v36, v40, v38, v36
	v_mul_f32_e32 v33, v36, v33
	v_mul_f32_e32 v36, 0xbfb8aa3b, v39
	v_exp_f32_e32 v36, v36
	v_cvt_pk_bf16_f32 v32,v32,v33
	s_nop 0
	v_add_f32_e32 v36, 1.0, v36
	v_div_scale_f32 v38, s[0:1], v36, v36, v39
	v_rcp_f32_e32 v40, v38
	s_nop 0
	v_fma_f32 v41, -v38, v40, 1.0
	v_fmac_f32_e32 v40, v41, v40
	v_div_scale_f32 v41, vcc, v39, v36, v39
	v_mul_f32_e32 v42, v41, v40
	v_fma_f32 v43, -v38, v42, v41
	v_fmac_f32_e32 v42, v43, v40
	v_fma_f32 v38, -v38, v42, v41
	v_div_fmas_f32 v38, v38, v40, v42
	v_div_fixup_f32 v36, v38, v36, v39
	v_mul_f32_e32 v34, v36, v34
	v_mul_f32_e32 v36, 0xbfb8aa3b, v37
	v_exp_f32_e32 v36, v36
	s_nop 0
	v_add_f32_e32 v36, 1.0, v36
	v_div_scale_f32 v38, s[0:1], v36, v36, v37
	v_rcp_f32_e32 v39, v38
	s_nop 0
	v_fma_f32 v40, -v38, v39, 1.0
	v_fmac_f32_e32 v39, v40, v39
	v_div_scale_f32 v40, vcc, v37, v36, v37
	v_mul_f32_e32 v41, v40, v39
	v_fma_f32 v42, -v38, v41, v40
	v_fmac_f32_e32 v41, v42, v39
	v_fma_f32 v38, -v38, v41, v40
	v_div_fmas_f32 v38, v38, v39, v41
	v_div_fixup_f32 v36, v38, v36, v37
	v_mul_f32_e32 v35, v36, v35
	v_cvt_pk_bf16_f32 v33,v34,v35
	flat_store_dwordx2 v[62:63], v[32:33] offset:192
	v_mov_b32_e32 v32, v112
	v_mov_b32_e32 v33, v113
	v_lshlrev_b32_e32 v34, 16, v32
	v_mul_f32_e32 v36, 0xbfb8aa3b, v34
	v_exp_f32_e32 v36, v36
	v_and_b32_e32 v32, 0xffff0000, v32
	v_lshlrev_b32_e32 v35, 16, v33
	v_and_b32_e32 v33, 0xffff0000, v33
	v_add_f32_e32 v36, 1.0, v36
	v_div_scale_f32 v37, s[0:1], v36, v36, v34
	v_rcp_f32_e32 v38, v37
	s_nop 0
	v_fma_f32 v39, -v37, v38, 1.0
	v_fmac_f32_e32 v38, v39, v38
	v_div_scale_f32 v39, vcc, v34, v36, v34
	v_mul_f32_e32 v40, v39, v38
	v_fma_f32 v41, -v37, v40, v39
	v_fmac_f32_e32 v40, v41, v38
	v_fma_f32 v37, -v37, v40, v39
	v_div_fmas_f32 v37, v37, v38, v40
	v_div_fixup_f32 v34, v37, v36, v34
	v_mul_f32_e32 v28, v34, v28
	v_mul_f32_e32 v34, 0xbfb8aa3b, v32
	v_exp_f32_e32 v34, v34
	s_nop 0
	v_add_f32_e32 v34, 1.0, v34
	v_div_scale_f32 v36, s[0:1], v34, v34, v32
	v_rcp_f32_e32 v37, v36
	s_nop 0
	v_fma_f32 v38, -v36, v37, 1.0
	v_fmac_f32_e32 v37, v38, v37
	v_div_scale_f32 v38, vcc, v32, v34, v32
	v_mul_f32_e32 v39, v38, v37
	v_fma_f32 v40, -v36, v39, v38
	v_fmac_f32_e32 v39, v40, v37
; __device__ __forceinline__ float bflo(unsigned u) { return __uint_as_float(u << 16); }
; __device__ __forceinline__ float bfhi(unsigned u) { return __uint_as_float(u & 0xffff0000u); }
; __device__ __forceinline__ void retq_item(const Params& p, int item, char* lds, int tid) {
;     ...
; #pragma unroll
;   for (int et = 0; et < 16; ++et) {
;     u32x2 graw = *reinterpret_cast<const u32x2*>(grow + 16 * et);
;     float gv[4] = {bflo(graw[0]), bfhi(graw[0]), bflo(graw[1]), bfhi(graw[1])};
;     float y[4];
; #pragma unroll
;     for (int j = 0; j < 4; ++j) y[j] = (o[et][j] - mu) * rstd * (gv[j] / (1.0f + __expf(-gv[j])));
;     *reinterpret_cast<u32x2*>(mix + 16 * et) = u32x2{pk2(y[0], y[1]), pk2(y[2], y[3])};
;   }
	v_fma_f32 v36, -v36, v39, v38
	v_div_fmas_f32 v36, v36, v37, v39
	v_div_fixup_f32 v32, v36, v34, v32
	v_mul_f32_e32 v29, v32, v29
	v_mul_f32_e32 v32, 0xbfb8aa3b, v35
	v_exp_f32_e32 v32, v32
	v_cvt_pk_bf16_f32 v28,v28,v29
	s_nop 0
	v_add_f32_e32 v32, 1.0, v32
	v_div_scale_f32 v34, s[0:1], v32, v32, v35
	v_rcp_f32_e32 v36, v34
	s_nop 0
	v_fma_f32 v37, -v34, v36, 1.0
	v_fmac_f32_e32 v36, v37, v36
	v_div_scale_f32 v37, vcc, v35, v32, v35
	v_mul_f32_e32 v38, v37, v36
	v_fma_f32 v39, -v34, v38, v37
	v_fmac_f32_e32 v38, v39, v36
	v_fma_f32 v34, -v34, v38, v37
	v_div_fmas_f32 v34, v34, v36, v38
	v_div_fixup_f32 v32, v34, v32, v35
	v_mul_f32_e32 v30, v32, v30
	v_mul_f32_e32 v32, 0xbfb8aa3b, v33
	v_exp_f32_e32 v32, v32
	s_nop 0
	v_add_f32_e32 v32, 1.0, v32
	v_div_scale_f32 v34, s[0:1], v32, v32, v33
	v_rcp_f32_e32 v35, v34
	s_nop 0
	v_fma_f32 v36, -v34, v35, 1.0
	v_fmac_f32_e32 v35, v36, v35
	v_div_scale_f32 v36, vcc, v33, v32, v33
	v_mul_f32_e32 v37, v36, v35
	v_fma_f32 v38, -v34, v37, v36
	v_fmac_f32_e32 v37, v38, v35
	v_fma_f32 v34, -v34, v37, v36
	v_div_fmas_f32 v34, v34, v35, v37
	v_div_fixup_f32 v32, v34, v32, v33
	v_mul_f32_e32 v31, v32, v31
	v_cvt_pk_bf16_f32 v29,v30,v31
	flat_store_dwordx2 v[62:63], v[28:29] offset:224
	v_mov_b32_e32 v28, v114
	v_mov_b32_e32 v29, v115
	v_lshlrev_b32_e32 v30, 16, v28
	v_mul_f32_e32 v32, 0xbfb8aa3b, v30
	v_exp_f32_e32 v32, v32
	v_and_b32_e32 v28, 0xffff0000, v28
	v_lshlrev_b32_e32 v31, 16, v29
	v_and_b32_e32 v29, 0xffff0000, v29
	v_add_f32_e32 v32, 1.0, v32
	v_div_scale_f32 v33, s[0:1], v32, v32, v30
	v_rcp_f32_e32 v34, v33
	s_nop 0
	v_fma_f32 v35, -v33, v34, 1.0
	v_fmac_f32_e32 v34, v35, v34
	v_div_scale_f32 v35, vcc, v30, v32, v30
	v_mul_f32_e32 v36, v35, v34
	v_fma_f32 v37, -v33, v36, v35
	v_fmac_f32_e32 v36, v37, v34
	v_fma_f32 v33, -v33, v36, v35
	v_div_fmas_f32 v33, v33, v34, v36
	v_div_fixup_f32 v30, v33, v32, v30
	v_mul_f32_e32 v24, v30, v24
	v_mul_f32_e32 v30, 0xbfb8aa3b, v28
	v_exp_f32_e32 v30, v30
	s_nop 0
	v_add_f32_e32 v30, 1.0, v30
	v_div_scale_f32 v32, s[0:1], v30, v30, v28
	v_rcp_f32_e32 v33, v32
	s_nop 0
	v_fma_f32 v34, -v32, v33, 1.0
	v_fmac_f32_e32 v33, v34, v33
	v_div_scale_f32 v34, vcc, v28, v30, v28
	v_mul_f32_e32 v35, v34, v33
	v_fma_f32 v36, -v32, v35, v34
	v_fmac_f32_e32 v35, v36, v33
	v_fma_f32 v32, -v32, v35, v34
	v_div_fmas_f32 v32, v32, v33, v35
	v_div_fixup_f32 v28, v32, v30, v28
	v_mul_f32_e32 v25, v28, v25
	v_mul_f32_e32 v28, 0xbfb8aa3b, v31
	v_exp_f32_e32 v28, v28
	v_cvt_pk_bf16_f32 v24,v24,v25
	s_nop 0
	v_add_f32_e32 v28, 1.0, v28
	v_div_scale_f32 v30, s[0:1], v28, v28, v31
	v_rcp_f32_e32 v32, v30
	s_nop 0
	v_fma_f32 v33, -v30, v32, 1.0
	v_fmac_f32_e32 v32, v33, v32
	v_div_scale_f32 v33, vcc, v31, v28, v31
	v_mul_f32_e32 v34, v33, v32
	v_fma_f32 v35, -v30, v34, v33
	v_fmac_f32_e32 v34, v35, v32
	v_fma_f32 v30, -v30, v34, v33
	v_div_fmas_f32 v30, v30, v32, v34
	v_div_fixup_f32 v28, v30, v28, v31
	v_mul_f32_e32 v26, v28, v26
	v_mul_f32_e32 v28, 0xbfb8aa3b, v29
	v_exp_f32_e32 v28, v28
	s_nop 0
	v_add_f32_e32 v28, 1.0, v28
	v_div_scale_f32 v30, s[0:1], v28, v28, v29
	v_rcp_f32_e32 v31, v30
	s_nop 0
	v_fma_f32 v32, -v30, v31, 1.0
	v_fmac_f32_e32 v31, v32, v31
	v_div_scale_f32 v32, vcc, v29, v28, v29
	v_mul_f32_e32 v33, v32, v31
	v_fma_f32 v34, -v30, v33, v32
	v_fmac_f32_e32 v33, v34, v31
	v_fma_f32 v30, -v30, v33, v32
	v_div_fmas_f32 v30, v30, v31, v33
	v_div_fixup_f32 v28, v30, v28, v29
	v_mul_f32_e32 v27, v28, v27
	v_cvt_pk_bf16_f32 v25,v26,v27
	flat_store_dwordx2 v[62:63], v[24:25] offset:256
	v_mov_b32_e32 v24, v116
	v_mov_b32_e32 v25, v117
	v_lshlrev_b32_e32 v26, 16, v24
	v_mul_f32_e32 v28, 0xbfb8aa3b, v26
	v_exp_f32_e32 v28, v28
	v_and_b32_e32 v24, 0xffff0000, v24
	v_lshlrev_b32_e32 v27, 16, v25
	v_and_b32_e32 v25, 0xffff0000, v25
	v_add_f32_e32 v28, 1.0, v28
	v_div_scale_f32 v29, s[0:1], v28, v28, v26
	v_rcp_f32_e32 v30, v29
	s_nop 0
	v_fma_f32 v31, -v29, v30, 1.0
	v_fmac_f32_e32 v30, v31, v30
	v_div_scale_f32 v31, vcc, v26, v28, v26
	v_mul_f32_e32 v32, v31, v30
	v_fma_f32 v33, -v29, v32, v31
	v_fmac_f32_e32 v32, v33, v30
	v_fma_f32 v29, -v29, v32, v31
	v_div_fmas_f32 v29, v29, v30, v32
	v_div_fixup_f32 v26, v29, v28, v26
	v_mul_f32_e32 v20, v26, v20
	v_mul_f32_e32 v26, 0xbfb8aa3b, v24
	v_exp_f32_e32 v26, v26
	s_nop 0
	v_add_f32_e32 v26, 1.0, v26
	v_div_scale_f32 v28, s[0:1], v26, v26, v24
	v_rcp_f32_e32 v29, v28
	s_nop 0
	v_fma_f32 v30, -v28, v29, 1.0
	v_fmac_f32_e32 v29, v30, v29
	v_div_scale_f32 v30, vcc, v24, v26, v24
	v_mul_f32_e32 v31, v30, v29
	v_fma_f32 v32, -v28, v31, v30
	v_fmac_f32_e32 v31, v32, v29
	v_fma_f32 v28, -v28, v31, v30
	v_div_fmas_f32 v28, v28, v29, v31
	v_div_fixup_f32 v24, v28, v26, v24
	v_mul_f32_e32 v21, v24, v21
	v_mul_f32_e32 v24, 0xbfb8aa3b, v27
	v_exp_f32_e32 v24, v24
	v_cvt_pk_bf16_f32 v20,v20,v21
	s_nop 0
	v_add_f32_e32 v24, 1.0, v24
	v_div_scale_f32 v26, s[0:1], v24, v24, v27
	v_rcp_f32_e32 v28, v26
	s_nop 0
	v_fma_f32 v29, -v26, v28, 1.0
	v_fmac_f32_e32 v28, v29, v28
	v_div_scale_f32 v29, vcc, v27, v24, v27
	v_mul_f32_e32 v30, v29, v28
	v_fma_f32 v31, -v26, v30, v29
	v_fmac_f32_e32 v30, v31, v28
	v_fma_f32 v26, -v26, v30, v29
	v_div_fmas_f32 v26, v26, v28, v30
	v_div_fixup_f32 v24, v26, v24, v27
	v_mul_f32_e32 v22, v24, v22
	v_mul_f32_e32 v24, 0xbfb8aa3b, v25
	v_exp_f32_e32 v24, v24
	s_nop 0
	v_add_f32_e32 v24, 1.0, v24
	v_div_scale_f32 v26, s[0:1], v24, v24, v25
	v_rcp_f32_e32 v27, v26
	s_nop 0
	v_fma_f32 v28, -v26, v27, 1.0
	v_fmac_f32_e32 v27, v28, v27
	v_div_scale_f32 v28, vcc, v25, v24, v25
	v_mul_f32_e32 v29, v28, v27
	v_fma_f32 v30, -v26, v29, v28
	v_fmac_f32_e32 v29, v30, v27
	v_fma_f32 v26, -v26, v29, v28
	v_div_fmas_f32 v26, v26, v27, v29
; __device__ __forceinline__ float bflo(unsigned u) { return __uint_as_float(u << 16); }
; __device__ __forceinline__ float bfhi(unsigned u) { return __uint_as_float(u & 0xffff0000u); }
; __device__ __forceinline__ void retq_item(const Params& p, int item, char* lds, int tid) {
;     ...
; #pragma unroll
;   for (int et = 0; et < 16; ++et) {
;     u32x2 graw = *reinterpret_cast<const u32x2*>(grow + 16 * et);
;     float gv[4] = {bflo(graw[0]), bfhi(graw[0]), bflo(graw[1]), bfhi(graw[1])};
;     float y[4];
; #pragma unroll
;     for (int j = 0; j < 4; ++j) y[j] = (o[et][j] - mu) * rstd * (gv[j] / (1.0f + __expf(-gv[j])));
;     *reinterpret_cast<u32x2*>(mix + 16 * et) = u32x2{pk2(y[0], y[1]), pk2(y[2], y[3])};
;   }
	v_div_fixup_f32 v24, v26, v24, v25
	v_mul_f32_e32 v23, v24, v23
	v_cvt_pk_bf16_f32 v21,v22,v23
	flat_store_dwordx2 v[62:63], v[20:21] offset:288
	v_mov_b32_e32 v20, v118
	v_mov_b32_e32 v21, v119
	v_lshlrev_b32_e32 v22, 16, v20
	v_mul_f32_e32 v24, 0xbfb8aa3b, v22
	v_exp_f32_e32 v24, v24
	v_and_b32_e32 v20, 0xffff0000, v20
	v_lshlrev_b32_e32 v23, 16, v21
	v_and_b32_e32 v21, 0xffff0000, v21
	v_add_f32_e32 v24, 1.0, v24
	v_div_scale_f32 v25, s[0:1], v24, v24, v22
	v_rcp_f32_e32 v26, v25
	s_nop 0
	v_fma_f32 v27, -v25, v26, 1.0
	v_fmac_f32_e32 v26, v27, v26
	v_div_scale_f32 v27, vcc, v22, v24, v22
	v_mul_f32_e32 v28, v27, v26
	v_fma_f32 v29, -v25, v28, v27
	v_fmac_f32_e32 v28, v29, v26
	v_fma_f32 v25, -v25, v28, v27
	v_div_fmas_f32 v25, v25, v26, v28
	v_div_fixup_f32 v22, v25, v24, v22
	v_mul_f32_e32 v16, v22, v16
	v_mul_f32_e32 v22, 0xbfb8aa3b, v20
	v_exp_f32_e32 v22, v22
	s_nop 0
	v_add_f32_e32 v22, 1.0, v22
	v_div_scale_f32 v24, s[0:1], v22, v22, v20
	v_rcp_f32_e32 v25, v24
	s_nop 0
	v_fma_f32 v26, -v24, v25, 1.0
	v_fmac_f32_e32 v25, v26, v25
	v_div_scale_f32 v26, vcc, v20, v22, v20
	v_mul_f32_e32 v27, v26, v25
	v_fma_f32 v28, -v24, v27, v26
	v_fmac_f32_e32 v27, v28, v25
	v_fma_f32 v24, -v24, v27, v26
	v_div_fmas_f32 v24, v24, v25, v27
	v_div_fixup_f32 v20, v24, v22, v20
	v_mul_f32_e32 v17, v20, v17
	v_mul_f32_e32 v20, 0xbfb8aa3b, v23
	v_exp_f32_e32 v20, v20
	v_cvt_pk_bf16_f32 v16,v16,v17
	s_nop 0
	v_add_f32_e32 v20, 1.0, v20
	v_div_scale_f32 v22, s[0:1], v20, v20, v23
	v_rcp_f32_e32 v24, v22
	s_nop 0
	v_fma_f32 v25, -v22, v24, 1.0
	v_fmac_f32_e32 v24, v25, v24
	v_div_scale_f32 v25, vcc, v23, v20, v23
	v_mul_f32_e32 v26, v25, v24
	v_fma_f32 v27, -v22, v26, v25
	v_fmac_f32_e32 v26, v27, v24
	v_fma_f32 v22, -v22, v26, v25
	v_div_fmas_f32 v22, v22, v24, v26
	v_div_fixup_f32 v20, v22, v20, v23
	v_mul_f32_e32 v18, v20, v18
	v_mul_f32_e32 v20, 0xbfb8aa3b, v21
	v_exp_f32_e32 v20, v20
	s_nop 0
	v_add_f32_e32 v20, 1.0, v20
	v_div_scale_f32 v22, s[0:1], v20, v20, v21
	v_rcp_f32_e32 v23, v22
	s_nop 0
	v_fma_f32 v24, -v22, v23, 1.0
	v_fmac_f32_e32 v23, v24, v23
	v_div_scale_f32 v24, vcc, v21, v20, v21
	v_mul_f32_e32 v25, v24, v23
	v_fma_f32 v26, -v22, v25, v24
	v_fmac_f32_e32 v25, v26, v23
	v_fma_f32 v22, -v22, v25, v24
	v_div_fmas_f32 v22, v22, v23, v25
	v_div_fixup_f32 v20, v22, v20, v21
	v_mul_f32_e32 v19, v20, v19
	v_cvt_pk_bf16_f32 v17,v18,v19
	flat_store_dwordx2 v[62:63], v[16:17] offset:320
	v_mov_b32_e32 v16, v120
	v_mov_b32_e32 v17, v121
	v_lshlrev_b32_e32 v18, 16, v16
	v_mul_f32_e32 v20, 0xbfb8aa3b, v18
	v_exp_f32_e32 v20, v20
	v_and_b32_e32 v16, 0xffff0000, v16
	v_lshlrev_b32_e32 v19, 16, v17
	v_and_b32_e32 v17, 0xffff0000, v17
	v_add_f32_e32 v20, 1.0, v20
	v_div_scale_f32 v21, s[0:1], v20, v20, v18
	v_rcp_f32_e32 v22, v21
	s_nop 0
	v_fma_f32 v23, -v21, v22, 1.0
	v_fmac_f32_e32 v22, v23, v22
	v_div_scale_f32 v23, vcc, v18, v20, v18
	v_mul_f32_e32 v24, v23, v22
	v_fma_f32 v25, -v21, v24, v23
	v_fmac_f32_e32 v24, v25, v22
	v_fma_f32 v21, -v21, v24, v23
	v_div_fmas_f32 v21, v21, v22, v24
	v_div_fixup_f32 v18, v21, v20, v18
	v_mul_f32_e32 v12, v18, v12
	v_mul_f32_e32 v18, 0xbfb8aa3b, v16
	v_exp_f32_e32 v18, v18
	s_nop 0
	v_add_f32_e32 v18, 1.0, v18
	v_div_scale_f32 v20, s[0:1], v18, v18, v16
	v_rcp_f32_e32 v21, v20
	s_nop 0
	v_fma_f32 v22, -v20, v21, 1.0
	v_fmac_f32_e32 v21, v22, v21
	v_div_scale_f32 v22, vcc, v16, v18, v16
	v_mul_f32_e32 v23, v22, v21
	v_fma_f32 v24, -v20, v23, v22
	v_fmac_f32_e32 v23, v24, v21
	v_fma_f32 v20, -v20, v23, v22
	v_div_fmas_f32 v20, v20, v21, v23
	v_div_fixup_f32 v16, v20, v18, v16
	v_mul_f32_e32 v13, v16, v13
	v_mul_f32_e32 v16, 0xbfb8aa3b, v19
	v_exp_f32_e32 v16, v16
	v_cvt_pk_bf16_f32 v12,v12,v13
	s_nop 0
	v_add_f32_e32 v16, 1.0, v16
	v_div_scale_f32 v18, s[0:1], v16, v16, v19
	v_rcp_f32_e32 v20, v18
	s_nop 0
	v_fma_f32 v21, -v18, v20, 1.0
	v_fmac_f32_e32 v20, v21, v20
	v_div_scale_f32 v21, vcc, v19, v16, v19
	v_mul_f32_e32 v22, v21, v20
	v_fma_f32 v23, -v18, v22, v21
	v_fmac_f32_e32 v22, v23, v20
	v_fma_f32 v18, -v18, v22, v21
	v_div_fmas_f32 v18, v18, v20, v22
	v_div_fixup_f32 v16, v18, v16, v19
	v_mul_f32_e32 v14, v16, v14
	v_mul_f32_e32 v16, 0xbfb8aa3b, v17
	v_exp_f32_e32 v16, v16
	s_nop 0
	v_add_f32_e32 v16, 1.0, v16
	v_div_scale_f32 v18, s[0:1], v16, v16, v17
	v_rcp_f32_e32 v19, v18
	s_nop 0
	v_fma_f32 v20, -v18, v19, 1.0
	v_fmac_f32_e32 v19, v20, v19
	v_div_scale_f32 v20, vcc, v17, v16, v17
	v_mul_f32_e32 v21, v20, v19
	v_fma_f32 v22, -v18, v21, v20
	v_fmac_f32_e32 v21, v22, v19
	v_fma_f32 v18, -v18, v21, v20
	v_div_fmas_f32 v18, v18, v19, v21
	v_div_fixup_f32 v16, v18, v16, v17
	v_mul_f32_e32 v15, v16, v15
	v_cvt_pk_bf16_f32 v13,v14,v15
	flat_store_dwordx2 v[62:63], v[12:13] offset:352
	v_mov_b32_e32 v12, v122
	v_mov_b32_e32 v13, v123
	v_lshlrev_b32_e32 v14, 16, v12
	v_mul_f32_e32 v16, 0xbfb8aa3b, v14
	v_exp_f32_e32 v16, v16
	v_and_b32_e32 v12, 0xffff0000, v12
	v_lshlrev_b32_e32 v15, 16, v13
	v_and_b32_e32 v13, 0xffff0000, v13
	v_add_f32_e32 v16, 1.0, v16
	v_div_scale_f32 v17, s[0:1], v16, v16, v14
	v_rcp_f32_e32 v18, v17
	s_nop 0
	v_fma_f32 v19, -v17, v18, 1.0
	v_fmac_f32_e32 v18, v19, v18
	v_div_scale_f32 v19, vcc, v14, v16, v14
	v_mul_f32_e32 v20, v19, v18
	v_fma_f32 v21, -v17, v20, v19
	v_fmac_f32_e32 v20, v21, v18
	v_fma_f32 v17, -v17, v20, v19
	v_div_fmas_f32 v17, v17, v18, v20
	v_div_fixup_f32 v14, v17, v16, v14
	v_mul_f32_e32 v8, v14, v8
	v_mul_f32_e32 v14, 0xbfb8aa3b, v12
	v_exp_f32_e32 v14, v14
	s_nop 0
	v_add_f32_e32 v14, 1.0, v14
	v_div_scale_f32 v16, s[0:1], v14, v14, v12
	v_rcp_f32_e32 v17, v16
	s_nop 0
	v_fma_f32 v18, -v16, v17, 1.0
	v_fmac_f32_e32 v17, v18, v17
	v_div_scale_f32 v18, vcc, v12, v14, v12
; __device__ __forceinline__ float bflo(unsigned u) { return __uint_as_float(u << 16); }
; __device__ __forceinline__ float bfhi(unsigned u) { return __uint_as_float(u & 0xffff0000u); }
; __device__ __forceinline__ void retq_item(const Params& p, int item, char* lds, int tid) {
;     ...
; #pragma unroll
;   for (int et = 0; et < 16; ++et) {
;     u32x2 graw = *reinterpret_cast<const u32x2*>(grow + 16 * et);
;     float gv[4] = {bflo(graw[0]), bfhi(graw[0]), bflo(graw[1]), bfhi(graw[1])};
;     float y[4];
; #pragma unroll
;     for (int j = 0; j < 4; ++j) y[j] = (o[et][j] - mu) * rstd * (gv[j] / (1.0f + __expf(-gv[j])));
;     *reinterpret_cast<u32x2*>(mix + 16 * et) = u32x2{pk2(y[0], y[1]), pk2(y[2], y[3])};
;   }
	v_mul_f32_e32 v19, v18, v17
	v_fma_f32 v20, -v16, v19, v18
	v_fmac_f32_e32 v19, v20, v17
	v_fma_f32 v16, -v16, v19, v18
	v_div_fmas_f32 v16, v16, v17, v19
	v_div_fixup_f32 v12, v16, v14, v12
	v_mul_f32_e32 v9, v12, v9
	v_mul_f32_e32 v12, 0xbfb8aa3b, v15
	v_exp_f32_e32 v12, v12
	v_cvt_pk_bf16_f32 v8,v8,v9
	s_nop 0
	v_add_f32_e32 v12, 1.0, v12
	v_div_scale_f32 v14, s[0:1], v12, v12, v15
	v_rcp_f32_e32 v16, v14
	s_nop 0
	v_fma_f32 v17, -v14, v16, 1.0
	v_fmac_f32_e32 v16, v17, v16
	v_div_scale_f32 v17, vcc, v15, v12, v15
	v_mul_f32_e32 v18, v17, v16
	v_fma_f32 v19, -v14, v18, v17
	v_fmac_f32_e32 v18, v19, v16
	v_fma_f32 v14, -v14, v18, v17
	v_div_fmas_f32 v14, v14, v16, v18
	v_div_fixup_f32 v12, v14, v12, v15
	v_mul_f32_e32 v10, v12, v10
	v_mul_f32_e32 v12, 0xbfb8aa3b, v13
	v_exp_f32_e32 v12, v12
	s_nop 0
	v_add_f32_e32 v12, 1.0, v12
	v_div_scale_f32 v14, s[0:1], v12, v12, v13
	v_rcp_f32_e32 v15, v14
	s_nop 0
	v_fma_f32 v16, -v14, v15, 1.0
	v_fmac_f32_e32 v15, v16, v15
	v_div_scale_f32 v16, vcc, v13, v12, v13
	v_mul_f32_e32 v17, v16, v15
	v_fma_f32 v18, -v14, v17, v16
	v_fmac_f32_e32 v17, v18, v15
	v_fma_f32 v14, -v14, v17, v16
	v_div_fmas_f32 v14, v14, v15, v17
	v_div_fixup_f32 v12, v14, v12, v13
	v_mul_f32_e32 v11, v12, v11
	v_cvt_pk_bf16_f32 v9,v10,v11
	flat_store_dwordx2 v[62:63], v[8:9] offset:384
	v_mov_b32_e32 v8, v124
	v_mov_b32_e32 v9, v125
	v_lshlrev_b32_e32 v10, 16, v8
	v_mul_f32_e32 v12, 0xbfb8aa3b, v10
	v_exp_f32_e32 v12, v12
	v_and_b32_e32 v8, 0xffff0000, v8
	v_lshlrev_b32_e32 v11, 16, v9
	v_and_b32_e32 v9, 0xffff0000, v9
	v_add_f32_e32 v12, 1.0, v12
	v_div_scale_f32 v13, s[0:1], v12, v12, v10
	v_rcp_f32_e32 v14, v13
	s_nop 0
	v_fma_f32 v15, -v13, v14, 1.0
	v_fmac_f32_e32 v14, v15, v14
	v_div_scale_f32 v15, vcc, v10, v12, v10
	v_mul_f32_e32 v16, v15, v14
	v_fma_f32 v17, -v13, v16, v15
	v_fmac_f32_e32 v16, v17, v14
	v_fma_f32 v13, -v13, v16, v15
	v_div_fmas_f32 v13, v13, v14, v16
	v_div_fixup_f32 v10, v13, v12, v10
	v_mul_f32_e32 v4, v10, v4
	v_mul_f32_e32 v10, 0xbfb8aa3b, v8
	v_exp_f32_e32 v10, v10
	s_nop 0
	v_add_f32_e32 v10, 1.0, v10
	v_div_scale_f32 v12, s[0:1], v10, v10, v8
	v_rcp_f32_e32 v13, v12
	s_nop 0
	v_fma_f32 v14, -v12, v13, 1.0
	v_fmac_f32_e32 v13, v14, v13
	v_div_scale_f32 v14, vcc, v8, v10, v8
	v_mul_f32_e32 v15, v14, v13
	v_fma_f32 v16, -v12, v15, v14
	v_fmac_f32_e32 v15, v16, v13
	v_fma_f32 v12, -v12, v15, v14
	v_div_fmas_f32 v12, v12, v13, v15
	v_div_fixup_f32 v8, v12, v10, v8
	v_mul_f32_e32 v5, v8, v5
	v_mul_f32_e32 v8, 0xbfb8aa3b, v11
	v_exp_f32_e32 v8, v8
	v_cvt_pk_bf16_f32 v4,v4,v5
	s_nop 0
	v_add_f32_e32 v8, 1.0, v8
	v_div_scale_f32 v10, s[0:1], v8, v8, v11
	v_rcp_f32_e32 v12, v10
	s_nop 0
	v_fma_f32 v13, -v10, v12, 1.0
	v_fmac_f32_e32 v12, v13, v12
	v_div_scale_f32 v13, vcc, v11, v8, v11
	v_mul_f32_e32 v14, v13, v12
	v_fma_f32 v15, -v10, v14, v13
	v_fmac_f32_e32 v14, v15, v12
	v_fma_f32 v10, -v10, v14, v13
	v_div_fmas_f32 v10, v10, v12, v14
	v_div_fixup_f32 v8, v10, v8, v11
	v_mul_f32_e32 v6, v8, v6
	v_mul_f32_e32 v8, 0xbfb8aa3b, v9
	v_exp_f32_e32 v8, v8
	s_nop 0
	v_add_f32_e32 v8, 1.0, v8
	v_div_scale_f32 v10, s[0:1], v8, v8, v9
	v_rcp_f32_e32 v11, v10
	s_nop 0
	v_fma_f32 v12, -v10, v11, 1.0
	v_fmac_f32_e32 v11, v12, v11
	v_div_scale_f32 v12, vcc, v9, v8, v9
	v_mul_f32_e32 v13, v12, v11
	v_fma_f32 v14, -v10, v13, v12
	v_fmac_f32_e32 v13, v14, v11
	v_fma_f32 v10, -v10, v13, v12
	v_div_fmas_f32 v10, v10, v11, v13
	v_div_fixup_f32 v8, v10, v8, v9
	v_mul_f32_e32 v7, v8, v7
	v_cvt_pk_bf16_f32 v5,v6,v7
	flat_store_dwordx2 v[62:63], v[4:5] offset:416
	v_mov_b32_e32 v4, v126
	v_mov_b32_e32 v5, v127
	v_mul_f32_e32 v8, v68, v0
	v_lshlrev_b32_e32 v6, 16, v4
	v_mul_f32_e32 v9, 0xbfb8aa3b, v6
	v_exp_f32_e32 v9, v9
	v_and_b32_e32 v4, 0xffff0000, v4
	v_lshlrev_b32_e32 v7, 16, v5
	v_and_b32_e32 v5, 0xffff0000, v5
	v_add_f32_e32 v9, 1.0, v9
	v_div_scale_f32 v10, s[0:1], v9, v9, v6
	v_rcp_f32_e32 v11, v10
	s_nop 0
	v_fma_f32 v12, -v10, v11, 1.0
	v_fmac_f32_e32 v11, v12, v11
	v_div_scale_f32 v12, vcc, v6, v9, v6
	v_mul_f32_e32 v13, v12, v11
; __device__ __forceinline__ float bflo(unsigned u) { return __uint_as_float(u << 16); }
; __device__ __forceinline__ float bfhi(unsigned u) { return __uint_as_float(u & 0xffff0000u); }
; __device__ __forceinline__ void retq_item(const Params& p, int item, char* lds, int tid) {
;     ...
; #pragma unroll
;   for (int et = 0; et < 16; ++et) {
;     u32x2 graw = *reinterpret_cast<const u32x2*>(grow + 16 * et);
;     float gv[4] = {bflo(graw[0]), bfhi(graw[0]), bflo(graw[1]), bfhi(graw[1])};
;     float y[4];
; #pragma unroll
;     for (int j = 0; j < 4; ++j) y[j] = (o[et][j] - mu) * rstd * (gv[j] / (1.0f + __expf(-gv[j])));
;     *reinterpret_cast<u32x2*>(mix + 16 * et) = u32x2{pk2(y[0], y[1]), pk2(y[2], y[3])};
;   }
	v_fma_f32 v14, -v10, v13, v12
	v_fmac_f32_e32 v13, v14, v11
	v_fma_f32 v10, -v10, v13, v12
	v_div_fmas_f32 v10, v10, v11, v13
	v_div_fixup_f32 v6, v10, v9, v6
	v_mul_f32_e32 v9, 0xbfb8aa3b, v4
	v_exp_f32_e32 v9, v9
	v_mul_f32_e32 v6, v6, v8
	v_mul_f32_e32 v8, v69, v0
	v_add_f32_e32 v9, 1.0, v9
	v_div_scale_f32 v10, s[0:1], v9, v9, v4
	v_rcp_f32_e32 v11, v10
	s_nop 0
	v_fma_f32 v12, -v10, v11, 1.0
	v_fmac_f32_e32 v11, v12, v11
	v_div_scale_f32 v12, vcc, v4, v9, v4
	v_mul_f32_e32 v13, v12, v11
	v_fma_f32 v14, -v10, v13, v12
	v_fmac_f32_e32 v13, v14, v11
	v_fma_f32 v10, -v10, v13, v12
	v_div_fmas_f32 v10, v10, v11, v13
	v_div_fixup_f32 v4, v10, v9, v4
	v_mul_f32_e32 v9, 0xbfb8aa3b, v7
	v_exp_f32_e32 v9, v9
	v_mul_f32_e32 v4, v4, v8
	v_mul_f32_e32 v8, v66, v0
	v_cvt_pk_bf16_f32 v4,v6,v4
	v_add_f32_e32 v9, 1.0, v9
	v_div_scale_f32 v10, s[0:1], v9, v9, v7
	v_rcp_f32_e32 v11, v10
	s_nop 0
	v_fma_f32 v12, -v10, v11, 1.0
	v_fmac_f32_e32 v11, v12, v11
	v_div_scale_f32 v12, vcc, v7, v9, v7
	v_mul_f32_e32 v13, v12, v11
	v_fma_f32 v14, -v10, v13, v12
	v_fmac_f32_e32 v13, v14, v11
	v_fma_f32 v10, -v10, v13, v12
	v_div_fmas_f32 v10, v10, v11, v13
	v_div_fixup_f32 v7, v10, v9, v7
	v_mul_f32_e32 v9, 0xbfb8aa3b, v5
	v_exp_f32_e32 v9, v9
	v_mul_f32_e32 v7, v7, v8
	v_mul_f32_e32 v8, v67, v0
	v_add_f32_e32 v9, 1.0, v9
	v_div_scale_f32 v10, s[0:1], v9, v9, v5
	v_rcp_f32_e32 v11, v10
	s_nop 0
	v_fma_f32 v12, -v10, v11, 1.0
	v_fmac_f32_e32 v11, v12, v11
	v_div_scale_f32 v12, vcc, v5, v9, v5
	v_mul_f32_e32 v13, v12, v11
	v_fma_f32 v14, -v10, v13, v12
	v_fmac_f32_e32 v13, v14, v11
	v_fma_f32 v10, -v10, v13, v12
	v_div_fmas_f32 v10, v10, v11, v13
	v_div_fixup_f32 v5, v10, v9, v5
	v_mul_f32_e32 v5, v5, v8
	v_cvt_pk_bf16_f32 v5,v7,v5
	flat_store_dwordx2 v[62:63], v[4:5] offset:448
	v_mov_b32_e32 v4, v128
	v_mov_b32_e32 v5, v129
	v_mul_f32_e32 v8, v60, v0
	v_lshlrev_b32_e32 v6, 16, v4
	v_mul_f32_e32 v9, 0xbfb8aa3b, v6
	v_exp_f32_e32 v9, v9
	v_and_b32_e32 v4, 0xffff0000, v4
	v_lshlrev_b32_e32 v7, 16, v5
	v_and_b32_e32 v5, 0xffff0000, v5
	v_add_f32_e32 v9, 1.0, v9
	v_div_scale_f32 v10, s[0:1], v9, v9, v6
	v_rcp_f32_e32 v11, v10
	s_nop 0
	v_fma_f32 v12, -v10, v11, 1.0
	v_fmac_f32_e32 v11, v12, v11
	v_div_scale_f32 v12, vcc, v6, v9, v6
	v_mul_f32_e32 v13, v12, v11
	v_fma_f32 v14, -v10, v13, v12
	v_fmac_f32_e32 v13, v14, v11
	v_fma_f32 v10, -v10, v13, v12
	v_div_fmas_f32 v10, v10, v11, v13
	v_div_fixup_f32 v6, v10, v9, v6
	v_mul_f32_e32 v9, 0xbfb8aa3b, v4
	v_exp_f32_e32 v9, v9
	v_mul_f32_e32 v6, v6, v8
	v_mul_f32_e32 v8, v61, v0
	v_mul_f32_e32 v0, v3, v0
	v_add_f32_e32 v9, 1.0, v9
	v_div_scale_f32 v10, s[0:1], v9, v9, v4
	v_rcp_f32_e32 v11, v10
	s_nop 0
	v_fma_f32 v12, -v10, v11, 1.0
	v_fmac_f32_e32 v11, v12, v11
	v_div_scale_f32 v12, vcc, v4, v9, v4
	v_mul_f32_e32 v13, v12, v11
	v_fma_f32 v14, -v10, v13, v12
	v_fmac_f32_e32 v13, v14, v11
	v_fma_f32 v10, -v10, v13, v12
	v_div_fmas_f32 v10, v10, v11, v13
	v_div_fixup_f32 v4, v10, v9, v4
	v_mul_f32_e32 v4, v4, v8
	v_mul_f32_e32 v8, 0xbfb8aa3b, v7
	v_exp_f32_e32 v8, v8
	s_nop 0
	v_add_f32_e32 v8, 1.0, v8
	v_div_scale_f32 v9, s[0:1], v8, v8, v7
	v_rcp_f32_e32 v10, v9
	s_nop 0
	v_fma_f32 v11, -v9, v10, 1.0
	v_fmac_f32_e32 v10, v11, v10
	v_div_scale_f32 v11, vcc, v7, v8, v7
	v_mul_f32_e32 v12, v11, v10
	v_fma_f32 v13, -v9, v12, v11
	v_fmac_f32_e32 v12, v13, v10
	v_fma_f32 v9, -v9, v12, v11
	v_div_fmas_f32 v9, v9, v10, v12
	v_div_fixup_f32 v7, v9, v8, v7
	v_mul_f32_e32 v7, v7, v2
	v_mul_f32_e32 v2, 0xbfb8aa3b, v5
	v_exp_f32_e32 v2, v2
	s_nop 0
	v_add_f32_e32 v2, 1.0, v2
	v_div_scale_f32 v3, s[0:1], v2, v2, v5
	v_rcp_f32_e32 v8, v3
	s_mov_b64 s[0:1], 0
	v_fma_f32 v9, -v3, v8, 1.0
	v_fmac_f32_e32 v8, v9, v8
	v_div_scale_f32 v9, vcc, v5, v2, v5
	v_mul_f32_e32 v10, v9, v8
	v_fma_f32 v11, -v3, v10, v9
	v_fmac_f32_e32 v10, v11, v8
	v_fma_f32 v3, -v3, v10, v9
	v_div_fmas_f32 v3, v3, v8, v10
	v_div_fixup_f32 v2, v3, v2, v5
	v_mul_f32_e32 v0, v2, v0
	v_cvt_pk_bf16_f32 v2,v6,v4
	v_cvt_pk_bf16_f32 v3,v7,v0
	flat_store_dwordx2 v[62:63], v[2:3] offset:480

; __device__ __forceinline__ void tr_store(const TDesc& d, int tid, const f32x4 (&v)[4], u16* lds) {
;     ...
;   const int nn = tid >> 2, ks = tid & 3;
;   const u32x2* s = reinterpret_cast<const u32x2*>(lds + nn * 68 + ks * 16);
;   u32x2 a = s[0], b = s[1], c = s[2], e2 = s[3];
;   u32x4* o = reinterpret_cast<u32x4*>(d.dst + (long)(d.n0 + nn) * d.K + d.k0 + ks * 16);
;   if (d.nt) {
;     __builtin_nontemporal_store(u32x4{a[0], a[1], b[0], b[1]}, o);
;     __builtin_nontemporal_store(u32x4{c[0], c[1], e2[0], e2[1]}, o + 1);
;   } else {
;     o[0] = u32x4{a[0], a[1], b[0], b[1]};
;     o[1] = u32x4{c[0], c[1], e2[0], e2[1]};
;   }
; }
; __device__ __forceinline__ void phase_convert(const Params& p, u16* lds) {
;     ...
;       tr_store(d0, tid, v0, lds + buf * (128 * 68));
;       buf ^= 1;
;       d0 = d1;
; #pragma unroll
;       for (int r = 0; r < 4; ++r) v0[r] = v1[r];
.LBB0_319:
	s_or_b64 exec, exec, s[2:3]
	s_mul_i32 s2, s39, 0x4400
	s_add_i32 s2, s2, 64
	v_lshlrev_b32_e32 v45, 1, v38
	s_waitcnt vmcnt(0)
	v_cvt_pk_bf16_f32 v36,v2,v6
	v_cvt_pk_bf16_f32 v37,v10,v14
	v_add3_u32 v6, s2, v45, v42
	v_cvt_pk_bf16_f32 v2,v3,v7
	v_cvt_pk_bf16_f32 v3,v11,v15
	v_add_u32_e32 v10, s37, v43
	ds_write2_b64 v6, v[36:37], v[2:3] offset1:17
	v_cvt_pk_bf16_f32 v2,v4,v8
	v_cvt_pk_bf16_f32 v3,v12,v16
	v_cvt_pk_bf16_f32 v4,v5,v9
	v_cvt_pk_bf16_f32 v5,v13,v17
	ds_write2_b64 v6, v[2:3], v[4:5] offset0:34 offset1:51
	v_add3_u32 v6, s2, v44, v0
	v_ashrrev_i32_e32 v13, 31, v10
	v_mad_u64_u32 v[10:11], s[2:3], s27, v10, 0
	v_mov_b32_e32 v12, v11
	s_waitcnt lgkmcnt(0)
	s_barrier
	ds_read2_b64 v[2:5], v6 offset1:1
	ds_read2_b64 v[6:9], v6 offset0:2 offset1:3
	v_mad_u64_u32 v[12:13], s[2:3], s27, v13, v[12:13]
	v_mov_b32_e32 v11, v12
	v_lshl_add_u64 v[10:11], v[10:11], 1, s[10:11]
	s_ashr_i32 s27, s26, 31
	v_lshl_add_u64 v[10:11], s[26:27], 1, v[10:11]
	s_xor_b64 s[0:1], s[34:35], -1
	v_lshl_add_u64 v[10:11], v[10:11], 0, v[0:1]
	s_waitcnt lgkmcnt(1)
	global_store_dwordx4 v[10:11], v[2:5], off
	s_waitcnt lgkmcnt(0)
	flat_store_dwordx4 v[10:11], v[6:9] offset:16
	s_xor_b32 s39, s39, 1
	s_add_i32 s38, s38, s94
	s_and_b64 vcc, exec, s[0:1]
	s_mov_b32 s37, s43
	s_mov_b32 s26, s44
	s_mov_b32 s27, s41
	s_mov_b64 s[10:11], s[28:29]
	v_mov_b32_e32 v2, v22
	v_mov_b32_e32 v3, v23
	v_mov_b32_e32 v4, v24
	v_mov_b32_e32 v5, v25
	v_mov_b32_e32 v6, v18
	v_mov_b32_e32 v7, v19
	v_mov_b32_e32 v8, v20
	v_mov_b32_e32 v9, v21
	v_mov_b32_e32 v10, v30
	v_mov_b32_e32 v11, v31
	v_mov_b32_e32 v12, v32
	v_mov_b32_e32 v13, v33
	v_mov_b32_e32 v14, v26
	v_mov_b32_e32 v15, v27
	v_mov_b32_e32 v16, v28
	v_mov_b32_e32 v17, v29
	s_cbranch_vccnz .LBB0_370

; __device__ __forceinline__ float bflo(unsigned u) { return __uint_as_float(u << 16); }
; __device__ __forceinline__ float bfhi(unsigned u) { return __uint_as_float(u & 0xffff0000u); }
; __device__ __forceinline__ void epilogue(const Params& p, int mode, const float* resid, int r, int c, f32x4 v) {
;     ...
;   } else if (mode == EPI_RESID_B) {
;     u32x2 xr = *reinterpret_cast<const u32x2*>(WSP(u16, WS_HB) + (long)c * D + r);
;     f32x4 o = {ALPHA * bflo(xr[0]) + v[0], ALPHA * bfhi(xr[0]) + v[1], ALPHA * bflo(xr[1]) + v[2], ALPHA * bfhi(xr[1]) + v[3]};
;     *reinterpret_cast<f32x4*>(WSP(float, WS_PRE) + (long)c * D + r) = o;
.LBB0_411:
	s_andn2_b64 vcc, exec, s[0:1]
	s_cbranch_vccnz .LBB0_416
	s_cmp_gt_i32 s90, 4
	s_mov_b64 s[0:1], -1
	s_cbranch_scc0 .LBB0_414
	v_ashrrev_i32_e32 v131, 31, v130
	v_lshlrev_b64 v[154:155], 13, v[130:131]
	v_lshl_add_u64 v[154:155], v[142:143], 0, v[154:155]
	global_load_dwordx2 v[156:157], v[154:155], off
	v_lshlrev_b64 v[158:159], 14, v[130:131]
	v_lshl_add_u64 v[158:159], v[140:141], 0, v[158:159]
	s_mov_b64 s[0:1], 0
	s_waitcnt vmcnt(0) lgkmcnt(0)
	v_lshlrev_b32_e32 v154, 16, v156
	v_and_b32_e32 v155, 0xffff0000, v156
	v_lshlrev_b32_e32 v156, 16, v157
	v_and_b32_e32 v157, 0xffff0000, v157
	v_pk_fma_f32 v[154:155], v[154:155], s[76:77], v[126:127] op_sel_hi:[1,0,1]
	v_pk_fma_f32 v[156:157], v[156:157], s[76:77], v[128:129] op_sel_hi:[1,0,1]
	flat_store_dwordx4 v[158:159], v[154:157]

; __device__ __forceinline__ float bflo(unsigned u) { return __uint_as_float(u << 16); }
; __device__ __forceinline__ float bfhi(unsigned u) { return __uint_as_float(u & 0xffff0000u); }
; __device__ __forceinline__ void epilogue(const Params& p, int mode, const float* resid, int r, int c, f32x4 v) {
;     ...
;   } else if (mode == EPI_RESID_B) {
;     u32x2 xr = *reinterpret_cast<const u32x2*>(WSP(u16, WS_HB) + (long)c * D + r);
;     f32x4 o = {ALPHA * bflo(xr[0]) + v[0], ALPHA * bfhi(xr[0]) + v[1], ALPHA * bflo(xr[1]) + v[2], ALPHA * bfhi(xr[1]) + v[3]};
;     *reinterpret_cast<f32x4*>(WSP(float, WS_PRE) + (long)c * D + r) = o;
.LBB0_438:
	s_andn2_b64 vcc, exec, s[0:1]
	s_cbranch_vccnz .LBB0_443
	s_cmp_gt_i32 s90, 4
	s_mov_b64 s[0:1], -1
	s_cbranch_scc0 .LBB0_441
	v_ashrrev_i32_e32 v127, 31, v126
	v_lshlrev_b64 v[128:129], 13, v[126:127]
	v_lshl_add_u64 v[128:129], v[142:143], 0, v[128:129]
	global_load_dwordx2 v[128:129], v[128:129], off
	s_mov_b64 s[0:1], 0
	s_waitcnt vmcnt(0) lgkmcnt(0)
	v_lshlrev_b32_e32 v154, 16, v128
	v_and_b32_e32 v155, 0xffff0000, v128
	v_lshlrev_b32_e32 v128, 16, v129
	v_and_b32_e32 v129, 0xffff0000, v129
	v_pk_fma_f32 v[160:161], v[128:129], s[76:77], v[124:125] op_sel_hi:[1,0,1]
	v_lshlrev_b64 v[128:129], 14, v[126:127]
	v_pk_fma_f32 v[158:159], v[154:155], s[76:77], v[122:123] op_sel_hi:[1,0,1]
	v_lshl_add_u64 v[128:129], v[140:141], 0, v[128:129]
	flat_store_dwordx4 v[128:129], v[158:161]

; __device__ __forceinline__ float bflo(unsigned u) { return __uint_as_float(u << 16); }
; __device__ __forceinline__ float bfhi(unsigned u) { return __uint_as_float(u & 0xffff0000u); }
; __device__ __forceinline__ void epilogue(const Params& p, int mode, const float* resid, int r, int c, f32x4 v) {
;     ...
;   } else if (mode == EPI_RESID_B) {
;     u32x2 xr = *reinterpret_cast<const u32x2*>(WSP(u16, WS_HB) + (long)c * D + r);
;     f32x4 o = {ALPHA * bflo(xr[0]) + v[0], ALPHA * bfhi(xr[0]) + v[1], ALPHA * bflo(xr[1]) + v[2], ALPHA * bfhi(xr[1]) + v[3]};
;     *reinterpret_cast<f32x4*>(WSP(float, WS_PRE) + (long)c * D + r) = o;
.LBB0_465:
	s_andn2_b64 vcc, exec, s[0:1]
	s_cbranch_vccnz .LBB0_470
	s_cmp_gt_i32 s90, 4
	s_mov_b64 s[0:1], -1
	s_cbranch_scc0 .LBB0_468
	v_ashrrev_i32_e32 v131, 31, v130
	v_lshlrev_b64 v[160:161], 13, v[130:131]
	v_lshl_add_u64 v[160:161], s[40:41], 0, v[160:161]
	v_lshl_add_u64 v[160:161], v[122:123], 1, v[160:161]
	global_load_dwordx2 v[162:163], v[160:161], off
	v_lshlrev_b64 v[196:197], 14, v[130:131]
	v_lshl_add_u64 v[196:197], s[42:43], 0, v[196:197]
	v_lshl_add_u64 v[196:197], v[122:123], 2, v[196:197]
	s_mov_b64 s[0:1], 0
	s_waitcnt vmcnt(0) lgkmcnt(0)
	v_lshlrev_b32_e32 v160, 16, v162
	v_and_b32_e32 v161, 0xffff0000, v162
	v_lshlrev_b32_e32 v162, 16, v163
	v_and_b32_e32 v163, 0xffff0000, v163
	v_pk_fma_f32 v[160:161], v[160:161], s[76:77], v[118:119] op_sel_hi:[1,0,1]
	v_pk_fma_f32 v[162:163], v[162:163], s[76:77], v[120:121] op_sel_hi:[1,0,1]
	flat_store_dwordx4 v[196:197], v[160:163]

; __device__ __forceinline__ float bflo(unsigned u) { return __uint_as_float(u << 16); }
; __device__ __forceinline__ float bfhi(unsigned u) { return __uint_as_float(u & 0xffff0000u); }
; __device__ __forceinline__ void epilogue(const Params& p, int mode, const float* resid, int r, int c, f32x4 v) {
;     ...
;   } else if (mode == EPI_RESID_B) {
;     u32x2 xr = *reinterpret_cast<const u32x2*>(WSP(u16, WS_HB) + (long)c * D + r);
;     f32x4 o = {ALPHA * bflo(xr[0]) + v[0], ALPHA * bfhi(xr[0]) + v[1], ALPHA * bflo(xr[1]) + v[2], ALPHA * bfhi(xr[1]) + v[3]};
;     *reinterpret_cast<f32x4*>(WSP(float, WS_PRE) + (long)c * D + r) = o;
.LBB0_492:
	s_andn2_b64 vcc, exec, s[0:1]
	s_cbranch_vccnz .LBB0_497
	s_cmp_gt_i32 s90, 4
	s_mov_b64 s[0:1], -1
	s_cbranch_scc0 .LBB0_495
	v_ashrrev_i32_e32 v127, 31, v126
	v_lshlrev_b64 v[118:119], 13, v[126:127]
	v_lshl_add_u64 v[118:119], s[40:41], 0, v[118:119]
	v_lshl_add_u64 v[118:119], v[122:123], 1, v[118:119]
	global_load_dwordx2 v[120:121], v[118:119], off
	v_lshlrev_b64 v[160:161], 14, v[126:127]
	v_lshl_add_u64 v[160:161], s[42:43], 0, v[160:161]
	v_lshl_add_u64 v[160:161], v[122:123], 2, v[160:161]
	s_mov_b64 s[0:1], 0
	s_waitcnt vmcnt(0) lgkmcnt(0)
	v_lshlrev_b32_e32 v118, 16, v120
	v_and_b32_e32 v119, 0xffff0000, v120
	v_lshlrev_b32_e32 v120, 16, v121
	v_and_b32_e32 v121, 0xffff0000, v121
	v_pk_fma_f32 v[118:119], v[118:119], s[76:77], v[114:115] op_sel_hi:[1,0,1]
	v_pk_fma_f32 v[120:121], v[120:121], s[76:77], v[116:117] op_sel_hi:[1,0,1]
	flat_store_dwordx4 v[160:161], v[118:121]

; __device__ __forceinline__ float bflo(unsigned u) { return __uint_as_float(u << 16); }
; __device__ __forceinline__ float bfhi(unsigned u) { return __uint_as_float(u & 0xffff0000u); }
; __device__ __forceinline__ void epilogue(const Params& p, int mode, const float* resid, int r, int c, f32x4 v) {
;     ...
;   } else if (mode == EPI_RESID_B) {
;     u32x2 xr = *reinterpret_cast<const u32x2*>(WSP(u16, WS_HB) + (long)c * D + r);
;     f32x4 o = {ALPHA * bflo(xr[0]) + v[0], ALPHA * bfhi(xr[0]) + v[1], ALPHA * bflo(xr[1]) + v[2], ALPHA * bfhi(xr[1]) + v[3]};
;     *reinterpret_cast<f32x4*>(WSP(float, WS_PRE) + (long)c * D + r) = o;
.LBB0_519:
	s_andn2_b64 vcc, exec, s[0:1]
	s_cbranch_vccnz .LBB0_524
	s_cmp_gt_i32 s90, 4
	s_mov_b64 s[0:1], -1
	s_cbranch_scc0 .LBB0_522
	v_ashrrev_i32_e32 v131, 31, v130
	v_lshlrev_b64 v[162:163], 13, v[130:131]
	v_lshl_add_u64 v[162:163], s[40:41], 0, v[162:163]
	v_lshl_add_u64 v[162:163], v[114:115], 1, v[162:163]
	global_load_dwordx2 v[162:163], v[162:163], off
	s_mov_b64 s[0:1], 0
	s_waitcnt vmcnt(0) lgkmcnt(0)
	v_lshlrev_b32_e32 v196, 16, v162
	v_and_b32_e32 v197, 0xffff0000, v162
	v_lshlrev_b32_e32 v162, 16, v163
	v_and_b32_e32 v163, 0xffff0000, v163
	v_pk_fma_f32 v[198:199], v[162:163], s[76:77], v[112:113] op_sel_hi:[1,0,1]
	v_lshlrev_b64 v[162:163], 14, v[130:131]
	v_lshl_add_u64 v[162:163], s[42:43], 0, v[162:163]
	v_pk_fma_f32 v[196:197], v[196:197], s[76:77], v[110:111] op_sel_hi:[1,0,1]
	v_lshl_add_u64 v[162:163], v[114:115], 2, v[162:163]
	flat_store_dwordx4 v[162:163], v[196:199]

; __device__ __forceinline__ float bflo(unsigned u) { return __uint_as_float(u << 16); }
; __device__ __forceinline__ float bfhi(unsigned u) { return __uint_as_float(u & 0xffff0000u); }
; __device__ __forceinline__ void epilogue(const Params& p, int mode, const float* resid, int r, int c, f32x4 v) {
;     ...
;   } else if (mode == EPI_RESID_B) {
;     u32x2 xr = *reinterpret_cast<const u32x2*>(WSP(u16, WS_HB) + (long)c * D + r);
;     f32x4 o = {ALPHA * bflo(xr[0]) + v[0], ALPHA * bfhi(xr[0]) + v[1], ALPHA * bflo(xr[1]) + v[2], ALPHA * bfhi(xr[1]) + v[3]};
;     *reinterpret_cast<f32x4*>(WSP(float, WS_PRE) + (long)c * D + r) = o;
.LBB0_546:
	s_andn2_b64 vcc, exec, s[0:1]
	s_cbranch_vccnz .LBB0_551
	s_cmp_gt_i32 s90, 4
	s_mov_b64 s[0:1], -1
	s_cbranch_scc0 .LBB0_549
	v_ashrrev_i32_e32 v127, 31, v126
	v_lshlrev_b64 v[110:111], 13, v[126:127]
	v_lshl_add_u64 v[110:111], s[40:41], 0, v[110:111]
	v_lshl_add_u64 v[110:111], v[114:115], 1, v[110:111]
	global_load_dwordx2 v[112:113], v[110:111], off
	v_lshlrev_b64 v[162:163], 14, v[126:127]
	v_lshl_add_u64 v[162:163], s[42:43], 0, v[162:163]
	v_lshl_add_u64 v[162:163], v[114:115], 2, v[162:163]
	s_mov_b64 s[0:1], 0
	s_waitcnt vmcnt(0) lgkmcnt(0)
	v_lshlrev_b32_e32 v110, 16, v112
	v_and_b32_e32 v111, 0xffff0000, v112
	v_lshlrev_b32_e32 v112, 16, v113
	v_and_b32_e32 v113, 0xffff0000, v113
	v_pk_fma_f32 v[110:111], v[110:111], s[76:77], v[106:107] op_sel_hi:[1,0,1]
	v_pk_fma_f32 v[112:113], v[112:113], s[76:77], v[108:109] op_sel_hi:[1,0,1]
	flat_store_dwordx4 v[162:163], v[110:113]

; __device__ __forceinline__ float bflo(unsigned u) { return __uint_as_float(u << 16); }
; __device__ __forceinline__ float bfhi(unsigned u) { return __uint_as_float(u & 0xffff0000u); }
; __device__ __forceinline__ void epilogue(const Params& p, int mode, const float* resid, int r, int c, f32x4 v) {
;     ...
;   } else if (mode == EPI_RESID_B) {
;     u32x2 xr = *reinterpret_cast<const u32x2*>(WSP(u16, WS_HB) + (long)c * D + r);
;     f32x4 o = {ALPHA * bflo(xr[0]) + v[0], ALPHA * bfhi(xr[0]) + v[1], ALPHA * bflo(xr[1]) + v[2], ALPHA * bfhi(xr[1]) + v[3]};
;     *reinterpret_cast<f32x4*>(WSP(float, WS_PRE) + (long)c * D + r) = o;
.LBB0_573:
	s_andn2_b64 vcc, exec, s[0:1]
	s_cbranch_vccnz .LBB0_578
	s_cmp_gt_i32 s90, 4
	s_mov_b64 s[0:1], -1
	s_cbranch_scc0 .LBB0_576
	v_ashrrev_i32_e32 v131, 31, v130
	v_lshlrev_b64 v[164:165], 13, v[130:131]
	v_lshl_add_u64 v[164:165], s[40:41], 0, v[164:165]
	v_lshl_add_u64 v[164:165], v[106:107], 1, v[164:165]
	global_load_dwordx2 v[164:165], v[164:165], off
	s_mov_b64 s[0:1], 0
	s_waitcnt vmcnt(0) lgkmcnt(0)
	v_lshlrev_b32_e32 v196, 16, v164
	v_and_b32_e32 v197, 0xffff0000, v164
	v_lshlrev_b32_e32 v164, 16, v165
	v_and_b32_e32 v165, 0xffff0000, v165
	v_pk_fma_f32 v[198:199], v[164:165], s[76:77], v[104:105] op_sel_hi:[1,0,1]
	v_lshlrev_b64 v[164:165], 14, v[130:131]
	v_lshl_add_u64 v[164:165], s[42:43], 0, v[164:165]
	v_pk_fma_f32 v[196:197], v[196:197], s[76:77], v[102:103] op_sel_hi:[1,0,1]
	v_lshl_add_u64 v[164:165], v[106:107], 2, v[164:165]
	flat_store_dwordx4 v[164:165], v[196:199]

; __device__ __forceinline__ float bflo(unsigned u) { return __uint_as_float(u << 16); }
; __device__ __forceinline__ float bfhi(unsigned u) { return __uint_as_float(u & 0xffff0000u); }
; __device__ __forceinline__ void epilogue(const Params& p, int mode, const float* resid, int r, int c, f32x4 v) {
;     ...
;   } else if (mode == EPI_RESID_B) {
;     u32x2 xr = *reinterpret_cast<const u32x2*>(WSP(u16, WS_HB) + (long)c * D + r);
;     f32x4 o = {ALPHA * bflo(xr[0]) + v[0], ALPHA * bfhi(xr[0]) + v[1], ALPHA * bflo(xr[1]) + v[2], ALPHA * bfhi(xr[1]) + v[3]};
;     *reinterpret_cast<f32x4*>(WSP(float, WS_PRE) + (long)c * D + r) = o;
.LBB0_600:
	s_andn2_b64 vcc, exec, s[0:1]
	s_cbranch_vccnz .LBB0_605
	s_cmp_gt_i32 s90, 4
	s_mov_b64 s[0:1], -1
	s_cbranch_scc0 .LBB0_603
	v_ashrrev_i32_e32 v127, 31, v126
	v_lshlrev_b64 v[102:103], 13, v[126:127]
	v_lshl_add_u64 v[102:103], s[40:41], 0, v[102:103]
	v_lshl_add_u64 v[102:103], v[106:107], 1, v[102:103]
	global_load_dwordx2 v[104:105], v[102:103], off
	v_lshlrev_b64 v[164:165], 14, v[126:127]
	v_lshl_add_u64 v[164:165], s[42:43], 0, v[164:165]
	v_lshl_add_u64 v[164:165], v[106:107], 2, v[164:165]
	s_mov_b64 s[0:1], 0
	s_waitcnt vmcnt(0) lgkmcnt(0)
	v_lshlrev_b32_e32 v102, 16, v104
	v_and_b32_e32 v103, 0xffff0000, v104
	v_lshlrev_b32_e32 v104, 16, v105
	v_and_b32_e32 v105, 0xffff0000, v105
	v_pk_fma_f32 v[102:103], v[102:103], s[76:77], v[98:99] op_sel_hi:[1,0,1]
	v_pk_fma_f32 v[104:105], v[104:105], s[76:77], v[100:101] op_sel_hi:[1,0,1]
	flat_store_dwordx4 v[164:165], v[102:105]

; __device__ __forceinline__ float bflo(unsigned u) { return __uint_as_float(u << 16); }
; __device__ __forceinline__ float bfhi(unsigned u) { return __uint_as_float(u & 0xffff0000u); }
; __device__ __forceinline__ void epilogue(const Params& p, int mode, const float* resid, int r, int c, f32x4 v) {
;     ...
;   } else if (mode == EPI_RESID_B) {
;     u32x2 xr = *reinterpret_cast<const u32x2*>(WSP(u16, WS_HB) + (long)c * D + r);
;     f32x4 o = {ALPHA * bflo(xr[0]) + v[0], ALPHA * bfhi(xr[0]) + v[1], ALPHA * bflo(xr[1]) + v[2], ALPHA * bfhi(xr[1]) + v[3]};
;     *reinterpret_cast<f32x4*>(WSP(float, WS_PRE) + (long)c * D + r) = o;
.LBB0_627:
	s_andn2_b64 vcc, exec, s[0:1]
	s_cbranch_vccnz .LBB0_632
	s_cmp_gt_i32 s90, 4
	s_mov_b64 s[0:1], -1
	s_cbranch_scc0 .LBB0_630
	v_ashrrev_i32_e32 v99, 31, v98
	v_lshlrev_b64 v[100:101], 13, v[98:99]
	v_lshl_add_u64 v[100:101], v[142:143], 0, v[100:101]
	global_load_dwordx2 v[102:103], v[100:101], off
	v_lshlrev_b64 v[104:105], 14, v[98:99]
	v_lshl_add_u64 v[104:105], v[140:141], 0, v[104:105]
	s_mov_b64 s[0:1], 0
	s_waitcnt vmcnt(0) lgkmcnt(0)
	v_lshlrev_b32_e32 v100, 16, v102
	v_and_b32_e32 v101, 0xffff0000, v102
	v_lshlrev_b32_e32 v102, 16, v103
	v_and_b32_e32 v103, 0xffff0000, v103
	v_pk_fma_f32 v[100:101], v[100:101], s[76:77], v[94:95] op_sel_hi:[1,0,1]
	v_pk_fma_f32 v[102:103], v[102:103], s[76:77], v[96:97] op_sel_hi:[1,0,1]
	flat_store_dwordx4 v[104:105], v[100:103]

; __device__ __forceinline__ float bflo(unsigned u) { return __uint_as_float(u << 16); }
; __device__ __forceinline__ float bfhi(unsigned u) { return __uint_as_float(u & 0xffff0000u); }
; __device__ __forceinline__ void epilogue(const Params& p, int mode, const float* resid, int r, int c, f32x4 v) {
;     ...
;   } else if (mode == EPI_RESID_B) {
;     u32x2 xr = *reinterpret_cast<const u32x2*>(WSP(u16, WS_HB) + (long)c * D + r);
;     f32x4 o = {ALPHA * bflo(xr[0]) + v[0], ALPHA * bfhi(xr[0]) + v[1], ALPHA * bflo(xr[1]) + v[2], ALPHA * bfhi(xr[1]) + v[3]};
;     *reinterpret_cast<f32x4*>(WSP(float, WS_PRE) + (long)c * D + r) = o;
.LBB0_654:
	s_andn2_b64 vcc, exec, s[0:1]
	s_cbranch_vccnz .LBB0_659
	s_cmp_gt_i32 s90, 4
	s_mov_b64 s[0:1], -1
	s_cbranch_scc0 .LBB0_657
	v_ashrrev_i32_e32 v95, 31, v94
	v_lshlrev_b64 v[96:97], 13, v[94:95]
	v_lshl_add_u64 v[96:97], v[142:143], 0, v[96:97]
	global_load_dwordx2 v[96:97], v[96:97], off
	s_mov_b64 s[0:1], 0
	s_waitcnt vmcnt(0) lgkmcnt(0)
	v_lshlrev_b32_e32 v100, 16, v96
	v_and_b32_e32 v101, 0xffff0000, v96
	v_lshlrev_b32_e32 v96, 16, v97
	v_and_b32_e32 v97, 0xffff0000, v97
	v_pk_fma_f32 v[102:103], v[96:97], s[76:77], v[92:93] op_sel_hi:[1,0,1]
	v_lshlrev_b64 v[96:97], 14, v[94:95]
	v_pk_fma_f32 v[100:101], v[100:101], s[76:77], v[90:91] op_sel_hi:[1,0,1]
	v_lshl_add_u64 v[96:97], v[140:141], 0, v[96:97]
	flat_store_dwordx4 v[96:97], v[100:103]

; __device__ __forceinline__ float bflo(unsigned u) { return __uint_as_float(u << 16); }
; __device__ __forceinline__ float bfhi(unsigned u) { return __uint_as_float(u & 0xffff0000u); }
; __device__ __forceinline__ void epilogue(const Params& p, int mode, const float* resid, int r, int c, f32x4 v) {
;     ...
;   } else if (mode == EPI_RESID_B) {
;     u32x2 xr = *reinterpret_cast<const u32x2*>(WSP(u16, WS_HB) + (long)c * D + r);
;     f32x4 o = {ALPHA * bflo(xr[0]) + v[0], ALPHA * bfhi(xr[0]) + v[1], ALPHA * bflo(xr[1]) + v[2], ALPHA * bfhi(xr[1]) + v[3]};
;     *reinterpret_cast<f32x4*>(WSP(float, WS_PRE) + (long)c * D + r) = o;
.LBB0_681:
	s_andn2_b64 vcc, exec, s[0:1]
	s_cbranch_vccnz .LBB0_686
	s_cmp_gt_i32 s90, 4
	s_mov_b64 s[0:1], -1
	s_cbranch_scc0 .LBB0_684
	v_ashrrev_i32_e32 v99, 31, v98
	v_lshlrev_b64 v[90:91], 13, v[98:99]
	v_lshl_add_u64 v[90:91], s[40:41], 0, v[90:91]
	v_lshl_add_u64 v[90:91], v[122:123], 1, v[90:91]
	global_load_dwordx2 v[92:93], v[90:91], off
	v_lshlrev_b64 v[96:97], 14, v[98:99]
	v_lshl_add_u64 v[96:97], s[42:43], 0, v[96:97]
	v_lshl_add_u64 v[96:97], v[122:123], 2, v[96:97]
	s_mov_b64 s[0:1], 0
	s_waitcnt vmcnt(0) lgkmcnt(0)
	v_lshlrev_b32_e32 v90, 16, v92
	v_and_b32_e32 v91, 0xffff0000, v92
	v_lshlrev_b32_e32 v92, 16, v93
	v_and_b32_e32 v93, 0xffff0000, v93
	v_pk_fma_f32 v[90:91], v[90:91], s[76:77], v[86:87] op_sel_hi:[1,0,1]
	v_pk_fma_f32 v[92:93], v[92:93], s[76:77], v[88:89] op_sel_hi:[1,0,1]
	flat_store_dwordx4 v[96:97], v[90:93]

; __device__ __forceinline__ float bflo(unsigned u) { return __uint_as_float(u << 16); }
; __device__ __forceinline__ float bfhi(unsigned u) { return __uint_as_float(u & 0xffff0000u); }
; __device__ __forceinline__ void epilogue(const Params& p, int mode, const float* resid, int r, int c, f32x4 v) {
;     ...
;   } else if (mode == EPI_RESID_B) {
;     u32x2 xr = *reinterpret_cast<const u32x2*>(WSP(u16, WS_HB) + (long)c * D + r);
;     f32x4 o = {ALPHA * bflo(xr[0]) + v[0], ALPHA * bfhi(xr[0]) + v[1], ALPHA * bflo(xr[1]) + v[2], ALPHA * bfhi(xr[1]) + v[3]};
;     *reinterpret_cast<f32x4*>(WSP(float, WS_PRE) + (long)c * D + r) = o;
.LBB0_708:
	s_andn2_b64 vcc, exec, s[0:1]
	s_cbranch_vccnz .LBB0_713
	s_cmp_gt_i32 s90, 4
	s_mov_b64 s[0:1], -1
	s_cbranch_scc0 .LBB0_711
	v_ashrrev_i32_e32 v95, 31, v94
	v_lshlrev_b64 v[86:87], 13, v[94:95]
	v_lshl_add_u64 v[86:87], s[40:41], 0, v[86:87]
	v_lshl_add_u64 v[86:87], v[122:123], 1, v[86:87]
	global_load_dwordx2 v[88:89], v[86:87], off
	v_lshlrev_b64 v[90:91], 14, v[94:95]
	v_lshl_add_u64 v[90:91], s[42:43], 0, v[90:91]
	v_lshl_add_u64 v[90:91], v[122:123], 2, v[90:91]
	s_mov_b64 s[0:1], 0
	s_waitcnt vmcnt(0) lgkmcnt(0)
	v_lshlrev_b32_e32 v86, 16, v88
	v_and_b32_e32 v87, 0xffff0000, v88
	v_lshlrev_b32_e32 v88, 16, v89
	v_and_b32_e32 v89, 0xffff0000, v89
	v_pk_fma_f32 v[86:87], v[86:87], s[76:77], v[82:83] op_sel_hi:[1,0,1]
	v_pk_fma_f32 v[88:89], v[88:89], s[76:77], v[84:85] op_sel_hi:[1,0,1]
	flat_store_dwordx4 v[90:91], v[86:89]

; __device__ __forceinline__ float bflo(unsigned u) { return __uint_as_float(u << 16); }
; __device__ __forceinline__ float bfhi(unsigned u) { return __uint_as_float(u & 0xffff0000u); }
; __device__ __forceinline__ void epilogue(const Params& p, int mode, const float* resid, int r, int c, f32x4 v) {
;     ...
;   } else if (mode == EPI_RESID_B) {
;     u32x2 xr = *reinterpret_cast<const u32x2*>(WSP(u16, WS_HB) + (long)c * D + r);
;     f32x4 o = {ALPHA * bflo(xr[0]) + v[0], ALPHA * bfhi(xr[0]) + v[1], ALPHA * bflo(xr[1]) + v[2], ALPHA * bfhi(xr[1]) + v[3]};
;     *reinterpret_cast<f32x4*>(WSP(float, WS_PRE) + (long)c * D + r) = o;
.LBB0_735:
	s_andn2_b64 vcc, exec, s[0:1]
	s_cbranch_vccnz .LBB0_740
	s_cmp_gt_i32 s90, 4
	s_mov_b64 s[0:1], -1
	s_cbranch_scc0 .LBB0_738
	v_ashrrev_i32_e32 v99, 31, v98
	v_lshlrev_b64 v[82:83], 13, v[98:99]
	v_lshl_add_u64 v[82:83], s[40:41], 0, v[82:83]
	v_lshl_add_u64 v[82:83], v[114:115], 1, v[82:83]
	global_load_dwordx2 v[84:85], v[82:83], off
	v_lshlrev_b64 v[86:87], 14, v[98:99]
	v_lshl_add_u64 v[86:87], s[42:43], 0, v[86:87]
	v_lshl_add_u64 v[86:87], v[114:115], 2, v[86:87]
	s_mov_b64 s[0:1], 0
	s_waitcnt vmcnt(0) lgkmcnt(0)
	v_lshlrev_b32_e32 v82, 16, v84
	v_and_b32_e32 v83, 0xffff0000, v84
	v_lshlrev_b32_e32 v84, 16, v85
	v_and_b32_e32 v85, 0xffff0000, v85
	v_pk_fma_f32 v[82:83], v[82:83], s[76:77], v[78:79] op_sel_hi:[1,0,1]
	v_pk_fma_f32 v[84:85], v[84:85], s[76:77], v[80:81] op_sel_hi:[1,0,1]
	flat_store_dwordx4 v[86:87], v[82:85]

; __device__ __forceinline__ float bflo(unsigned u) { return __uint_as_float(u << 16); }
; __device__ __forceinline__ float bfhi(unsigned u) { return __uint_as_float(u & 0xffff0000u); }
; __device__ __forceinline__ void epilogue(const Params& p, int mode, const float* resid, int r, int c, f32x4 v) {
;     ...
;   } else if (mode == EPI_RESID_B) {
;     u32x2 xr = *reinterpret_cast<const u32x2*>(WSP(u16, WS_HB) + (long)c * D + r);
;     f32x4 o = {ALPHA * bflo(xr[0]) + v[0], ALPHA * bfhi(xr[0]) + v[1], ALPHA * bflo(xr[1]) + v[2], ALPHA * bfhi(xr[1]) + v[3]};
;     *reinterpret_cast<f32x4*>(WSP(float, WS_PRE) + (long)c * D + r) = o;
.LBB0_762:
	s_andn2_b64 vcc, exec, s[0:1]
	s_cbranch_vccnz .LBB0_767
	s_cmp_gt_i32 s90, 4
	s_mov_b64 s[0:1], -1
	s_cbranch_scc0 .LBB0_765
	v_ashrrev_i32_e32 v95, 31, v94
	v_lshlrev_b64 v[78:79], 13, v[94:95]
	v_lshl_add_u64 v[78:79], s[40:41], 0, v[78:79]
	v_lshl_add_u64 v[78:79], v[114:115], 1, v[78:79]
	global_load_dwordx2 v[80:81], v[78:79], off
	v_lshlrev_b64 v[82:83], 14, v[94:95]
	v_lshl_add_u64 v[82:83], s[42:43], 0, v[82:83]
	v_lshl_add_u64 v[82:83], v[114:115], 2, v[82:83]
	s_mov_b64 s[0:1], 0
	s_waitcnt vmcnt(0) lgkmcnt(0)
	v_lshlrev_b32_e32 v78, 16, v80
	v_and_b32_e32 v79, 0xffff0000, v80
	v_lshlrev_b32_e32 v80, 16, v81
	v_and_b32_e32 v81, 0xffff0000, v81
	v_pk_fma_f32 v[78:79], v[78:79], s[76:77], v[74:75] op_sel_hi:[1,0,1]
	v_pk_fma_f32 v[80:81], v[80:81], s[76:77], v[76:77] op_sel_hi:[1,0,1]
	flat_store_dwordx4 v[82:83], v[78:81]

; __device__ __forceinline__ float bflo(unsigned u) { return __uint_as_float(u << 16); }
; __device__ __forceinline__ float bfhi(unsigned u) { return __uint_as_float(u & 0xffff0000u); }
; __device__ __forceinline__ void epilogue(const Params& p, int mode, const float* resid, int r, int c, f32x4 v) {
;     ...
;   } else if (mode == EPI_RESID_B) {
;     u32x2 xr = *reinterpret_cast<const u32x2*>(WSP(u16, WS_HB) + (long)c * D + r);
;     f32x4 o = {ALPHA * bflo(xr[0]) + v[0], ALPHA * bfhi(xr[0]) + v[1], ALPHA * bflo(xr[1]) + v[2], ALPHA * bfhi(xr[1]) + v[3]};
;     *reinterpret_cast<f32x4*>(WSP(float, WS_PRE) + (long)c * D + r) = o;
.LBB0_789:
	s_andn2_b64 vcc, exec, s[0:1]
	s_cbranch_vccnz .LBB0_794
	s_cmp_gt_i32 s90, 4
	s_mov_b64 s[0:1], -1
	s_cbranch_scc0 .LBB0_792
	v_ashrrev_i32_e32 v99, 31, v98
	v_lshlrev_b64 v[74:75], 13, v[98:99]
	v_lshl_add_u64 v[74:75], s[40:41], 0, v[74:75]
	v_lshl_add_u64 v[74:75], v[106:107], 1, v[74:75]
	global_load_dwordx2 v[76:77], v[74:75], off
	v_lshlrev_b64 v[78:79], 14, v[98:99]
	v_lshl_add_u64 v[78:79], s[42:43], 0, v[78:79]
	v_lshl_add_u64 v[78:79], v[106:107], 2, v[78:79]
	s_mov_b64 s[0:1], 0
	s_waitcnt vmcnt(0) lgkmcnt(0)
	v_lshlrev_b32_e32 v74, 16, v76
	v_and_b32_e32 v75, 0xffff0000, v76
	v_lshlrev_b32_e32 v76, 16, v77
	v_and_b32_e32 v77, 0xffff0000, v77
	v_pk_fma_f32 v[74:75], v[74:75], s[76:77], v[70:71] op_sel_hi:[1,0,1]
	v_pk_fma_f32 v[76:77], v[76:77], s[76:77], v[72:73] op_sel_hi:[1,0,1]
	flat_store_dwordx4 v[78:79], v[74:77]

; __device__ __forceinline__ float bflo(unsigned u) { return __uint_as_float(u << 16); }
; __device__ __forceinline__ float bfhi(unsigned u) { return __uint_as_float(u & 0xffff0000u); }
; __device__ __forceinline__ void epilogue(const Params& p, int mode, const float* resid, int r, int c, f32x4 v) {
;     ...
;   } else if (mode == EPI_RESID_B) {
;     u32x2 xr = *reinterpret_cast<const u32x2*>(WSP(u16, WS_HB) + (long)c * D + r);
;     f32x4 o = {ALPHA * bflo(xr[0]) + v[0], ALPHA * bfhi(xr[0]) + v[1], ALPHA * bflo(xr[1]) + v[2], ALPHA * bfhi(xr[1]) + v[3]};
;     *reinterpret_cast<f32x4*>(WSP(float, WS_PRE) + (long)c * D + r) = o;
.LBB0_816:
	s_andn2_b64 vcc, exec, s[0:1]
	s_cbranch_vccnz .LBB0_821
	s_cmp_gt_i32 s90, 4
	s_mov_b64 s[0:1], -1
	s_cbranch_scc0 .LBB0_819
	v_ashrrev_i32_e32 v95, 31, v94
	v_lshlrev_b64 v[70:71], 13, v[94:95]
	v_lshl_add_u64 v[70:71], s[40:41], 0, v[70:71]
	v_lshl_add_u64 v[70:71], v[106:107], 1, v[70:71]
	global_load_dwordx2 v[72:73], v[70:71], off
	v_lshlrev_b64 v[74:75], 14, v[94:95]
	v_lshl_add_u64 v[74:75], s[42:43], 0, v[74:75]
	v_lshl_add_u64 v[74:75], v[106:107], 2, v[74:75]
	s_mov_b64 s[0:1], 0
	s_waitcnt vmcnt(0) lgkmcnt(0)
	v_lshlrev_b32_e32 v70, 16, v72
	v_and_b32_e32 v71, 0xffff0000, v72
	v_lshlrev_b32_e32 v72, 16, v73
	v_and_b32_e32 v73, 0xffff0000, v73
	v_pk_fma_f32 v[70:71], v[70:71], s[76:77], v[66:67] op_sel_hi:[1,0,1]
	v_pk_fma_f32 v[72:73], v[72:73], s[76:77], v[68:69] op_sel_hi:[1,0,1]
	flat_store_dwordx4 v[74:75], v[70:73]

; __device__ __forceinline__ float bflo(unsigned u) { return __uint_as_float(u << 16); }
; __device__ __forceinline__ float bfhi(unsigned u) { return __uint_as_float(u & 0xffff0000u); }
; __device__ __forceinline__ void epilogue(const Params& p, int mode, const float* resid, int r, int c, f32x4 v) {
;     ...
;   } else if (mode == EPI_RESID_B) {
;     u32x2 xr = *reinterpret_cast<const u32x2*>(WSP(u16, WS_HB) + (long)c * D + r);
;     f32x4 o = {ALPHA * bflo(xr[0]) + v[0], ALPHA * bfhi(xr[0]) + v[1], ALPHA * bflo(xr[1]) + v[2], ALPHA * bfhi(xr[1]) + v[3]};
;     *reinterpret_cast<f32x4*>(WSP(float, WS_PRE) + (long)c * D + r) = o;
.LBB0_843:
	s_andn2_b64 vcc, exec, s[0:1]
	s_cbranch_vccnz .LBB0_848
	s_cmp_gt_i32 s90, 4
	s_mov_b64 s[0:1], -1
	s_cbranch_scc0 .LBB0_846
	v_ashrrev_i32_e32 v131, 31, v130
	v_lshlrev_b64 v[84:85], 13, v[130:131]
	v_lshl_add_u64 v[84:85], v[74:75], 0, v[84:85]
	global_load_dwordx2 v[86:87], v[84:85], off
	v_lshlrev_b64 v[88:89], 14, v[130:131]
	v_lshl_add_u64 v[88:89], v[70:71], 0, v[88:89]
	s_mov_b64 s[0:1], 0
	s_waitcnt vmcnt(0) lgkmcnt(0)
	v_lshlrev_b32_e32 v84, 16, v86
	v_and_b32_e32 v85, 0xffff0000, v86
	v_lshlrev_b32_e32 v86, 16, v87
	v_and_b32_e32 v87, 0xffff0000, v87
	v_pk_fma_f32 v[84:85], v[84:85], s[76:77], v[62:63] op_sel_hi:[1,0,1]
	v_pk_fma_f32 v[86:87], v[86:87], s[76:77], v[64:65] op_sel_hi:[1,0,1]
	flat_store_dwordx4 v[88:89], v[84:87]

; __device__ __forceinline__ float bflo(unsigned u) { return __uint_as_float(u << 16); }
; __device__ __forceinline__ float bfhi(unsigned u) { return __uint_as_float(u & 0xffff0000u); }
; __device__ __forceinline__ void epilogue(const Params& p, int mode, const float* resid, int r, int c, f32x4 v) {
;     ...
;   } else if (mode == EPI_RESID_B) {
;     u32x2 xr = *reinterpret_cast<const u32x2*>(WSP(u16, WS_HB) + (long)c * D + r);
;     f32x4 o = {ALPHA * bflo(xr[0]) + v[0], ALPHA * bfhi(xr[0]) + v[1], ALPHA * bflo(xr[1]) + v[2], ALPHA * bfhi(xr[1]) + v[3]};
;     *reinterpret_cast<f32x4*>(WSP(float, WS_PRE) + (long)c * D + r) = o;
.LBB0_870:
	s_andn2_b64 vcc, exec, s[0:1]
	s_cbranch_vccnz .LBB0_875
	s_cmp_gt_i32 s90, 4
	s_mov_b64 s[0:1], -1
	s_cbranch_scc0 .LBB0_873
	v_ashrrev_i32_e32 v127, 31, v126
	v_lshlrev_b64 v[62:63], 13, v[126:127]
	v_lshl_add_u64 v[62:63], v[74:75], 0, v[62:63]
	global_load_dwordx2 v[64:65], v[62:63], off
	v_lshlrev_b64 v[86:87], 14, v[126:127]
	v_lshl_add_u64 v[86:87], v[70:71], 0, v[86:87]
	s_mov_b64 s[0:1], 0
	s_waitcnt vmcnt(0) lgkmcnt(0)
	v_lshlrev_b32_e32 v62, 16, v64
	v_and_b32_e32 v63, 0xffff0000, v64
	v_lshlrev_b32_e32 v64, 16, v65
	v_and_b32_e32 v65, 0xffff0000, v65
	v_pk_fma_f32 v[62:63], v[62:63], s[76:77], v[58:59] op_sel_hi:[1,0,1]
	v_pk_fma_f32 v[64:65], v[64:65], s[76:77], v[60:61] op_sel_hi:[1,0,1]
	flat_store_dwordx4 v[86:87], v[62:65]

; __device__ __forceinline__ float bflo(unsigned u) { return __uint_as_float(u << 16); }
; __device__ __forceinline__ float bfhi(unsigned u) { return __uint_as_float(u & 0xffff0000u); }
; __device__ __forceinline__ void epilogue(const Params& p, int mode, const float* resid, int r, int c, f32x4 v) {
;     ...
;   } else if (mode == EPI_RESID_B) {
;     u32x2 xr = *reinterpret_cast<const u32x2*>(WSP(u16, WS_HB) + (long)c * D + r);
;     f32x4 o = {ALPHA * bflo(xr[0]) + v[0], ALPHA * bfhi(xr[0]) + v[1], ALPHA * bflo(xr[1]) + v[2], ALPHA * bfhi(xr[1]) + v[3]};
;     *reinterpret_cast<f32x4*>(WSP(float, WS_PRE) + (long)c * D + r) = o;
.LBB0_897:
	s_andn2_b64 vcc, exec, s[0:1]
	s_cbranch_vccnz .LBB0_902
	s_cmp_gt_i32 s90, 4
	s_mov_b64 s[0:1], -1
	s_cbranch_scc0 .LBB0_900
	v_ashrrev_i32_e32 v131, 31, v130
	v_lshlrev_b64 v[88:89], 13, v[130:131]
	v_lshl_add_u64 v[88:89], s[40:41], 0, v[88:89]
	v_lshl_add_u64 v[88:89], v[58:59], 1, v[88:89]
	global_load_dwordx2 v[90:91], v[88:89], off
	v_lshlrev_b64 v[102:103], 14, v[130:131]
	v_lshl_add_u64 v[102:103], s[42:43], 0, v[102:103]
	v_lshl_add_u64 v[102:103], v[58:59], 2, v[102:103]
	s_mov_b64 s[0:1], 0
	s_waitcnt vmcnt(0) lgkmcnt(0)
	v_lshlrev_b32_e32 v88, 16, v90
	v_and_b32_e32 v89, 0xffff0000, v90
	v_lshlrev_b32_e32 v90, 16, v91
	v_and_b32_e32 v91, 0xffff0000, v91
	v_pk_fma_f32 v[88:89], v[88:89], s[76:77], v[54:55] op_sel_hi:[1,0,1]
	v_pk_fma_f32 v[90:91], v[90:91], s[76:77], v[56:57] op_sel_hi:[1,0,1]
	flat_store_dwordx4 v[102:103], v[88:91]

; __device__ __forceinline__ float bflo(unsigned u) { return __uint_as_float(u << 16); }
; __device__ __forceinline__ float bfhi(unsigned u) { return __uint_as_float(u & 0xffff0000u); }
; __device__ __forceinline__ void epilogue(const Params& p, int mode, const float* resid, int r, int c, f32x4 v) {
;     ...
;   } else if (mode == EPI_RESID_B) {
;     u32x2 xr = *reinterpret_cast<const u32x2*>(WSP(u16, WS_HB) + (long)c * D + r);
;     f32x4 o = {ALPHA * bflo(xr[0]) + v[0], ALPHA * bfhi(xr[0]) + v[1], ALPHA * bflo(xr[1]) + v[2], ALPHA * bfhi(xr[1]) + v[3]};
;     *reinterpret_cast<f32x4*>(WSP(float, WS_PRE) + (long)c * D + r) = o;
.LBB0_924:
	s_andn2_b64 vcc, exec, s[0:1]
	s_cbranch_vccnz .LBB0_929
	s_cmp_gt_i32 s90, 4
	s_mov_b64 s[0:1], -1
	s_cbranch_scc0 .LBB0_927
	v_ashrrev_i32_e32 v127, 31, v126
	v_lshlrev_b64 v[54:55], 13, v[126:127]
	v_lshl_add_u64 v[54:55], s[40:41], 0, v[54:55]
	v_lshl_add_u64 v[54:55], v[58:59], 1, v[54:55]
	global_load_dwordx2 v[56:57], v[54:55], off
	v_lshlrev_b64 v[88:89], 14, v[126:127]
	v_lshl_add_u64 v[88:89], s[42:43], 0, v[88:89]
	v_lshl_add_u64 v[88:89], v[58:59], 2, v[88:89]
	s_mov_b64 s[0:1], 0
	s_waitcnt vmcnt(0) lgkmcnt(0)
	v_lshlrev_b32_e32 v54, 16, v56
	v_and_b32_e32 v55, 0xffff0000, v56
	v_lshlrev_b32_e32 v56, 16, v57
	v_and_b32_e32 v57, 0xffff0000, v57
	v_pk_fma_f32 v[54:55], v[54:55], s[76:77], v[50:51] op_sel_hi:[1,0,1]
	v_pk_fma_f32 v[56:57], v[56:57], s[76:77], v[52:53] op_sel_hi:[1,0,1]
	flat_store_dwordx4 v[88:89], v[54:57]

; __device__ __forceinline__ float bflo(unsigned u) { return __uint_as_float(u << 16); }
; __device__ __forceinline__ float bfhi(unsigned u) { return __uint_as_float(u & 0xffff0000u); }
; __device__ __forceinline__ void epilogue(const Params& p, int mode, const float* resid, int r, int c, f32x4 v) {
;     ...
;   } else if (mode == EPI_RESID_B) {
;     u32x2 xr = *reinterpret_cast<const u32x2*>(WSP(u16, WS_HB) + (long)c * D + r);
;     f32x4 o = {ALPHA * bflo(xr[0]) + v[0], ALPHA * bfhi(xr[0]) + v[1], ALPHA * bflo(xr[1]) + v[2], ALPHA * bfhi(xr[1]) + v[3]};
;     *reinterpret_cast<f32x4*>(WSP(float, WS_PRE) + (long)c * D + r) = o;
.LBB0_951:
	s_andn2_b64 vcc, exec, s[0:1]
	s_cbranch_vccnz .LBB0_956
	s_cmp_gt_i32 s90, 4
	s_mov_b64 s[0:1], -1
	s_cbranch_scc0 .LBB0_954
	v_ashrrev_i32_e32 v131, 31, v130
	v_lshlrev_b64 v[90:91], 13, v[130:131]
	v_lshl_add_u64 v[90:91], s[40:41], 0, v[90:91]
	v_lshl_add_u64 v[90:91], v[50:51], 1, v[90:91]
	global_load_dwordx2 v[90:91], v[90:91], off
	s_mov_b64 s[0:1], 0
	s_waitcnt vmcnt(0) lgkmcnt(0)
	v_lshlrev_b32_e32 v102, 16, v90
	v_and_b32_e32 v103, 0xffff0000, v90
	v_lshlrev_b32_e32 v90, 16, v91
	v_and_b32_e32 v91, 0xffff0000, v91
	v_pk_fma_f32 v[104:105], v[90:91], s[76:77], v[48:49] op_sel_hi:[1,0,1]
	v_lshlrev_b64 v[90:91], 14, v[130:131]
	v_lshl_add_u64 v[90:91], s[42:43], 0, v[90:91]
	v_pk_fma_f32 v[102:103], v[102:103], s[76:77], v[46:47] op_sel_hi:[1,0,1]
	v_lshl_add_u64 v[90:91], v[50:51], 2, v[90:91]
	flat_store_dwordx4 v[90:91], v[102:105]

; __device__ __forceinline__ float bflo(unsigned u) { return __uint_as_float(u << 16); }
; __device__ __forceinline__ float bfhi(unsigned u) { return __uint_as_float(u & 0xffff0000u); }
; __device__ __forceinline__ void epilogue(const Params& p, int mode, const float* resid, int r, int c, f32x4 v) {
;     ...
;   } else if (mode == EPI_RESID_B) {
;     u32x2 xr = *reinterpret_cast<const u32x2*>(WSP(u16, WS_HB) + (long)c * D + r);
;     f32x4 o = {ALPHA * bflo(xr[0]) + v[0], ALPHA * bfhi(xr[0]) + v[1], ALPHA * bflo(xr[1]) + v[2], ALPHA * bfhi(xr[1]) + v[3]};
;     *reinterpret_cast<f32x4*>(WSP(float, WS_PRE) + (long)c * D + r) = o;
.LBB0_978:
	s_andn2_b64 vcc, exec, s[0:1]
	s_cbranch_vccnz .LBB0_983
	s_cmp_gt_i32 s90, 4
	s_mov_b64 s[0:1], -1
	s_cbranch_scc0 .LBB0_981
	v_ashrrev_i32_e32 v127, 31, v126
	v_lshlrev_b64 v[46:47], 13, v[126:127]
	v_lshl_add_u64 v[46:47], s[40:41], 0, v[46:47]
	v_lshl_add_u64 v[46:47], v[50:51], 1, v[46:47]
	global_load_dwordx2 v[48:49], v[46:47], off
	v_lshlrev_b64 v[90:91], 14, v[126:127]
	v_lshl_add_u64 v[90:91], s[42:43], 0, v[90:91]
	v_lshl_add_u64 v[90:91], v[50:51], 2, v[90:91]
	s_mov_b64 s[0:1], 0
	s_waitcnt vmcnt(0) lgkmcnt(0)
	v_lshlrev_b32_e32 v46, 16, v48
	v_and_b32_e32 v47, 0xffff0000, v48
	v_lshlrev_b32_e32 v48, 16, v49
	v_and_b32_e32 v49, 0xffff0000, v49
	v_pk_fma_f32 v[46:47], v[46:47], s[76:77], v[42:43] op_sel_hi:[1,0,1]
	v_pk_fma_f32 v[48:49], v[48:49], s[76:77], v[44:45] op_sel_hi:[1,0,1]
	flat_store_dwordx4 v[90:91], v[46:49]

; __device__ __forceinline__ float bflo(unsigned u) { return __uint_as_float(u << 16); }
; __device__ __forceinline__ float bfhi(unsigned u) { return __uint_as_float(u & 0xffff0000u); }
; __device__ __forceinline__ void epilogue(const Params& p, int mode, const float* resid, int r, int c, f32x4 v) {
;     ...
;   } else if (mode == EPI_RESID_B) {
;     u32x2 xr = *reinterpret_cast<const u32x2*>(WSP(u16, WS_HB) + (long)c * D + r);
;     f32x4 o = {ALPHA * bflo(xr[0]) + v[0], ALPHA * bfhi(xr[0]) + v[1], ALPHA * bflo(xr[1]) + v[2], ALPHA * bfhi(xr[1]) + v[3]};
;     *reinterpret_cast<f32x4*>(WSP(float, WS_PRE) + (long)c * D + r) = o;
.LBB0_1005:
	s_andn2_b64 vcc, exec, s[0:1]
	s_cbranch_vccnz .LBB0_1010
	s_cmp_gt_i32 s90, 4
	s_mov_b64 s[0:1], -1
	s_cbranch_scc0 .LBB0_1008
	v_ashrrev_i32_e32 v131, 31, v130
	v_lshlrev_b64 v[92:93], 13, v[130:131]
	v_lshl_add_u64 v[92:93], s[40:41], 0, v[92:93]
	v_lshl_add_u64 v[92:93], v[42:43], 1, v[92:93]
	global_load_dwordx2 v[92:93], v[92:93], off
	s_mov_b64 s[0:1], 0
	s_waitcnt vmcnt(0) lgkmcnt(0)
	v_lshlrev_b32_e32 v102, 16, v92
	v_and_b32_e32 v103, 0xffff0000, v92
	v_lshlrev_b32_e32 v92, 16, v93
	v_and_b32_e32 v93, 0xffff0000, v93
	v_pk_fma_f32 v[104:105], v[92:93], s[76:77], v[40:41] op_sel_hi:[1,0,1]
	v_lshlrev_b64 v[92:93], 14, v[130:131]
	v_lshl_add_u64 v[92:93], s[42:43], 0, v[92:93]
	v_pk_fma_f32 v[102:103], v[102:103], s[76:77], v[38:39] op_sel_hi:[1,0,1]
	v_lshl_add_u64 v[92:93], v[42:43], 2, v[92:93]
	flat_store_dwordx4 v[92:93], v[102:105]

; __device__ __forceinline__ float bflo(unsigned u) { return __uint_as_float(u << 16); }
; __device__ __forceinline__ float bfhi(unsigned u) { return __uint_as_float(u & 0xffff0000u); }
; __device__ __forceinline__ void epilogue(const Params& p, int mode, const float* resid, int r, int c, f32x4 v) {
;     ...
;   } else if (mode == EPI_RESID_B) {
;     u32x2 xr = *reinterpret_cast<const u32x2*>(WSP(u16, WS_HB) + (long)c * D + r);
;     f32x4 o = {ALPHA * bflo(xr[0]) + v[0], ALPHA * bfhi(xr[0]) + v[1], ALPHA * bflo(xr[1]) + v[2], ALPHA * bfhi(xr[1]) + v[3]};
;     *reinterpret_cast<f32x4*>(WSP(float, WS_PRE) + (long)c * D + r) = o;
.LBB0_1032:
	s_andn2_b64 vcc, exec, s[0:1]
	s_cbranch_vccnz .LBB0_1037
	s_cmp_gt_i32 s90, 4
	s_mov_b64 s[0:1], -1
	s_cbranch_scc0 .LBB0_1035
	v_ashrrev_i32_e32 v127, 31, v126
	v_lshlrev_b64 v[38:39], 13, v[126:127]
	v_lshl_add_u64 v[38:39], s[40:41], 0, v[38:39]
	v_lshl_add_u64 v[38:39], v[42:43], 1, v[38:39]
	global_load_dwordx2 v[40:41], v[38:39], off
	v_lshlrev_b64 v[92:93], 14, v[126:127]
	v_lshl_add_u64 v[92:93], s[42:43], 0, v[92:93]
	v_lshl_add_u64 v[92:93], v[42:43], 2, v[92:93]
	s_mov_b64 s[0:1], 0
	s_waitcnt vmcnt(0) lgkmcnt(0)
	v_lshlrev_b32_e32 v38, 16, v40
	v_and_b32_e32 v39, 0xffff0000, v40
	v_lshlrev_b32_e32 v40, 16, v41
	v_and_b32_e32 v41, 0xffff0000, v41
	v_pk_fma_f32 v[38:39], v[38:39], s[76:77], v[34:35] op_sel_hi:[1,0,1]
	v_pk_fma_f32 v[40:41], v[40:41], s[76:77], v[36:37] op_sel_hi:[1,0,1]
	flat_store_dwordx4 v[92:93], v[38:41]

; __device__ __forceinline__ float bflo(unsigned u) { return __uint_as_float(u << 16); }
; __device__ __forceinline__ float bfhi(unsigned u) { return __uint_as_float(u & 0xffff0000u); }
; __device__ __forceinline__ void epilogue(const Params& p, int mode, const float* resid, int r, int c, f32x4 v) {
;     ...
;   } else if (mode == EPI_RESID_B) {
;     u32x2 xr = *reinterpret_cast<const u32x2*>(WSP(u16, WS_HB) + (long)c * D + r);
;     f32x4 o = {ALPHA * bflo(xr[0]) + v[0], ALPHA * bfhi(xr[0]) + v[1], ALPHA * bflo(xr[1]) + v[2], ALPHA * bfhi(xr[1]) + v[3]};
;     *reinterpret_cast<f32x4*>(WSP(float, WS_PRE) + (long)c * D + r) = o;
.LBB0_1059:
	s_andn2_b64 vcc, exec, s[0:1]
	s_cbranch_vccnz .LBB0_1064
	s_cmp_gt_i32 s90, 4
	s_mov_b64 s[0:1], -1
	s_cbranch_scc0 .LBB0_1062
	v_ashrrev_i32_e32 v99, 31, v98
	v_lshlrev_b64 v[34:35], 13, v[98:99]
	v_lshl_add_u64 v[34:35], v[74:75], 0, v[34:35]
	global_load_dwordx2 v[36:37], v[34:35], off
	v_lshlrev_b64 v[38:39], 14, v[98:99]
	v_lshl_add_u64 v[38:39], v[70:71], 0, v[38:39]
	s_mov_b64 s[0:1], 0
	s_waitcnt vmcnt(0) lgkmcnt(0)
	v_lshlrev_b32_e32 v34, 16, v36
	v_and_b32_e32 v35, 0xffff0000, v36
	v_lshlrev_b32_e32 v36, 16, v37
	v_and_b32_e32 v37, 0xffff0000, v37
	v_pk_fma_f32 v[34:35], v[34:35], s[76:77], v[30:31] op_sel_hi:[1,0,1]
	v_pk_fma_f32 v[36:37], v[36:37], s[76:77], v[32:33] op_sel_hi:[1,0,1]
	flat_store_dwordx4 v[38:39], v[34:37]

; __device__ __forceinline__ float bflo(unsigned u) { return __uint_as_float(u << 16); }
; __device__ __forceinline__ float bfhi(unsigned u) { return __uint_as_float(u & 0xffff0000u); }
; __device__ __forceinline__ void epilogue(const Params& p, int mode, const float* resid, int r, int c, f32x4 v) {
;     ...
;   } else if (mode == EPI_RESID_B) {
;     u32x2 xr = *reinterpret_cast<const u32x2*>(WSP(u16, WS_HB) + (long)c * D + r);
;     f32x4 o = {ALPHA * bflo(xr[0]) + v[0], ALPHA * bfhi(xr[0]) + v[1], ALPHA * bflo(xr[1]) + v[2], ALPHA * bfhi(xr[1]) + v[3]};
;     *reinterpret_cast<f32x4*>(WSP(float, WS_PRE) + (long)c * D + r) = o;
.LBB0_1086:
	s_andn2_b64 vcc, exec, s[0:1]
	s_cbranch_vccnz .LBB0_1091
	s_cmp_gt_i32 s90, 4
	s_mov_b64 s[0:1], -1
	s_cbranch_scc0 .LBB0_1089
	v_ashrrev_i32_e32 v95, 31, v94
	v_lshlrev_b64 v[30:31], 13, v[94:95]
	v_lshl_add_u64 v[30:31], v[74:75], 0, v[30:31]
	global_load_dwordx2 v[32:33], v[30:31], off
	v_lshlrev_b64 v[34:35], 14, v[94:95]
	v_lshl_add_u64 v[34:35], v[70:71], 0, v[34:35]
	s_mov_b64 s[0:1], 0
	s_waitcnt vmcnt(0) lgkmcnt(0)
	v_lshlrev_b32_e32 v30, 16, v32
	v_and_b32_e32 v31, 0xffff0000, v32
	v_lshlrev_b32_e32 v32, 16, v33
	v_and_b32_e32 v33, 0xffff0000, v33
	v_pk_fma_f32 v[30:31], v[30:31], s[76:77], v[26:27] op_sel_hi:[1,0,1]
	v_pk_fma_f32 v[32:33], v[32:33], s[76:77], v[28:29] op_sel_hi:[1,0,1]
	flat_store_dwordx4 v[34:35], v[30:33]

; __device__ __forceinline__ float bflo(unsigned u) { return __uint_as_float(u << 16); }
; __device__ __forceinline__ float bfhi(unsigned u) { return __uint_as_float(u & 0xffff0000u); }
; __device__ __forceinline__ void epilogue(const Params& p, int mode, const float* resid, int r, int c, f32x4 v) {
;     ...
;   } else if (mode == EPI_RESID_B) {
;     u32x2 xr = *reinterpret_cast<const u32x2*>(WSP(u16, WS_HB) + (long)c * D + r);
;     f32x4 o = {ALPHA * bflo(xr[0]) + v[0], ALPHA * bfhi(xr[0]) + v[1], ALPHA * bflo(xr[1]) + v[2], ALPHA * bfhi(xr[1]) + v[3]};
;     *reinterpret_cast<f32x4*>(WSP(float, WS_PRE) + (long)c * D + r) = o;
.LBB0_1113:
	s_andn2_b64 vcc, exec, s[0:1]
	s_cbranch_vccnz .LBB0_1118
	s_cmp_gt_i32 s90, 4
	s_mov_b64 s[0:1], -1
	s_cbranch_scc0 .LBB0_1116
	v_ashrrev_i32_e32 v99, 31, v98
	v_lshlrev_b64 v[26:27], 13, v[98:99]
	v_lshl_add_u64 v[26:27], s[40:41], 0, v[26:27]
	v_lshl_add_u64 v[26:27], v[58:59], 1, v[26:27]
	global_load_dwordx2 v[28:29], v[26:27], off
	v_lshlrev_b64 v[30:31], 14, v[98:99]
	v_lshl_add_u64 v[30:31], s[42:43], 0, v[30:31]
	v_lshl_add_u64 v[30:31], v[58:59], 2, v[30:31]
	s_mov_b64 s[0:1], 0
	s_waitcnt vmcnt(0) lgkmcnt(0)
	v_lshlrev_b32_e32 v26, 16, v28
	v_and_b32_e32 v27, 0xffff0000, v28
	v_lshlrev_b32_e32 v28, 16, v29
	v_and_b32_e32 v29, 0xffff0000, v29
	v_pk_fma_f32 v[26:27], v[26:27], s[76:77], v[22:23] op_sel_hi:[1,0,1]
	v_pk_fma_f32 v[28:29], v[28:29], s[76:77], v[24:25] op_sel_hi:[1,0,1]
	flat_store_dwordx4 v[30:31], v[26:29]

; __device__ __forceinline__ float bflo(unsigned u) { return __uint_as_float(u << 16); }
; __device__ __forceinline__ float bfhi(unsigned u) { return __uint_as_float(u & 0xffff0000u); }
; __device__ __forceinline__ void epilogue(const Params& p, int mode, const float* resid, int r, int c, f32x4 v) {
;     ...
;   } else if (mode == EPI_RESID_B) {
;     u32x2 xr = *reinterpret_cast<const u32x2*>(WSP(u16, WS_HB) + (long)c * D + r);
;     f32x4 o = {ALPHA * bflo(xr[0]) + v[0], ALPHA * bfhi(xr[0]) + v[1], ALPHA * bflo(xr[1]) + v[2], ALPHA * bfhi(xr[1]) + v[3]};
;     *reinterpret_cast<f32x4*>(WSP(float, WS_PRE) + (long)c * D + r) = o;
.LBB0_1140:
	s_andn2_b64 vcc, exec, s[0:1]
	s_cbranch_vccnz .LBB0_1145
	s_cmp_gt_i32 s90, 4
	s_mov_b64 s[0:1], -1
	s_cbranch_scc0 .LBB0_1143
	v_ashrrev_i32_e32 v95, 31, v94
	v_lshlrev_b64 v[22:23], 13, v[94:95]
	v_lshl_add_u64 v[22:23], s[40:41], 0, v[22:23]
	v_lshl_add_u64 v[22:23], v[58:59], 1, v[22:23]
	global_load_dwordx2 v[24:25], v[22:23], off
	v_lshlrev_b64 v[26:27], 14, v[94:95]
	v_lshl_add_u64 v[26:27], s[42:43], 0, v[26:27]
	v_lshl_add_u64 v[26:27], v[58:59], 2, v[26:27]
	s_mov_b64 s[0:1], 0
	s_waitcnt vmcnt(0) lgkmcnt(0)
	v_lshlrev_b32_e32 v22, 16, v24
	v_and_b32_e32 v23, 0xffff0000, v24
	v_lshlrev_b32_e32 v24, 16, v25
	v_and_b32_e32 v25, 0xffff0000, v25
	v_pk_fma_f32 v[22:23], v[22:23], s[76:77], v[18:19] op_sel_hi:[1,0,1]
	v_pk_fma_f32 v[24:25], v[24:25], s[76:77], v[20:21] op_sel_hi:[1,0,1]
	flat_store_dwordx4 v[26:27], v[22:25]

; __device__ __forceinline__ float bflo(unsigned u) { return __uint_as_float(u << 16); }
; __device__ __forceinline__ float bfhi(unsigned u) { return __uint_as_float(u & 0xffff0000u); }
; __device__ __forceinline__ void epilogue(const Params& p, int mode, const float* resid, int r, int c, f32x4 v) {
;     ...
;   } else if (mode == EPI_RESID_B) {
;     u32x2 xr = *reinterpret_cast<const u32x2*>(WSP(u16, WS_HB) + (long)c * D + r);
;     f32x4 o = {ALPHA * bflo(xr[0]) + v[0], ALPHA * bfhi(xr[0]) + v[1], ALPHA * bflo(xr[1]) + v[2], ALPHA * bfhi(xr[1]) + v[3]};
;     *reinterpret_cast<f32x4*>(WSP(float, WS_PRE) + (long)c * D + r) = o;
.LBB0_1167:
	s_andn2_b64 vcc, exec, s[0:1]
	s_cbranch_vccnz .LBB0_1172
	s_cmp_gt_i32 s90, 4
	s_mov_b64 s[0:1], -1
	s_cbranch_scc0 .LBB0_1170
	v_ashrrev_i32_e32 v99, 31, v98
	v_lshlrev_b64 v[18:19], 13, v[98:99]
	v_lshl_add_u64 v[18:19], s[40:41], 0, v[18:19]
	v_lshl_add_u64 v[18:19], v[50:51], 1, v[18:19]
	global_load_dwordx2 v[20:21], v[18:19], off
	v_lshlrev_b64 v[22:23], 14, v[98:99]
	v_lshl_add_u64 v[22:23], s[42:43], 0, v[22:23]
	v_lshl_add_u64 v[22:23], v[50:51], 2, v[22:23]
	s_mov_b64 s[0:1], 0
	s_waitcnt vmcnt(0) lgkmcnt(0)
	v_lshlrev_b32_e32 v18, 16, v20
	v_and_b32_e32 v19, 0xffff0000, v20
	v_lshlrev_b32_e32 v20, 16, v21
	v_and_b32_e32 v21, 0xffff0000, v21
	v_pk_fma_f32 v[18:19], v[18:19], s[76:77], v[14:15] op_sel_hi:[1,0,1]
	v_pk_fma_f32 v[20:21], v[20:21], s[76:77], v[16:17] op_sel_hi:[1,0,1]
	flat_store_dwordx4 v[22:23], v[18:21]

; __device__ __forceinline__ float bflo(unsigned u) { return __uint_as_float(u << 16); }
; __device__ __forceinline__ float bfhi(unsigned u) { return __uint_as_float(u & 0xffff0000u); }
; __device__ __forceinline__ void epilogue(const Params& p, int mode, const float* resid, int r, int c, f32x4 v) {
;     ...
;   } else if (mode == EPI_RESID_B) {
;     u32x2 xr = *reinterpret_cast<const u32x2*>(WSP(u16, WS_HB) + (long)c * D + r);
;     f32x4 o = {ALPHA * bflo(xr[0]) + v[0], ALPHA * bfhi(xr[0]) + v[1], ALPHA * bflo(xr[1]) + v[2], ALPHA * bfhi(xr[1]) + v[3]};
;     *reinterpret_cast<f32x4*>(WSP(float, WS_PRE) + (long)c * D + r) = o;
.LBB0_1194:
	s_andn2_b64 vcc, exec, s[0:1]
	s_cbranch_vccnz .LBB0_1199
	s_cmp_gt_i32 s90, 4
	s_mov_b64 s[0:1], -1
	s_cbranch_scc0 .LBB0_1197
	v_ashrrev_i32_e32 v95, 31, v94
	v_lshlrev_b64 v[14:15], 13, v[94:95]
	v_lshl_add_u64 v[14:15], s[40:41], 0, v[14:15]
	v_lshl_add_u64 v[14:15], v[50:51], 1, v[14:15]
	global_load_dwordx2 v[16:17], v[14:15], off
	v_lshlrev_b64 v[18:19], 14, v[94:95]
	v_lshl_add_u64 v[18:19], s[42:43], 0, v[18:19]
	v_lshl_add_u64 v[18:19], v[50:51], 2, v[18:19]
	s_mov_b64 s[0:1], 0
	s_waitcnt vmcnt(0) lgkmcnt(0)
	v_lshlrev_b32_e32 v14, 16, v16
	v_and_b32_e32 v15, 0xffff0000, v16
	v_lshlrev_b32_e32 v16, 16, v17
	v_and_b32_e32 v17, 0xffff0000, v17
	v_pk_fma_f32 v[14:15], v[14:15], s[76:77], v[10:11] op_sel_hi:[1,0,1]
	v_pk_fma_f32 v[16:17], v[16:17], s[76:77], v[12:13] op_sel_hi:[1,0,1]
	flat_store_dwordx4 v[18:19], v[14:17]

; __device__ __forceinline__ float bflo(unsigned u) { return __uint_as_float(u << 16); }
; __device__ __forceinline__ float bfhi(unsigned u) { return __uint_as_float(u & 0xffff0000u); }
; __device__ __forceinline__ void epilogue(const Params& p, int mode, const float* resid, int r, int c, f32x4 v) {
;     ...
;   } else if (mode == EPI_RESID_B) {
;     u32x2 xr = *reinterpret_cast<const u32x2*>(WSP(u16, WS_HB) + (long)c * D + r);
;     f32x4 o = {ALPHA * bflo(xr[0]) + v[0], ALPHA * bfhi(xr[0]) + v[1], ALPHA * bflo(xr[1]) + v[2], ALPHA * bfhi(xr[1]) + v[3]};
;     *reinterpret_cast<f32x4*>(WSP(float, WS_PRE) + (long)c * D + r) = o;
.LBB0_1221:
	s_andn2_b64 vcc, exec, s[0:1]
	s_cbranch_vccnz .LBB0_1226
	s_cmp_gt_i32 s90, 4
	s_mov_b64 s[0:1], -1
	s_cbranch_scc0 .LBB0_1224
	v_ashrrev_i32_e32 v99, 31, v98
	v_lshlrev_b64 v[10:11], 13, v[98:99]
	v_lshl_add_u64 v[10:11], s[40:41], 0, v[10:11]
	v_lshl_add_u64 v[10:11], v[42:43], 1, v[10:11]
	global_load_dwordx2 v[12:13], v[10:11], off
	v_lshlrev_b64 v[14:15], 14, v[98:99]
	v_lshl_add_u64 v[14:15], s[42:43], 0, v[14:15]
	v_lshl_add_u64 v[14:15], v[42:43], 2, v[14:15]
	s_mov_b64 s[0:1], 0
	s_waitcnt vmcnt(0) lgkmcnt(0)
	v_lshlrev_b32_e32 v10, 16, v12
	v_and_b32_e32 v11, 0xffff0000, v12
	v_lshlrev_b32_e32 v12, 16, v13
	v_and_b32_e32 v13, 0xffff0000, v13
	v_pk_fma_f32 v[10:11], v[10:11], s[76:77], v[6:7] op_sel_hi:[1,0,1]
	v_pk_fma_f32 v[12:13], v[12:13], s[76:77], v[8:9] op_sel_hi:[1,0,1]
	flat_store_dwordx4 v[14:15], v[10:13]

; __device__ __forceinline__ float bflo(unsigned u) { return __uint_as_float(u << 16); }
; __device__ __forceinline__ float bfhi(unsigned u) { return __uint_as_float(u & 0xffff0000u); }
; __device__ __forceinline__ void epilogue(const Params& p, int mode, const float* resid, int r, int c, f32x4 v) {
;     ...
;   } else if (mode == EPI_RESID_B) {
;     u32x2 xr = *reinterpret_cast<const u32x2*>(WSP(u16, WS_HB) + (long)c * D + r);
;     f32x4 o = {ALPHA * bflo(xr[0]) + v[0], ALPHA * bfhi(xr[0]) + v[1], ALPHA * bflo(xr[1]) + v[2], ALPHA * bfhi(xr[1]) + v[3]};
;     *reinterpret_cast<f32x4*>(WSP(float, WS_PRE) + (long)c * D + r) = o;
.LBB0_1248:
	s_andn2_b64 vcc, exec, s[0:1]
	s_cbranch_vccnz .LBB0_1253
	s_cmp_gt_i32 s90, 4
	s_mov_b64 s[0:1], -1
	s_cbranch_scc0 .LBB0_1251
	v_ashrrev_i32_e32 v95, 31, v94
	v_lshlrev_b64 v[6:7], 13, v[94:95]
	v_lshl_add_u64 v[6:7], s[40:41], 0, v[6:7]
	v_lshl_add_u64 v[6:7], v[42:43], 1, v[6:7]
	global_load_dwordx2 v[8:9], v[6:7], off
	v_lshlrev_b64 v[10:11], 14, v[94:95]
	v_lshl_add_u64 v[10:11], s[42:43], 0, v[10:11]
	v_lshl_add_u64 v[10:11], v[42:43], 2, v[10:11]
	s_mov_b64 s[0:1], 0
	s_waitcnt vmcnt(0) lgkmcnt(0)
	v_lshlrev_b32_e32 v6, 16, v8
	v_and_b32_e32 v7, 0xffff0000, v8
	v_lshlrev_b32_e32 v8, 16, v9
	v_and_b32_e32 v9, 0xffff0000, v9
	v_pk_fma_f32 v[6:7], v[6:7], s[76:77], v[2:3] op_sel_hi:[1,0,1]
	v_pk_fma_f32 v[8:9], v[8:9], s[76:77], v[4:5] op_sel_hi:[1,0,1]
	flat_store_dwordx4 v[10:11], v[6:9]

; __device__ __forceinline__ unsigned xb_ld(unsigned* p) { return __hip_atomic_load(p, __ATOMIC_RELAXED, __HIP_MEMORY_SCOPE_AGENT); }
; __device__ __forceinline__ unsigned xb_add(unsigned* p, unsigned v) { return __hip_atomic_fetch_add(p, v, __ATOMIC_RELAXED, __HIP_MEMORY_SCOPE_AGENT); }
; #define XB_SPIN(cond, bar) do { unsigned _sp = 0; while (cond) { __builtin_amdgcn_s_sleep(1); \
;     if ((++_sp & 255u) == 0u) { if (xb_ld(&(bar)[XB_TMO])) break; if (_sp > XB_SPIN_CAP) { atomicAdd(&(bar)[XB_TMO], 1u); break; } } } } while (0)
; __device__ __forceinline__ void xcd_barrier(const XcdBarrier& b) {
;   asm volatile("s_waitcnt vmcnt(0)" ::: "memory");
;   __syncthreads();
;   if (threadIdx.x == 0) {
;     unsigned* bar = b.bar;
;     __builtin_amdgcn_s_waitcnt(0);
;     const unsigned old = xb_add(&bar[XB_XSUB(b.x)], 1u);
;     const unsigned gen = old / b.nloc;
;     if (old + 1u == (gen + 1u) * b.nloc) {
;       __builtin_amdgcn_fence(__ATOMIC_RELEASE, "agent");
;       asm volatile("s_waitcnt vmcnt(0)" ::: "memory");
;       const unsigned og = xb_add(&bar[XB_TOP], 1u);
;       const unsigned tg = og / b.nx;
;       if (og + 1u == (tg + 1u) * b.nx) xb_add(&bar[XB_TOPGEN], 1u);
;       else XB_SPIN(xb_ld(&bar[XB_TOPGEN]) == tg, bar);
;       __builtin_amdgcn_fence(__ATOMIC_ACQUIRE, "agent");
;       xb_add(&bar[XB_XGEN(b.x)], 1u);
;     } else {
;       XB_SPIN(xb_ld(&bar[XB_XGEN(b.x)]) == gen, bar);
.LBB0_1338:
	s_add_i32 s24, s84, 1
	s_cmp_ge_i32 s24, s31
	s_cbranch_scc1 .LBB0_2
	s_cmp_lg_u32 s84, s30
	s_mov_b64 s[0:1], -1
	s_cbranch_scc0 .LBB0_1371
	s_waitcnt vmcnt(0)
	s_waitcnt lgkmcnt(0)
	s_barrier
	s_mov_b64 s[4:5], exec
	v_readlane_b32 s0, v248, 21
	v_readlane_b32 s1, v248, 22
	s_and_b64 s[0:1], s[4:5], s[0:1]
	s_mov_b64 exec, s[0:1]
	s_cbranch_execz .LBB0_1370
	v_readlane_b32 s6, v248, 59
	s_lshl_b32 s22, s6, 6
	s_add_i32 s96, s22, 0x500
	s_lshl_b64 s[0:1], s[96:97], 2
	v_readlane_b32 s2, v248, 3
	v_readlane_b32 s3, v248, 4
	s_add_u32 s0, s2, s0
	s_addc_u32 s1, s3, s1
	v_mov_b64_e32 v[2:3], s[0:1]
	s_waitcnt vmcnt(0) expcnt(0) lgkmcnt(0)
	flat_atomic_add v2, v[2:3], v166 sc0
	v_readlane_b32 s7, v248, 60
	s_sub_i32 s0, 0, s7
	s_nop 0
	v_cvt_f32_u32_e32 v0, s7
	v_rcp_iflag_f32_e32 v0, v0
	s_nop 0
	v_mul_f32_e32 v0, 0x4f7ffffe, v0
	v_cvt_u32_f32_e32 v0, v0
	v_mul_lo_u32 v3, s0, v0
	v_mul_hi_u32 v3, v0, v3
	v_add_u32_e32 v0, v0, v3
	s_waitcnt vmcnt(0) lgkmcnt(0)
	v_mul_hi_u32 v0, v2, v0
	v_mul_lo_u32 v3, v0, s7
	v_sub_u32_e32 v3, v2, v3
	v_add_u32_e32 v4, 1, v0
	v_cmp_le_u32_e32 vcc, s7, v3
	v_add_u32_e32 v2, 1, v2
	s_nop 0
	v_cndmask_b32_e32 v0, v0, v4, vcc
	v_subrev_u32_e32 v4, s7, v3
	v_cndmask_b32_e32 v3, v3, v4, vcc
	v_add_u32_e32 v4, 1, v0
	v_cmp_le_u32_e32 vcc, s7, v3
	s_nop 1
	v_cndmask_b32_e32 v0, v0, v4, vcc
	v_mul_lo_u32 v3, s7, v0
	v_add_u32_e32 v3, s7, v3
	v_cmp_ne_u32_e32 vcc, v2, v3
	s_and_saveexec_b64 s[0:1], vcc
	s_xor_b64 s[2:3], exec, s[0:1]
	s_cbranch_execz .LBB0_1354
	s_add_i32 s96, s22, 0x900
	s_lshl_b64 s[0:1], s[96:97], 2
	v_readlane_b32 s6, v248, 3
	v_readlane_b32 s7, v248, 4
	s_add_u32 s6, s6, s0
	s_addc_u32 s7, s7, s1
	v_mov_b64_e32 v[2:3], s[6:7]
	global_load_dword v2, v[2:3], off sc1
	s_waitcnt vmcnt(0) lgkmcnt(0)
	v_cmp_eq_u32_e32 vcc, v2, v0
	s_and_saveexec_b64 s[0:1], vcc
	s_cbranch_execz .LBB0_1353
	s_mov_b32 s23, 1
	s_mov_b64 s[8:9], 0
	s_branch .LBB0_1345

; __device__ __forceinline__ unsigned xb_ld(unsigned* p) { return __hip_atomic_load(p, __ATOMIC_RELAXED, __HIP_MEMORY_SCOPE_AGENT); }
; #define XB_SPIN(cond, bar) do { unsigned _sp = 0; while (cond) { __builtin_amdgcn_s_sleep(1); \
;     if ((++_sp & 255u) == 0u) { if (xb_ld(&(bar)[XB_TMO])) break; if (_sp > XB_SPIN_CAP) { atomicAdd(&(bar)[XB_TMO], 1u); break; } } } } while (0)
; __device__ __forceinline__ void xcd_barrier(const XcdBarrier& b) {
;     ...
;       XB_SPIN(xb_ld(&bar[XB_XGEN(b.x)]) == gen, bar);
.LBB0_1345:
	s_and_b32 s16, s23, 0xff
	s_mov_b64 s[14:15], -1
	s_cmp_lg_u32 s16, 0
	s_mov_b64 s[16:17], -1
	s_sleep 1
	s_cbranch_scc1 .LBB0_1349
	v_readlane_b32 s16, v248, 3
	v_readlane_b32 s17, v248, 4
	s_mov_b64 s[18:19], -1
	s_nop 0
	v_mov_b64_e32 v[2:3], s[16:17]
	global_load_dword v2, v[2:3], off offset:512 sc1
	s_mov_b64 s[16:17], 0
	s_waitcnt vmcnt(0) lgkmcnt(0)
	v_cmp_eq_u32_e32 vcc, 0, v2
	s_and_saveexec_b64 s[20:21], vcc
	s_cmp_lt_u32 s23, 0x100001
	s_cselect_b64 s[16:17], -1, 0
	s_xor_b64 s[18:19], exec, -1
	s_and_b64 s[16:17], s[16:17], exec
	s_or_b64 exec, exec, s[20:21]
.LBB0_1349:
	s_andn2_b64 s[12:13], s[12:13], exec
	s_and_b64 s[18:19], s[18:19], exec
	s_or_b64 s[12:13], s[12:13], s[18:19]
	s_and_saveexec_b64 s[18:19], s[16:17]
	s_cbranch_execz .LBB0_1344
	v_mov_b64_e32 v[2:3], s[6:7]
	global_load_dword v2, v[2:3], off sc1
	s_add_i32 s23, s23, 1
	s_or_b64 s[12:13], s[12:13], exec
	s_waitcnt vmcnt(0) lgkmcnt(0)
	v_cmp_ne_u32_e32 vcc, v2, v0
	s_orn2_b64 s[14:15], vcc, exec
	s_branch .LBB0_1344

; __device__ __forceinline__ unsigned xb_ld(unsigned* p) { return __hip_atomic_load(p, __ATOMIC_RELAXED, __HIP_MEMORY_SCOPE_AGENT); }
; __device__ __forceinline__ unsigned xb_add(unsigned* p, unsigned v) { return __hip_atomic_fetch_add(p, v, __ATOMIC_RELAXED, __HIP_MEMORY_SCOPE_AGENT); }
; #define XB_SPIN(cond, bar) do { unsigned _sp = 0; while (cond) { __builtin_amdgcn_s_sleep(1); \
;     if ((++_sp & 255u) == 0u) { if (xb_ld(&(bar)[XB_TMO])) break; if (_sp > XB_SPIN_CAP) { atomicAdd(&(bar)[XB_TMO], 1u); break; } } } } while (0)
; __device__ __forceinline__ void xcd_barrier(const XcdBarrier& b) {
;     ...
;     if (old + 1u == (gen + 1u) * b.nloc) {
;       __builtin_amdgcn_fence(__ATOMIC_RELEASE, "agent");
;       asm volatile("s_waitcnt vmcnt(0)" ::: "memory");
;       const unsigned og = xb_add(&bar[XB_TOP], 1u);
;       const unsigned tg = og / b.nx;
;       if (og + 1u == (tg + 1u) * b.nx) xb_add(&bar[XB_TOPGEN], 1u);
;       else XB_SPIN(xb_ld(&bar[XB_TOPGEN]) == tg, bar);
.LBB0_1354:
	s_andn2_saveexec_b64 s[0:1], s[2:3]
	s_cbranch_execz .LBB0_1370
	v_readlane_b32 s0, v248, 3
	v_readlane_b32 s1, v248, 4
	buffer_wbl2 sc1
	v_mov_b32_e32 v0, s0
	v_add_co_u32_e32 v2, vcc, 0x3000, v0
	v_mov_b32_e32 v0, s1
	s_waitcnt vmcnt(0)
	s_nop 0
	v_addc_co_u32_e32 v3, vcc, 0, v0, vcc
	flat_atomic_add v2, v[2:3], v166 offset:1024 sc0
	v_cvt_f32_u32_e32 v0, v132
	v_sub_u32_e32 v3, 0, v132
	s_add_u32 s6, s0, 0x3500
	s_addc_u32 s7, s1, 0
	v_rcp_iflag_f32_e32 v0, v0
	s_mov_b64 s[0:1], -1
	v_mul_f32_e32 v0, 0x4f7ffffe, v0
	v_cvt_u32_f32_e32 v0, v0
	v_mul_lo_u32 v3, v3, v0
	v_mul_hi_u32 v3, v0, v3
	v_add_u32_e32 v0, v0, v3
	s_waitcnt vmcnt(0) lgkmcnt(0)
	v_mul_hi_u32 v0, v2, v0
	v_mul_lo_u32 v3, v0, v132
	v_sub_u32_e32 v3, v2, v3
	v_cmp_ge_u32_e32 vcc, v3, v132
	v_add_u32_e32 v4, 1, v0
	v_add_u32_e32 v2, 1, v2
	v_cndmask_b32_e32 v0, v0, v4, vcc
	v_sub_u32_e32 v4, v3, v132
	v_cndmask_b32_e32 v3, v3, v4, vcc
	v_cmp_ge_u32_e32 vcc, v3, v132
	v_add_u32_e32 v3, 1, v0
	s_nop 0
	v_cndmask_b32_e32 v0, v0, v3, vcc
	v_mul_lo_u32 v3, v132, v0
	v_add_u32_e32 v3, v3, v132
	v_cmp_ne_u32_e32 vcc, v2, v3
	v_mov_b64_e32 v[2:3], s[6:7]
	s_and_saveexec_b64 s[2:3], vcc
	s_cbranch_execz .LBB0_1367
	v_mov_b64_e32 v[2:3], s[6:7]
	global_load_dword v2, v[2:3], off sc1
	s_mov_b64 s[10:11], 0
	s_waitcnt vmcnt(0) lgkmcnt(0)
	v_cmp_eq_u32_e32 vcc, v2, v0
	s_and_saveexec_b64 s[8:9], vcc
	s_cbranch_execz .LBB0_1366
	v_readlane_b32 s0, v248, 3
	v_readlane_b32 s1, v248, 4
	s_add_u32 s0, s0, 0x200
	s_addc_u32 s1, s1, 0
	s_mov_b32 s23, 1
	s_branch .LBB0_1359

; __device__ __forceinline__ unsigned xb_ld(unsigned* p) { return __hip_atomic_load(p, __ATOMIC_RELAXED, __HIP_MEMORY_SCOPE_AGENT); }
; #define XB_SPIN(cond, bar) do { unsigned _sp = 0; while (cond) { __builtin_amdgcn_s_sleep(1); \
;     if ((++_sp & 255u) == 0u) { if (xb_ld(&(bar)[XB_TMO])) break; if (_sp > XB_SPIN_CAP) { atomicAdd(&(bar)[XB_TMO], 1u); break; } } } } while (0)
; __device__ __forceinline__ void xcd_barrier(const XcdBarrier& b) {
;     ...
;       else XB_SPIN(xb_ld(&bar[XB_TOPGEN]) == tg, bar);
.LBB0_1361:
	v_mov_b64_e32 v[2:3], s[0:1]
	global_load_dword v2, v[2:3], off sc1
	s_mov_b64 s[18:19], 0
	s_mov_b64 s[16:17], -1
	s_waitcnt vmcnt(0) lgkmcnt(0)
	v_cmp_eq_u32_e32 vcc, 0, v2
	s_and_saveexec_b64 s[20:21], vcc
	s_cmp_lt_u32 s23, 0x100001
	s_cselect_b64 s[18:19], -1, 0
	s_xor_b64 s[16:17], exec, -1
	s_and_b64 s[18:19], s[18:19], exec
	s_or_b64 exec, exec, s[20:21]
	s_and_saveexec_b64 s[20:21], s[18:19]
	s_cbranch_execz .LBB0_1358
.LBB0_1364:
	v_mov_b64_e32 v[2:3], s[6:7]
	global_load_dword v2, v[2:3], off sc1
	s_add_i32 s23, s23, 1
	s_or_b64 s[16:17], s[16:17], exec
	s_waitcnt vmcnt(0) lgkmcnt(0)
	v_cmp_ne_u32_e32 vcc, v2, v0
	s_orn2_b64 s[14:15], vcc, exec
	s_branch .LBB0_1358

; __device__ __forceinline__ unsigned xb_ld(unsigned* p) { return __hip_atomic_load(p, __ATOMIC_RELAXED, __HIP_MEMORY_SCOPE_AGENT); }
; __device__ __forceinline__ unsigned xb_add(unsigned* p, unsigned v) { return __hip_atomic_fetch_add(p, v, __ATOMIC_RELAXED, __HIP_MEMORY_SCOPE_AGENT); }
; __device__ __forceinline__ unsigned xb_xcc_id() { return (unsigned)__builtin_amdgcn_s_getreg((3 << 11) | 20) & 0xFu; }
; #define XB_SPIN(cond, bar) do { unsigned _sp = 0; while (cond) { __builtin_amdgcn_s_sleep(1); \
;     if ((++_sp & 255u) == 0u) { if (xb_ld(&(bar)[XB_TMO])) break; if (_sp > XB_SPIN_CAP) { atomicAdd(&(bar)[XB_TMO], 1u); break; } } } } while (0)
;   __shared__ uint4 xb_sh;
;   if (threadIdx.x == 0) {
;     const unsigned x = xb_xcc_id();
;     xb_add(&bar[XB_XCNT(x)], 1u);
;     __threadfence();
;     const unsigned G = gridDim.x * gridDim.y * gridDim.z;
;     const unsigned old = xb_add(&bar[XB_CNT], 1u), gen = old / G;
;     if (old + 1u == (gen + 1u) * G) xb_add(&bar[XB_GEN], 1u); else XB_SPIN(xb_ld(&bar[XB_GEN]) == gen, bar);
.LBB0_1382:
	s_or_b64 exec, exec, s[0:1]
	s_add_u32 s0, s82, 0x3dc10400
	s_addc_u32 s1, s83, 0
	v_writelane_b32 v248, s0, 3
	s_barrier
	s_nop 0
	v_writelane_b32 v248, s1, 4
	s_mov_b64 s[4:5], exec
	v_readlane_b32 s0, v248, 21
	v_readlane_b32 s1, v248, 22
	s_and_b64 s[0:1], s[4:5], s[0:1]
	s_mov_b64 exec, s[0:1]
	s_cbranch_execz .LBB0_1399
	s_getreg_b32 s0, hwreg(HW_REG_XCC_ID, 0, 4)
	s_and_b32 s25, s0, 15
	s_lshl_b32 s0, s25, 8
	v_readlane_b32 s2, v248, 3
	v_readlane_b32 s3, v248, 4
	s_add_u32 s6, s2, s0
	s_addc_u32 s7, s3, 0
	v_mov_b64_e32 v[2:3], s[6:7]
	flat_atomic_add v[2:3], v166 offset:1024
	v_mov_b64_e32 v[2:3], s[2:3]
	buffer_wbl2 sc1
	s_waitcnt vmcnt(0) lgkmcnt(0)
	buffer_inv sc1
	flat_atomic_add v2, v[2:3], v166 sc0
	v_readlane_b32 s0, v248, 45
	s_add_u32 s8, s82, 0x3dc10500
	s_addc_u32 s9, s83, 0
	s_waitcnt vmcnt(0) lgkmcnt(0)
	v_mul_hi_u32 v0, v2, v181
	v_mul_lo_u32 v3, v0, s0
	v_sub_u32_e32 v3, v2, v3
	v_cmp_le_u32_e32 vcc, s0, v3
	v_add_u32_e32 v4, 1, v0
	v_add_u32_e32 v2, 1, v2
	v_cndmask_b32_e32 v0, v0, v4, vcc
	v_subrev_u32_e32 v4, s0, v3
	v_cndmask_b32_e32 v3, v3, v4, vcc
	v_cmp_le_u32_e32 vcc, s0, v3
	v_add_u32_e32 v3, 1, v0
	s_nop 0
	v_cndmask_b32_e32 v0, v0, v3, vcc
	v_mul_lo_u32 v3, s0, v0
	v_add_u32_e32 v3, s0, v3
	v_cmp_ne_u32_e32 vcc, v2, v3
	s_mov_b64 s[0:1], -1
	v_mov_b64_e32 v[2:3], s[8:9]
	s_and_saveexec_b64 s[2:3], vcc
	s_cbranch_execz .LBB0_1396
	v_mov_b64_e32 v[2:3], s[8:9]
	global_load_dword v2, v[2:3], off sc1
	s_mov_b64 s[12:13], 0
	s_waitcnt vmcnt(0) lgkmcnt(0)
	v_cmp_eq_u32_e32 vcc, v2, v0
	s_and_saveexec_b64 s[10:11], vcc
	s_cbranch_execz .LBB0_1395
	s_add_u32 s0, s82, 0x3dc10600
	s_addc_u32 s1, s83, 0
	s_mov_b32 s26, 1
	s_branch .LBB0_1387

; __device__ __forceinline__ unsigned xb_ld(unsigned* p) { return __hip_atomic_load(p, __ATOMIC_RELAXED, __HIP_MEMORY_SCOPE_AGENT); }
; __device__ __forceinline__ unsigned xb_add(unsigned* p, unsigned v) { return __hip_atomic_fetch_add(p, v, __ATOMIC_RELAXED, __HIP_MEMORY_SCOPE_AGENT); }
; #define XB_SPIN(cond, bar) do { unsigned _sp = 0; while (cond) { __builtin_amdgcn_s_sleep(1); \
;     if ((++_sp & 255u) == 0u) { if (xb_ld(&(bar)[XB_TMO])) break; if (_sp > XB_SPIN_CAP) { atomicAdd(&(bar)[XB_TMO], 1u); break; } } } } while (0)
;     ...
;     if (old + 1u == (gen + 1u) * G) xb_add(&bar[XB_GEN], 1u); else XB_SPIN(xb_ld(&bar[XB_GEN]) == gen, bar);
.LBB0_1389:
	v_mov_b64_e32 v[2:3], s[0:1]
	global_load_dword v2, v[2:3], off sc1
	s_mov_b64 s[20:21], 0
	s_mov_b64 s[18:19], -1
	s_waitcnt vmcnt(0) lgkmcnt(0)
	v_cmp_eq_u32_e32 vcc, 0, v2
	s_and_saveexec_b64 s[22:23], vcc
	s_cmp_lt_u32 s26, 0x100001
	s_cselect_b64 s[20:21], -1, 0
	s_xor_b64 s[18:19], exec, -1
	s_and_b64 s[20:21], s[20:21], exec
	s_or_b64 exec, exec, s[22:23]
	s_and_saveexec_b64 s[22:23], s[20:21]
	s_cbranch_execz .LBB0_1386
.LBB0_1392:
	v_mov_b64_e32 v[2:3], s[8:9]
	global_load_dword v2, v[2:3], off sc1
	s_add_i32 s26, s26, 1
	s_or_b64 s[18:19], s[18:19], exec
	s_waitcnt vmcnt(0) lgkmcnt(0)
	v_cmp_ne_u32_e32 vcc, v2, v0
	s_orn2_b64 s[16:17], vcc, exec
	s_branch .LBB0_1386

; __device__ __forceinline__ unsigned xb_ld(unsigned* p) { return __hip_atomic_load(p, __ATOMIC_RELAXED, __HIP_MEMORY_SCOPE_AGENT); }
;     ...
;     __threadfence();
;     unsigned nx = 0; for (unsigned j = 0; j < 16; ++j) nx += (xb_ld(&bar[XB_XCNT(j)]) > 0u);
;     xb_sh = make_uint4(x, xb_ld(&bar[XB_XCNT(x)]), nx, 0u);
.LBB0_1398:
	s_or_b64 exec, exec, s[2:3]
	v_mov_b32_e32 v0, s82
	v_add_co_u32_e32 v2, vcc, 0x3dc10000, v0
	v_mov_b32_e32 v4, s83
	s_nop 0
	v_addc_co_u32_e32 v3, vcc, 0, v4, vcc
	buffer_wbl2 sc1
	s_waitcnt vmcnt(0) lgkmcnt(0)
	buffer_inv sc1
	global_load_dword v5, v[2:3], off offset:2048 sc1
	global_load_dword v6, v[2:3], off offset:2304 sc1
	global_load_dword v7, v[2:3], off offset:2560 sc1
	global_load_dword v8, v[2:3], off offset:2816 sc1
	global_load_dword v9, v[2:3], off offset:3072 sc1
	global_load_dword v10, v[2:3], off offset:3328 sc1
	global_load_dword v11, v[2:3], off offset:3584 sc1
	global_load_dword v12, v[2:3], off offset:3840 sc1
	s_mov_b32 s0, 0x3dc11000
	v_add_co_u32_e32 v2, vcc, s0, v0
	s_nop 1
	v_addc_co_u32_e32 v3, vcc, 0, v4, vcc
	global_load_dword v0, v[2:3], off sc1
	global_load_dword v4, v[2:3], off offset:256 sc1
	global_load_dword v13, v[2:3], off offset:512 sc1
	global_load_dword v14, v[2:3], off offset:768 sc1
	global_load_dword v15, v[2:3], off offset:1024 sc1
	global_load_dword v16, v[2:3], off offset:1280 sc1
	global_load_dword v17, v[2:3], off offset:1536 sc1
	global_load_dword v18, v[2:3], off offset:1792 sc1
	v_mov_b64_e32 v[2:3], s[6:7]
	global_load_dword v3, v[2:3], off offset:1024 sc1
	v_mov_b32_e32 v2, s25
	s_waitcnt vmcnt(0) lgkmcnt(0)
	v_cmp_ne_u32_e32 vcc, 0, v5
	s_nop 1
	v_cndmask_b32_e64 v5, 0, 1, vcc
	v_cmp_ne_u32_e32 vcc, 0, v7
	s_nop 1
	v_cndmask_b32_e64 v7, 0, 1, vcc
	v_cmp_ne_u32_e32 vcc, 0, v9
	s_nop 1
	v_cndmask_b32_e64 v9, 0, 1, vcc
	v_cmp_ne_u32_e32 vcc, 0, v11
	s_nop 1
	v_cndmask_b32_e64 v11, 0, 1, vcc
	v_cmp_ne_u32_e32 vcc, 0, v0
	s_nop 1
	v_cndmask_b32_e64 v0, 0, 1, vcc
	v_cmp_ne_u32_e32 vcc, 0, v13
	s_nop 1
	v_cndmask_b32_e64 v13, 0, 1, vcc
	v_cmp_ne_u32_e32 vcc, 0, v15
	s_nop 1
	v_cndmask_b32_e64 v15, 0, 1, vcc
	v_cmp_ne_u32_e32 vcc, 0, v17
	s_nop 1
	v_cndmask_b32_e64 v17, 0, 1, vcc
	v_cmp_ne_u32_e32 vcc, 0, v6
	s_nop 1
	v_addc_co_u32_e32 v5, vcc, 0, v5, vcc
	v_cmp_ne_u32_e32 vcc, 0, v8
	s_nop 1
	v_addc_co_u32_e32 v5, vcc, v5, v7, vcc
	v_cmp_ne_u32_e32 vcc, 0, v10
	s_nop 1
	v_addc_co_u32_e32 v5, vcc, v5, v9, vcc
	v_cmp_ne_u32_e32 vcc, 0, v12
	s_nop 1
	v_addc_co_u32_e32 v5, vcc, v5, v11, vcc
	v_cmp_ne_u32_e32 vcc, 0, v4
	s_nop 1
	v_addc_co_u32_e32 v0, vcc, v5, v0, vcc
	v_cmp_ne_u32_e32 vcc, 0, v14
	v_mov_b32_e32 v5, v1
	s_nop 0
	v_addc_co_u32_e32 v0, vcc, v0, v13, vcc
	v_cmp_ne_u32_e32 vcc, 0, v16
	s_nop 1
	v_addc_co_u32_e32 v0, vcc, v0, v15, vcc
	v_cmp_ne_u32_e32 vcc, 0, v18
	s_nop 1
	v_addc_co_u32_e32 v4, vcc, v0, v17, vcc
	ds_write_b128 v1, v[2:5] offset:16
